# v13 + 350 already-satisfied lgkmcnt waits removed from the GEMM MMA segments (explicit lgkmcnt(0)+barrier precedes each)
# baseline (speedup 1.0000x reference)
; #define LDA(dst, b, h) for (int m = 0; m < 4; ++m) for (int k = 0; k < 2; ++k) \
;     dst[m][k] = *reinterpret_cast<const bf16x8*>((char*)SA(b, h) + lds_byte(wr * 64 + m * 16 + fr, k * 32 + fq * 8))
; #define LDB(dst, b, h) for (int n = 0; n < 2; ++n) for (int k = 0; k < 2; ++k) \
;     dst[n][k] = *reinterpret_cast<const bf16x8*>((char*)SB(b, h) + lds_byte(wc * 32 + n * 16 + fr, k * 32 + fq * 8))
; #define MMA(ai, bj, At, Bt_) do { __builtin_amdgcn_s_setprio(1); \
;     for (int m = 0; m < 4; ++m) for (int n = 0; n < 2; ++n) for (int k = 0; k < 2; ++k) \
;       acc[ai][bj][m][n] = __builtin_amdgcn_mfma_f32_16x16x32_bf16(Bt_[n][k], At[m][k], acc[ai][bj][m][n], 0, 0, 0); \
;     __builtin_amdgcn_s_setprio(0); } while (0)
; #define WAIT_V(n) asm volatile("s_waitcnt vmcnt(" #n ")" ::: "memory")
; #define WAIT_L(n) asm volatile("s_waitcnt lgkmcnt(" #n ")" ::: "memory")
; #define BAR __builtin_amdgcn_s_barrier()
; #define SCHED __builtin_amdgcn_sched_barrier(0)
; template <int MODE>
; DI void gemm_phase(const bf16_t* __restrict__ A, const bf16_t* __restrict__ Bt, int M, int N, int K, const Epi& ep) {
;     ...
;             LDB(B0, 0, 0); LDB(B1, 0, 1); SCHED; LDA(At, 0, 0); STAGE(SA(1, 1), rsA, brow + HALF, t + 1);
;             WAIT_V(8); WAIT_L(0); BAR; MMA(0, 0, At, B0); MMA(0, 1, At, B1); BAR; SCHED;
;             LDA(At, 0, 1); STAGE(SB(0, 0), rsB, bcol, t + 2); STAGE(SB(0, 1), rsB, bcol + HALF, t + 2); STAGE(SA(0, 0), rsA, brow, t + 2);
;             WAIT_V(8); WAIT_L(0); BAR; MMA(1, 0, At, B0); MMA(1, 1, At, B1); BAR; SCHED;
.LBB0_91:
	ds_read_b128 v[156:159], v146
	ds_read_b128 v[160:163], v146 offset:1024
	ds_read_b128 v[164:167], v146 offset:2048
	ds_read_b128 v[168:171], v146 offset:3072
	ds_read_b128 v[172:175], v147
	ds_read_b128 v[176:179], v147 offset:1024
	ds_read_b128 v[180:183], v147 offset:2048
	ds_read_b128 v[184:187], v147 offset:3072
	s_add_i32 s41, s0, s40
	v_readfirstlane_b32 s7, v144
	s_add_i32 s6, s41, 0x40080
	s_mov_b32 m0, s7
	v_readfirstlane_b32 s7, v145
	ds_read_b128 v[188:191], v148
	ds_read_b128 v[192:195], v148 offset:1024
	ds_read_b128 v[196:199], v149
	ds_read_b128 v[200:203], v149 offset:1024
	ds_read_b128 v[204:207], v150
	ds_read_b128 v[208:211], v150 offset:1024
	ds_read_b128 v[214:217], v151
	ds_read_b128 v[218:221], v151 offset:1024
	buffer_load_dwordx4 v128, s[8:11], s6 offen lds
	s_mov_b32 m0, s7
	s_nop 0
	buffer_load_dwordx4 v129, s[8:11], s6 offen lds
	s_waitcnt vmcnt(8)
	s_waitcnt lgkmcnt(0)
	s_barrier
	s_setprio 1
	v_mfma_f32_16x16x32_bf16 v[124:127], v[156:159], v[188:191], v[124:127]
	v_mfma_f32_16x16x32_bf16 v[120:123], v[164:167], v[188:191], v[120:123]
	v_mfma_f32_16x16x32_bf16 v[116:119], v[156:159], v[196:199], v[116:119]
	v_mfma_f32_16x16x32_bf16 v[112:115], v[164:167], v[196:199], v[112:115]
	v_mfma_f32_16x16x32_bf16 v[108:111], v[156:159], v[204:207], v[108:111]
	v_mfma_f32_16x16x32_bf16 v[104:107], v[164:167], v[204:207], v[104:107]
	v_mfma_f32_16x16x32_bf16 v[100:103], v[156:159], v[214:217], v[100:103]
	v_mfma_f32_16x16x32_bf16 v[96:99], v[164:167], v[214:217], v[96:99]
	v_mfma_f32_16x16x32_bf16 v[124:127], v[160:163], v[192:195], v[124:127]
	v_mfma_f32_16x16x32_bf16 v[120:123], v[168:171], v[192:195], v[120:123]
	v_mfma_f32_16x16x32_bf16 v[116:119], v[160:163], v[200:203], v[116:119]
	v_mfma_f32_16x16x32_bf16 v[112:115], v[168:171], v[200:203], v[112:115]
	v_mfma_f32_16x16x32_bf16 v[108:111], v[160:163], v[208:211], v[108:111]
	v_mfma_f32_16x16x32_bf16 v[104:107], v[168:171], v[208:211], v[104:107]
	v_mfma_f32_16x16x32_bf16 v[100:103], v[160:163], v[218:221], v[100:103]
	v_mfma_f32_16x16x32_bf16 v[96:99], v[168:171], v[218:221], v[96:99]
	s_setprio 0
	s_setprio 1
	v_mfma_f32_16x16x32_bf16 v[92:95], v[172:175], v[188:191], v[92:95]
	v_mfma_f32_16x16x32_bf16 v[88:91], v[180:183], v[188:191], v[88:91]
	v_mfma_f32_16x16x32_bf16 v[84:87], v[172:175], v[196:199], v[84:87]
	v_mfma_f32_16x16x32_bf16 v[80:83], v[180:183], v[196:199], v[80:83]
	v_mfma_f32_16x16x32_bf16 v[76:79], v[172:175], v[204:207], v[76:79]
	v_mfma_f32_16x16x32_bf16 v[72:75], v[180:183], v[204:207], v[72:75]
	v_mfma_f32_16x16x32_bf16 v[68:71], v[172:175], v[214:217], v[68:71]
	v_mfma_f32_16x16x32_bf16 v[64:67], v[180:183], v[214:217], v[64:67]
	v_mfma_f32_16x16x32_bf16 v[92:95], v[176:179], v[192:195], v[92:95]
	v_mfma_f32_16x16x32_bf16 v[88:91], v[184:187], v[192:195], v[88:91]
	v_mfma_f32_16x16x32_bf16 v[84:87], v[176:179], v[200:203], v[84:87]
	v_mfma_f32_16x16x32_bf16 v[80:83], v[184:187], v[200:203], v[80:83]
	v_mfma_f32_16x16x32_bf16 v[76:79], v[176:179], v[208:211], v[76:79]
	v_mfma_f32_16x16x32_bf16 v[72:75], v[184:187], v[208:211], v[72:75]
	v_mfma_f32_16x16x32_bf16 v[68:71], v[176:179], v[218:221], v[68:71]
	v_mfma_f32_16x16x32_bf16 v[64:67], v[184:187], v[218:221], v[64:67]
	s_setprio 0
	s_barrier
	s_add_i32 s42, s1, s40
	v_readfirstlane_b32 s44, v130
	s_add_i32 s43, s42, 0x100
	s_mov_b32 s6, s10
	s_mov_b32 s7, s11
	s_mov_b32 m0, s44
	v_readfirstlane_b32 s44, v131
	ds_read_b128 v[188:191], v148 offset:16384
	ds_read_b128 v[192:195], v148 offset:17408
	ds_read_b128 v[196:199], v149 offset:16384
	ds_read_b128 v[200:203], v149 offset:17408
	ds_read_b128 v[204:207], v150 offset:16384
	ds_read_b128 v[208:211], v150 offset:17408
	ds_read_b128 v[214:217], v151 offset:16384
	ds_read_b128 v[218:221], v151 offset:17408
	buffer_load_dwordx4 v128, s[4:7], s43 offen lds
	s_mov_b32 m0, s44
	v_readfirstlane_b32 s44, v132
	buffer_load_dwordx4 v129, s[4:7], s43 offen lds
	s_add_i32 s43, s42, 0x40100
	s_mov_b32 m0, s44
	v_readfirstlane_b32 s44, v133
	buffer_load_dwordx4 v128, s[4:7], s43 offen lds
	s_mov_b32 m0, s44
	v_readfirstlane_b32 s44, v134
	buffer_load_dwordx4 v129, s[4:7], s43 offen lds
	s_add_i32 s43, s41, 0x100
	s_mov_b32 m0, s44
	v_readfirstlane_b32 s44, v135
	buffer_load_dwordx4 v128, s[8:11], s43 offen lds
	s_mov_b32 m0, s44
	s_nop 0
	buffer_load_dwordx4 v129, s[8:11], s43 offen lds
	s_waitcnt vmcnt(8)
	s_waitcnt lgkmcnt(0)
	s_barrier
	s_setprio 1
	v_mfma_f32_16x16x32_bf16 v[60:63], v[156:159], v[188:191], v[60:63]
	v_mfma_f32_16x16x32_bf16 v[56:59], v[164:167], v[188:191], v[56:59]
	v_mfma_f32_16x16x32_bf16 v[52:55], v[156:159], v[196:199], v[52:55]
	v_mfma_f32_16x16x32_bf16 v[48:51], v[164:167], v[196:199], v[48:51]
	v_mfma_f32_16x16x32_bf16 v[44:47], v[156:159], v[204:207], v[44:47]
	v_mfma_f32_16x16x32_bf16 v[40:43], v[164:167], v[204:207], v[40:43]
	v_mfma_f32_16x16x32_bf16 v[36:39], v[156:159], v[214:217], v[36:39]
	v_mfma_f32_16x16x32_bf16 v[32:35], v[164:167], v[214:217], v[32:35]
	v_mfma_f32_16x16x32_bf16 v[60:63], v[160:163], v[192:195], v[60:63]
	v_mfma_f32_16x16x32_bf16 v[56:59], v[168:171], v[192:195], v[56:59]
	v_mfma_f32_16x16x32_bf16 v[52:55], v[160:163], v[200:203], v[52:55]
	v_mfma_f32_16x16x32_bf16 v[48:51], v[168:171], v[200:203], v[48:51]
	v_mfma_f32_16x16x32_bf16 v[44:47], v[160:163], v[208:211], v[44:47]
	v_mfma_f32_16x16x32_bf16 v[40:43], v[168:171], v[208:211], v[40:43]
	v_mfma_f32_16x16x32_bf16 v[36:39], v[160:163], v[218:221], v[36:39]
	v_mfma_f32_16x16x32_bf16 v[32:35], v[168:171], v[218:221], v[32:35]
	s_setprio 0
	s_setprio 1
	v_mfma_f32_16x16x32_bf16 v[28:31], v[172:175], v[188:191], v[28:31]
	v_mfma_f32_16x16x32_bf16 v[24:27], v[180:183], v[188:191], v[24:27]
	v_mfma_f32_16x16x32_bf16 v[20:23], v[172:175], v[196:199], v[20:23]
	v_mfma_f32_16x16x32_bf16 v[16:19], v[180:183], v[196:199], v[16:19]
	v_mfma_f32_16x16x32_bf16 v[12:15], v[172:175], v[204:207], v[12:15]
	v_mfma_f32_16x16x32_bf16 v[8:11], v[180:183], v[204:207], v[8:11]
	v_mfma_f32_16x16x32_bf16 v[4:7], v[172:175], v[214:217], v[4:7]
	v_mfma_f32_16x16x32_bf16 v[0:3], v[180:183], v[214:217], v[0:3]
	v_mfma_f32_16x16x32_bf16 v[28:31], v[176:179], v[192:195], v[28:31]
	v_mfma_f32_16x16x32_bf16 v[24:27], v[184:187], v[192:195], v[24:27]
	v_mfma_f32_16x16x32_bf16 v[20:23], v[176:179], v[200:203], v[20:23]
	v_mfma_f32_16x16x32_bf16 v[16:19], v[184:187], v[200:203], v[16:19]
	v_mfma_f32_16x16x32_bf16 v[12:15], v[176:179], v[208:211], v[12:15]
	v_mfma_f32_16x16x32_bf16 v[8:11], v[184:187], v[208:211], v[8:11]
	v_mfma_f32_16x16x32_bf16 v[4:7], v[176:179], v[218:221], v[4:7]
	v_mfma_f32_16x16x32_bf16 v[0:3], v[184:187], v[218:221], v[0:3]
	s_setprio 0
	s_barrier
; #define LDA(dst, b, h) for (int m = 0; m < 4; ++m) for (int k = 0; k < 2; ++k) \
;     dst[m][k] = *reinterpret_cast<const bf16x8*>((char*)SA(b, h) + lds_byte(wr * 64 + m * 16 + fr, k * 32 + fq * 8))
; #define LDB(dst, b, h) for (int n = 0; n < 2; ++n) for (int k = 0; k < 2; ++k) \
;     dst[n][k] = *reinterpret_cast<const bf16x8*>((char*)SB(b, h) + lds_byte(wc * 32 + n * 16 + fr, k * 32 + fq * 8))
; #define MMA(ai, bj, At, Bt_) do { __builtin_amdgcn_s_setprio(1); \
;     for (int m = 0; m < 4; ++m) for (int n = 0; n < 2; ++n) for (int k = 0; k < 2; ++k) \
;       acc[ai][bj][m][n] = __builtin_amdgcn_mfma_f32_16x16x32_bf16(Bt_[n][k], At[m][k], acc[ai][bj][m][n], 0, 0, 0); \
;     __builtin_amdgcn_s_setprio(0); } while (0)
; #define WAIT_V(n) asm volatile("s_waitcnt vmcnt(" #n ")" ::: "memory")
; #define WAIT_L(n) asm volatile("s_waitcnt lgkmcnt(" #n ")" ::: "memory")
; #define BAR __builtin_amdgcn_s_barrier()
; #define SCHED __builtin_amdgcn_sched_barrier(0)
; template <int MODE>
; DI void gemm_phase(const bf16_t* __restrict__ A, const bf16_t* __restrict__ Bt, int M, int N, int K, const Epi& ep) {
;     ...
;             LDB(B0, 1, 0); LDB(B1, 1, 1); SCHED; LDA(At, 1, 0); STAGE(SA(0, 1), rsA, brow + HALF, t + 2);
;             WAIT_V(8); WAIT_L(0); BAR; MMA(0, 0, At, B0); MMA(0, 1, At, B1); BAR; SCHED;
;             LDA(At, 1, 1); STAGE(SB(1, 0), rsB, bcol, t + 3); STAGE(SB(1, 1), rsB, bcol + HALF, t + 3); STAGE(SA(1, 0), rsA, brow, t + 3);
;             WAIT_V(8); WAIT_L(0); BAR; MMA(1, 0, At, B0); MMA(1, 1, At, B1); BAR; SCHED;
	ds_read_b128 v[156:159], v152
	ds_read_b128 v[160:163], v152 offset:1024
	ds_read_b128 v[164:167], v152 offset:2048
	ds_read_b128 v[168:171], v152 offset:3072
	ds_read_b128 v[172:175], v153
	ds_read_b128 v[176:179], v153 offset:1024
	ds_read_b128 v[180:183], v153 offset:2048
	ds_read_b128 v[184:187], v153 offset:3072
	v_readfirstlane_b32 s44, v136
	s_add_i32 s43, s41, 0x40100
	s_mov_b32 m0, s44
	v_readfirstlane_b32 s44, v137
	ds_read_b128 v[188:191], v148 offset:32768
	ds_read_b128 v[192:195], v148 offset:33792
	ds_read_b128 v[196:199], v149 offset:32768
	ds_read_b128 v[200:203], v149 offset:33792
	ds_read_b128 v[204:207], v150 offset:32768
	ds_read_b128 v[208:211], v150 offset:33792
	ds_read_b128 v[214:217], v151 offset:32768
	ds_read_b128 v[218:221], v151 offset:33792
	buffer_load_dwordx4 v128, s[8:11], s43 offen lds
	s_mov_b32 m0, s44
	s_nop 0
	buffer_load_dwordx4 v129, s[8:11], s43 offen lds
	s_waitcnt vmcnt(8)
	s_waitcnt lgkmcnt(0)
	s_barrier
	s_setprio 1
	v_mfma_f32_16x16x32_bf16 v[124:127], v[156:159], v[188:191], v[124:127]
	v_mfma_f32_16x16x32_bf16 v[120:123], v[164:167], v[188:191], v[120:123]
	v_mfma_f32_16x16x32_bf16 v[116:119], v[156:159], v[196:199], v[116:119]
	v_mfma_f32_16x16x32_bf16 v[112:115], v[164:167], v[196:199], v[112:115]
	v_mfma_f32_16x16x32_bf16 v[108:111], v[156:159], v[204:207], v[108:111]
	v_mfma_f32_16x16x32_bf16 v[104:107], v[164:167], v[204:207], v[104:107]
	v_mfma_f32_16x16x32_bf16 v[100:103], v[156:159], v[214:217], v[100:103]
	v_mfma_f32_16x16x32_bf16 v[96:99], v[164:167], v[214:217], v[96:99]
	v_mfma_f32_16x16x32_bf16 v[124:127], v[160:163], v[192:195], v[124:127]
	v_mfma_f32_16x16x32_bf16 v[120:123], v[168:171], v[192:195], v[120:123]
	v_mfma_f32_16x16x32_bf16 v[116:119], v[160:163], v[200:203], v[116:119]
	v_mfma_f32_16x16x32_bf16 v[112:115], v[168:171], v[200:203], v[112:115]
	v_mfma_f32_16x16x32_bf16 v[108:111], v[160:163], v[208:211], v[108:111]
	v_mfma_f32_16x16x32_bf16 v[104:107], v[168:171], v[208:211], v[104:107]
	v_mfma_f32_16x16x32_bf16 v[100:103], v[160:163], v[218:221], v[100:103]
	v_mfma_f32_16x16x32_bf16 v[96:99], v[168:171], v[218:221], v[96:99]
	s_setprio 0
	s_setprio 1
	v_mfma_f32_16x16x32_bf16 v[92:95], v[172:175], v[188:191], v[92:95]
	v_mfma_f32_16x16x32_bf16 v[88:91], v[180:183], v[188:191], v[88:91]
	v_mfma_f32_16x16x32_bf16 v[84:87], v[172:175], v[196:199], v[84:87]
	v_mfma_f32_16x16x32_bf16 v[80:83], v[180:183], v[196:199], v[80:83]
	v_mfma_f32_16x16x32_bf16 v[76:79], v[172:175], v[204:207], v[76:79]
	v_mfma_f32_16x16x32_bf16 v[72:75], v[180:183], v[204:207], v[72:75]
	v_mfma_f32_16x16x32_bf16 v[68:71], v[172:175], v[214:217], v[68:71]
	v_mfma_f32_16x16x32_bf16 v[64:67], v[180:183], v[214:217], v[64:67]
	v_mfma_f32_16x16x32_bf16 v[92:95], v[176:179], v[192:195], v[92:95]
	v_mfma_f32_16x16x32_bf16 v[88:91], v[184:187], v[192:195], v[88:91]
	v_mfma_f32_16x16x32_bf16 v[84:87], v[176:179], v[200:203], v[84:87]
	v_mfma_f32_16x16x32_bf16 v[80:83], v[184:187], v[200:203], v[80:83]
	v_mfma_f32_16x16x32_bf16 v[76:79], v[176:179], v[208:211], v[76:79]
	v_mfma_f32_16x16x32_bf16 v[72:75], v[184:187], v[208:211], v[72:75]
	v_mfma_f32_16x16x32_bf16 v[68:71], v[176:179], v[218:221], v[68:71]
	v_mfma_f32_16x16x32_bf16 v[64:67], v[184:187], v[218:221], v[64:67]
	s_setprio 0
	s_barrier
	v_readfirstlane_b32 s44, v138
	s_add_i32 s43, s42, 0x180
	s_mov_b32 m0, s44
	v_readfirstlane_b32 s44, v139
	ds_read_b128 v[188:191], v148 offset:49152
	ds_read_b128 v[192:195], v148 offset:50176
	ds_read_b128 v[196:199], v149 offset:49152
	ds_read_b128 v[200:203], v149 offset:50176
	ds_read_b128 v[204:207], v150 offset:49152
	ds_read_b128 v[208:211], v150 offset:50176
	ds_read_b128 v[214:217], v151 offset:49152
	ds_read_b128 v[218:221], v151 offset:50176
	buffer_load_dwordx4 v128, s[4:7], s43 offen lds
	s_mov_b32 m0, s44
	s_add_i32 s42, s42, 0x40180
	buffer_load_dwordx4 v129, s[4:7], s43 offen lds
	v_readfirstlane_b32 s43, v142
	s_mov_b32 m0, s43
	v_readfirstlane_b32 s43, v143
	buffer_load_dwordx4 v128, s[4:7], s42 offen lds
	s_mov_b32 m0, s43
	s_addk_i32 s41, 0x180
	buffer_load_dwordx4 v129, s[4:7], s42 offen lds
	v_readfirstlane_b32 s6, v140
	s_mov_b32 m0, s6
	v_readfirstlane_b32 s6, v141
	buffer_load_dwordx4 v128, s[8:11], s41 offen lds
	s_mov_b32 m0, s6
	s_nop 0
	buffer_load_dwordx4 v129, s[8:11], s41 offen lds
	s_waitcnt vmcnt(8)
	s_waitcnt lgkmcnt(0)
	s_barrier
	s_setprio 1
	v_mfma_f32_16x16x32_bf16 v[60:63], v[156:159], v[188:191], v[60:63]
	v_mfma_f32_16x16x32_bf16 v[56:59], v[164:167], v[188:191], v[56:59]
	v_mfma_f32_16x16x32_bf16 v[52:55], v[156:159], v[196:199], v[52:55]
	v_mfma_f32_16x16x32_bf16 v[48:51], v[164:167], v[196:199], v[48:51]
	v_mfma_f32_16x16x32_bf16 v[44:47], v[156:159], v[204:207], v[44:47]
	v_mfma_f32_16x16x32_bf16 v[40:43], v[164:167], v[204:207], v[40:43]
	v_mfma_f32_16x16x32_bf16 v[36:39], v[156:159], v[214:217], v[36:39]
	v_mfma_f32_16x16x32_bf16 v[32:35], v[164:167], v[214:217], v[32:35]
	v_mfma_f32_16x16x32_bf16 v[60:63], v[160:163], v[192:195], v[60:63]
	v_mfma_f32_16x16x32_bf16 v[56:59], v[168:171], v[192:195], v[56:59]
	v_mfma_f32_16x16x32_bf16 v[52:55], v[160:163], v[200:203], v[52:55]
	v_mfma_f32_16x16x32_bf16 v[48:51], v[168:171], v[200:203], v[48:51]
	v_mfma_f32_16x16x32_bf16 v[44:47], v[160:163], v[208:211], v[44:47]
	v_mfma_f32_16x16x32_bf16 v[40:43], v[168:171], v[208:211], v[40:43]
	v_mfma_f32_16x16x32_bf16 v[36:39], v[160:163], v[218:221], v[36:39]
	v_mfma_f32_16x16x32_bf16 v[32:35], v[168:171], v[218:221], v[32:35]
	s_setprio 0
	s_setprio 1
	v_mfma_f32_16x16x32_bf16 v[28:31], v[172:175], v[188:191], v[28:31]
	v_mfma_f32_16x16x32_bf16 v[24:27], v[180:183], v[188:191], v[24:27]
	v_mfma_f32_16x16x32_bf16 v[20:23], v[172:175], v[196:199], v[20:23]
	v_mfma_f32_16x16x32_bf16 v[16:19], v[180:183], v[196:199], v[16:19]
	v_mfma_f32_16x16x32_bf16 v[12:15], v[172:175], v[204:207], v[12:15]
	v_mfma_f32_16x16x32_bf16 v[8:11], v[180:183], v[204:207], v[8:11]
	v_mfma_f32_16x16x32_bf16 v[4:7], v[172:175], v[214:217], v[4:7]
	v_mfma_f32_16x16x32_bf16 v[0:3], v[180:183], v[214:217], v[0:3]
	v_mfma_f32_16x16x32_bf16 v[28:31], v[176:179], v[192:195], v[28:31]
	v_mfma_f32_16x16x32_bf16 v[24:27], v[184:187], v[192:195], v[24:27]
	v_mfma_f32_16x16x32_bf16 v[20:23], v[176:179], v[200:203], v[20:23]
	v_mfma_f32_16x16x32_bf16 v[16:19], v[184:187], v[200:203], v[16:19]
	v_mfma_f32_16x16x32_bf16 v[12:15], v[176:179], v[208:211], v[12:15]
	v_mfma_f32_16x16x32_bf16 v[8:11], v[184:187], v[208:211], v[8:11]
	v_mfma_f32_16x16x32_bf16 v[4:7], v[176:179], v[218:221], v[4:7]
	v_mfma_f32_16x16x32_bf16 v[0:3], v[184:187], v[218:221], v[0:3]
	s_setprio 0
	s_barrier
; #define LDA(dst, b, h) for (int m = 0; m < 4; ++m) for (int k = 0; k < 2; ++k) \
;     dst[m][k] = *reinterpret_cast<const bf16x8*>((char*)SA(b, h) + lds_byte(wr * 64 + m * 16 + fr, k * 32 + fq * 8))
; #define LDB(dst, b, h) for (int n = 0; n < 2; ++n) for (int k = 0; k < 2; ++k) \
;     dst[n][k] = *reinterpret_cast<const bf16x8*>((char*)SB(b, h) + lds_byte(wc * 32 + n * 16 + fr, k * 32 + fq * 8))
; #define MMA(ai, bj, At, Bt_) do { __builtin_amdgcn_s_setprio(1); \
;     for (int m = 0; m < 4; ++m) for (int n = 0; n < 2; ++n) for (int k = 0; k < 2; ++k) \
;       acc[ai][bj][m][n] = __builtin_amdgcn_mfma_f32_16x16x32_bf16(Bt_[n][k], At[m][k], acc[ai][bj][m][n], 0, 0, 0); \
;     __builtin_amdgcn_s_setprio(0); } while (0)
; #define WAIT_V(n) asm volatile("s_waitcnt vmcnt(" #n ")" ::: "memory")
; #define WAIT_L(n) asm volatile("s_waitcnt lgkmcnt(" #n ")" ::: "memory")
; #define BAR __builtin_amdgcn_s_barrier()
; #define SCHED __builtin_amdgcn_sched_barrier(0)
; template <int MODE>
; DI void gemm_phase(const bf16_t* __restrict__ A, const bf16_t* __restrict__ Bt, int M, int N, int K, const Epi& ep) {
;     ...
;         for (int t = 0; t < nt - 2; t += 2) {
;             LDB(B0, 0, 0); LDB(B1, 0, 1); SCHED; LDA(At, 0, 0); STAGE(SA(1, 1), rsA, brow + HALF, t + 1);
;             WAIT_V(8); WAIT_L(0); BAR; MMA(0, 0, At, B0); MMA(0, 1, At, B1); BAR; SCHED;
;             LDA(At, 0, 1); STAGE(SB(0, 0), rsB, bcol, t + 2); STAGE(SB(0, 1), rsB, bcol + HALF, t + 2); STAGE(SA(0, 0), rsA, brow, t + 2);
;             WAIT_V(8); WAIT_L(0); BAR; MMA(1, 0, At, B0); MMA(1, 1, At, B1); BAR; SCHED;
;             LDB(B0, 1, 0); LDB(B1, 1, 1); SCHED; LDA(At, 1, 0); STAGE(SA(0, 1), rsA, brow + HALF, t + 2);
;             WAIT_V(8); WAIT_L(0); BAR; MMA(0, 0, At, B0); MMA(0, 1, At, B1); BAR; SCHED;
;             LDA(At, 1, 1); STAGE(SB(1, 0), rsB, bcol, t + 3); STAGE(SB(1, 1), rsB, bcol + HALF, t + 3); STAGE(SA(1, 0), rsA, brow, t + 3);
;             WAIT_V(8); WAIT_L(0); BAR; MMA(1, 0, At, B0); MMA(1, 1, At, B1); BAR; SCHED;
;         }
;         {
;             LDB(B0, 0, 0); LDB(B1, 0, 1); SCHED; LDA(At, 0, 0); STAGE(SA(1, 1), rsA, brow + HALF, nt - 1);
;             WAIT_V(8); WAIT_L(0); BAR; MMA(0, 0, At, B0); MMA(0, 1, At, B1); BAR; SCHED;
;             LDA(At, 0, 1);
;             WAIT_V(2); WAIT_L(0); BAR; MMA(1, 0, At, B0); MMA(1, 1, At, B1); BAR; SCHED;
	s_add_i32 s31, s31, 2
	s_addk_i32 s40, 0x100
	s_cmp_lt_u32 s31, 12
	s_cbranch_scc1 .LBB0_91
	ds_read_b128 v[156:159], v146
	ds_read_b128 v[160:163], v146 offset:1024
	ds_read_b128 v[164:167], v146 offset:2048
	ds_read_b128 v[168:171], v146 offset:3072
	ds_read_b128 v[172:175], v147
	ds_read_b128 v[176:179], v147 offset:1024
	ds_read_b128 v[180:183], v147 offset:2048
	ds_read_b128 v[184:187], v147 offset:3072
	v_readfirstlane_b32 s1, v144
	s_or_b32 s0, s30, 0x40780
	s_mov_b32 m0, s1
	v_readfirstlane_b32 s1, v145
	ds_read_b128 v[188:191], v148
	ds_read_b128 v[192:195], v148 offset:1024
	ds_read_b128 v[196:199], v149
	ds_read_b128 v[200:203], v149 offset:1024
	ds_read_b128 v[204:207], v150
	ds_read_b128 v[208:211], v150 offset:1024
	ds_read_b128 v[214:217], v151
	ds_read_b128 v[218:221], v151 offset:1024
	buffer_load_dwordx4 v128, s[8:11], s0 offen lds
	s_mov_b32 m0, s1
	s_nop 0
	buffer_load_dwordx4 v129, s[8:11], s0 offen lds
	s_waitcnt vmcnt(8)
	s_waitcnt lgkmcnt(0)
	s_barrier
	s_setprio 1
	v_mfma_f32_16x16x32_bf16 v[124:127], v[156:159], v[188:191], v[124:127]
	v_mfma_f32_16x16x32_bf16 v[120:123], v[164:167], v[188:191], v[120:123]
	v_mfma_f32_16x16x32_bf16 v[116:119], v[156:159], v[196:199], v[116:119]
	v_mfma_f32_16x16x32_bf16 v[112:115], v[164:167], v[196:199], v[112:115]
	v_mfma_f32_16x16x32_bf16 v[108:111], v[156:159], v[204:207], v[108:111]
	v_mfma_f32_16x16x32_bf16 v[124:127], v[160:163], v[192:195], v[124:127]
	v_mfma_f32_16x16x32_bf16 v[120:123], v[168:171], v[192:195], v[120:123]
	v_mfma_f32_16x16x32_bf16 v[116:119], v[160:163], v[200:203], v[116:119]
	v_mfma_f32_16x16x32_bf16 v[112:115], v[168:171], v[200:203], v[112:115]
	v_mfma_f32_16x16x32_bf16 v[222:225], v[160:163], v[208:211], v[108:111]
	v_mfma_f32_16x16x32_bf16 v[104:107], v[164:167], v[204:207], v[104:107]
	v_mfma_f32_16x16x32_bf16 v[100:103], v[156:159], v[214:217], v[100:103]
	v_mfma_f32_16x16x32_bf16 v[96:99], v[164:167], v[214:217], v[96:99]
	v_mfma_f32_16x16x32_bf16 v[226:229], v[168:171], v[208:211], v[104:107]
	v_mfma_f32_16x16x32_bf16 v[230:233], v[160:163], v[218:221], v[100:103]
	v_mfma_f32_16x16x32_bf16 v[234:237], v[168:171], v[218:221], v[96:99]
	s_setprio 0
	s_setprio 1
	v_mfma_f32_16x16x32_bf16 v[92:95], v[172:175], v[188:191], v[92:95]
	v_mfma_f32_16x16x32_bf16 v[88:91], v[180:183], v[188:191], v[88:91]
	v_mfma_f32_16x16x32_bf16 v[84:87], v[172:175], v[196:199], v[84:87]
	v_mfma_f32_16x16x32_bf16 v[80:83], v[180:183], v[196:199], v[80:83]
	v_mfma_f32_16x16x32_bf16 v[92:95], v[176:179], v[192:195], v[92:95]
	v_mfma_f32_16x16x32_bf16 v[88:91], v[184:187], v[192:195], v[88:91]
	v_mfma_f32_16x16x32_bf16 v[84:87], v[176:179], v[200:203], v[84:87]
	v_mfma_f32_16x16x32_bf16 v[80:83], v[184:187], v[200:203], v[80:83]
	v_mfma_f32_16x16x32_bf16 v[76:79], v[172:175], v[204:207], v[76:79]
	v_mfma_f32_16x16x32_bf16 v[72:75], v[180:183], v[204:207], v[72:75]
	v_mfma_f32_16x16x32_bf16 v[68:71], v[172:175], v[214:217], v[68:71]
	v_mfma_f32_16x16x32_bf16 v[64:67], v[180:183], v[214:217], v[64:67]
	v_mfma_f32_16x16x32_bf16 v[188:191], v[176:179], v[208:211], v[76:79]
	v_mfma_f32_16x16x32_bf16 v[192:195], v[184:187], v[208:211], v[72:75]
	v_mfma_f32_16x16x32_bf16 v[196:199], v[176:179], v[218:221], v[68:71]
	v_mfma_f32_16x16x32_bf16 v[200:203], v[184:187], v[218:221], v[64:67]
	s_setprio 0
	s_barrier
	s_nop 1
	ds_read_b128 v[64:67], v148 offset:16384
	ds_read_b128 v[68:71], v148 offset:17408
	ds_read_b128 v[72:75], v149 offset:16384
	ds_read_b128 v[76:79], v149 offset:17408
	ds_read_b128 v[96:99], v150 offset:16384
	ds_read_b128 v[100:103], v150 offset:17408
	ds_read_b128 v[104:107], v151 offset:16384
	ds_read_b128 v[108:111], v151 offset:17408
	s_waitcnt vmcnt(2)
	s_waitcnt lgkmcnt(0)
	s_barrier
	s_setprio 1
	v_mfma_f32_16x16x32_bf16 v[60:63], v[156:159], v[64:67], v[60:63]
	v_mfma_f32_16x16x32_bf16 v[56:59], v[164:167], v[64:67], v[56:59]
	v_mfma_f32_16x16x32_bf16 v[52:55], v[156:159], v[72:75], v[52:55]
	v_mfma_f32_16x16x32_bf16 v[48:51], v[164:167], v[72:75], v[48:51]
	v_mfma_f32_16x16x32_bf16 v[60:63], v[160:163], v[68:71], v[60:63]
	v_mfma_f32_16x16x32_bf16 v[56:59], v[168:171], v[68:71], v[56:59]
	v_mfma_f32_16x16x32_bf16 v[52:55], v[160:163], v[76:79], v[52:55]
	v_mfma_f32_16x16x32_bf16 v[48:51], v[168:171], v[76:79], v[48:51]
	v_mfma_f32_16x16x32_bf16 v[44:47], v[156:159], v[96:99], v[44:47]
	v_mfma_f32_16x16x32_bf16 v[40:43], v[164:167], v[96:99], v[40:43]
	v_mfma_f32_16x16x32_bf16 v[36:39], v[156:159], v[104:107], v[36:39]
	v_mfma_f32_16x16x32_bf16 v[32:35], v[164:167], v[104:107], v[32:35]
	v_mfma_f32_16x16x32_bf16 v[204:207], v[160:163], v[100:103], v[44:47]
	v_mfma_f32_16x16x32_bf16 v[208:211], v[168:171], v[100:103], v[40:43]
	v_mfma_f32_16x16x32_bf16 v[156:159], v[160:163], v[108:111], v[36:39]
	v_mfma_f32_16x16x32_bf16 v[160:163], v[168:171], v[108:111], v[32:35]
	s_setprio 0
	s_setprio 1
	v_mfma_f32_16x16x32_bf16 v[28:31], v[172:175], v[64:67], v[28:31]
	v_mfma_f32_16x16x32_bf16 v[24:27], v[180:183], v[64:67], v[24:27]
	v_mfma_f32_16x16x32_bf16 v[20:23], v[172:175], v[72:75], v[20:23]
	v_mfma_f32_16x16x32_bf16 v[16:19], v[180:183], v[72:75], v[16:19]
	v_mfma_f32_16x16x32_bf16 v[28:31], v[176:179], v[68:71], v[28:31]
	v_mfma_f32_16x16x32_bf16 v[24:27], v[184:187], v[68:71], v[24:27]
	v_mfma_f32_16x16x32_bf16 v[20:23], v[176:179], v[76:79], v[20:23]
	v_mfma_f32_16x16x32_bf16 v[16:19], v[184:187], v[76:79], v[16:19]
	v_mfma_f32_16x16x32_bf16 v[12:15], v[172:175], v[96:99], v[12:15]
	v_mfma_f32_16x16x32_bf16 v[8:11], v[180:183], v[96:99], v[8:11]
	v_mfma_f32_16x16x32_bf16 v[4:7], v[172:175], v[104:107], v[4:7]
	v_mfma_f32_16x16x32_bf16 v[0:3], v[180:183], v[104:107], v[0:3]
	v_mfma_f32_16x16x32_bf16 v[164:167], v[176:179], v[100:103], v[12:15]
	v_mfma_f32_16x16x32_bf16 v[168:171], v[184:187], v[100:103], v[8:11]
	v_mfma_f32_16x16x32_bf16 v[172:175], v[176:179], v[108:111], v[4:7]
	v_mfma_f32_16x16x32_bf16 v[176:179], v[184:187], v[108:111], v[0:3]
	s_setprio 0
	s_barrier
; #define LDA(dst, b, h) for (int m = 0; m < 4; ++m) for (int k = 0; k < 2; ++k) \
;     dst[m][k] = *reinterpret_cast<const bf16x8*>((char*)SA(b, h) + lds_byte(wr * 64 + m * 16 + fr, k * 32 + fq * 8))
; #define LDB(dst, b, h) for (int n = 0; n < 2; ++n) for (int k = 0; k < 2; ++k) \
;     dst[n][k] = *reinterpret_cast<const bf16x8*>((char*)SB(b, h) + lds_byte(wc * 32 + n * 16 + fr, k * 32 + fq * 8))
; #define MMA(ai, bj, At, Bt_) do { __builtin_amdgcn_s_setprio(1); \
;     for (int m = 0; m < 4; ++m) for (int n = 0; n < 2; ++n) for (int k = 0; k < 2; ++k) \
;       acc[ai][bj][m][n] = __builtin_amdgcn_mfma_f32_16x16x32_bf16(Bt_[n][k], At[m][k], acc[ai][bj][m][n], 0, 0, 0); \
;     __builtin_amdgcn_s_setprio(0); } while (0)
; #define WAIT_V(n) asm volatile("s_waitcnt vmcnt(" #n ")" ::: "memory")
; #define WAIT_L(n) asm volatile("s_waitcnt lgkmcnt(" #n ")" ::: "memory")
; #define BAR __builtin_amdgcn_s_barrier()
; #define SCHED __builtin_amdgcn_sched_barrier(0)
; template <int MODE>
; DI void gemm_phase(const bf16_t* __restrict__ A, const bf16_t* __restrict__ Bt, int M, int N, int K, const Epi& ep) {
;     ...
;             LDB(B0, 1, 0); LDB(B1, 1, 1); SCHED; LDA(At, 1, 0);
;             WAIT_V(0); WAIT_L(0); BAR; MMA(0, 0, At, B0); MMA(0, 1, At, B1); BAR; SCHED;
;             LDA(At, 1, 1);
;             WAIT_L(0); BAR; MMA(1, 0, At, B0); MMA(1, 1, At, B1); BAR; SCHED;
;         }
;         if (wr == 0) BAR;
	s_nop 1
	ds_read_b128 v[0:3], v152
	ds_read_b128 v[4:7], v152 offset:1024
	ds_read_b128 v[8:11], v152 offset:2048
	ds_read_b128 v[12:15], v152 offset:3072
	ds_read_b128 v[180:183], v153
	ds_read_b128 v[184:187], v153 offset:1024
	ds_read_b128 v[214:217], v153 offset:2048
	ds_read_b128 v[218:221], v153 offset:3072
	ds_read_b128 v[32:35], v148 offset:32768
	ds_read_b128 v[36:39], v148 offset:33792
	ds_read_b128 v[40:43], v149 offset:32768
	ds_read_b128 v[44:47], v149 offset:33792
	ds_read_b128 v[238:241], v150 offset:32768
	ds_read_b128 v[242:245], v150 offset:33792
	ds_read_b128 v[246:249], v151 offset:32768
	ds_read_b128 v[64:67], v151 offset:33792
	s_waitcnt vmcnt(0)
	s_waitcnt lgkmcnt(0)
	s_barrier
	s_setprio 1
	v_mfma_f32_16x16x32_bf16 v[68:71], v[0:3], v[32:35], v[124:127]
	v_mfma_f32_16x16x32_bf16 v[96:99], v[4:7], v[36:39], v[68:71]
	v_mfma_f32_16x16x32_bf16 v[68:71], v[8:11], v[32:35], v[120:123]
	v_mfma_f32_16x16x32_bf16 v[100:103], v[12:15], v[36:39], v[68:71]
	v_mfma_f32_16x16x32_bf16 v[68:71], v[0:3], v[40:43], v[116:119]
	v_mfma_f32_16x16x32_bf16 v[104:107], v[4:7], v[44:47], v[68:71]
	v_mfma_f32_16x16x32_bf16 v[68:71], v[8:11], v[40:43], v[112:115]
	v_mfma_f32_16x16x32_bf16 v[108:111], v[12:15], v[44:47], v[68:71]
	v_mfma_f32_16x16x32_bf16 v[68:71], v[0:3], v[238:241], v[222:225]
	v_mfma_f32_16x16x32_bf16 v[112:115], v[4:7], v[242:245], v[68:71]
	v_mfma_f32_16x16x32_bf16 v[68:71], v[8:11], v[238:241], v[226:229]
	v_mfma_f32_16x16x32_bf16 v[116:119], v[12:15], v[242:245], v[68:71]
	v_mfma_f32_16x16x32_bf16 v[68:71], v[0:3], v[246:249], v[230:233]
	v_mfma_f32_16x16x32_bf16 v[120:123], v[4:7], v[64:67], v[68:71]
	v_mfma_f32_16x16x32_bf16 v[68:71], v[8:11], v[246:249], v[234:237]
	v_mfma_f32_16x16x32_bf16 v[124:127], v[12:15], v[64:67], v[68:71]
	s_setprio 0
	s_setprio 1
	v_mfma_f32_16x16x32_bf16 v[68:71], v[180:183], v[32:35], v[92:95]
	v_mfma_f32_16x16x32_bf16 v[32:35], v[214:217], v[32:35], v[88:91]
	v_mfma_f32_16x16x32_bf16 v[222:225], v[184:187], v[36:39], v[68:71]
	v_mfma_f32_16x16x32_bf16 v[68:71], v[218:221], v[36:39], v[32:35]
	v_mfma_f32_16x16x32_bf16 v[32:35], v[180:183], v[40:43], v[84:87]
	v_mfma_f32_16x16x32_bf16 v[72:75], v[184:187], v[44:47], v[32:35]
	v_mfma_f32_16x16x32_bf16 v[32:35], v[214:217], v[40:43], v[80:83]
	v_mfma_f32_16x16x32_bf16 v[76:79], v[218:221], v[44:47], v[32:35]
	v_mfma_f32_16x16x32_bf16 v[32:35], v[180:183], v[238:241], v[188:191]
	v_mfma_f32_16x16x32_bf16 v[80:83], v[184:187], v[242:245], v[32:35]
	v_mfma_f32_16x16x32_bf16 v[32:35], v[214:217], v[238:241], v[192:195]
	v_mfma_f32_16x16x32_bf16 v[84:87], v[218:221], v[242:245], v[32:35]
	v_mfma_f32_16x16x32_bf16 v[32:35], v[180:183], v[246:249], v[196:199]
	v_mfma_f32_16x16x32_bf16 v[88:91], v[184:187], v[64:67], v[32:35]
	v_mfma_f32_16x16x32_bf16 v[32:35], v[214:217], v[246:249], v[200:203]
	v_mfma_f32_16x16x32_bf16 v[92:95], v[218:221], v[64:67], v[32:35]
	s_setprio 0
	s_barrier
	ds_read_b128 v[64:67], v148 offset:49152
	ds_read_b128 v[188:191], v148 offset:50176
	ds_read_b128 v[192:195], v149 offset:49152
	ds_read_b128 v[196:199], v149 offset:50176
	ds_read_b128 v[200:203], v150 offset:49152
	ds_read_b128 v[226:229], v150 offset:50176
	ds_read_b128 v[230:233], v151 offset:49152
	ds_read_b128 v[234:237], v151 offset:50176
	s_waitcnt lgkmcnt(0)
	s_barrier
	s_setprio 1
	v_mfma_f32_16x16x32_bf16 v[32:35], v[0:3], v[64:67], v[60:63]
	v_mfma_f32_16x16x32_bf16 v[40:43], v[0:3], v[192:195], v[52:55]
	v_mfma_f32_16x16x32_bf16 v[44:47], v[8:11], v[192:195], v[48:51]
	v_mfma_f32_16x16x32_bf16 v[48:51], v[0:3], v[200:203], v[204:207]
	v_mfma_f32_16x16x32_bf16 v[0:3], v[0:3], v[230:233], v[156:159]
	v_mfma_f32_16x16x32_bf16 v[36:39], v[8:11], v[64:67], v[56:59]
	v_mfma_f32_16x16x32_bf16 v[52:55], v[8:11], v[200:203], v[208:211]
	v_mfma_f32_16x16x32_bf16 v[56:59], v[4:7], v[234:237], v[0:3]
	v_mfma_f32_16x16x32_bf16 v[0:3], v[8:11], v[230:233], v[160:163]
	v_mfma_f32_16x16x32_bf16 v[32:35], v[4:7], v[188:191], v[32:35]
	v_mfma_f32_16x16x32_bf16 v[36:39], v[12:15], v[188:191], v[36:39]
	v_mfma_f32_16x16x32_bf16 v[40:43], v[4:7], v[196:199], v[40:43]
	v_mfma_f32_16x16x32_bf16 v[44:47], v[12:15], v[196:199], v[44:47]
	v_mfma_f32_16x16x32_bf16 v[48:51], v[4:7], v[226:229], v[48:51]
	v_mfma_f32_16x16x32_bf16 v[52:55], v[12:15], v[226:229], v[52:55]
	v_mfma_f32_16x16x32_bf16 v[60:63], v[12:15], v[234:237], v[0:3]
	s_setprio 0
	s_setprio 1
	v_mfma_f32_16x16x32_bf16 v[0:3], v[180:183], v[64:67], v[28:31]
	v_mfma_f32_16x16x32_bf16 v[4:7], v[214:217], v[64:67], v[24:27]
	v_mfma_f32_16x16x32_bf16 v[8:11], v[180:183], v[192:195], v[20:23]
	v_mfma_f32_16x16x32_bf16 v[12:15], v[214:217], v[192:195], v[16:19]
	v_mfma_f32_16x16x32_bf16 v[16:19], v[180:183], v[200:203], v[164:167]
	v_mfma_f32_16x16x32_bf16 v[20:23], v[214:217], v[200:203], v[168:171]
	v_mfma_f32_16x16x32_bf16 v[24:27], v[180:183], v[230:233], v[172:175]
	v_mfma_f32_16x16x32_bf16 v[28:31], v[214:217], v[230:233], v[176:179]
	v_mfma_f32_16x16x32_bf16 v[0:3], v[184:187], v[188:191], v[0:3]
	v_mfma_f32_16x16x32_bf16 v[4:7], v[218:221], v[188:191], v[4:7]
	v_mfma_f32_16x16x32_bf16 v[8:11], v[184:187], v[196:199], v[8:11]
	v_mfma_f32_16x16x32_bf16 v[12:15], v[218:221], v[196:199], v[12:15]
	v_mfma_f32_16x16x32_bf16 v[16:19], v[184:187], v[226:229], v[16:19]
	v_mfma_f32_16x16x32_bf16 v[20:23], v[218:221], v[226:229], v[20:23]
	v_mfma_f32_16x16x32_bf16 v[24:27], v[184:187], v[234:237], v[24:27]
	v_mfma_f32_16x16x32_bf16 v[28:31], v[218:221], v[234:237], v[28:31]
	s_setprio 0
	s_barrier
	s_and_saveexec_b64 s[0:1], s[38:39]
	s_cbranch_execz .LBB0_94
	s_barrier

; #define LDA(dst, b, h) for (int m = 0; m < 4; ++m) for (int k = 0; k < 2; ++k) \
;     dst[m][k] = *reinterpret_cast<const bf16x8*>((char*)SA(b, h) + lds_byte(wr * 64 + m * 16 + fr, k * 32 + fq * 8))
; #define LDB(dst, b, h) for (int n = 0; n < 2; ++n) for (int k = 0; k < 2; ++k) \
;     dst[n][k] = *reinterpret_cast<const bf16x8*>((char*)SB(b, h) + lds_byte(wc * 32 + n * 16 + fr, k * 32 + fq * 8))
; #define MMA(ai, bj, At, Bt_) do { __builtin_amdgcn_s_setprio(1); \
;     for (int m = 0; m < 4; ++m) for (int n = 0; n < 2; ++n) for (int k = 0; k < 2; ++k) \
;       acc[ai][bj][m][n] = __builtin_amdgcn_mfma_f32_16x16x32_bf16(Bt_[n][k], At[m][k], acc[ai][bj][m][n], 0, 0, 0); \
;     __builtin_amdgcn_s_setprio(0); } while (0)
; #define WAIT_V(n) asm volatile("s_waitcnt vmcnt(" #n ")" ::: "memory")
; #define WAIT_L(n) asm volatile("s_waitcnt lgkmcnt(" #n ")" ::: "memory")
; #define BAR __builtin_amdgcn_s_barrier()
; #define SCHED __builtin_amdgcn_sched_barrier(0)
; template <int MODE>
; DI void gemm_phase(const bf16_t* __restrict__ A, const bf16_t* __restrict__ Bt, int M, int N, int K, const Epi& ep) {
;     ...
;             LDB(B0, 0, 0); LDB(B1, 0, 1); SCHED; LDA(At, 0, 0); STAGE(SA(1, 1), rsA, brow + HALF, t + 1);
;             WAIT_V(8); WAIT_L(0); BAR; MMA(0, 0, At, B0); MMA(0, 1, At, B1); BAR; SCHED;
;             LDA(At, 0, 1); STAGE(SB(0, 0), rsB, bcol, t + 2); STAGE(SB(0, 1), rsB, bcol + HALF, t + 2); STAGE(SA(0, 0), rsA, brow, t + 2);
;             WAIT_V(8); WAIT_L(0); BAR; MMA(1, 0, At, B0); MMA(1, 1, At, B1); BAR; SCHED;
;             LDB(B0, 1, 0); LDB(B1, 1, 1); SCHED; LDA(At, 1, 0); STAGE(SA(0, 1), rsA, brow + HALF, t + 2);
;             WAIT_V(8); WAIT_L(0); BAR; MMA(0, 0, At, B0); MMA(0, 1, At, B1); BAR; SCHED;
;             LDA(At, 1, 1); STAGE(SB(1, 0), rsB, bcol, t + 3); STAGE(SB(1, 1), rsB, bcol + HALF, t + 3); STAGE(SA(1, 0), rsA, brow, t + 3);
;             WAIT_V(8); WAIT_L(0); BAR; MMA(1, 0, At, B0); MMA(1, 1, At, B1); BAR; SCHED;
.LBB0_488:
	ds_read_b128 v[156:159], v147
	ds_read_b128 v[160:163], v147 offset:1024
	ds_read_b128 v[164:167], v147 offset:2048
	ds_read_b128 v[168:171], v147 offset:3072
	ds_read_b128 v[172:175], v148
	ds_read_b128 v[176:179], v148 offset:1024
	ds_read_b128 v[180:183], v148 offset:2048
	ds_read_b128 v[184:187], v148 offset:3072
	s_add_i32 s42, s27, s41
	v_readfirstlane_b32 s15, v144
	s_add_i32 s14, s42, 0x40080
	s_mov_b32 s30, s10
	s_mov_b32 s31, s11
	s_mov_b32 m0, s15
	v_readfirstlane_b32 s15, v145
	ds_read_b128 v[188:191], v149
	ds_read_b128 v[192:195], v149 offset:1024
	ds_read_b128 v[196:199], v150
	ds_read_b128 v[200:203], v150 offset:1024
	ds_read_b128 v[204:207], v151
	ds_read_b128 v[208:211], v151 offset:1024
	ds_read_b128 v[214:217], v152
	ds_read_b128 v[218:221], v152 offset:1024
	buffer_load_dwordx4 v128, s[28:31], s14 offen lds
	s_mov_b32 m0, s15
	s_nop 0
	buffer_load_dwordx4 v129, s[28:31], s14 offen lds
	s_waitcnt vmcnt(8)
	s_waitcnt lgkmcnt(0)
	s_barrier
	s_setprio 1
	v_mfma_f32_16x16x32_bf16 v[124:127], v[156:159], v[188:191], v[124:127]
	v_mfma_f32_16x16x32_bf16 v[120:123], v[164:167], v[188:191], v[120:123]
	v_mfma_f32_16x16x32_bf16 v[116:119], v[156:159], v[196:199], v[116:119]
	v_mfma_f32_16x16x32_bf16 v[112:115], v[164:167], v[196:199], v[112:115]
	v_mfma_f32_16x16x32_bf16 v[108:111], v[156:159], v[204:207], v[108:111]
	v_mfma_f32_16x16x32_bf16 v[104:107], v[164:167], v[204:207], v[104:107]
	v_mfma_f32_16x16x32_bf16 v[100:103], v[156:159], v[214:217], v[100:103]
	v_mfma_f32_16x16x32_bf16 v[96:99], v[164:167], v[214:217], v[96:99]
	v_mfma_f32_16x16x32_bf16 v[124:127], v[160:163], v[192:195], v[124:127]
	v_mfma_f32_16x16x32_bf16 v[120:123], v[168:171], v[192:195], v[120:123]
	v_mfma_f32_16x16x32_bf16 v[116:119], v[160:163], v[200:203], v[116:119]
	v_mfma_f32_16x16x32_bf16 v[112:115], v[168:171], v[200:203], v[112:115]
	v_mfma_f32_16x16x32_bf16 v[108:111], v[160:163], v[208:211], v[108:111]
	v_mfma_f32_16x16x32_bf16 v[104:107], v[168:171], v[208:211], v[104:107]
	v_mfma_f32_16x16x32_bf16 v[100:103], v[160:163], v[218:221], v[100:103]
	v_mfma_f32_16x16x32_bf16 v[96:99], v[168:171], v[218:221], v[96:99]
	s_setprio 0
	s_setprio 1
	v_mfma_f32_16x16x32_bf16 v[92:95], v[172:175], v[188:191], v[92:95]
	v_mfma_f32_16x16x32_bf16 v[88:91], v[180:183], v[188:191], v[88:91]
	v_mfma_f32_16x16x32_bf16 v[84:87], v[172:175], v[196:199], v[84:87]
	v_mfma_f32_16x16x32_bf16 v[80:83], v[180:183], v[196:199], v[80:83]
	v_mfma_f32_16x16x32_bf16 v[76:79], v[172:175], v[204:207], v[76:79]
	v_mfma_f32_16x16x32_bf16 v[72:75], v[180:183], v[204:207], v[72:75]
	v_mfma_f32_16x16x32_bf16 v[68:71], v[172:175], v[214:217], v[68:71]
	v_mfma_f32_16x16x32_bf16 v[64:67], v[180:183], v[214:217], v[64:67]
	v_mfma_f32_16x16x32_bf16 v[92:95], v[176:179], v[192:195], v[92:95]
	v_mfma_f32_16x16x32_bf16 v[88:91], v[184:187], v[192:195], v[88:91]
	v_mfma_f32_16x16x32_bf16 v[84:87], v[176:179], v[200:203], v[84:87]
	v_mfma_f32_16x16x32_bf16 v[80:83], v[184:187], v[200:203], v[80:83]
	v_mfma_f32_16x16x32_bf16 v[76:79], v[176:179], v[208:211], v[76:79]
	v_mfma_f32_16x16x32_bf16 v[72:75], v[184:187], v[208:211], v[72:75]
	v_mfma_f32_16x16x32_bf16 v[68:71], v[176:179], v[218:221], v[68:71]
	v_mfma_f32_16x16x32_bf16 v[64:67], v[184:187], v[218:221], v[64:67]
	s_setprio 0
	s_barrier
	s_add_i32 s43, s6, s41
	v_readfirstlane_b32 s45, v130
	s_add_i32 s44, s43, 0x100
	s_mov_b32 s14, s10
	s_mov_b32 s15, s11
	s_mov_b32 m0, s45
	v_readfirstlane_b32 s45, v131
	ds_read_b128 v[188:191], v149 offset:16384
	ds_read_b128 v[192:195], v149 offset:17408
	ds_read_b128 v[196:199], v150 offset:16384
	ds_read_b128 v[200:203], v150 offset:17408
	ds_read_b128 v[204:207], v151 offset:16384
	ds_read_b128 v[208:211], v151 offset:17408
	ds_read_b128 v[214:217], v152 offset:16384
	ds_read_b128 v[218:221], v152 offset:17408
	buffer_load_dwordx4 v128, s[12:15], s44 offen lds
	s_mov_b32 m0, s45
	v_readfirstlane_b32 s45, v132
	buffer_load_dwordx4 v129, s[12:15], s44 offen lds
	s_add_i32 s44, s43, 0x40100
	s_mov_b32 m0, s45
	v_readfirstlane_b32 s45, v133
	buffer_load_dwordx4 v128, s[12:15], s44 offen lds
	s_mov_b32 m0, s45
	v_readfirstlane_b32 s45, v134
	buffer_load_dwordx4 v129, s[12:15], s44 offen lds
	s_add_i32 s44, s42, 0x100
	s_mov_b32 m0, s45
	v_readfirstlane_b32 s45, v135
	buffer_load_dwordx4 v128, s[28:31], s44 offen lds
	s_mov_b32 m0, s45
	s_nop 0
	buffer_load_dwordx4 v129, s[28:31], s44 offen lds
	s_waitcnt vmcnt(8)
	s_waitcnt lgkmcnt(0)
	s_barrier
	s_setprio 1
	v_mfma_f32_16x16x32_bf16 v[60:63], v[156:159], v[188:191], v[60:63]
	v_mfma_f32_16x16x32_bf16 v[56:59], v[164:167], v[188:191], v[56:59]
	v_mfma_f32_16x16x32_bf16 v[52:55], v[156:159], v[196:199], v[52:55]
	v_mfma_f32_16x16x32_bf16 v[48:51], v[164:167], v[196:199], v[48:51]
	v_mfma_f32_16x16x32_bf16 v[44:47], v[156:159], v[204:207], v[44:47]
	v_mfma_f32_16x16x32_bf16 v[40:43], v[164:167], v[204:207], v[40:43]
	v_mfma_f32_16x16x32_bf16 v[36:39], v[156:159], v[214:217], v[36:39]
	v_mfma_f32_16x16x32_bf16 v[32:35], v[164:167], v[214:217], v[32:35]
	v_mfma_f32_16x16x32_bf16 v[60:63], v[160:163], v[192:195], v[60:63]
	v_mfma_f32_16x16x32_bf16 v[56:59], v[168:171], v[192:195], v[56:59]
	v_mfma_f32_16x16x32_bf16 v[52:55], v[160:163], v[200:203], v[52:55]
	v_mfma_f32_16x16x32_bf16 v[48:51], v[168:171], v[200:203], v[48:51]
	v_mfma_f32_16x16x32_bf16 v[44:47], v[160:163], v[208:211], v[44:47]
	v_mfma_f32_16x16x32_bf16 v[40:43], v[168:171], v[208:211], v[40:43]
	v_mfma_f32_16x16x32_bf16 v[36:39], v[160:163], v[218:221], v[36:39]
	v_mfma_f32_16x16x32_bf16 v[32:35], v[168:171], v[218:221], v[32:35]
	s_setprio 0
	s_setprio 1
	v_mfma_f32_16x16x32_bf16 v[28:31], v[172:175], v[188:191], v[28:31]
	v_mfma_f32_16x16x32_bf16 v[24:27], v[180:183], v[188:191], v[24:27]
	v_mfma_f32_16x16x32_bf16 v[20:23], v[172:175], v[196:199], v[20:23]
	v_mfma_f32_16x16x32_bf16 v[16:19], v[180:183], v[196:199], v[16:19]
	v_mfma_f32_16x16x32_bf16 v[12:15], v[172:175], v[204:207], v[12:15]
	v_mfma_f32_16x16x32_bf16 v[8:11], v[180:183], v[204:207], v[8:11]
	v_mfma_f32_16x16x32_bf16 v[4:7], v[172:175], v[214:217], v[4:7]
	v_mfma_f32_16x16x32_bf16 v[0:3], v[180:183], v[214:217], v[0:3]
	v_mfma_f32_16x16x32_bf16 v[28:31], v[176:179], v[192:195], v[28:31]
	v_mfma_f32_16x16x32_bf16 v[24:27], v[184:187], v[192:195], v[24:27]
	v_mfma_f32_16x16x32_bf16 v[20:23], v[176:179], v[200:203], v[20:23]
	v_mfma_f32_16x16x32_bf16 v[16:19], v[184:187], v[200:203], v[16:19]
	v_mfma_f32_16x16x32_bf16 v[12:15], v[176:179], v[208:211], v[12:15]
	v_mfma_f32_16x16x32_bf16 v[8:11], v[184:187], v[208:211], v[8:11]
	v_mfma_f32_16x16x32_bf16 v[4:7], v[176:179], v[218:221], v[4:7]
	v_mfma_f32_16x16x32_bf16 v[0:3], v[184:187], v[218:221], v[0:3]
	s_setprio 0
	s_barrier
; #define LDA(dst, b, h) for (int m = 0; m < 4; ++m) for (int k = 0; k < 2; ++k) \
;     dst[m][k] = *reinterpret_cast<const bf16x8*>((char*)SA(b, h) + lds_byte(wr * 64 + m * 16 + fr, k * 32 + fq * 8))
; #define LDB(dst, b, h) for (int n = 0; n < 2; ++n) for (int k = 0; k < 2; ++k) \
;     dst[n][k] = *reinterpret_cast<const bf16x8*>((char*)SB(b, h) + lds_byte(wc * 32 + n * 16 + fr, k * 32 + fq * 8))
; #define MMA(ai, bj, At, Bt_) do { __builtin_amdgcn_s_setprio(1); \
;     for (int m = 0; m < 4; ++m) for (int n = 0; n < 2; ++n) for (int k = 0; k < 2; ++k) \
;       acc[ai][bj][m][n] = __builtin_amdgcn_mfma_f32_16x16x32_bf16(Bt_[n][k], At[m][k], acc[ai][bj][m][n], 0, 0, 0); \
;     __builtin_amdgcn_s_setprio(0); } while (0)
; #define WAIT_V(n) asm volatile("s_waitcnt vmcnt(" #n ")" ::: "memory")
; #define WAIT_L(n) asm volatile("s_waitcnt lgkmcnt(" #n ")" ::: "memory")
; #define BAR __builtin_amdgcn_s_barrier()
; #define SCHED __builtin_amdgcn_sched_barrier(0)
; template <int MODE>
; DI void gemm_phase(const bf16_t* __restrict__ A, const bf16_t* __restrict__ Bt, int M, int N, int K, const Epi& ep) {
;     ...
;             LDB(B0, 1, 0); LDB(B1, 1, 1); SCHED; LDA(At, 1, 0); STAGE(SA(0, 1), rsA, brow + HALF, t + 2);
;             WAIT_V(8); WAIT_L(0); BAR; MMA(0, 0, At, B0); MMA(0, 1, At, B1); BAR; SCHED;
;             LDA(At, 1, 1); STAGE(SB(1, 0), rsB, bcol, t + 3); STAGE(SB(1, 1), rsB, bcol + HALF, t + 3); STAGE(SA(1, 0), rsA, brow, t + 3);
;             WAIT_V(8); WAIT_L(0); BAR; MMA(1, 0, At, B0); MMA(1, 1, At, B1); BAR; SCHED;
	ds_read_b128 v[156:159], v153
	ds_read_b128 v[160:163], v153 offset:1024
	ds_read_b128 v[164:167], v153 offset:2048
	ds_read_b128 v[168:171], v153 offset:3072
	ds_read_b128 v[172:175], v154
	ds_read_b128 v[176:179], v154 offset:1024
	ds_read_b128 v[180:183], v154 offset:2048
	ds_read_b128 v[184:187], v154 offset:3072
	v_readfirstlane_b32 s45, v136
	s_add_i32 s44, s42, 0x40100
	s_mov_b32 m0, s45
	v_readfirstlane_b32 s45, v137
	ds_read_b128 v[188:191], v149 offset:32768
	ds_read_b128 v[192:195], v149 offset:33792
	ds_read_b128 v[196:199], v150 offset:32768
	ds_read_b128 v[200:203], v150 offset:33792
	ds_read_b128 v[204:207], v151 offset:32768
	ds_read_b128 v[208:211], v151 offset:33792
	ds_read_b128 v[214:217], v152 offset:32768
	ds_read_b128 v[218:221], v152 offset:33792
	buffer_load_dwordx4 v128, s[28:31], s44 offen lds
	s_mov_b32 m0, s45
	s_nop 0
	buffer_load_dwordx4 v129, s[28:31], s44 offen lds
	s_waitcnt vmcnt(8)
	s_waitcnt lgkmcnt(0)
	s_barrier
	s_setprio 1
	v_mfma_f32_16x16x32_bf16 v[124:127], v[156:159], v[188:191], v[124:127]
	v_mfma_f32_16x16x32_bf16 v[120:123], v[164:167], v[188:191], v[120:123]
	v_mfma_f32_16x16x32_bf16 v[116:119], v[156:159], v[196:199], v[116:119]
	v_mfma_f32_16x16x32_bf16 v[112:115], v[164:167], v[196:199], v[112:115]
	v_mfma_f32_16x16x32_bf16 v[108:111], v[156:159], v[204:207], v[108:111]
	v_mfma_f32_16x16x32_bf16 v[104:107], v[164:167], v[204:207], v[104:107]
	v_mfma_f32_16x16x32_bf16 v[100:103], v[156:159], v[214:217], v[100:103]
	v_mfma_f32_16x16x32_bf16 v[96:99], v[164:167], v[214:217], v[96:99]
	v_mfma_f32_16x16x32_bf16 v[124:127], v[160:163], v[192:195], v[124:127]
	v_mfma_f32_16x16x32_bf16 v[120:123], v[168:171], v[192:195], v[120:123]
	v_mfma_f32_16x16x32_bf16 v[116:119], v[160:163], v[200:203], v[116:119]
	v_mfma_f32_16x16x32_bf16 v[112:115], v[168:171], v[200:203], v[112:115]
	v_mfma_f32_16x16x32_bf16 v[108:111], v[160:163], v[208:211], v[108:111]
	v_mfma_f32_16x16x32_bf16 v[104:107], v[168:171], v[208:211], v[104:107]
	v_mfma_f32_16x16x32_bf16 v[100:103], v[160:163], v[218:221], v[100:103]
	v_mfma_f32_16x16x32_bf16 v[96:99], v[168:171], v[218:221], v[96:99]
	s_setprio 0
	s_setprio 1
	v_mfma_f32_16x16x32_bf16 v[92:95], v[172:175], v[188:191], v[92:95]
	v_mfma_f32_16x16x32_bf16 v[88:91], v[180:183], v[188:191], v[88:91]
	v_mfma_f32_16x16x32_bf16 v[84:87], v[172:175], v[196:199], v[84:87]
	v_mfma_f32_16x16x32_bf16 v[80:83], v[180:183], v[196:199], v[80:83]
	v_mfma_f32_16x16x32_bf16 v[76:79], v[172:175], v[204:207], v[76:79]
	v_mfma_f32_16x16x32_bf16 v[72:75], v[180:183], v[204:207], v[72:75]
	v_mfma_f32_16x16x32_bf16 v[68:71], v[172:175], v[214:217], v[68:71]
	v_mfma_f32_16x16x32_bf16 v[64:67], v[180:183], v[214:217], v[64:67]
	v_mfma_f32_16x16x32_bf16 v[92:95], v[176:179], v[192:195], v[92:95]
	v_mfma_f32_16x16x32_bf16 v[88:91], v[184:187], v[192:195], v[88:91]
	v_mfma_f32_16x16x32_bf16 v[84:87], v[176:179], v[200:203], v[84:87]
	v_mfma_f32_16x16x32_bf16 v[80:83], v[184:187], v[200:203], v[80:83]
	v_mfma_f32_16x16x32_bf16 v[76:79], v[176:179], v[208:211], v[76:79]
	v_mfma_f32_16x16x32_bf16 v[72:75], v[184:187], v[208:211], v[72:75]
	v_mfma_f32_16x16x32_bf16 v[68:71], v[176:179], v[218:221], v[68:71]
	v_mfma_f32_16x16x32_bf16 v[64:67], v[184:187], v[218:221], v[64:67]
	s_setprio 0
	s_barrier
	v_readfirstlane_b32 s45, v138
	s_add_i32 s44, s43, 0x180
	s_mov_b32 m0, s45
	v_readfirstlane_b32 s45, v139
	ds_read_b128 v[188:191], v149 offset:49152
	ds_read_b128 v[192:195], v149 offset:50176
	ds_read_b128 v[196:199], v150 offset:49152
	ds_read_b128 v[200:203], v150 offset:50176
	ds_read_b128 v[204:207], v151 offset:49152
	ds_read_b128 v[208:211], v151 offset:50176
	ds_read_b128 v[214:217], v152 offset:49152
	ds_read_b128 v[218:221], v152 offset:50176
	buffer_load_dwordx4 v128, s[12:15], s44 offen lds
	s_mov_b32 m0, s45
	s_add_i32 s43, s43, 0x40180
	buffer_load_dwordx4 v129, s[12:15], s44 offen lds
	v_readfirstlane_b32 s44, v142
	s_mov_b32 m0, s44
	v_readfirstlane_b32 s44, v143
	buffer_load_dwordx4 v128, s[12:15], s43 offen lds
	s_mov_b32 m0, s44
	s_addk_i32 s42, 0x180
	buffer_load_dwordx4 v129, s[12:15], s43 offen lds
	v_readfirstlane_b32 s14, v140
	s_mov_b32 m0, s14
	v_readfirstlane_b32 s14, v141
	buffer_load_dwordx4 v128, s[28:31], s42 offen lds
	s_mov_b32 m0, s14
	s_nop 0
	buffer_load_dwordx4 v129, s[28:31], s42 offen lds
	s_waitcnt vmcnt(8)
	s_waitcnt lgkmcnt(0)
	s_barrier
	s_setprio 1
	v_mfma_f32_16x16x32_bf16 v[60:63], v[156:159], v[188:191], v[60:63]
	v_mfma_f32_16x16x32_bf16 v[56:59], v[164:167], v[188:191], v[56:59]
	v_mfma_f32_16x16x32_bf16 v[52:55], v[156:159], v[196:199], v[52:55]
	v_mfma_f32_16x16x32_bf16 v[48:51], v[164:167], v[196:199], v[48:51]
	v_mfma_f32_16x16x32_bf16 v[44:47], v[156:159], v[204:207], v[44:47]
	v_mfma_f32_16x16x32_bf16 v[40:43], v[164:167], v[204:207], v[40:43]
	v_mfma_f32_16x16x32_bf16 v[36:39], v[156:159], v[214:217], v[36:39]
	v_mfma_f32_16x16x32_bf16 v[32:35], v[164:167], v[214:217], v[32:35]
	v_mfma_f32_16x16x32_bf16 v[60:63], v[160:163], v[192:195], v[60:63]
	v_mfma_f32_16x16x32_bf16 v[56:59], v[168:171], v[192:195], v[56:59]
	v_mfma_f32_16x16x32_bf16 v[52:55], v[160:163], v[200:203], v[52:55]
	v_mfma_f32_16x16x32_bf16 v[48:51], v[168:171], v[200:203], v[48:51]
	v_mfma_f32_16x16x32_bf16 v[44:47], v[160:163], v[208:211], v[44:47]
	v_mfma_f32_16x16x32_bf16 v[40:43], v[168:171], v[208:211], v[40:43]
	v_mfma_f32_16x16x32_bf16 v[36:39], v[160:163], v[218:221], v[36:39]
	v_mfma_f32_16x16x32_bf16 v[32:35], v[168:171], v[218:221], v[32:35]
	s_setprio 0
	s_setprio 1
	v_mfma_f32_16x16x32_bf16 v[28:31], v[172:175], v[188:191], v[28:31]
	v_mfma_f32_16x16x32_bf16 v[24:27], v[180:183], v[188:191], v[24:27]
	v_mfma_f32_16x16x32_bf16 v[20:23], v[172:175], v[196:199], v[20:23]
	v_mfma_f32_16x16x32_bf16 v[16:19], v[180:183], v[196:199], v[16:19]
	v_mfma_f32_16x16x32_bf16 v[12:15], v[172:175], v[204:207], v[12:15]
	v_mfma_f32_16x16x32_bf16 v[8:11], v[180:183], v[204:207], v[8:11]
	v_mfma_f32_16x16x32_bf16 v[4:7], v[172:175], v[214:217], v[4:7]
	v_mfma_f32_16x16x32_bf16 v[0:3], v[180:183], v[214:217], v[0:3]
	v_mfma_f32_16x16x32_bf16 v[28:31], v[176:179], v[192:195], v[28:31]
	v_mfma_f32_16x16x32_bf16 v[24:27], v[184:187], v[192:195], v[24:27]
	v_mfma_f32_16x16x32_bf16 v[20:23], v[176:179], v[200:203], v[20:23]
	v_mfma_f32_16x16x32_bf16 v[16:19], v[184:187], v[200:203], v[16:19]
	v_mfma_f32_16x16x32_bf16 v[12:15], v[176:179], v[208:211], v[12:15]
	v_mfma_f32_16x16x32_bf16 v[8:11], v[184:187], v[208:211], v[8:11]
	v_mfma_f32_16x16x32_bf16 v[4:7], v[176:179], v[218:221], v[4:7]
	v_mfma_f32_16x16x32_bf16 v[0:3], v[184:187], v[218:221], v[0:3]
	s_setprio 0
	s_barrier
; #define LDA(dst, b, h) for (int m = 0; m < 4; ++m) for (int k = 0; k < 2; ++k) \
;     dst[m][k] = *reinterpret_cast<const bf16x8*>((char*)SA(b, h) + lds_byte(wr * 64 + m * 16 + fr, k * 32 + fq * 8))
; #define LDB(dst, b, h) for (int n = 0; n < 2; ++n) for (int k = 0; k < 2; ++k) \
;     dst[n][k] = *reinterpret_cast<const bf16x8*>((char*)SB(b, h) + lds_byte(wc * 32 + n * 16 + fr, k * 32 + fq * 8))
; #define MMA(ai, bj, At, Bt_) do { __builtin_amdgcn_s_setprio(1); \
;     for (int m = 0; m < 4; ++m) for (int n = 0; n < 2; ++n) for (int k = 0; k < 2; ++k) \
;       acc[ai][bj][m][n] = __builtin_amdgcn_mfma_f32_16x16x32_bf16(Bt_[n][k], At[m][k], acc[ai][bj][m][n], 0, 0, 0); \
;     __builtin_amdgcn_s_setprio(0); } while (0)
; #define WAIT_V(n) asm volatile("s_waitcnt vmcnt(" #n ")" ::: "memory")
; #define WAIT_L(n) asm volatile("s_waitcnt lgkmcnt(" #n ")" ::: "memory")
; #define BAR __builtin_amdgcn_s_barrier()
; #define SCHED __builtin_amdgcn_sched_barrier(0)
; template <int MODE>
; DI void gemm_phase(const bf16_t* __restrict__ A, const bf16_t* __restrict__ Bt, int M, int N, int K, const Epi& ep) {
;     ...
;             WAIT_V(8); WAIT_L(0); BAR; MMA(1, 0, At, B0); MMA(1, 1, At, B1); BAR; SCHED;
;             LDB(B0, 1, 0); LDB(B1, 1, 1); SCHED; LDA(At, 1, 0); STAGE(SA(0, 1), rsA, brow + HALF, t + 2);
;             WAIT_V(8); WAIT_L(0); BAR; MMA(0, 0, At, B0); MMA(0, 1, At, B1); BAR; SCHED;
;             LDA(At, 1, 1); STAGE(SB(1, 0), rsB, bcol, t + 3); STAGE(SB(1, 1), rsB, bcol + HALF, t + 3); STAGE(SA(1, 0), rsA, brow, t + 3);
;             WAIT_V(8); WAIT_L(0); BAR; MMA(1, 0, At, B0); MMA(1, 1, At, B1); BAR; SCHED;
;         }
;         {
;             LDB(B0, 0, 0); LDB(B1, 0, 1); SCHED; LDA(At, 0, 0); STAGE(SA(1, 1), rsA, brow + HALF, nt - 1);
;             WAIT_V(8); WAIT_L(0); BAR; MMA(0, 0, At, B0); MMA(0, 1, At, B1); BAR; SCHED;
;             LDA(At, 0, 1);
;             WAIT_V(2); WAIT_L(0); BAR; MMA(1, 0, At, B0); MMA(1, 1, At, B1); BAR; SCHED;
	s_add_i32 s40, s40, 2
	s_addk_i32 s41, 0x100
	s_cmp_gt_u32 s40, 11
	s_cbranch_scc0 .LBB0_488
	ds_read_b128 v[156:159], v147
	ds_read_b128 v[160:163], v147 offset:1024
	ds_read_b128 v[164:167], v147 offset:2048
	ds_read_b128 v[168:171], v147 offset:3072
	ds_read_b128 v[172:175], v148
	ds_read_b128 v[176:179], v148 offset:1024
	ds_read_b128 v[180:183], v148 offset:2048
	ds_read_b128 v[184:187], v148 offset:3072
	s_or_b32 s6, s7, 0x780
	v_readfirstlane_b32 s7, v144
	s_mov_b32 m0, s7
	v_readfirstlane_b32 s7, v145
	ds_read_b128 v[188:191], v149
	ds_read_b128 v[192:195], v149 offset:1024
	ds_read_b128 v[196:199], v150
	ds_read_b128 v[200:203], v150 offset:1024
	ds_read_b128 v[204:207], v151
	ds_read_b128 v[208:211], v151 offset:1024
	ds_read_b128 v[214:217], v152
	ds_read_b128 v[218:221], v152 offset:1024
	buffer_load_dwordx4 v128, s[28:31], s6 offen lds
	s_mov_b32 m0, s7
	s_nop 0
	buffer_load_dwordx4 v129, s[28:31], s6 offen lds
	s_waitcnt vmcnt(8)
	s_waitcnt lgkmcnt(0)
	s_barrier
	s_setprio 1
	v_mfma_f32_16x16x32_bf16 v[124:127], v[156:159], v[188:191], v[124:127]
	v_mfma_f32_16x16x32_bf16 v[120:123], v[164:167], v[188:191], v[120:123]
	v_mfma_f32_16x16x32_bf16 v[116:119], v[156:159], v[196:199], v[116:119]
	v_mfma_f32_16x16x32_bf16 v[112:115], v[164:167], v[196:199], v[112:115]
	v_mfma_f32_16x16x32_bf16 v[108:111], v[156:159], v[204:207], v[108:111]
	v_mfma_f32_16x16x32_bf16 v[124:127], v[160:163], v[192:195], v[124:127]
	v_mfma_f32_16x16x32_bf16 v[120:123], v[168:171], v[192:195], v[120:123]
	v_mfma_f32_16x16x32_bf16 v[116:119], v[160:163], v[200:203], v[116:119]
	v_mfma_f32_16x16x32_bf16 v[112:115], v[168:171], v[200:203], v[112:115]
	v_mfma_f32_16x16x32_bf16 v[222:225], v[160:163], v[208:211], v[108:111]
	v_mfma_f32_16x16x32_bf16 v[104:107], v[164:167], v[204:207], v[104:107]
	v_mfma_f32_16x16x32_bf16 v[100:103], v[156:159], v[214:217], v[100:103]
	v_mfma_f32_16x16x32_bf16 v[96:99], v[164:167], v[214:217], v[96:99]
	v_mfma_f32_16x16x32_bf16 v[226:229], v[168:171], v[208:211], v[104:107]
	v_mfma_f32_16x16x32_bf16 v[230:233], v[160:163], v[218:221], v[100:103]
	v_mfma_f32_16x16x32_bf16 v[234:237], v[168:171], v[218:221], v[96:99]
	s_setprio 0
	s_setprio 1
	v_mfma_f32_16x16x32_bf16 v[92:95], v[172:175], v[188:191], v[92:95]
	v_mfma_f32_16x16x32_bf16 v[88:91], v[180:183], v[188:191], v[88:91]
	v_mfma_f32_16x16x32_bf16 v[84:87], v[172:175], v[196:199], v[84:87]
	v_mfma_f32_16x16x32_bf16 v[80:83], v[180:183], v[196:199], v[80:83]
	v_mfma_f32_16x16x32_bf16 v[92:95], v[176:179], v[192:195], v[92:95]
	v_mfma_f32_16x16x32_bf16 v[88:91], v[184:187], v[192:195], v[88:91]
	v_mfma_f32_16x16x32_bf16 v[84:87], v[176:179], v[200:203], v[84:87]
	v_mfma_f32_16x16x32_bf16 v[80:83], v[184:187], v[200:203], v[80:83]
	v_mfma_f32_16x16x32_bf16 v[76:79], v[172:175], v[204:207], v[76:79]
	v_mfma_f32_16x16x32_bf16 v[72:75], v[180:183], v[204:207], v[72:75]
	v_mfma_f32_16x16x32_bf16 v[68:71], v[172:175], v[214:217], v[68:71]
	v_mfma_f32_16x16x32_bf16 v[64:67], v[180:183], v[214:217], v[64:67]
	v_mfma_f32_16x16x32_bf16 v[188:191], v[176:179], v[208:211], v[76:79]
	v_mfma_f32_16x16x32_bf16 v[192:195], v[184:187], v[208:211], v[72:75]
	v_mfma_f32_16x16x32_bf16 v[196:199], v[176:179], v[218:221], v[68:71]
	v_mfma_f32_16x16x32_bf16 v[200:203], v[184:187], v[218:221], v[64:67]
	s_setprio 0
	s_barrier
	s_nop 1
	ds_read_b128 v[64:67], v149 offset:16384
	ds_read_b128 v[68:71], v149 offset:17408
	ds_read_b128 v[72:75], v150 offset:16384
	ds_read_b128 v[76:79], v150 offset:17408
	ds_read_b128 v[96:99], v151 offset:16384
	ds_read_b128 v[100:103], v151 offset:17408
	ds_read_b128 v[104:107], v152 offset:16384
	ds_read_b128 v[108:111], v152 offset:17408
	s_waitcnt vmcnt(2)
	s_waitcnt lgkmcnt(0)
	s_barrier
	s_setprio 1
	v_mfma_f32_16x16x32_bf16 v[60:63], v[156:159], v[64:67], v[60:63]
	v_mfma_f32_16x16x32_bf16 v[56:59], v[164:167], v[64:67], v[56:59]
	v_mfma_f32_16x16x32_bf16 v[52:55], v[156:159], v[72:75], v[52:55]
	v_mfma_f32_16x16x32_bf16 v[48:51], v[164:167], v[72:75], v[48:51]
	v_mfma_f32_16x16x32_bf16 v[60:63], v[160:163], v[68:71], v[60:63]
	v_mfma_f32_16x16x32_bf16 v[56:59], v[168:171], v[68:71], v[56:59]
	v_mfma_f32_16x16x32_bf16 v[52:55], v[160:163], v[76:79], v[52:55]
	v_mfma_f32_16x16x32_bf16 v[48:51], v[168:171], v[76:79], v[48:51]
	v_mfma_f32_16x16x32_bf16 v[44:47], v[156:159], v[96:99], v[44:47]
	v_mfma_f32_16x16x32_bf16 v[40:43], v[164:167], v[96:99], v[40:43]
	v_mfma_f32_16x16x32_bf16 v[36:39], v[156:159], v[104:107], v[36:39]
	v_mfma_f32_16x16x32_bf16 v[32:35], v[164:167], v[104:107], v[32:35]
	v_mfma_f32_16x16x32_bf16 v[204:207], v[160:163], v[100:103], v[44:47]
	v_mfma_f32_16x16x32_bf16 v[208:211], v[168:171], v[100:103], v[40:43]
	v_mfma_f32_16x16x32_bf16 v[156:159], v[160:163], v[108:111], v[36:39]
	v_mfma_f32_16x16x32_bf16 v[160:163], v[168:171], v[108:111], v[32:35]
	s_setprio 0
	s_setprio 1
	v_mfma_f32_16x16x32_bf16 v[28:31], v[172:175], v[64:67], v[28:31]
	v_mfma_f32_16x16x32_bf16 v[24:27], v[180:183], v[64:67], v[24:27]
	v_mfma_f32_16x16x32_bf16 v[20:23], v[172:175], v[72:75], v[20:23]
	v_mfma_f32_16x16x32_bf16 v[16:19], v[180:183], v[72:75], v[16:19]
	v_mfma_f32_16x16x32_bf16 v[28:31], v[176:179], v[68:71], v[28:31]
	v_mfma_f32_16x16x32_bf16 v[24:27], v[184:187], v[68:71], v[24:27]
	v_mfma_f32_16x16x32_bf16 v[20:23], v[176:179], v[76:79], v[20:23]
	v_mfma_f32_16x16x32_bf16 v[16:19], v[184:187], v[76:79], v[16:19]
	v_mfma_f32_16x16x32_bf16 v[12:15], v[172:175], v[96:99], v[12:15]
	v_mfma_f32_16x16x32_bf16 v[8:11], v[180:183], v[96:99], v[8:11]
	v_mfma_f32_16x16x32_bf16 v[4:7], v[172:175], v[104:107], v[4:7]
	v_mfma_f32_16x16x32_bf16 v[0:3], v[180:183], v[104:107], v[0:3]
	v_mfma_f32_16x16x32_bf16 v[164:167], v[176:179], v[100:103], v[12:15]
	v_mfma_f32_16x16x32_bf16 v[168:171], v[184:187], v[100:103], v[8:11]
	v_mfma_f32_16x16x32_bf16 v[172:175], v[176:179], v[108:111], v[4:7]
	v_mfma_f32_16x16x32_bf16 v[176:179], v[184:187], v[108:111], v[0:3]
	s_setprio 0
	s_barrier
; #define LDA(dst, b, h) for (int m = 0; m < 4; ++m) for (int k = 0; k < 2; ++k) \
;     dst[m][k] = *reinterpret_cast<const bf16x8*>((char*)SA(b, h) + lds_byte(wr * 64 + m * 16 + fr, k * 32 + fq * 8))
; #define LDB(dst, b, h) for (int n = 0; n < 2; ++n) for (int k = 0; k < 2; ++k) \
;     dst[n][k] = *reinterpret_cast<const bf16x8*>((char*)SB(b, h) + lds_byte(wc * 32 + n * 16 + fr, k * 32 + fq * 8))
; #define MMA(ai, bj, At, Bt_) do { __builtin_amdgcn_s_setprio(1); \
;     for (int m = 0; m < 4; ++m) for (int n = 0; n < 2; ++n) for (int k = 0; k < 2; ++k) \
;       acc[ai][bj][m][n] = __builtin_amdgcn_mfma_f32_16x16x32_bf16(Bt_[n][k], At[m][k], acc[ai][bj][m][n], 0, 0, 0); \
;     __builtin_amdgcn_s_setprio(0); } while (0)
; #define WAIT_V(n) asm volatile("s_waitcnt vmcnt(" #n ")" ::: "memory")
; #define WAIT_L(n) asm volatile("s_waitcnt lgkmcnt(" #n ")" ::: "memory")
; #define BAR __builtin_amdgcn_s_barrier()
; #define SCHED __builtin_amdgcn_sched_barrier(0)
; template <int MODE>
; DI void gemm_phase(const bf16_t* __restrict__ A, const bf16_t* __restrict__ Bt, int M, int N, int K, const Epi& ep) {
;     ...
;             LDB(B0, 1, 0); LDB(B1, 1, 1); SCHED; LDA(At, 1, 0);
;             WAIT_V(0); WAIT_L(0); BAR; MMA(0, 0, At, B0); MMA(0, 1, At, B1); BAR; SCHED;
;             LDA(At, 1, 1);
;             WAIT_L(0); BAR; MMA(1, 0, At, B0); MMA(1, 1, At, B1); BAR; SCHED;
;         }
;         if (wr == 0) BAR;
	s_nop 1
	ds_read_b128 v[0:3], v153
	ds_read_b128 v[4:7], v153 offset:1024
	ds_read_b128 v[8:11], v153 offset:2048
	ds_read_b128 v[12:15], v153 offset:3072
	ds_read_b128 v[180:183], v154
	ds_read_b128 v[184:187], v154 offset:1024
	ds_read_b128 v[214:217], v154 offset:2048
	ds_read_b128 v[218:221], v154 offset:3072
	ds_read_b128 v[32:35], v149 offset:32768
	ds_read_b128 v[36:39], v149 offset:33792
	ds_read_b128 v[40:43], v150 offset:32768
	ds_read_b128 v[44:47], v150 offset:33792
	ds_read_b128 v[238:241], v151 offset:32768
	ds_read_b128 v[242:245], v151 offset:33792
	ds_read_b128 v[246:249], v152 offset:32768
	ds_read_b128 v[64:67], v152 offset:33792
	s_waitcnt vmcnt(0)
	s_waitcnt lgkmcnt(0)
	s_barrier
	s_setprio 1
	v_mfma_f32_16x16x32_bf16 v[68:71], v[0:3], v[32:35], v[124:127]
	v_mfma_f32_16x16x32_bf16 v[96:99], v[4:7], v[36:39], v[68:71]
	v_mfma_f32_16x16x32_bf16 v[68:71], v[8:11], v[32:35], v[120:123]
	v_mfma_f32_16x16x32_bf16 v[100:103], v[12:15], v[36:39], v[68:71]
	v_mfma_f32_16x16x32_bf16 v[68:71], v[0:3], v[40:43], v[116:119]
	v_mfma_f32_16x16x32_bf16 v[104:107], v[4:7], v[44:47], v[68:71]
	v_mfma_f32_16x16x32_bf16 v[68:71], v[8:11], v[40:43], v[112:115]
	v_mfma_f32_16x16x32_bf16 v[108:111], v[12:15], v[44:47], v[68:71]
	v_mfma_f32_16x16x32_bf16 v[68:71], v[0:3], v[238:241], v[222:225]
	v_mfma_f32_16x16x32_bf16 v[112:115], v[4:7], v[242:245], v[68:71]
	v_mfma_f32_16x16x32_bf16 v[68:71], v[8:11], v[238:241], v[226:229]
	v_mfma_f32_16x16x32_bf16 v[116:119], v[12:15], v[242:245], v[68:71]
	v_mfma_f32_16x16x32_bf16 v[68:71], v[0:3], v[246:249], v[230:233]
	v_mfma_f32_16x16x32_bf16 v[120:123], v[4:7], v[64:67], v[68:71]
	v_mfma_f32_16x16x32_bf16 v[68:71], v[8:11], v[246:249], v[234:237]
	v_mfma_f32_16x16x32_bf16 v[124:127], v[12:15], v[64:67], v[68:71]
	s_setprio 0
	s_setprio 1
	v_mfma_f32_16x16x32_bf16 v[68:71], v[180:183], v[32:35], v[92:95]
	v_mfma_f32_16x16x32_bf16 v[32:35], v[214:217], v[32:35], v[88:91]
	v_mfma_f32_16x16x32_bf16 v[222:225], v[184:187], v[36:39], v[68:71]
	v_mfma_f32_16x16x32_bf16 v[68:71], v[218:221], v[36:39], v[32:35]
	v_mfma_f32_16x16x32_bf16 v[32:35], v[180:183], v[40:43], v[84:87]
	v_mfma_f32_16x16x32_bf16 v[72:75], v[184:187], v[44:47], v[32:35]
	v_mfma_f32_16x16x32_bf16 v[32:35], v[214:217], v[40:43], v[80:83]
	v_mfma_f32_16x16x32_bf16 v[76:79], v[218:221], v[44:47], v[32:35]
	v_mfma_f32_16x16x32_bf16 v[32:35], v[180:183], v[238:241], v[188:191]
	v_mfma_f32_16x16x32_bf16 v[80:83], v[184:187], v[242:245], v[32:35]
	v_mfma_f32_16x16x32_bf16 v[32:35], v[214:217], v[238:241], v[192:195]
	v_mfma_f32_16x16x32_bf16 v[84:87], v[218:221], v[242:245], v[32:35]
	v_mfma_f32_16x16x32_bf16 v[32:35], v[180:183], v[246:249], v[196:199]
	v_mfma_f32_16x16x32_bf16 v[88:91], v[184:187], v[64:67], v[32:35]
	v_mfma_f32_16x16x32_bf16 v[32:35], v[214:217], v[246:249], v[200:203]
	v_mfma_f32_16x16x32_bf16 v[92:95], v[218:221], v[64:67], v[32:35]
	s_setprio 0
	s_barrier
	ds_read_b128 v[64:67], v149 offset:49152
	ds_read_b128 v[188:191], v149 offset:50176
	ds_read_b128 v[192:195], v150 offset:49152
	ds_read_b128 v[196:199], v150 offset:50176
	ds_read_b128 v[200:203], v151 offset:49152
	ds_read_b128 v[226:229], v151 offset:50176
	ds_read_b128 v[230:233], v152 offset:49152
	ds_read_b128 v[234:237], v152 offset:50176
	s_waitcnt lgkmcnt(0)
	s_barrier
	s_setprio 1
	v_mfma_f32_16x16x32_bf16 v[32:35], v[0:3], v[64:67], v[60:63]
	v_mfma_f32_16x16x32_bf16 v[40:43], v[0:3], v[192:195], v[52:55]
	v_mfma_f32_16x16x32_bf16 v[44:47], v[8:11], v[192:195], v[48:51]
	v_mfma_f32_16x16x32_bf16 v[48:51], v[0:3], v[200:203], v[204:207]
	v_mfma_f32_16x16x32_bf16 v[0:3], v[0:3], v[230:233], v[156:159]
	v_mfma_f32_16x16x32_bf16 v[36:39], v[8:11], v[64:67], v[56:59]
	v_mfma_f32_16x16x32_bf16 v[52:55], v[8:11], v[200:203], v[208:211]
	v_mfma_f32_16x16x32_bf16 v[56:59], v[4:7], v[234:237], v[0:3]
	v_mfma_f32_16x16x32_bf16 v[0:3], v[8:11], v[230:233], v[160:163]
	v_mfma_f32_16x16x32_bf16 v[32:35], v[4:7], v[188:191], v[32:35]
	v_mfma_f32_16x16x32_bf16 v[36:39], v[12:15], v[188:191], v[36:39]
	v_mfma_f32_16x16x32_bf16 v[40:43], v[4:7], v[196:199], v[40:43]
	v_mfma_f32_16x16x32_bf16 v[44:47], v[12:15], v[196:199], v[44:47]
	v_mfma_f32_16x16x32_bf16 v[48:51], v[4:7], v[226:229], v[48:51]
	v_mfma_f32_16x16x32_bf16 v[52:55], v[12:15], v[226:229], v[52:55]
	v_mfma_f32_16x16x32_bf16 v[60:63], v[12:15], v[234:237], v[0:3]
	s_setprio 0
	s_setprio 1
	v_mfma_f32_16x16x32_bf16 v[0:3], v[180:183], v[64:67], v[28:31]
	v_mfma_f32_16x16x32_bf16 v[4:7], v[214:217], v[64:67], v[24:27]
	v_mfma_f32_16x16x32_bf16 v[8:11], v[180:183], v[192:195], v[20:23]
	v_mfma_f32_16x16x32_bf16 v[12:15], v[214:217], v[192:195], v[16:19]
	v_mfma_f32_16x16x32_bf16 v[16:19], v[180:183], v[200:203], v[164:167]
	v_mfma_f32_16x16x32_bf16 v[20:23], v[214:217], v[200:203], v[168:171]
	v_mfma_f32_16x16x32_bf16 v[24:27], v[180:183], v[230:233], v[172:175]
	v_mfma_f32_16x16x32_bf16 v[28:31], v[214:217], v[230:233], v[176:179]
	v_mfma_f32_16x16x32_bf16 v[0:3], v[184:187], v[188:191], v[0:3]
	v_mfma_f32_16x16x32_bf16 v[4:7], v[218:221], v[188:191], v[4:7]
	v_mfma_f32_16x16x32_bf16 v[8:11], v[184:187], v[196:199], v[8:11]
	v_mfma_f32_16x16x32_bf16 v[12:15], v[218:221], v[196:199], v[12:15]
	v_mfma_f32_16x16x32_bf16 v[16:19], v[184:187], v[226:229], v[16:19]
	v_mfma_f32_16x16x32_bf16 v[20:23], v[218:221], v[226:229], v[20:23]
	v_mfma_f32_16x16x32_bf16 v[24:27], v[184:187], v[234:237], v[24:27]
	v_mfma_f32_16x16x32_bf16 v[28:31], v[218:221], v[234:237], v[28:31]
	s_setprio 0
	s_barrier
	s_and_saveexec_b64 s[6:7], s[38:39]
	s_cbranch_execz .LBB0_480
	s_barrier
	s_branch .LBB0_480

; #define LDA(dst, b, h) for (int m = 0; m < 4; ++m) for (int k = 0; k < 2; ++k) \
;     dst[m][k] = *reinterpret_cast<const bf16x8*>((char*)SA(b, h) + lds_byte(wr * 64 + m * 16 + fr, k * 32 + fq * 8))
; #define LDB(dst, b, h) for (int n = 0; n < 2; ++n) for (int k = 0; k < 2; ++k) \
;     dst[n][k] = *reinterpret_cast<const bf16x8*>((char*)SB(b, h) + lds_byte(wc * 32 + n * 16 + fr, k * 32 + fq * 8))
; #define MMA(ai, bj, At, Bt_) do { __builtin_amdgcn_s_setprio(1); \
;     for (int m = 0; m < 4; ++m) for (int n = 0; n < 2; ++n) for (int k = 0; k < 2; ++k) \
;       acc[ai][bj][m][n] = __builtin_amdgcn_mfma_f32_16x16x32_bf16(Bt_[n][k], At[m][k], acc[ai][bj][m][n], 0, 0, 0); \
;     __builtin_amdgcn_s_setprio(0); } while (0)
; #define WAIT_V(n) asm volatile("s_waitcnt vmcnt(" #n ")" ::: "memory")
; #define WAIT_L(n) asm volatile("s_waitcnt lgkmcnt(" #n ")" ::: "memory")
; #define BAR __builtin_amdgcn_s_barrier()
; #define SCHED __builtin_amdgcn_sched_barrier(0)
; template <int MODE>
; DI void gemm_phase(const bf16_t* __restrict__ A, const bf16_t* __restrict__ Bt, int M, int N, int K, const Epi& ep) {
;     ...
;             LDB(B0, 0, 0); LDB(B1, 0, 1); SCHED; LDA(At, 0, 0); STAGE(SA(1, 1), rsA, brow + HALF, t + 1);
;             WAIT_V(8); WAIT_L(0); BAR; MMA(0, 0, At, B0); MMA(0, 1, At, B1); BAR; SCHED;
;             LDA(At, 0, 1); STAGE(SB(0, 0), rsB, bcol, t + 2); STAGE(SB(0, 1), rsB, bcol + HALF, t + 2); STAGE(SA(0, 0), rsA, brow, t + 2);
;             WAIT_V(8); WAIT_L(0); BAR; MMA(1, 0, At, B0); MMA(1, 1, At, B1); BAR; SCHED;
;             LDB(B0, 1, 0); LDB(B1, 1, 1); SCHED; LDA(At, 1, 0); STAGE(SA(0, 1), rsA, brow + HALF, t + 2);
;             WAIT_V(8); WAIT_L(0); BAR; MMA(0, 0, At, B0); MMA(0, 1, At, B1); BAR; SCHED;
;             LDA(At, 1, 1); STAGE(SB(1, 0), rsB, bcol, t + 3); STAGE(SB(1, 1), rsB, bcol + HALF, t + 3); STAGE(SA(1, 0), rsA, brow, t + 3);
;             WAIT_V(8); WAIT_L(0); BAR; MMA(1, 0, At, B0); MMA(1, 1, At, B1); BAR; SCHED;
.LBB0_558:
	ds_read_b128 v[156:159], v147
	ds_read_b128 v[160:163], v147 offset:1024
	ds_read_b128 v[164:167], v147 offset:2048
	ds_read_b128 v[168:171], v147 offset:3072
	ds_read_b128 v[172:175], v148
	ds_read_b128 v[176:179], v148 offset:1024
	ds_read_b128 v[180:183], v148 offset:2048
	ds_read_b128 v[184:187], v148 offset:3072
	s_add_i32 s40, s27, s31
	v_readfirstlane_b32 s7, v144
	s_add_i32 s6, s40, 0x40080
	s_mov_b32 m0, s7
	v_readfirstlane_b32 s7, v145
	ds_read_b128 v[188:191], v149
	ds_read_b128 v[192:195], v149 offset:1024
	ds_read_b128 v[196:199], v150
	ds_read_b128 v[200:203], v150 offset:1024
	ds_read_b128 v[204:207], v151
	ds_read_b128 v[208:211], v151 offset:1024
	ds_read_b128 v[214:217], v152
	ds_read_b128 v[218:221], v152 offset:1024
	buffer_load_dwordx4 v128, s[8:11], s6 offen lds
	s_mov_b32 m0, s7
	s_nop 0
	buffer_load_dwordx4 v129, s[8:11], s6 offen lds
	s_waitcnt vmcnt(8)
	s_waitcnt lgkmcnt(0)
	s_barrier
	s_setprio 1
	v_mfma_f32_16x16x32_bf16 v[124:127], v[156:159], v[188:191], v[124:127]
	v_mfma_f32_16x16x32_bf16 v[120:123], v[164:167], v[188:191], v[120:123]
	v_mfma_f32_16x16x32_bf16 v[116:119], v[156:159], v[196:199], v[116:119]
	v_mfma_f32_16x16x32_bf16 v[112:115], v[164:167], v[196:199], v[112:115]
	v_mfma_f32_16x16x32_bf16 v[108:111], v[156:159], v[204:207], v[108:111]
	v_mfma_f32_16x16x32_bf16 v[104:107], v[164:167], v[204:207], v[104:107]
	v_mfma_f32_16x16x32_bf16 v[100:103], v[156:159], v[214:217], v[100:103]
	v_mfma_f32_16x16x32_bf16 v[96:99], v[164:167], v[214:217], v[96:99]
	v_mfma_f32_16x16x32_bf16 v[124:127], v[160:163], v[192:195], v[124:127]
	v_mfma_f32_16x16x32_bf16 v[120:123], v[168:171], v[192:195], v[120:123]
	v_mfma_f32_16x16x32_bf16 v[116:119], v[160:163], v[200:203], v[116:119]
	v_mfma_f32_16x16x32_bf16 v[112:115], v[168:171], v[200:203], v[112:115]
	v_mfma_f32_16x16x32_bf16 v[108:111], v[160:163], v[208:211], v[108:111]
	v_mfma_f32_16x16x32_bf16 v[104:107], v[168:171], v[208:211], v[104:107]
	v_mfma_f32_16x16x32_bf16 v[100:103], v[160:163], v[218:221], v[100:103]
	v_mfma_f32_16x16x32_bf16 v[96:99], v[168:171], v[218:221], v[96:99]
	s_setprio 0
	s_setprio 1
	v_mfma_f32_16x16x32_bf16 v[92:95], v[172:175], v[188:191], v[92:95]
	v_mfma_f32_16x16x32_bf16 v[88:91], v[180:183], v[188:191], v[88:91]
	v_mfma_f32_16x16x32_bf16 v[84:87], v[172:175], v[196:199], v[84:87]
	v_mfma_f32_16x16x32_bf16 v[80:83], v[180:183], v[196:199], v[80:83]
	v_mfma_f32_16x16x32_bf16 v[76:79], v[172:175], v[204:207], v[76:79]
	v_mfma_f32_16x16x32_bf16 v[72:75], v[180:183], v[204:207], v[72:75]
	v_mfma_f32_16x16x32_bf16 v[68:71], v[172:175], v[214:217], v[68:71]
	v_mfma_f32_16x16x32_bf16 v[64:67], v[180:183], v[214:217], v[64:67]
	v_mfma_f32_16x16x32_bf16 v[92:95], v[176:179], v[192:195], v[92:95]
	v_mfma_f32_16x16x32_bf16 v[88:91], v[184:187], v[192:195], v[88:91]
	v_mfma_f32_16x16x32_bf16 v[84:87], v[176:179], v[200:203], v[84:87]
	v_mfma_f32_16x16x32_bf16 v[80:83], v[184:187], v[200:203], v[80:83]
	v_mfma_f32_16x16x32_bf16 v[76:79], v[176:179], v[208:211], v[76:79]
	v_mfma_f32_16x16x32_bf16 v[72:75], v[184:187], v[208:211], v[72:75]
	v_mfma_f32_16x16x32_bf16 v[68:71], v[176:179], v[218:221], v[68:71]
	v_mfma_f32_16x16x32_bf16 v[64:67], v[184:187], v[218:221], v[64:67]
	s_setprio 0
	s_barrier
	s_add_i32 s41, s23, s31
	v_readfirstlane_b32 s43, v130
	s_add_i32 s42, s41, 0x100
	s_mov_b32 s6, s10
	s_mov_b32 s7, s11
	s_mov_b32 m0, s43
	v_readfirstlane_b32 s43, v131
	ds_read_b128 v[188:191], v149 offset:16384
	ds_read_b128 v[192:195], v149 offset:17408
	ds_read_b128 v[196:199], v150 offset:16384
	ds_read_b128 v[200:203], v150 offset:17408
	ds_read_b128 v[204:207], v151 offset:16384
	ds_read_b128 v[208:211], v151 offset:17408
	ds_read_b128 v[214:217], v152 offset:16384
	ds_read_b128 v[218:221], v152 offset:17408
	buffer_load_dwordx4 v128, s[4:7], s42 offen lds
	s_mov_b32 m0, s43
	v_readfirstlane_b32 s43, v132
	buffer_load_dwordx4 v129, s[4:7], s42 offen lds
	s_add_i32 s42, s41, 0x40100
	s_mov_b32 m0, s43
	v_readfirstlane_b32 s43, v133
	buffer_load_dwordx4 v128, s[4:7], s42 offen lds
	s_mov_b32 m0, s43
	v_readfirstlane_b32 s43, v134
	buffer_load_dwordx4 v129, s[4:7], s42 offen lds
	s_add_i32 s42, s40, 0x100
	s_mov_b32 m0, s43
	v_readfirstlane_b32 s43, v135
	buffer_load_dwordx4 v128, s[8:11], s42 offen lds
	s_mov_b32 m0, s43
	s_nop 0
	buffer_load_dwordx4 v129, s[8:11], s42 offen lds
	s_waitcnt vmcnt(8)
	s_waitcnt lgkmcnt(0)
	s_barrier
	s_setprio 1
	v_mfma_f32_16x16x32_bf16 v[60:63], v[156:159], v[188:191], v[60:63]
	v_mfma_f32_16x16x32_bf16 v[56:59], v[164:167], v[188:191], v[56:59]
	v_mfma_f32_16x16x32_bf16 v[52:55], v[156:159], v[196:199], v[52:55]
	v_mfma_f32_16x16x32_bf16 v[48:51], v[164:167], v[196:199], v[48:51]
	v_mfma_f32_16x16x32_bf16 v[44:47], v[156:159], v[204:207], v[44:47]
	v_mfma_f32_16x16x32_bf16 v[40:43], v[164:167], v[204:207], v[40:43]
	v_mfma_f32_16x16x32_bf16 v[36:39], v[156:159], v[214:217], v[36:39]
	v_mfma_f32_16x16x32_bf16 v[32:35], v[164:167], v[214:217], v[32:35]
	v_mfma_f32_16x16x32_bf16 v[60:63], v[160:163], v[192:195], v[60:63]
	v_mfma_f32_16x16x32_bf16 v[56:59], v[168:171], v[192:195], v[56:59]
	v_mfma_f32_16x16x32_bf16 v[52:55], v[160:163], v[200:203], v[52:55]
	v_mfma_f32_16x16x32_bf16 v[48:51], v[168:171], v[200:203], v[48:51]
	v_mfma_f32_16x16x32_bf16 v[44:47], v[160:163], v[208:211], v[44:47]
	v_mfma_f32_16x16x32_bf16 v[40:43], v[168:171], v[208:211], v[40:43]
	v_mfma_f32_16x16x32_bf16 v[36:39], v[160:163], v[218:221], v[36:39]
	v_mfma_f32_16x16x32_bf16 v[32:35], v[168:171], v[218:221], v[32:35]
	s_setprio 0
	s_setprio 1
	v_mfma_f32_16x16x32_bf16 v[28:31], v[172:175], v[188:191], v[28:31]
	v_mfma_f32_16x16x32_bf16 v[24:27], v[180:183], v[188:191], v[24:27]
	v_mfma_f32_16x16x32_bf16 v[20:23], v[172:175], v[196:199], v[20:23]
	v_mfma_f32_16x16x32_bf16 v[16:19], v[180:183], v[196:199], v[16:19]
	v_mfma_f32_16x16x32_bf16 v[12:15], v[172:175], v[204:207], v[12:15]
	v_mfma_f32_16x16x32_bf16 v[8:11], v[180:183], v[204:207], v[8:11]
	v_mfma_f32_16x16x32_bf16 v[4:7], v[172:175], v[214:217], v[4:7]
	v_mfma_f32_16x16x32_bf16 v[0:3], v[180:183], v[214:217], v[0:3]
	v_mfma_f32_16x16x32_bf16 v[28:31], v[176:179], v[192:195], v[28:31]
	v_mfma_f32_16x16x32_bf16 v[24:27], v[184:187], v[192:195], v[24:27]
	v_mfma_f32_16x16x32_bf16 v[20:23], v[176:179], v[200:203], v[20:23]
	v_mfma_f32_16x16x32_bf16 v[16:19], v[184:187], v[200:203], v[16:19]
	v_mfma_f32_16x16x32_bf16 v[12:15], v[176:179], v[208:211], v[12:15]
	v_mfma_f32_16x16x32_bf16 v[8:11], v[184:187], v[208:211], v[8:11]
	v_mfma_f32_16x16x32_bf16 v[4:7], v[176:179], v[218:221], v[4:7]
	v_mfma_f32_16x16x32_bf16 v[0:3], v[184:187], v[218:221], v[0:3]
	s_setprio 0
	s_barrier
; #define LDA(dst, b, h) for (int m = 0; m < 4; ++m) for (int k = 0; k < 2; ++k) \
;     dst[m][k] = *reinterpret_cast<const bf16x8*>((char*)SA(b, h) + lds_byte(wr * 64 + m * 16 + fr, k * 32 + fq * 8))
; #define LDB(dst, b, h) for (int n = 0; n < 2; ++n) for (int k = 0; k < 2; ++k) \
;     dst[n][k] = *reinterpret_cast<const bf16x8*>((char*)SB(b, h) + lds_byte(wc * 32 + n * 16 + fr, k * 32 + fq * 8))
; #define MMA(ai, bj, At, Bt_) do { __builtin_amdgcn_s_setprio(1); \
;     for (int m = 0; m < 4; ++m) for (int n = 0; n < 2; ++n) for (int k = 0; k < 2; ++k) \
;       acc[ai][bj][m][n] = __builtin_amdgcn_mfma_f32_16x16x32_bf16(Bt_[n][k], At[m][k], acc[ai][bj][m][n], 0, 0, 0); \
;     __builtin_amdgcn_s_setprio(0); } while (0)
; #define WAIT_V(n) asm volatile("s_waitcnt vmcnt(" #n ")" ::: "memory")
; #define WAIT_L(n) asm volatile("s_waitcnt lgkmcnt(" #n ")" ::: "memory")
; #define BAR __builtin_amdgcn_s_barrier()
; #define SCHED __builtin_amdgcn_sched_barrier(0)
; template <int MODE>
; DI void gemm_phase(const bf16_t* __restrict__ A, const bf16_t* __restrict__ Bt, int M, int N, int K, const Epi& ep) {
;     ...
;             LDB(B0, 1, 0); LDB(B1, 1, 1); SCHED; LDA(At, 1, 0); STAGE(SA(0, 1), rsA, brow + HALF, t + 2);
;             WAIT_V(8); WAIT_L(0); BAR; MMA(0, 0, At, B0); MMA(0, 1, At, B1); BAR; SCHED;
;             LDA(At, 1, 1); STAGE(SB(1, 0), rsB, bcol, t + 3); STAGE(SB(1, 1), rsB, bcol + HALF, t + 3); STAGE(SA(1, 0), rsA, brow, t + 3);
;             WAIT_V(8); WAIT_L(0); BAR; MMA(1, 0, At, B0); MMA(1, 1, At, B1); BAR; SCHED;
	ds_read_b128 v[156:159], v153
	ds_read_b128 v[160:163], v153 offset:1024
	ds_read_b128 v[164:167], v153 offset:2048
	ds_read_b128 v[168:171], v153 offset:3072
	ds_read_b128 v[172:175], v154
	ds_read_b128 v[176:179], v154 offset:1024
	ds_read_b128 v[180:183], v154 offset:2048
	ds_read_b128 v[184:187], v154 offset:3072
	v_readfirstlane_b32 s43, v136
	s_add_i32 s42, s40, 0x40100
	s_mov_b32 m0, s43
	v_readfirstlane_b32 s43, v137
	ds_read_b128 v[188:191], v149 offset:32768
	ds_read_b128 v[192:195], v149 offset:33792
	ds_read_b128 v[196:199], v150 offset:32768
	ds_read_b128 v[200:203], v150 offset:33792
	ds_read_b128 v[204:207], v151 offset:32768
	ds_read_b128 v[208:211], v151 offset:33792
	ds_read_b128 v[214:217], v152 offset:32768
	ds_read_b128 v[218:221], v152 offset:33792
	buffer_load_dwordx4 v128, s[8:11], s42 offen lds
	s_mov_b32 m0, s43
	s_nop 0
	buffer_load_dwordx4 v129, s[8:11], s42 offen lds
	s_waitcnt vmcnt(8)
	s_waitcnt lgkmcnt(0)
	s_barrier
	s_setprio 1
	v_mfma_f32_16x16x32_bf16 v[124:127], v[156:159], v[188:191], v[124:127]
	v_mfma_f32_16x16x32_bf16 v[120:123], v[164:167], v[188:191], v[120:123]
	v_mfma_f32_16x16x32_bf16 v[116:119], v[156:159], v[196:199], v[116:119]
	v_mfma_f32_16x16x32_bf16 v[112:115], v[164:167], v[196:199], v[112:115]
	v_mfma_f32_16x16x32_bf16 v[108:111], v[156:159], v[204:207], v[108:111]
	v_mfma_f32_16x16x32_bf16 v[104:107], v[164:167], v[204:207], v[104:107]
	v_mfma_f32_16x16x32_bf16 v[100:103], v[156:159], v[214:217], v[100:103]
	v_mfma_f32_16x16x32_bf16 v[96:99], v[164:167], v[214:217], v[96:99]
	v_mfma_f32_16x16x32_bf16 v[124:127], v[160:163], v[192:195], v[124:127]
	v_mfma_f32_16x16x32_bf16 v[120:123], v[168:171], v[192:195], v[120:123]
	v_mfma_f32_16x16x32_bf16 v[116:119], v[160:163], v[200:203], v[116:119]
	v_mfma_f32_16x16x32_bf16 v[112:115], v[168:171], v[200:203], v[112:115]
	v_mfma_f32_16x16x32_bf16 v[108:111], v[160:163], v[208:211], v[108:111]
	v_mfma_f32_16x16x32_bf16 v[104:107], v[168:171], v[208:211], v[104:107]
	v_mfma_f32_16x16x32_bf16 v[100:103], v[160:163], v[218:221], v[100:103]
	v_mfma_f32_16x16x32_bf16 v[96:99], v[168:171], v[218:221], v[96:99]
	s_setprio 0
	s_setprio 1
	v_mfma_f32_16x16x32_bf16 v[92:95], v[172:175], v[188:191], v[92:95]
	v_mfma_f32_16x16x32_bf16 v[88:91], v[180:183], v[188:191], v[88:91]
	v_mfma_f32_16x16x32_bf16 v[84:87], v[172:175], v[196:199], v[84:87]
	v_mfma_f32_16x16x32_bf16 v[80:83], v[180:183], v[196:199], v[80:83]
	v_mfma_f32_16x16x32_bf16 v[76:79], v[172:175], v[204:207], v[76:79]
	v_mfma_f32_16x16x32_bf16 v[72:75], v[180:183], v[204:207], v[72:75]
	v_mfma_f32_16x16x32_bf16 v[68:71], v[172:175], v[214:217], v[68:71]
	v_mfma_f32_16x16x32_bf16 v[64:67], v[180:183], v[214:217], v[64:67]
	v_mfma_f32_16x16x32_bf16 v[92:95], v[176:179], v[192:195], v[92:95]
	v_mfma_f32_16x16x32_bf16 v[88:91], v[184:187], v[192:195], v[88:91]
	v_mfma_f32_16x16x32_bf16 v[84:87], v[176:179], v[200:203], v[84:87]
	v_mfma_f32_16x16x32_bf16 v[80:83], v[184:187], v[200:203], v[80:83]
	v_mfma_f32_16x16x32_bf16 v[76:79], v[176:179], v[208:211], v[76:79]
	v_mfma_f32_16x16x32_bf16 v[72:75], v[184:187], v[208:211], v[72:75]
	v_mfma_f32_16x16x32_bf16 v[68:71], v[176:179], v[218:221], v[68:71]
	v_mfma_f32_16x16x32_bf16 v[64:67], v[184:187], v[218:221], v[64:67]
	s_setprio 0
	s_barrier
	v_readfirstlane_b32 s43, v138
	s_add_i32 s42, s41, 0x180
	s_mov_b32 m0, s43
	v_readfirstlane_b32 s43, v139
	ds_read_b128 v[188:191], v149 offset:49152
	ds_read_b128 v[192:195], v149 offset:50176
	ds_read_b128 v[196:199], v150 offset:49152
	ds_read_b128 v[200:203], v150 offset:50176
	ds_read_b128 v[204:207], v151 offset:49152
	ds_read_b128 v[208:211], v151 offset:50176
	ds_read_b128 v[214:217], v152 offset:49152
	ds_read_b128 v[218:221], v152 offset:50176
	buffer_load_dwordx4 v128, s[4:7], s42 offen lds
	s_mov_b32 m0, s43
	s_add_i32 s41, s41, 0x40180
	buffer_load_dwordx4 v129, s[4:7], s42 offen lds
	v_readfirstlane_b32 s42, v142
	s_mov_b32 m0, s42
	v_readfirstlane_b32 s42, v143
	buffer_load_dwordx4 v128, s[4:7], s41 offen lds
	s_mov_b32 m0, s42
	s_addk_i32 s40, 0x180
	buffer_load_dwordx4 v129, s[4:7], s41 offen lds
	v_readfirstlane_b32 s6, v140
	s_mov_b32 m0, s6
	v_readfirstlane_b32 s6, v141
	buffer_load_dwordx4 v128, s[8:11], s40 offen lds
	s_mov_b32 m0, s6
	s_nop 0
	buffer_load_dwordx4 v129, s[8:11], s40 offen lds
	s_waitcnt vmcnt(8)
	s_waitcnt lgkmcnt(0)
	s_barrier
	s_setprio 1
	v_mfma_f32_16x16x32_bf16 v[60:63], v[156:159], v[188:191], v[60:63]
	v_mfma_f32_16x16x32_bf16 v[56:59], v[164:167], v[188:191], v[56:59]
	v_mfma_f32_16x16x32_bf16 v[52:55], v[156:159], v[196:199], v[52:55]
	v_mfma_f32_16x16x32_bf16 v[48:51], v[164:167], v[196:199], v[48:51]
	v_mfma_f32_16x16x32_bf16 v[44:47], v[156:159], v[204:207], v[44:47]
	v_mfma_f32_16x16x32_bf16 v[40:43], v[164:167], v[204:207], v[40:43]
	v_mfma_f32_16x16x32_bf16 v[36:39], v[156:159], v[214:217], v[36:39]
	v_mfma_f32_16x16x32_bf16 v[32:35], v[164:167], v[214:217], v[32:35]
	v_mfma_f32_16x16x32_bf16 v[60:63], v[160:163], v[192:195], v[60:63]
	v_mfma_f32_16x16x32_bf16 v[56:59], v[168:171], v[192:195], v[56:59]
	v_mfma_f32_16x16x32_bf16 v[52:55], v[160:163], v[200:203], v[52:55]
	v_mfma_f32_16x16x32_bf16 v[48:51], v[168:171], v[200:203], v[48:51]
	v_mfma_f32_16x16x32_bf16 v[44:47], v[160:163], v[208:211], v[44:47]
	v_mfma_f32_16x16x32_bf16 v[40:43], v[168:171], v[208:211], v[40:43]
	v_mfma_f32_16x16x32_bf16 v[36:39], v[160:163], v[218:221], v[36:39]
	v_mfma_f32_16x16x32_bf16 v[32:35], v[168:171], v[218:221], v[32:35]
	s_setprio 0
	s_setprio 1
	v_mfma_f32_16x16x32_bf16 v[28:31], v[172:175], v[188:191], v[28:31]
	v_mfma_f32_16x16x32_bf16 v[24:27], v[180:183], v[188:191], v[24:27]
	v_mfma_f32_16x16x32_bf16 v[20:23], v[172:175], v[196:199], v[20:23]
	v_mfma_f32_16x16x32_bf16 v[16:19], v[180:183], v[196:199], v[16:19]
	v_mfma_f32_16x16x32_bf16 v[12:15], v[172:175], v[204:207], v[12:15]
	v_mfma_f32_16x16x32_bf16 v[8:11], v[180:183], v[204:207], v[8:11]
	v_mfma_f32_16x16x32_bf16 v[4:7], v[172:175], v[214:217], v[4:7]
	v_mfma_f32_16x16x32_bf16 v[0:3], v[180:183], v[214:217], v[0:3]
	v_mfma_f32_16x16x32_bf16 v[28:31], v[176:179], v[192:195], v[28:31]
	v_mfma_f32_16x16x32_bf16 v[24:27], v[184:187], v[192:195], v[24:27]
	v_mfma_f32_16x16x32_bf16 v[20:23], v[176:179], v[200:203], v[20:23]
	v_mfma_f32_16x16x32_bf16 v[16:19], v[184:187], v[200:203], v[16:19]
	v_mfma_f32_16x16x32_bf16 v[12:15], v[176:179], v[208:211], v[12:15]
	v_mfma_f32_16x16x32_bf16 v[8:11], v[184:187], v[208:211], v[8:11]
	v_mfma_f32_16x16x32_bf16 v[4:7], v[176:179], v[218:221], v[4:7]
	v_mfma_f32_16x16x32_bf16 v[0:3], v[184:187], v[218:221], v[0:3]
	s_setprio 0
	s_barrier
; #define LDA(dst, b, h) for (int m = 0; m < 4; ++m) for (int k = 0; k < 2; ++k) \
;     dst[m][k] = *reinterpret_cast<const bf16x8*>((char*)SA(b, h) + lds_byte(wr * 64 + m * 16 + fr, k * 32 + fq * 8))
; #define LDB(dst, b, h) for (int n = 0; n < 2; ++n) for (int k = 0; k < 2; ++k) \
;     dst[n][k] = *reinterpret_cast<const bf16x8*>((char*)SB(b, h) + lds_byte(wc * 32 + n * 16 + fr, k * 32 + fq * 8))
; #define MMA(ai, bj, At, Bt_) do { __builtin_amdgcn_s_setprio(1); \
;     for (int m = 0; m < 4; ++m) for (int n = 0; n < 2; ++n) for (int k = 0; k < 2; ++k) \
;       acc[ai][bj][m][n] = __builtin_amdgcn_mfma_f32_16x16x32_bf16(Bt_[n][k], At[m][k], acc[ai][bj][m][n], 0, 0, 0); \
;     __builtin_amdgcn_s_setprio(0); } while (0)
; #define WAIT_V(n) asm volatile("s_waitcnt vmcnt(" #n ")" ::: "memory")
; #define WAIT_L(n) asm volatile("s_waitcnt lgkmcnt(" #n ")" ::: "memory")
; #define BAR __builtin_amdgcn_s_barrier()
; #define SCHED __builtin_amdgcn_sched_barrier(0)
; template <int MODE>
; DI void gemm_phase(const bf16_t* __restrict__ A, const bf16_t* __restrict__ Bt, int M, int N, int K, const Epi& ep) {
;     ...
;             WAIT_V(8); WAIT_L(0); BAR; MMA(1, 0, At, B0); MMA(1, 1, At, B1); BAR; SCHED;
;             LDB(B0, 1, 0); LDB(B1, 1, 1); SCHED; LDA(At, 1, 0); STAGE(SA(0, 1), rsA, brow + HALF, t + 2);
;             WAIT_V(8); WAIT_L(0); BAR; MMA(0, 0, At, B0); MMA(0, 1, At, B1); BAR; SCHED;
;             LDA(At, 1, 1); STAGE(SB(1, 0), rsB, bcol, t + 3); STAGE(SB(1, 1), rsB, bcol + HALF, t + 3); STAGE(SA(1, 0), rsA, brow, t + 3);
;             WAIT_V(8); WAIT_L(0); BAR; MMA(1, 0, At, B0); MMA(1, 1, At, B1); BAR; SCHED;
;         }
;         {
;             LDB(B0, 0, 0); LDB(B1, 0, 1); SCHED; LDA(At, 0, 0); STAGE(SA(1, 1), rsA, brow + HALF, nt - 1);
;             WAIT_V(8); WAIT_L(0); BAR; MMA(0, 0, At, B0); MMA(0, 1, At, B1); BAR; SCHED;
;             LDA(At, 0, 1);
;             WAIT_V(2); WAIT_L(0); BAR; MMA(1, 0, At, B0); MMA(1, 1, At, B1); BAR; SCHED;
	s_add_i32 s30, s30, 2
	s_addk_i32 s31, 0x100
	s_cmp_gt_u32 s30, 11
	s_cbranch_scc0 .LBB0_558
	ds_read_b128 v[164:167], v147
	ds_read_b128 v[168:171], v147 offset:1024
	ds_read_b128 v[172:175], v147 offset:2048
	ds_read_b128 v[176:179], v147 offset:3072
	ds_read_b128 v[180:183], v148
	ds_read_b128 v[184:187], v148 offset:1024
	ds_read_b128 v[188:191], v148 offset:2048
	ds_read_b128 v[192:195], v148 offset:3072
	v_readfirstlane_b32 s7, v144
	s_or_b32 s6, s26, 0x780
	s_mov_b32 m0, s7
	v_readfirstlane_b32 s7, v145
	ds_read_b128 v[196:199], v149
	ds_read_b128 v[200:203], v149 offset:1024
	ds_read_b128 v[214:217], v150
	ds_read_b128 v[218:221], v150 offset:1024
	ds_read_b128 v[222:225], v151
	ds_read_b128 v[226:229], v151 offset:1024
	ds_read_b128 v[230:233], v152
	ds_read_b128 v[234:237], v152 offset:1024
	buffer_load_dwordx4 v128, s[8:11], s6 offen lds
	s_mov_b32 m0, s7
	s_nop 0
	buffer_load_dwordx4 v129, s[8:11], s6 offen lds
	s_waitcnt vmcnt(8)
	s_waitcnt lgkmcnt(0)
	s_barrier
	s_setprio 1
	v_mfma_f32_16x16x32_bf16 v[124:127], v[164:167], v[196:199], v[124:127]
	v_mfma_f32_16x16x32_bf16 v[120:123], v[172:175], v[196:199], v[120:123]
	v_mfma_f32_16x16x32_bf16 v[116:119], v[164:167], v[214:217], v[116:119]
	v_mfma_f32_16x16x32_bf16 v[112:115], v[172:175], v[214:217], v[112:115]
	v_mfma_f32_16x16x32_bf16 v[96:99], v[172:175], v[230:233], v[96:99]
	v_mfma_f32_16x16x32_bf16 v[124:127], v[168:171], v[200:203], v[124:127]
	v_mfma_f32_16x16x32_bf16 v[120:123], v[176:179], v[200:203], v[120:123]
	v_mfma_f32_16x16x32_bf16 v[116:119], v[168:171], v[218:221], v[116:119]
	v_mfma_f32_16x16x32_bf16 v[112:115], v[176:179], v[218:221], v[112:115]
	v_mfma_f32_16x16x32_bf16 v[108:111], v[164:167], v[222:225], v[108:111]
	v_mfma_f32_16x16x32_bf16 v[104:107], v[172:175], v[222:225], v[104:107]
	v_mfma_f32_16x16x32_bf16 v[100:103], v[164:167], v[230:233], v[100:103]
	v_mfma_f32_16x16x32_bf16 v[160:163], v[176:179], v[234:237], v[96:99]
	v_mfma_f32_16x16x32_bf16 v[238:241], v[168:171], v[226:229], v[108:111]
	v_mfma_f32_16x16x32_bf16 v[242:245], v[176:179], v[226:229], v[104:107]
	v_mfma_f32_16x16x32_bf16 v[246:249], v[168:171], v[234:237], v[100:103]
	s_setprio 0
	s_setprio 1
	v_mfma_f32_16x16x32_bf16 v[92:95], v[180:183], v[196:199], v[92:95]
	v_mfma_f32_16x16x32_bf16 v[88:91], v[188:191], v[196:199], v[88:91]
	v_mfma_f32_16x16x32_bf16 v[84:87], v[180:183], v[214:217], v[84:87]
	v_mfma_f32_16x16x32_bf16 v[80:83], v[188:191], v[214:217], v[80:83]
	v_mfma_f32_16x16x32_bf16 v[92:95], v[184:187], v[200:203], v[92:95]
	v_mfma_f32_16x16x32_bf16 v[88:91], v[192:195], v[200:203], v[88:91]
	v_mfma_f32_16x16x32_bf16 v[84:87], v[184:187], v[218:221], v[84:87]
	v_mfma_f32_16x16x32_bf16 v[80:83], v[192:195], v[218:221], v[80:83]
	v_mfma_f32_16x16x32_bf16 v[76:79], v[180:183], v[222:225], v[76:79]
	v_mfma_f32_16x16x32_bf16 v[72:75], v[188:191], v[222:225], v[72:75]
	v_mfma_f32_16x16x32_bf16 v[68:71], v[180:183], v[230:233], v[68:71]
	v_mfma_f32_16x16x32_bf16 v[64:67], v[188:191], v[230:233], v[64:67]
	v_mfma_f32_16x16x32_bf16 v[196:199], v[184:187], v[226:229], v[76:79]
	v_mfma_f32_16x16x32_bf16 v[200:203], v[192:195], v[226:229], v[72:75]
	v_mfma_f32_16x16x32_bf16 v[214:217], v[184:187], v[234:237], v[68:71]
	v_mfma_f32_16x16x32_bf16 v[218:221], v[192:195], v[234:237], v[64:67]
	s_setprio 0
	s_barrier
	s_nop 1
	ds_read_b128 v[64:67], v149 offset:16384
	ds_read_b128 v[68:71], v149 offset:17408
	ds_read_b128 v[72:75], v150 offset:16384
	ds_read_b128 v[76:79], v150 offset:17408
	ds_read_b128 v[96:99], v151 offset:16384
	ds_read_b128 v[100:103], v151 offset:17408
	ds_read_b128 v[104:107], v152 offset:16384
	ds_read_b128 v[108:111], v152 offset:17408
	s_waitcnt vmcnt(2)
	s_waitcnt lgkmcnt(0)
	s_barrier
	s_setprio 1
	v_mfma_f32_16x16x32_bf16 v[60:63], v[164:167], v[64:67], v[60:63]
	v_mfma_f32_16x16x32_bf16 v[56:59], v[172:175], v[64:67], v[56:59]
	v_mfma_f32_16x16x32_bf16 v[52:55], v[164:167], v[72:75], v[52:55]
	v_mfma_f32_16x16x32_bf16 v[48:51], v[172:175], v[72:75], v[48:51]
	v_mfma_f32_16x16x32_bf16 v[60:63], v[168:171], v[68:71], v[60:63]
	v_mfma_f32_16x16x32_bf16 v[56:59], v[176:179], v[68:71], v[56:59]
	v_mfma_f32_16x16x32_bf16 v[52:55], v[168:171], v[76:79], v[52:55]
	v_mfma_f32_16x16x32_bf16 v[48:51], v[176:179], v[76:79], v[48:51]
	v_mfma_f32_16x16x32_bf16 v[44:47], v[164:167], v[96:99], v[44:47]
	v_mfma_f32_16x16x32_bf16 v[40:43], v[172:175], v[96:99], v[40:43]
	v_mfma_f32_16x16x32_bf16 v[36:39], v[164:167], v[104:107], v[36:39]
	v_mfma_f32_16x16x32_bf16 v[32:35], v[172:175], v[104:107], v[32:35]
	v_mfma_f32_16x16x32_bf16 v[222:225], v[168:171], v[100:103], v[44:47]
	v_mfma_f32_16x16x32_bf16 v[226:229], v[176:179], v[100:103], v[40:43]
	v_mfma_f32_16x16x32_bf16 v[164:167], v[168:171], v[108:111], v[36:39]
	v_mfma_f32_16x16x32_bf16 v[168:171], v[176:179], v[108:111], v[32:35]
	s_setprio 0
	s_setprio 1
	v_mfma_f32_16x16x32_bf16 v[28:31], v[180:183], v[64:67], v[28:31]
	v_mfma_f32_16x16x32_bf16 v[24:27], v[188:191], v[64:67], v[24:27]
	v_mfma_f32_16x16x32_bf16 v[20:23], v[180:183], v[72:75], v[20:23]
	v_mfma_f32_16x16x32_bf16 v[16:19], v[188:191], v[72:75], v[16:19]
	v_mfma_f32_16x16x32_bf16 v[28:31], v[184:187], v[68:71], v[28:31]
	v_mfma_f32_16x16x32_bf16 v[24:27], v[192:195], v[68:71], v[24:27]
	v_mfma_f32_16x16x32_bf16 v[20:23], v[184:187], v[76:79], v[20:23]
	v_mfma_f32_16x16x32_bf16 v[16:19], v[192:195], v[76:79], v[16:19]
	v_mfma_f32_16x16x32_bf16 v[12:15], v[180:183], v[96:99], v[12:15]
	v_mfma_f32_16x16x32_bf16 v[8:11], v[188:191], v[96:99], v[8:11]
	v_mfma_f32_16x16x32_bf16 v[4:7], v[180:183], v[104:107], v[4:7]
	v_mfma_f32_16x16x32_bf16 v[0:3], v[188:191], v[104:107], v[0:3]
	v_mfma_f32_16x16x32_bf16 v[172:175], v[184:187], v[100:103], v[12:15]
	v_mfma_f32_16x16x32_bf16 v[176:179], v[192:195], v[100:103], v[8:11]
	v_mfma_f32_16x16x32_bf16 v[180:183], v[184:187], v[108:111], v[4:7]
	v_mfma_f32_16x16x32_bf16 v[184:187], v[192:195], v[108:111], v[0:3]
	s_setprio 0
	s_barrier
; #define LDA(dst, b, h) for (int m = 0; m < 4; ++m) for (int k = 0; k < 2; ++k) \
;     dst[m][k] = *reinterpret_cast<const bf16x8*>((char*)SA(b, h) + lds_byte(wr * 64 + m * 16 + fr, k * 32 + fq * 8))
; #define LDB(dst, b, h) for (int n = 0; n < 2; ++n) for (int k = 0; k < 2; ++k) \
;     dst[n][k] = *reinterpret_cast<const bf16x8*>((char*)SB(b, h) + lds_byte(wc * 32 + n * 16 + fr, k * 32 + fq * 8))
; #define MMA(ai, bj, At, Bt_) do { __builtin_amdgcn_s_setprio(1); \
;     for (int m = 0; m < 4; ++m) for (int n = 0; n < 2; ++n) for (int k = 0; k < 2; ++k) \
;       acc[ai][bj][m][n] = __builtin_amdgcn_mfma_f32_16x16x32_bf16(Bt_[n][k], At[m][k], acc[ai][bj][m][n], 0, 0, 0); \
;     __builtin_amdgcn_s_setprio(0); } while (0)
; #define WAIT_V(n) asm volatile("s_waitcnt vmcnt(" #n ")" ::: "memory")
; #define WAIT_L(n) asm volatile("s_waitcnt lgkmcnt(" #n ")" ::: "memory")
; #define BAR __builtin_amdgcn_s_barrier()
; #define SCHED __builtin_amdgcn_sched_barrier(0)
; template <int MODE>
; DI void gemm_phase(const bf16_t* __restrict__ A, const bf16_t* __restrict__ Bt, int M, int N, int K, const Epi& ep) {
;     ...
;             LDB(B0, 1, 0); LDB(B1, 1, 1); SCHED; LDA(At, 1, 0);
;             WAIT_V(0); WAIT_L(0); BAR; MMA(0, 0, At, B0); MMA(0, 1, At, B1); BAR; SCHED;
;             LDA(At, 1, 1);
;             WAIT_L(0); BAR; MMA(1, 0, At, B0); MMA(1, 1, At, B1); BAR; SCHED;
;         }
;         if (wr == 0) BAR;
	s_nop 1
	ds_read_b128 v[0:3], v153
	ds_read_b128 v[4:7], v153 offset:1024
	ds_read_b128 v[8:11], v153 offset:2048
	ds_read_b128 v[12:15], v153 offset:3072
	ds_read_b128 v[188:191], v154
	ds_read_b128 v[192:195], v154 offset:1024
	ds_read_b128 v[230:233], v154 offset:2048
	ds_read_b128 v[234:237], v154 offset:3072
	ds_read_b128 v[32:35], v149 offset:32768
	ds_read_b128 v[36:39], v149 offset:33792
	ds_read_b128 v[40:43], v150 offset:32768
	ds_read_b128 v[44:47], v150 offset:33792
	ds_read_b128 v[208:211], v151 offset:32768
	ds_read_b128 v[204:207], v151 offset:33792
	ds_read_b128 v[156:159], v152 offset:32768
	ds_read_b128 v[64:67], v152 offset:33792
	s_waitcnt vmcnt(0)
	s_waitcnt lgkmcnt(0)
	s_barrier
	s_setprio 1
	v_mfma_f32_16x16x32_bf16 v[68:71], v[0:3], v[32:35], v[124:127]
	v_mfma_f32_16x16x32_bf16 v[96:99], v[4:7], v[36:39], v[68:71]
	v_mfma_f32_16x16x32_bf16 v[68:71], v[8:11], v[32:35], v[120:123]
	v_mfma_f32_16x16x32_bf16 v[100:103], v[12:15], v[36:39], v[68:71]
	v_mfma_f32_16x16x32_bf16 v[68:71], v[0:3], v[40:43], v[116:119]
	v_mfma_f32_16x16x32_bf16 v[104:107], v[4:7], v[44:47], v[68:71]
	v_mfma_f32_16x16x32_bf16 v[68:71], v[8:11], v[40:43], v[112:115]
	v_mfma_f32_16x16x32_bf16 v[108:111], v[12:15], v[44:47], v[68:71]
	v_mfma_f32_16x16x32_bf16 v[68:71], v[0:3], v[208:211], v[238:241]
	v_mfma_f32_16x16x32_bf16 v[112:115], v[4:7], v[204:207], v[68:71]
	v_mfma_f32_16x16x32_bf16 v[68:71], v[8:11], v[208:211], v[242:245]
	v_mfma_f32_16x16x32_bf16 v[116:119], v[12:15], v[204:207], v[68:71]
	v_mfma_f32_16x16x32_bf16 v[68:71], v[0:3], v[156:159], v[246:249]
	v_mfma_f32_16x16x32_bf16 v[120:123], v[4:7], v[64:67], v[68:71]
	v_mfma_f32_16x16x32_bf16 v[68:71], v[8:11], v[156:159], v[160:163]
	v_mfma_f32_16x16x32_bf16 v[124:127], v[12:15], v[64:67], v[68:71]
	s_setprio 0
	s_setprio 1
	v_mfma_f32_16x16x32_bf16 v[68:71], v[188:191], v[32:35], v[92:95]
	v_mfma_f32_16x16x32_bf16 v[32:35], v[230:233], v[32:35], v[88:91]
	v_mfma_f32_16x16x32_bf16 v[160:163], v[192:195], v[36:39], v[68:71]
	v_mfma_f32_16x16x32_bf16 v[68:71], v[234:237], v[36:39], v[32:35]
	v_mfma_f32_16x16x32_bf16 v[32:35], v[188:191], v[40:43], v[84:87]
	v_mfma_f32_16x16x32_bf16 v[72:75], v[192:195], v[44:47], v[32:35]
	v_mfma_f32_16x16x32_bf16 v[32:35], v[230:233], v[40:43], v[80:83]
	v_mfma_f32_16x16x32_bf16 v[76:79], v[234:237], v[44:47], v[32:35]
	v_mfma_f32_16x16x32_bf16 v[32:35], v[188:191], v[208:211], v[196:199]
	v_mfma_f32_16x16x32_bf16 v[80:83], v[192:195], v[204:207], v[32:35]
	v_mfma_f32_16x16x32_bf16 v[32:35], v[230:233], v[208:211], v[200:203]
	v_mfma_f32_16x16x32_bf16 v[84:87], v[234:237], v[204:207], v[32:35]
	v_mfma_f32_16x16x32_bf16 v[32:35], v[188:191], v[156:159], v[214:217]
	v_mfma_f32_16x16x32_bf16 v[88:91], v[192:195], v[64:67], v[32:35]
	v_mfma_f32_16x16x32_bf16 v[32:35], v[230:233], v[156:159], v[218:221]
	v_mfma_f32_16x16x32_bf16 v[92:95], v[234:237], v[64:67], v[32:35]
	s_setprio 0
	s_barrier
	ds_read_b128 v[64:67], v149 offset:49152
	ds_read_b128 v[156:159], v149 offset:50176
	ds_read_b128 v[196:199], v150 offset:49152
	ds_read_b128 v[200:203], v150 offset:50176
	ds_read_b128 v[204:207], v151 offset:49152
	ds_read_b128 v[208:211], v151 offset:50176
	ds_read_b128 v[214:217], v152 offset:49152
	ds_read_b128 v[218:221], v152 offset:50176
	s_waitcnt lgkmcnt(0)
	s_barrier
	s_setprio 1
	v_mfma_f32_16x16x32_bf16 v[32:35], v[0:3], v[64:67], v[60:63]
	v_mfma_f32_16x16x32_bf16 v[40:43], v[0:3], v[196:199], v[52:55]
	v_mfma_f32_16x16x32_bf16 v[44:47], v[8:11], v[196:199], v[48:51]
	v_mfma_f32_16x16x32_bf16 v[48:51], v[0:3], v[204:207], v[222:225]
	v_mfma_f32_16x16x32_bf16 v[0:3], v[0:3], v[214:217], v[164:167]
	v_mfma_f32_16x16x32_bf16 v[36:39], v[8:11], v[64:67], v[56:59]
	v_mfma_f32_16x16x32_bf16 v[52:55], v[8:11], v[204:207], v[226:229]
	v_mfma_f32_16x16x32_bf16 v[56:59], v[4:7], v[218:221], v[0:3]
	v_mfma_f32_16x16x32_bf16 v[0:3], v[8:11], v[214:217], v[168:171]
	v_mfma_f32_16x16x32_bf16 v[32:35], v[4:7], v[156:159], v[32:35]
	v_mfma_f32_16x16x32_bf16 v[36:39], v[12:15], v[156:159], v[36:39]
	v_mfma_f32_16x16x32_bf16 v[40:43], v[4:7], v[200:203], v[40:43]
	v_mfma_f32_16x16x32_bf16 v[44:47], v[12:15], v[200:203], v[44:47]
	v_mfma_f32_16x16x32_bf16 v[48:51], v[4:7], v[208:211], v[48:51]
	v_mfma_f32_16x16x32_bf16 v[52:55], v[12:15], v[208:211], v[52:55]
	v_mfma_f32_16x16x32_bf16 v[60:63], v[12:15], v[218:221], v[0:3]
	s_setprio 0
	s_setprio 1
	v_mfma_f32_16x16x32_bf16 v[0:3], v[188:191], v[64:67], v[28:31]
	v_mfma_f32_16x16x32_bf16 v[4:7], v[230:233], v[64:67], v[24:27]
	v_mfma_f32_16x16x32_bf16 v[8:11], v[188:191], v[196:199], v[20:23]
	v_mfma_f32_16x16x32_bf16 v[12:15], v[230:233], v[196:199], v[16:19]
	v_mfma_f32_16x16x32_bf16 v[16:19], v[188:191], v[204:207], v[172:175]
	v_mfma_f32_16x16x32_bf16 v[20:23], v[230:233], v[204:207], v[176:179]
	v_mfma_f32_16x16x32_bf16 v[24:27], v[188:191], v[214:217], v[180:183]
	v_mfma_f32_16x16x32_bf16 v[28:31], v[230:233], v[214:217], v[184:187]
	v_mfma_f32_16x16x32_bf16 v[0:3], v[192:195], v[156:159], v[0:3]
	v_mfma_f32_16x16x32_bf16 v[4:7], v[234:237], v[156:159], v[4:7]
	v_mfma_f32_16x16x32_bf16 v[8:11], v[192:195], v[200:203], v[8:11]
	v_mfma_f32_16x16x32_bf16 v[12:15], v[234:237], v[200:203], v[12:15]
	v_mfma_f32_16x16x32_bf16 v[16:19], v[192:195], v[208:211], v[16:19]
	v_mfma_f32_16x16x32_bf16 v[20:23], v[234:237], v[208:211], v[20:23]
	v_mfma_f32_16x16x32_bf16 v[24:27], v[192:195], v[218:221], v[24:27]
	v_mfma_f32_16x16x32_bf16 v[28:31], v[234:237], v[218:221], v[28:31]
	s_setprio 0
	s_barrier
	s_and_saveexec_b64 s[6:7], s[38:39]
	s_cbranch_execz .LBB0_550
	s_barrier
	s_branch .LBB0_550

; #define LDA(dst, b, h) for (int m = 0; m < 4; ++m) for (int k = 0; k < 2; ++k) \
;     dst[m][k] = *reinterpret_cast<const bf16x8*>((char*)SA(b, h) + lds_byte(wr * 64 + m * 16 + fr, k * 32 + fq * 8))
; #define LDB(dst, b, h) for (int n = 0; n < 2; ++n) for (int k = 0; k < 2; ++k) \
;     dst[n][k] = *reinterpret_cast<const bf16x8*>((char*)SB(b, h) + lds_byte(wc * 32 + n * 16 + fr, k * 32 + fq * 8))
; #define MMA(ai, bj, At, Bt_) do { __builtin_amdgcn_s_setprio(1); \
;     for (int m = 0; m < 4; ++m) for (int n = 0; n < 2; ++n) for (int k = 0; k < 2; ++k) \
;       acc[ai][bj][m][n] = __builtin_amdgcn_mfma_f32_16x16x32_bf16(Bt_[n][k], At[m][k], acc[ai][bj][m][n], 0, 0, 0); \
;     __builtin_amdgcn_s_setprio(0); } while (0)
; #define WAIT_V(n) asm volatile("s_waitcnt vmcnt(" #n ")" ::: "memory")
; #define WAIT_L(n) asm volatile("s_waitcnt lgkmcnt(" #n ")" ::: "memory")
; #define BAR __builtin_amdgcn_s_barrier()
; #define SCHED __builtin_amdgcn_sched_barrier(0)
; template <int MODE>
; DI void gemm_phase(const bf16_t* __restrict__ A, const bf16_t* __restrict__ Bt, int M, int N, int K, const Epi& ep) {
;     ...
;         STAGE(SB(0, 0), rsB, bcol, 0); STAGE(SB(0, 1), rsB, bcol + HALF, 0); STAGE(SA(0, 0), rsA, brow, 0); STAGE(SA(0, 1), rsA, brow + HALF, 0);
;         if (wr == 1) BAR;
;         WAIT_V(2); BAR;
;         STAGE(SB(1, 0), rsB, bcol, 1); STAGE(SA(1, 0), rsA, brow, 1); STAGE(SB(1, 1), rsB, bcol + HALF, 1);
;         WAIT_V(6); BAR;
;         for (int t = 0; t < nt - 2; t += 2) {
;             LDB(B0, 0, 0); LDB(B1, 0, 1); SCHED; LDA(At, 0, 0); STAGE(SA(1, 1), rsA, brow + HALF, t + 1);
;             WAIT_V(8); WAIT_L(0); BAR; MMA(0, 0, At, B0); MMA(0, 1, At, B1); BAR; SCHED;
.LBB0_745:
	s_or_b64 exec, exec, s[6:7]
	v_readfirstlane_b32 s45, v141
	v_add_u32_e32 v0, 0x2000, v141
	s_or_b32 s6, s31, 0x80
	s_mov_b32 m0, s45
	v_readfirstlane_b32 s42, v0
	s_waitcnt vmcnt(2)
	s_barrier
	buffer_load_dwordx4 v128, s[20:23], s6 offen lds
	s_mov_b32 m0, s42
	v_add_u32_e32 v0, 0x8000, v134
	buffer_load_dwordx4 v129, s[20:23], s6 offen lds
	v_readfirstlane_b32 s6, v0
	v_add_u32_e32 v0, 0xa000, v134
	s_or_b32 s43, s41, 0x80
	s_mov_b32 m0, s6
	v_readfirstlane_b32 s7, v0
	buffer_load_dwordx4 v128, s[16:19], s43 offen lds
	s_mov_b32 m0, s7
	s_or_b32 s46, s40, 0x80
	buffer_load_dwordx4 v129, s[16:19], s43 offen lds
	v_readfirstlane_b32 s43, v142
	s_mov_b32 m0, s43
	v_readfirstlane_b32 s44, v143
	buffer_load_dwordx4 v128, s[20:23], s46 offen lds
	s_mov_b32 m0, s44
	s_or_b32 s48, s1, 0x80
	buffer_load_dwordx4 v129, s[20:23], s46 offen lds
	s_waitcnt vmcnt(6)
	s_barrier
	ds_read_b128 v[0:3], v146
	ds_read_b128 v[4:7], v146 offset:1024
	ds_read_b128 v[8:11], v146 offset:2048
	ds_read_b128 v[12:15], v146 offset:3072
	ds_read_b128 v[16:19], v147
	s_waitcnt vmcnt(14)
	ds_read_b128 v[20:23], v147 offset:1024
	ds_read_b128 v[24:27], v147 offset:2048
	ds_read_b128 v[28:31], v147 offset:3072
	v_readfirstlane_b32 s46, v144
	s_mov_b32 m0, s46
	v_readfirstlane_b32 s47, v145
	s_waitcnt vmcnt(14)
	ds_read_b128 v[32:35], v148
	ds_read_b128 v[36:39], v148 offset:1024
	ds_read_b128 v[40:43], v149
	ds_read_b128 v[44:47], v149 offset:1024
	ds_read_b128 v[48:51], v150
	ds_read_b128 v[52:55], v150 offset:1024
	ds_read_b128 v[56:59], v151
	ds_read_b128 v[60:63], v151 offset:1024
	buffer_load_dwordx4 v128, s[16:19], s48 offen lds
	s_mov_b32 m0, s47
	s_nop 0
	buffer_load_dwordx4 v129, s[16:19], s48 offen lds
	s_waitcnt vmcnt(8)
	s_waitcnt lgkmcnt(0)
	s_barrier
	s_setprio 1
	v_mfma_f32_16x16x32_bf16 v[64:67], v[0:3], v[32:35], 0
	v_mfma_f32_16x16x32_bf16 v[68:71], v[8:11], v[32:35], 0
	v_mfma_f32_16x16x32_bf16 v[72:75], v[0:3], v[40:43], 0
	v_mfma_f32_16x16x32_bf16 v[76:79], v[8:11], v[40:43], 0
	v_mfma_f32_16x16x32_bf16 v[80:83], v[0:3], v[48:51], 0
	v_mfma_f32_16x16x32_bf16 v[84:87], v[8:11], v[48:51], 0
	v_mfma_f32_16x16x32_bf16 v[88:91], v[0:3], v[56:59], 0
	v_mfma_f32_16x16x32_bf16 v[92:95], v[8:11], v[56:59], 0
	v_mfma_f32_16x16x32_bf16 v[64:67], v[4:7], v[36:39], v[64:67]
	v_mfma_f32_16x16x32_bf16 v[68:71], v[12:15], v[36:39], v[68:71]
	v_mfma_f32_16x16x32_bf16 v[72:75], v[4:7], v[44:47], v[72:75]
	v_mfma_f32_16x16x32_bf16 v[76:79], v[12:15], v[44:47], v[76:79]
	v_mfma_f32_16x16x32_bf16 v[80:83], v[4:7], v[52:55], v[80:83]
	v_mfma_f32_16x16x32_bf16 v[84:87], v[12:15], v[52:55], v[84:87]
	v_mfma_f32_16x16x32_bf16 v[88:91], v[4:7], v[60:63], v[88:91]
	v_mfma_f32_16x16x32_bf16 v[92:95], v[12:15], v[60:63], v[92:95]
	s_setprio 0
	s_setprio 1
	v_mfma_f32_16x16x32_bf16 v[96:99], v[16:19], v[32:35], 0
	v_mfma_f32_16x16x32_bf16 v[32:35], v[24:27], v[32:35], 0
	v_mfma_f32_16x16x32_bf16 v[96:99], v[20:23], v[36:39], v[96:99]
	v_mfma_f32_16x16x32_bf16 v[32:35], v[28:31], v[36:39], v[32:35]
	v_mfma_f32_16x16x32_bf16 v[36:39], v[16:19], v[40:43], 0
	v_mfma_f32_16x16x32_bf16 v[40:43], v[24:27], v[40:43], 0
	v_mfma_f32_16x16x32_bf16 v[36:39], v[20:23], v[44:47], v[36:39]
	v_mfma_f32_16x16x32_bf16 v[40:43], v[28:31], v[44:47], v[40:43]
	v_mfma_f32_16x16x32_bf16 v[44:47], v[16:19], v[48:51], 0
	v_mfma_f32_16x16x32_bf16 v[48:51], v[24:27], v[48:51], 0
	v_mfma_f32_16x16x32_bf16 v[44:47], v[20:23], v[52:55], v[44:47]
	v_mfma_f32_16x16x32_bf16 v[48:51], v[28:31], v[52:55], v[48:51]
	v_mfma_f32_16x16x32_bf16 v[52:55], v[16:19], v[56:59], 0
	v_mfma_f32_16x16x32_bf16 v[56:59], v[24:27], v[56:59], 0
	v_mfma_f32_16x16x32_bf16 v[52:55], v[20:23], v[60:63], v[52:55]
	v_mfma_f32_16x16x32_bf16 v[56:59], v[28:31], v[60:63], v[56:59]
	s_setprio 0
	s_barrier
	v_readfirstlane_b32 s66, v130
	s_or_b32 s49, s31, 0x100
	s_mov_b32 m0, s66
	v_readfirstlane_b32 s48, v131
	ds_read_b128 v[60:63], v148 offset:16384
	ds_read_b128 v[100:103], v148 offset:17408
	ds_read_b128 v[104:107], v149 offset:16384
	ds_read_b128 v[108:111], v149 offset:17408
	ds_read_b128 v[112:115], v150 offset:16384
	ds_read_b128 v[116:119], v150 offset:17408
	ds_read_b128 v[120:123], v151 offset:16384
	ds_read_b128 v[124:127], v151 offset:17408
	buffer_load_dwordx4 v128, s[20:23], s49 offen lds
	s_mov_b32 m0, s48
	s_or_b32 s54, s40, 0x100
	buffer_load_dwordx4 v129, s[20:23], s49 offen lds
	v_readfirstlane_b32 s49, v132
	s_mov_b32 m0, s49
	v_readfirstlane_b32 s50, v133
	buffer_load_dwordx4 v128, s[20:23], s54 offen lds
	s_mov_b32 m0, s50
	s_or_b32 s58, s41, 0x100
	buffer_load_dwordx4 v129, s[20:23], s54 offen lds
	v_readfirstlane_b32 s54, v134
	s_mov_b32 m0, s54
	v_readfirstlane_b32 s55, v135
	buffer_load_dwordx4 v128, s[16:19], s58 offen lds
	s_mov_b32 m0, s55
	s_nop 0
	buffer_load_dwordx4 v129, s[16:19], s58 offen lds
	s_waitcnt vmcnt(8)
	s_waitcnt lgkmcnt(0)
	s_barrier
; #define LDA(dst, b, h) for (int m = 0; m < 4; ++m) for (int k = 0; k < 2; ++k) \
;     dst[m][k] = *reinterpret_cast<const bf16x8*>((char*)SA(b, h) + lds_byte(wr * 64 + m * 16 + fr, k * 32 + fq * 8))
; #define LDB(dst, b, h) for (int n = 0; n < 2; ++n) for (int k = 0; k < 2; ++k) \
;     dst[n][k] = *reinterpret_cast<const bf16x8*>((char*)SB(b, h) + lds_byte(wc * 32 + n * 16 + fr, k * 32 + fq * 8))
; #define MMA(ai, bj, At, Bt_) do { __builtin_amdgcn_s_setprio(1); \
;     for (int m = 0; m < 4; ++m) for (int n = 0; n < 2; ++n) for (int k = 0; k < 2; ++k) \
;       acc[ai][bj][m][n] = __builtin_amdgcn_mfma_f32_16x16x32_bf16(Bt_[n][k], At[m][k], acc[ai][bj][m][n], 0, 0, 0); \
;     __builtin_amdgcn_s_setprio(0); } while (0)
; #define WAIT_V(n) asm volatile("s_waitcnt vmcnt(" #n ")" ::: "memory")
; #define WAIT_L(n) asm volatile("s_waitcnt lgkmcnt(" #n ")" ::: "memory")
; #define BAR __builtin_amdgcn_s_barrier()
; #define SCHED __builtin_amdgcn_sched_barrier(0)
; template <int MODE>
; DI void gemm_phase(const bf16_t* __restrict__ A, const bf16_t* __restrict__ Bt, int M, int N, int K, const Epi& ep) {
;     ...
;             WAIT_V(8); WAIT_L(0); BAR; MMA(0, 0, At, B0); MMA(0, 1, At, B1); BAR; SCHED;
;             LDA(At, 0, 1); STAGE(SB(0, 0), rsB, bcol, t + 2); STAGE(SB(0, 1), rsB, bcol + HALF, t + 2); STAGE(SA(0, 0), rsA, brow, t + 2);
;             WAIT_V(8); WAIT_L(0); BAR; MMA(1, 0, At, B0); MMA(1, 1, At, B1); BAR; SCHED;
;             LDB(B0, 1, 0); LDB(B1, 1, 1); SCHED; LDA(At, 1, 0); STAGE(SA(0, 1), rsA, brow + HALF, t + 2);
;             WAIT_V(8); WAIT_L(0); BAR; MMA(0, 0, At, B0); MMA(0, 1, At, B1); BAR; SCHED;
	s_setprio 1
	v_mfma_f32_16x16x32_bf16 v[156:159], v[0:3], v[60:63], 0
	v_mfma_f32_16x16x32_bf16 v[164:167], v[0:3], v[104:107], 0
	v_mfma_f32_16x16x32_bf16 v[172:175], v[0:3], v[112:115], 0
	v_mfma_f32_16x16x32_bf16 v[0:3], v[0:3], v[120:123], 0
	v_mfma_f32_16x16x32_bf16 v[156:159], v[4:7], v[100:103], v[156:159]
	v_mfma_f32_16x16x32_bf16 v[164:167], v[4:7], v[108:111], v[164:167]
	v_mfma_f32_16x16x32_bf16 v[172:175], v[4:7], v[116:119], v[172:175]
	v_mfma_f32_16x16x32_bf16 v[0:3], v[4:7], v[124:127], v[0:3]
	v_mfma_f32_16x16x32_bf16 v[4:7], v[8:11], v[120:123], 0
	v_mfma_f32_16x16x32_bf16 v[160:163], v[8:11], v[60:63], 0
	v_mfma_f32_16x16x32_bf16 v[168:171], v[8:11], v[104:107], 0
	v_mfma_f32_16x16x32_bf16 v[176:179], v[8:11], v[112:115], 0
	v_mfma_f32_16x16x32_bf16 v[4:7], v[12:15], v[124:127], v[4:7]
	v_mfma_f32_16x16x32_bf16 v[160:163], v[12:15], v[100:103], v[160:163]
	v_mfma_f32_16x16x32_bf16 v[168:171], v[12:15], v[108:111], v[168:171]
	v_mfma_f32_16x16x32_bf16 v[176:179], v[12:15], v[116:119], v[176:179]
	s_setprio 0
	s_setprio 1
	v_mfma_f32_16x16x32_bf16 v[8:11], v[16:19], v[60:63], 0
	v_mfma_f32_16x16x32_bf16 v[12:15], v[24:27], v[60:63], 0
	v_mfma_f32_16x16x32_bf16 v[8:11], v[20:23], v[100:103], v[8:11]
	v_mfma_f32_16x16x32_bf16 v[12:15], v[28:31], v[100:103], v[12:15]
	v_mfma_f32_16x16x32_bf16 v[60:63], v[16:19], v[104:107], 0
	v_mfma_f32_16x16x32_bf16 v[100:103], v[24:27], v[104:107], 0
	v_mfma_f32_16x16x32_bf16 v[104:107], v[16:19], v[112:115], 0
	v_mfma_f32_16x16x32_bf16 v[16:19], v[16:19], v[120:123], 0
	v_mfma_f32_16x16x32_bf16 v[60:63], v[20:23], v[108:111], v[60:63]
	v_mfma_f32_16x16x32_bf16 v[100:103], v[28:31], v[108:111], v[100:103]
	v_mfma_f32_16x16x32_bf16 v[104:107], v[20:23], v[116:119], v[104:107]
	v_mfma_f32_16x16x32_bf16 v[108:111], v[24:27], v[112:115], 0
	v_mfma_f32_16x16x32_bf16 v[16:19], v[20:23], v[124:127], v[16:19]
	v_mfma_f32_16x16x32_bf16 v[20:23], v[24:27], v[120:123], 0
	v_mfma_f32_16x16x32_bf16 v[108:111], v[28:31], v[116:119], v[108:111]
	v_mfma_f32_16x16x32_bf16 v[20:23], v[28:31], v[124:127], v[20:23]
	s_setprio 0
	s_barrier
	ds_read_b128 v[24:27], v152
	ds_read_b128 v[28:31], v152 offset:1024
	ds_read_b128 v[112:115], v152 offset:2048
	ds_read_b128 v[116:119], v152 offset:3072
	ds_read_b128 v[120:123], v153
	ds_read_b128 v[124:127], v153 offset:1024
	ds_read_b128 v[180:183], v153 offset:2048
	ds_read_b128 v[184:187], v153 offset:3072
	v_readfirstlane_b32 s58, v155
	s_or_b32 s67, s1, 0x100
	s_mov_b32 m0, s58
	v_readfirstlane_b32 s59, v140
	ds_read_b128 v[188:191], v148 offset:32768
	ds_read_b128 v[192:195], v148 offset:33792
	ds_read_b128 v[196:199], v149 offset:32768
	ds_read_b128 v[200:203], v149 offset:33792
	ds_read_b128 v[204:207], v150 offset:32768
	ds_read_b128 v[208:211], v150 offset:33792
	ds_read_b128 v[214:217], v151 offset:32768
	ds_read_b128 v[218:221], v151 offset:33792
	buffer_load_dwordx4 v128, s[16:19], s67 offen lds
	s_mov_b32 m0, s59
	s_nop 0
	buffer_load_dwordx4 v129, s[16:19], s67 offen lds
	s_waitcnt vmcnt(8)
	s_waitcnt lgkmcnt(0)
	s_barrier
	s_setprio 1
	v_mfma_f32_16x16x32_bf16 v[64:67], v[24:27], v[188:191], v[64:67]
	v_mfma_f32_16x16x32_bf16 v[68:71], v[112:115], v[188:191], v[68:71]
	v_mfma_f32_16x16x32_bf16 v[72:75], v[24:27], v[196:199], v[72:75]
	v_mfma_f32_16x16x32_bf16 v[76:79], v[112:115], v[196:199], v[76:79]
	v_mfma_f32_16x16x32_bf16 v[80:83], v[24:27], v[204:207], v[80:83]
	v_mfma_f32_16x16x32_bf16 v[84:87], v[112:115], v[204:207], v[84:87]
	v_mfma_f32_16x16x32_bf16 v[88:91], v[24:27], v[214:217], v[88:91]
	v_mfma_f32_16x16x32_bf16 v[92:95], v[112:115], v[214:217], v[92:95]
	v_mfma_f32_16x16x32_bf16 v[64:67], v[28:31], v[192:195], v[64:67]
	v_mfma_f32_16x16x32_bf16 v[68:71], v[116:119], v[192:195], v[68:71]
	v_mfma_f32_16x16x32_bf16 v[72:75], v[28:31], v[200:203], v[72:75]
	v_mfma_f32_16x16x32_bf16 v[76:79], v[116:119], v[200:203], v[76:79]
	v_mfma_f32_16x16x32_bf16 v[80:83], v[28:31], v[208:211], v[80:83]
	v_mfma_f32_16x16x32_bf16 v[84:87], v[116:119], v[208:211], v[84:87]
	v_mfma_f32_16x16x32_bf16 v[88:91], v[28:31], v[218:221], v[88:91]
	v_mfma_f32_16x16x32_bf16 v[92:95], v[116:119], v[218:221], v[92:95]
	s_setprio 0
	s_setprio 1
	v_mfma_f32_16x16x32_bf16 v[96:99], v[120:123], v[188:191], v[96:99]
	v_mfma_f32_16x16x32_bf16 v[32:35], v[180:183], v[188:191], v[32:35]
	v_mfma_f32_16x16x32_bf16 v[36:39], v[120:123], v[196:199], v[36:39]
	v_mfma_f32_16x16x32_bf16 v[40:43], v[180:183], v[196:199], v[40:43]
	v_mfma_f32_16x16x32_bf16 v[44:47], v[120:123], v[204:207], v[44:47]
	v_mfma_f32_16x16x32_bf16 v[48:51], v[180:183], v[204:207], v[48:51]
	v_mfma_f32_16x16x32_bf16 v[52:55], v[120:123], v[214:217], v[52:55]
	v_mfma_f32_16x16x32_bf16 v[56:59], v[180:183], v[214:217], v[56:59]
	v_mfma_f32_16x16x32_bf16 v[96:99], v[124:127], v[192:195], v[96:99]
	v_mfma_f32_16x16x32_bf16 v[32:35], v[184:187], v[192:195], v[32:35]
	v_mfma_f32_16x16x32_bf16 v[36:39], v[124:127], v[200:203], v[36:39]
	v_mfma_f32_16x16x32_bf16 v[40:43], v[184:187], v[200:203], v[40:43]
	v_mfma_f32_16x16x32_bf16 v[44:47], v[124:127], v[208:211], v[44:47]
	v_mfma_f32_16x16x32_bf16 v[48:51], v[184:187], v[208:211], v[48:51]
	v_mfma_f32_16x16x32_bf16 v[52:55], v[124:127], v[218:221], v[52:55]
	v_mfma_f32_16x16x32_bf16 v[56:59], v[184:187], v[218:221], v[56:59]
	s_setprio 0
	s_barrier
; #define LDA(dst, b, h) for (int m = 0; m < 4; ++m) for (int k = 0; k < 2; ++k) \
;     dst[m][k] = *reinterpret_cast<const bf16x8*>((char*)SA(b, h) + lds_byte(wr * 64 + m * 16 + fr, k * 32 + fq * 8))
; #define LDB(dst, b, h) for (int n = 0; n < 2; ++n) for (int k = 0; k < 2; ++k) \
;     dst[n][k] = *reinterpret_cast<const bf16x8*>((char*)SB(b, h) + lds_byte(wc * 32 + n * 16 + fr, k * 32 + fq * 8))
; #define MMA(ai, bj, At, Bt_) do { __builtin_amdgcn_s_setprio(1); \
;     for (int m = 0; m < 4; ++m) for (int n = 0; n < 2; ++n) for (int k = 0; k < 2; ++k) \
;       acc[ai][bj][m][n] = __builtin_amdgcn_mfma_f32_16x16x32_bf16(Bt_[n][k], At[m][k], acc[ai][bj][m][n], 0, 0, 0); \
;     __builtin_amdgcn_s_setprio(0); } while (0)
; #define WAIT_V(n) asm volatile("s_waitcnt vmcnt(" #n ")" ::: "memory")
; #define WAIT_L(n) asm volatile("s_waitcnt lgkmcnt(" #n ")" ::: "memory")
; #define BAR __builtin_amdgcn_s_barrier()
; #define SCHED __builtin_amdgcn_sched_barrier(0)
; template <int MODE>
; DI void gemm_phase(const bf16_t* __restrict__ A, const bf16_t* __restrict__ Bt, int M, int N, int K, const Epi& ep) {
;     ...
;             LDB(B0, 0, 0); LDB(B1, 0, 1); SCHED; LDA(At, 0, 0); STAGE(SA(1, 1), rsA, brow + HALF, t + 1);
;             WAIT_V(8); WAIT_L(0); BAR; MMA(0, 0, At, B0); MMA(0, 1, At, B1); BAR; SCHED;
;             LDA(At, 0, 1); STAGE(SB(0, 0), rsB, bcol, t + 2); STAGE(SB(0, 1), rsB, bcol + HALF, t + 2); STAGE(SA(0, 0), rsA, brow, t + 2);
;             WAIT_V(8); WAIT_L(0); BAR; MMA(1, 0, At, B0); MMA(1, 1, At, B1); BAR; SCHED;
;             LDB(B0, 1, 0); LDB(B1, 1, 1); SCHED; LDA(At, 1, 0); STAGE(SA(0, 1), rsA, brow + HALF, t + 2);
;             WAIT_V(8); WAIT_L(0); BAR; MMA(0, 0, At, B0); MMA(0, 1, At, B1); BAR; SCHED;
;             LDA(At, 1, 1); STAGE(SB(1, 0), rsB, bcol, t + 3); STAGE(SB(1, 1), rsB, bcol + HALF, t + 3); STAGE(SA(1, 0), rsA, brow, t + 3);
;             WAIT_V(8); WAIT_L(0); BAR; MMA(1, 0, At, B0); MMA(1, 1, At, B1); BAR; SCHED;
	s_mov_b32 m0, s45
	s_or_b32 s67, s31, 0x180
	ds_read_b128 v[188:191], v148 offset:49152
	ds_read_b128 v[192:195], v148 offset:50176
	ds_read_b128 v[196:199], v149 offset:49152
	ds_read_b128 v[200:203], v149 offset:50176
	ds_read_b128 v[204:207], v150 offset:49152
	ds_read_b128 v[208:211], v150 offset:50176
	ds_read_b128 v[214:217], v151 offset:49152
	ds_read_b128 v[218:221], v151 offset:50176
	buffer_load_dwordx4 v128, s[20:23], s67 offen lds
	s_mov_b32 m0, s42
	s_nop 0
	buffer_load_dwordx4 v129, s[20:23], s67 offen lds
	s_or_b32 s67, s40, 0x180
	s_mov_b32 m0, s43
	s_nop 0
	buffer_load_dwordx4 v128, s[20:23], s67 offen lds
	s_mov_b32 m0, s44
	s_nop 0
	buffer_load_dwordx4 v129, s[20:23], s67 offen lds
	s_or_b32 s67, s41, 0x180
	s_mov_b32 m0, s6
	s_nop 0
	buffer_load_dwordx4 v128, s[16:19], s67 offen lds
	s_mov_b32 m0, s7
	s_nop 0
	buffer_load_dwordx4 v129, s[16:19], s67 offen lds
	s_waitcnt vmcnt(8)
	s_waitcnt lgkmcnt(0)
	s_barrier
	s_setprio 1
	v_mfma_f32_16x16x32_bf16 v[0:3], v[24:27], v[214:217], v[0:3]
	v_mfma_f32_16x16x32_bf16 v[4:7], v[112:115], v[214:217], v[4:7]
	v_mfma_f32_16x16x32_bf16 v[156:159], v[24:27], v[188:191], v[156:159]
	v_mfma_f32_16x16x32_bf16 v[160:163], v[112:115], v[188:191], v[160:163]
	v_mfma_f32_16x16x32_bf16 v[164:167], v[24:27], v[196:199], v[164:167]
	v_mfma_f32_16x16x32_bf16 v[168:171], v[112:115], v[196:199], v[168:171]
	v_mfma_f32_16x16x32_bf16 v[172:175], v[24:27], v[204:207], v[172:175]
	v_mfma_f32_16x16x32_bf16 v[176:179], v[112:115], v[204:207], v[176:179]
	v_mfma_f32_16x16x32_bf16 v[0:3], v[28:31], v[218:221], v[0:3]
	v_mfma_f32_16x16x32_bf16 v[4:7], v[116:119], v[218:221], v[4:7]
	v_mfma_f32_16x16x32_bf16 v[156:159], v[28:31], v[192:195], v[156:159]
	v_mfma_f32_16x16x32_bf16 v[160:163], v[116:119], v[192:195], v[160:163]
	v_mfma_f32_16x16x32_bf16 v[164:167], v[28:31], v[200:203], v[164:167]
	v_mfma_f32_16x16x32_bf16 v[168:171], v[116:119], v[200:203], v[168:171]
	v_mfma_f32_16x16x32_bf16 v[172:175], v[28:31], v[208:211], v[172:175]
	v_mfma_f32_16x16x32_bf16 v[176:179], v[116:119], v[208:211], v[176:179]
	s_setprio 0
	s_setprio 1
	v_mfma_f32_16x16x32_bf16 v[8:11], v[120:123], v[188:191], v[8:11]
	v_mfma_f32_16x16x32_bf16 v[12:15], v[180:183], v[188:191], v[12:15]
	v_mfma_f32_16x16x32_bf16 v[24:27], v[120:123], v[196:199], v[60:63]
	v_mfma_f32_16x16x32_bf16 v[28:31], v[180:183], v[196:199], v[100:103]
	v_mfma_f32_16x16x32_bf16 v[60:63], v[120:123], v[204:207], v[104:107]
	v_mfma_f32_16x16x32_bf16 v[100:103], v[180:183], v[204:207], v[108:111]
	v_mfma_f32_16x16x32_bf16 v[16:19], v[120:123], v[214:217], v[16:19]
	v_mfma_f32_16x16x32_bf16 v[20:23], v[180:183], v[214:217], v[20:23]
	v_mfma_f32_16x16x32_bf16 v[8:11], v[124:127], v[192:195], v[8:11]
	v_mfma_f32_16x16x32_bf16 v[12:15], v[184:187], v[192:195], v[12:15]
	v_mfma_f32_16x16x32_bf16 v[24:27], v[124:127], v[200:203], v[24:27]
	v_mfma_f32_16x16x32_bf16 v[28:31], v[184:187], v[200:203], v[28:31]
	v_mfma_f32_16x16x32_bf16 v[60:63], v[124:127], v[208:211], v[60:63]
	v_mfma_f32_16x16x32_bf16 v[100:103], v[184:187], v[208:211], v[100:103]
	v_mfma_f32_16x16x32_bf16 v[16:19], v[124:127], v[218:221], v[16:19]
	v_mfma_f32_16x16x32_bf16 v[20:23], v[184:187], v[218:221], v[20:23]
	s_setprio 0
	s_barrier
	ds_read_b128 v[104:107], v146
	ds_read_b128 v[108:111], v146 offset:1024
	ds_read_b128 v[112:115], v146 offset:2048
	ds_read_b128 v[116:119], v146 offset:3072
	ds_read_b128 v[120:123], v147
	ds_read_b128 v[124:127], v147 offset:1024
	ds_read_b128 v[180:183], v147 offset:2048
	ds_read_b128 v[184:187], v147 offset:3072
	s_or_b32 s67, s1, 0x180
	s_mov_b32 m0, s46
	ds_read_b128 v[188:191], v148
	ds_read_b128 v[192:195], v148 offset:1024
	ds_read_b128 v[196:199], v149
	ds_read_b128 v[200:203], v149 offset:1024
	ds_read_b128 v[204:207], v150
	ds_read_b128 v[208:211], v150 offset:1024
	ds_read_b128 v[214:217], v151
	ds_read_b128 v[218:221], v151 offset:1024
	buffer_load_dwordx4 v128, s[16:19], s67 offen lds
	s_mov_b32 m0, s47
	s_nop 0
	buffer_load_dwordx4 v129, s[16:19], s67 offen lds
	s_waitcnt vmcnt(8)
	s_waitcnt lgkmcnt(0)
	s_barrier
	s_setprio 1
	v_mfma_f32_16x16x32_bf16 v[64:67], v[104:107], v[188:191], v[64:67]
	v_mfma_f32_16x16x32_bf16 v[68:71], v[112:115], v[188:191], v[68:71]
	v_mfma_f32_16x16x32_bf16 v[72:75], v[104:107], v[196:199], v[72:75]
	v_mfma_f32_16x16x32_bf16 v[76:79], v[112:115], v[196:199], v[76:79]
	v_mfma_f32_16x16x32_bf16 v[80:83], v[104:107], v[204:207], v[80:83]
	v_mfma_f32_16x16x32_bf16 v[84:87], v[112:115], v[204:207], v[84:87]
	v_mfma_f32_16x16x32_bf16 v[88:91], v[104:107], v[214:217], v[88:91]
	v_mfma_f32_16x16x32_bf16 v[92:95], v[112:115], v[214:217], v[92:95]
	v_mfma_f32_16x16x32_bf16 v[64:67], v[108:111], v[192:195], v[64:67]
	v_mfma_f32_16x16x32_bf16 v[68:71], v[116:119], v[192:195], v[68:71]
	v_mfma_f32_16x16x32_bf16 v[72:75], v[108:111], v[200:203], v[72:75]
	v_mfma_f32_16x16x32_bf16 v[76:79], v[116:119], v[200:203], v[76:79]
	v_mfma_f32_16x16x32_bf16 v[80:83], v[108:111], v[208:211], v[80:83]
	v_mfma_f32_16x16x32_bf16 v[84:87], v[116:119], v[208:211], v[84:87]
	v_mfma_f32_16x16x32_bf16 v[88:91], v[108:111], v[218:221], v[88:91]
	v_mfma_f32_16x16x32_bf16 v[92:95], v[116:119], v[218:221], v[92:95]
	s_setprio 0
	s_setprio 1
	v_mfma_f32_16x16x32_bf16 v[96:99], v[120:123], v[188:191], v[96:99]
	v_mfma_f32_16x16x32_bf16 v[32:35], v[180:183], v[188:191], v[32:35]
	v_mfma_f32_16x16x32_bf16 v[36:39], v[120:123], v[196:199], v[36:39]
	v_mfma_f32_16x16x32_bf16 v[40:43], v[180:183], v[196:199], v[40:43]
	v_mfma_f32_16x16x32_bf16 v[44:47], v[120:123], v[204:207], v[44:47]
	v_mfma_f32_16x16x32_bf16 v[48:51], v[180:183], v[204:207], v[48:51]
	v_mfma_f32_16x16x32_bf16 v[52:55], v[120:123], v[214:217], v[52:55]
	v_mfma_f32_16x16x32_bf16 v[56:59], v[180:183], v[214:217], v[56:59]
	v_mfma_f32_16x16x32_bf16 v[96:99], v[124:127], v[192:195], v[96:99]
	v_mfma_f32_16x16x32_bf16 v[32:35], v[184:187], v[192:195], v[32:35]
	v_mfma_f32_16x16x32_bf16 v[36:39], v[124:127], v[200:203], v[36:39]
	v_mfma_f32_16x16x32_bf16 v[40:43], v[184:187], v[200:203], v[40:43]
	v_mfma_f32_16x16x32_bf16 v[44:47], v[124:127], v[208:211], v[44:47]
	v_mfma_f32_16x16x32_bf16 v[48:51], v[184:187], v[208:211], v[48:51]
	v_mfma_f32_16x16x32_bf16 v[52:55], v[124:127], v[218:221], v[52:55]
	v_mfma_f32_16x16x32_bf16 v[56:59], v[184:187], v[218:221], v[56:59]
	s_setprio 0
	s_barrier
; #define LDA(dst, b, h) for (int m = 0; m < 4; ++m) for (int k = 0; k < 2; ++k) \
;     dst[m][k] = *reinterpret_cast<const bf16x8*>((char*)SA(b, h) + lds_byte(wr * 64 + m * 16 + fr, k * 32 + fq * 8))
; #define LDB(dst, b, h) for (int n = 0; n < 2; ++n) for (int k = 0; k < 2; ++k) \
;     dst[n][k] = *reinterpret_cast<const bf16x8*>((char*)SB(b, h) + lds_byte(wc * 32 + n * 16 + fr, k * 32 + fq * 8))
; #define MMA(ai, bj, At, Bt_) do { __builtin_amdgcn_s_setprio(1); \
;     for (int m = 0; m < 4; ++m) for (int n = 0; n < 2; ++n) for (int k = 0; k < 2; ++k) \
;       acc[ai][bj][m][n] = __builtin_amdgcn_mfma_f32_16x16x32_bf16(Bt_[n][k], At[m][k], acc[ai][bj][m][n], 0, 0, 0); \
;     __builtin_amdgcn_s_setprio(0); } while (0)
; #define WAIT_V(n) asm volatile("s_waitcnt vmcnt(" #n ")" ::: "memory")
; #define WAIT_L(n) asm volatile("s_waitcnt lgkmcnt(" #n ")" ::: "memory")
; #define BAR __builtin_amdgcn_s_barrier()
; #define SCHED __builtin_amdgcn_sched_barrier(0)
; template <int MODE>
; DI void gemm_phase(const bf16_t* __restrict__ A, const bf16_t* __restrict__ Bt, int M, int N, int K, const Epi& ep) {
;     ...
;             LDA(At, 0, 1); STAGE(SB(0, 0), rsB, bcol, t + 2); STAGE(SB(0, 1), rsB, bcol + HALF, t + 2); STAGE(SA(0, 0), rsA, brow, t + 2);
;             WAIT_V(8); WAIT_L(0); BAR; MMA(1, 0, At, B0); MMA(1, 1, At, B1); BAR; SCHED;
;             LDB(B0, 1, 0); LDB(B1, 1, 1); SCHED; LDA(At, 1, 0); STAGE(SA(0, 1), rsA, brow + HALF, t + 2);
;             WAIT_V(8); WAIT_L(0); BAR; MMA(0, 0, At, B0); MMA(0, 1, At, B1); BAR; SCHED;
	s_mov_b32 m0, s66
	s_or_b32 s46, s31, 0x200
	ds_read_b128 v[188:191], v148 offset:16384
	ds_read_b128 v[192:195], v148 offset:17408
	ds_read_b128 v[196:199], v149 offset:16384
	ds_read_b128 v[200:203], v149 offset:17408
	ds_read_b128 v[204:207], v150 offset:16384
	ds_read_b128 v[208:211], v150 offset:17408
	ds_read_b128 v[214:217], v151 offset:16384
	ds_read_b128 v[218:221], v151 offset:17408
	buffer_load_dwordx4 v128, s[20:23], s46 offen lds
	s_mov_b32 m0, s48
	s_nop 0
	buffer_load_dwordx4 v129, s[20:23], s46 offen lds
	s_or_b32 s46, s40, 0x200
	s_mov_b32 m0, s49
	s_nop 0
	buffer_load_dwordx4 v128, s[20:23], s46 offen lds
	s_mov_b32 m0, s50
	s_nop 0
	buffer_load_dwordx4 v129, s[20:23], s46 offen lds
	s_or_b32 s46, s41, 0x200
	s_mov_b32 m0, s54
	s_nop 0
	buffer_load_dwordx4 v128, s[16:19], s46 offen lds
	s_mov_b32 m0, s55
	s_nop 0
	buffer_load_dwordx4 v129, s[16:19], s46 offen lds
	s_waitcnt vmcnt(8)
	s_waitcnt lgkmcnt(0)
	s_barrier
	s_setprio 1
	v_mfma_f32_16x16x32_bf16 v[0:3], v[104:107], v[214:217], v[0:3]
	v_mfma_f32_16x16x32_bf16 v[4:7], v[112:115], v[214:217], v[4:7]
	v_mfma_f32_16x16x32_bf16 v[156:159], v[104:107], v[188:191], v[156:159]
	v_mfma_f32_16x16x32_bf16 v[160:163], v[112:115], v[188:191], v[160:163]
	v_mfma_f32_16x16x32_bf16 v[164:167], v[104:107], v[196:199], v[164:167]
	v_mfma_f32_16x16x32_bf16 v[168:171], v[112:115], v[196:199], v[168:171]
	v_mfma_f32_16x16x32_bf16 v[172:175], v[104:107], v[204:207], v[172:175]
	v_mfma_f32_16x16x32_bf16 v[176:179], v[112:115], v[204:207], v[176:179]
	v_mfma_f32_16x16x32_bf16 v[0:3], v[108:111], v[218:221], v[0:3]
	v_mfma_f32_16x16x32_bf16 v[4:7], v[116:119], v[218:221], v[4:7]
	v_mfma_f32_16x16x32_bf16 v[156:159], v[108:111], v[192:195], v[156:159]
	v_mfma_f32_16x16x32_bf16 v[160:163], v[116:119], v[192:195], v[160:163]
	v_mfma_f32_16x16x32_bf16 v[164:167], v[108:111], v[200:203], v[164:167]
	v_mfma_f32_16x16x32_bf16 v[168:171], v[116:119], v[200:203], v[168:171]
	v_mfma_f32_16x16x32_bf16 v[172:175], v[108:111], v[208:211], v[172:175]
	v_mfma_f32_16x16x32_bf16 v[176:179], v[116:119], v[208:211], v[176:179]
	s_setprio 0
	s_setprio 1
	v_mfma_f32_16x16x32_bf16 v[8:11], v[120:123], v[188:191], v[8:11]
	v_mfma_f32_16x16x32_bf16 v[12:15], v[180:183], v[188:191], v[12:15]
	v_mfma_f32_16x16x32_bf16 v[24:27], v[120:123], v[196:199], v[24:27]
	v_mfma_f32_16x16x32_bf16 v[28:31], v[180:183], v[196:199], v[28:31]
	v_mfma_f32_16x16x32_bf16 v[60:63], v[120:123], v[204:207], v[60:63]
	v_mfma_f32_16x16x32_bf16 v[100:103], v[180:183], v[204:207], v[100:103]
	v_mfma_f32_16x16x32_bf16 v[16:19], v[120:123], v[214:217], v[16:19]
	v_mfma_f32_16x16x32_bf16 v[20:23], v[180:183], v[214:217], v[20:23]
	v_mfma_f32_16x16x32_bf16 v[8:11], v[124:127], v[192:195], v[8:11]
	v_mfma_f32_16x16x32_bf16 v[12:15], v[184:187], v[192:195], v[12:15]
	v_mfma_f32_16x16x32_bf16 v[24:27], v[124:127], v[200:203], v[24:27]
	v_mfma_f32_16x16x32_bf16 v[28:31], v[184:187], v[200:203], v[28:31]
	v_mfma_f32_16x16x32_bf16 v[60:63], v[124:127], v[208:211], v[60:63]
	v_mfma_f32_16x16x32_bf16 v[100:103], v[184:187], v[208:211], v[100:103]
	v_mfma_f32_16x16x32_bf16 v[16:19], v[124:127], v[218:221], v[16:19]
	v_mfma_f32_16x16x32_bf16 v[20:23], v[184:187], v[218:221], v[20:23]
	s_setprio 0
	s_barrier
	ds_read_b128 v[104:107], v152
	ds_read_b128 v[108:111], v152 offset:1024
	ds_read_b128 v[112:115], v152 offset:2048
	ds_read_b128 v[116:119], v152 offset:3072
	ds_read_b128 v[120:123], v153
	ds_read_b128 v[124:127], v153 offset:1024
	ds_read_b128 v[180:183], v153 offset:2048
	ds_read_b128 v[184:187], v153 offset:3072
	s_or_b32 s46, s1, 0x200
	s_mov_b32 m0, s58
	ds_read_b128 v[188:191], v148 offset:32768
	ds_read_b128 v[192:195], v148 offset:33792
	ds_read_b128 v[196:199], v149 offset:32768
	ds_read_b128 v[200:203], v149 offset:33792
	ds_read_b128 v[204:207], v150 offset:32768
	ds_read_b128 v[208:211], v150 offset:33792
	ds_read_b128 v[214:217], v151 offset:32768
	ds_read_b128 v[218:221], v151 offset:33792
	buffer_load_dwordx4 v128, s[16:19], s46 offen lds
	s_mov_b32 m0, s59
	s_nop 0
	buffer_load_dwordx4 v129, s[16:19], s46 offen lds
	s_waitcnt vmcnt(8)
	s_waitcnt lgkmcnt(0)
	s_barrier
	s_setprio 1
	v_mfma_f32_16x16x32_bf16 v[64:67], v[104:107], v[188:191], v[64:67]
	v_mfma_f32_16x16x32_bf16 v[68:71], v[112:115], v[188:191], v[68:71]
	v_mfma_f32_16x16x32_bf16 v[72:75], v[104:107], v[196:199], v[72:75]
	v_mfma_f32_16x16x32_bf16 v[76:79], v[112:115], v[196:199], v[76:79]
	v_mfma_f32_16x16x32_bf16 v[80:83], v[104:107], v[204:207], v[80:83]
	v_mfma_f32_16x16x32_bf16 v[84:87], v[112:115], v[204:207], v[84:87]
	v_mfma_f32_16x16x32_bf16 v[88:91], v[104:107], v[214:217], v[88:91]
	v_mfma_f32_16x16x32_bf16 v[92:95], v[112:115], v[214:217], v[92:95]
	v_mfma_f32_16x16x32_bf16 v[64:67], v[108:111], v[192:195], v[64:67]
	v_mfma_f32_16x16x32_bf16 v[68:71], v[116:119], v[192:195], v[68:71]
	v_mfma_f32_16x16x32_bf16 v[72:75], v[108:111], v[200:203], v[72:75]
	v_mfma_f32_16x16x32_bf16 v[76:79], v[116:119], v[200:203], v[76:79]
	v_mfma_f32_16x16x32_bf16 v[80:83], v[108:111], v[208:211], v[80:83]
	v_mfma_f32_16x16x32_bf16 v[84:87], v[116:119], v[208:211], v[84:87]
	v_mfma_f32_16x16x32_bf16 v[88:91], v[108:111], v[218:221], v[88:91]
	v_mfma_f32_16x16x32_bf16 v[92:95], v[116:119], v[218:221], v[92:95]
	s_setprio 0
	s_setprio 1
	v_mfma_f32_16x16x32_bf16 v[96:99], v[120:123], v[188:191], v[96:99]
	v_mfma_f32_16x16x32_bf16 v[32:35], v[180:183], v[188:191], v[32:35]
	v_mfma_f32_16x16x32_bf16 v[36:39], v[120:123], v[196:199], v[36:39]
	v_mfma_f32_16x16x32_bf16 v[40:43], v[180:183], v[196:199], v[40:43]
	v_mfma_f32_16x16x32_bf16 v[44:47], v[120:123], v[204:207], v[44:47]
	v_mfma_f32_16x16x32_bf16 v[48:51], v[180:183], v[204:207], v[48:51]
	v_mfma_f32_16x16x32_bf16 v[52:55], v[120:123], v[214:217], v[52:55]
	v_mfma_f32_16x16x32_bf16 v[56:59], v[180:183], v[214:217], v[56:59]
	v_mfma_f32_16x16x32_bf16 v[96:99], v[124:127], v[192:195], v[96:99]
	v_mfma_f32_16x16x32_bf16 v[32:35], v[184:187], v[192:195], v[32:35]
	v_mfma_f32_16x16x32_bf16 v[36:39], v[124:127], v[200:203], v[36:39]
	v_mfma_f32_16x16x32_bf16 v[40:43], v[184:187], v[200:203], v[40:43]
	v_mfma_f32_16x16x32_bf16 v[44:47], v[124:127], v[208:211], v[44:47]
	v_mfma_f32_16x16x32_bf16 v[48:51], v[184:187], v[208:211], v[48:51]
	v_mfma_f32_16x16x32_bf16 v[52:55], v[124:127], v[218:221], v[52:55]
	v_mfma_f32_16x16x32_bf16 v[56:59], v[184:187], v[218:221], v[56:59]
	s_setprio 0
	s_barrier
; #define LDA(dst, b, h) for (int m = 0; m < 4; ++m) for (int k = 0; k < 2; ++k) \
;     dst[m][k] = *reinterpret_cast<const bf16x8*>((char*)SA(b, h) + lds_byte(wr * 64 + m * 16 + fr, k * 32 + fq * 8))
; #define LDB(dst, b, h) for (int n = 0; n < 2; ++n) for (int k = 0; k < 2; ++k) \
;     dst[n][k] = *reinterpret_cast<const bf16x8*>((char*)SB(b, h) + lds_byte(wc * 32 + n * 16 + fr, k * 32 + fq * 8))
; #define MMA(ai, bj, At, Bt_) do { __builtin_amdgcn_s_setprio(1); \
;     for (int m = 0; m < 4; ++m) for (int n = 0; n < 2; ++n) for (int k = 0; k < 2; ++k) \
;       acc[ai][bj][m][n] = __builtin_amdgcn_mfma_f32_16x16x32_bf16(Bt_[n][k], At[m][k], acc[ai][bj][m][n], 0, 0, 0); \
;     __builtin_amdgcn_s_setprio(0); } while (0)
; #define WAIT_V(n) asm volatile("s_waitcnt vmcnt(" #n ")" ::: "memory")
; #define WAIT_L(n) asm volatile("s_waitcnt lgkmcnt(" #n ")" ::: "memory")
; #define BAR __builtin_amdgcn_s_barrier()
; #define SCHED __builtin_amdgcn_sched_barrier(0)
; template <int MODE>
; DI void gemm_phase(const bf16_t* __restrict__ A, const bf16_t* __restrict__ Bt, int M, int N, int K, const Epi& ep) {
;     ...
;             LDA(At, 1, 1); STAGE(SB(1, 0), rsB, bcol, t + 3); STAGE(SB(1, 1), rsB, bcol + HALF, t + 3); STAGE(SA(1, 0), rsA, brow, t + 3);
;             WAIT_V(8); WAIT_L(0); BAR; MMA(1, 0, At, B0); MMA(1, 1, At, B1); BAR; SCHED;
;         }
;         {
;             LDB(B0, 0, 0); LDB(B1, 0, 1); SCHED; LDA(At, 0, 0); STAGE(SA(1, 1), rsA, brow + HALF, nt - 1);
;             WAIT_V(8); WAIT_L(0); BAR; MMA(0, 0, At, B0); MMA(0, 1, At, B1); BAR; SCHED;
	s_mov_b32 m0, s45
	s_or_b32 s31, s31, 0x280
	ds_read_b128 v[188:191], v148 offset:49152
	ds_read_b128 v[192:195], v148 offset:50176
	ds_read_b128 v[196:199], v149 offset:49152
	ds_read_b128 v[200:203], v149 offset:50176
	ds_read_b128 v[204:207], v150 offset:49152
	ds_read_b128 v[208:211], v150 offset:50176
	ds_read_b128 v[214:217], v151 offset:49152
	ds_read_b128 v[218:221], v151 offset:50176
	buffer_load_dwordx4 v128, s[20:23], s31 offen lds
	s_mov_b32 m0, s42
	s_nop 0
	buffer_load_dwordx4 v129, s[20:23], s31 offen lds
	s_or_b32 s31, s40, 0x280
	s_mov_b32 m0, s43
	s_nop 0
	buffer_load_dwordx4 v128, s[20:23], s31 offen lds
	s_mov_b32 m0, s44
	s_nop 0
	buffer_load_dwordx4 v129, s[20:23], s31 offen lds
	s_or_b32 s22, s41, 0x280
	s_mov_b32 m0, s6
	s_nop 0
	buffer_load_dwordx4 v128, s[16:19], s22 offen lds
	s_mov_b32 m0, s7
	s_nop 0
	buffer_load_dwordx4 v129, s[16:19], s22 offen lds
	s_waitcnt vmcnt(8)
	s_waitcnt lgkmcnt(0)
	s_barrier
	s_setprio 1
	v_mfma_f32_16x16x32_bf16 v[0:3], v[104:107], v[214:217], v[0:3]
	v_mfma_f32_16x16x32_bf16 v[4:7], v[112:115], v[214:217], v[4:7]
	v_mfma_f32_16x16x32_bf16 v[156:159], v[104:107], v[188:191], v[156:159]
	v_mfma_f32_16x16x32_bf16 v[160:163], v[112:115], v[188:191], v[160:163]
	v_mfma_f32_16x16x32_bf16 v[164:167], v[104:107], v[196:199], v[164:167]
	v_mfma_f32_16x16x32_bf16 v[168:171], v[112:115], v[196:199], v[168:171]
	v_mfma_f32_16x16x32_bf16 v[172:175], v[104:107], v[204:207], v[172:175]
	v_mfma_f32_16x16x32_bf16 v[176:179], v[112:115], v[204:207], v[176:179]
	v_mfma_f32_16x16x32_bf16 v[0:3], v[108:111], v[218:221], v[0:3]
	v_mfma_f32_16x16x32_bf16 v[4:7], v[116:119], v[218:221], v[4:7]
	v_mfma_f32_16x16x32_bf16 v[156:159], v[108:111], v[192:195], v[156:159]
	v_mfma_f32_16x16x32_bf16 v[160:163], v[116:119], v[192:195], v[160:163]
	v_mfma_f32_16x16x32_bf16 v[164:167], v[108:111], v[200:203], v[164:167]
	v_mfma_f32_16x16x32_bf16 v[168:171], v[116:119], v[200:203], v[168:171]
	v_mfma_f32_16x16x32_bf16 v[172:175], v[108:111], v[208:211], v[172:175]
	v_mfma_f32_16x16x32_bf16 v[176:179], v[116:119], v[208:211], v[176:179]
	s_setprio 0
	s_setprio 1
	v_mfma_f32_16x16x32_bf16 v[8:11], v[120:123], v[188:191], v[8:11]
	v_mfma_f32_16x16x32_bf16 v[12:15], v[180:183], v[188:191], v[12:15]
	v_mfma_f32_16x16x32_bf16 v[24:27], v[120:123], v[196:199], v[24:27]
	v_mfma_f32_16x16x32_bf16 v[28:31], v[180:183], v[196:199], v[28:31]
	v_mfma_f32_16x16x32_bf16 v[60:63], v[120:123], v[204:207], v[60:63]
	v_mfma_f32_16x16x32_bf16 v[100:103], v[180:183], v[204:207], v[100:103]
	v_mfma_f32_16x16x32_bf16 v[16:19], v[120:123], v[214:217], v[16:19]
	v_mfma_f32_16x16x32_bf16 v[20:23], v[180:183], v[214:217], v[20:23]
	v_mfma_f32_16x16x32_bf16 v[8:11], v[124:127], v[192:195], v[8:11]
	v_mfma_f32_16x16x32_bf16 v[12:15], v[184:187], v[192:195], v[12:15]
	v_mfma_f32_16x16x32_bf16 v[24:27], v[124:127], v[200:203], v[24:27]
	v_mfma_f32_16x16x32_bf16 v[28:31], v[184:187], v[200:203], v[28:31]
	v_mfma_f32_16x16x32_bf16 v[60:63], v[124:127], v[208:211], v[60:63]
	v_mfma_f32_16x16x32_bf16 v[100:103], v[184:187], v[208:211], v[100:103]
	v_mfma_f32_16x16x32_bf16 v[16:19], v[124:127], v[218:221], v[16:19]
	v_mfma_f32_16x16x32_bf16 v[20:23], v[184:187], v[218:221], v[20:23]
	s_setprio 0
	s_barrier
	ds_read_b128 v[104:107], v146
	ds_read_b128 v[108:111], v146 offset:1024
	ds_read_b128 v[112:115], v146 offset:2048
	ds_read_b128 v[116:119], v146 offset:3072
	ds_read_b128 v[120:123], v147
	ds_read_b128 v[124:127], v147 offset:1024
	ds_read_b128 v[180:183], v147 offset:2048
	ds_read_b128 v[184:187], v147 offset:3072
	v_readfirstlane_b32 s6, v144
	s_or_b32 s1, s1, 0x280
	s_mov_b32 m0, s6
	v_readfirstlane_b32 s6, v145
	ds_read_b128 v[188:191], v148
	ds_read_b128 v[192:195], v148 offset:1024
	ds_read_b128 v[196:199], v149
	ds_read_b128 v[200:203], v149 offset:1024
	ds_read_b128 v[204:207], v150
	ds_read_b128 v[208:211], v150 offset:1024
	ds_read_b128 v[214:217], v151
	ds_read_b128 v[218:221], v151 offset:1024
	buffer_load_dwordx4 v128, s[16:19], s1 offen lds
	s_mov_b32 m0, s6
	s_nop 0
	buffer_load_dwordx4 v129, s[16:19], s1 offen lds
	s_waitcnt vmcnt(8)
	s_waitcnt lgkmcnt(0)
	s_barrier
	s_setprio 1
	v_mfma_f32_16x16x32_bf16 v[64:67], v[104:107], v[188:191], v[64:67]
	v_mfma_f32_16x16x32_bf16 v[68:71], v[112:115], v[188:191], v[68:71]
	v_mfma_f32_16x16x32_bf16 v[72:75], v[104:107], v[196:199], v[72:75]
	v_mfma_f32_16x16x32_bf16 v[76:79], v[112:115], v[196:199], v[76:79]
	v_mfma_f32_16x16x32_bf16 v[80:83], v[104:107], v[204:207], v[80:83]
	v_mfma_f32_16x16x32_bf16 v[84:87], v[112:115], v[204:207], v[84:87]
	v_mfma_f32_16x16x32_bf16 v[88:91], v[104:107], v[214:217], v[88:91]
	v_mfma_f32_16x16x32_bf16 v[92:95], v[112:115], v[214:217], v[92:95]
	v_mfma_f32_16x16x32_bf16 v[64:67], v[108:111], v[192:195], v[64:67]
	v_mfma_f32_16x16x32_bf16 v[68:71], v[116:119], v[192:195], v[68:71]
	v_mfma_f32_16x16x32_bf16 v[72:75], v[108:111], v[200:203], v[72:75]
	v_mfma_f32_16x16x32_bf16 v[76:79], v[116:119], v[200:203], v[76:79]
	v_mfma_f32_16x16x32_bf16 v[80:83], v[108:111], v[208:211], v[80:83]
	v_mfma_f32_16x16x32_bf16 v[84:87], v[116:119], v[208:211], v[84:87]
	v_mfma_f32_16x16x32_bf16 v[88:91], v[108:111], v[218:221], v[88:91]
	v_mfma_f32_16x16x32_bf16 v[92:95], v[116:119], v[218:221], v[92:95]
	s_setprio 0
	s_setprio 1
	v_mfma_f32_16x16x32_bf16 v[32:35], v[180:183], v[188:191], v[32:35]
	v_mfma_f32_16x16x32_bf16 v[36:39], v[120:123], v[196:199], v[36:39]
	v_mfma_f32_16x16x32_bf16 v[40:43], v[180:183], v[196:199], v[40:43]
	v_mfma_f32_16x16x32_bf16 v[44:47], v[120:123], v[204:207], v[44:47]
	v_mfma_f32_16x16x32_bf16 v[48:51], v[180:183], v[204:207], v[48:51]
	v_mfma_f32_16x16x32_bf16 v[52:55], v[120:123], v[214:217], v[52:55]
	v_mfma_f32_16x16x32_bf16 v[56:59], v[180:183], v[214:217], v[56:59]
	v_mfma_f32_16x16x32_bf16 v[96:99], v[120:123], v[188:191], v[96:99]
	v_mfma_f32_16x16x32_bf16 v[32:35], v[184:187], v[192:195], v[32:35]
	v_mfma_f32_16x16x32_bf16 v[36:39], v[124:127], v[200:203], v[36:39]
	v_mfma_f32_16x16x32_bf16 v[40:43], v[184:187], v[200:203], v[40:43]
	v_mfma_f32_16x16x32_bf16 v[44:47], v[124:127], v[208:211], v[44:47]
	v_mfma_f32_16x16x32_bf16 v[48:51], v[184:187], v[208:211], v[48:51]
	v_mfma_f32_16x16x32_bf16 v[52:55], v[124:127], v[218:221], v[52:55]
	v_mfma_f32_16x16x32_bf16 v[56:59], v[184:187], v[218:221], v[56:59]
	v_mfma_f32_16x16x32_bf16 v[222:225], v[124:127], v[192:195], v[96:99]
	s_setprio 0
	s_barrier
; #define LDA(dst, b, h) for (int m = 0; m < 4; ++m) for (int k = 0; k < 2; ++k) \
;     dst[m][k] = *reinterpret_cast<const bf16x8*>((char*)SA(b, h) + lds_byte(wr * 64 + m * 16 + fr, k * 32 + fq * 8))
; #define LDB(dst, b, h) for (int n = 0; n < 2; ++n) for (int k = 0; k < 2; ++k) \
;     dst[n][k] = *reinterpret_cast<const bf16x8*>((char*)SB(b, h) + lds_byte(wc * 32 + n * 16 + fr, k * 32 + fq * 8))
; #define MMA(ai, bj, At, Bt_) do { __builtin_amdgcn_s_setprio(1); \
;     for (int m = 0; m < 4; ++m) for (int n = 0; n < 2; ++n) for (int k = 0; k < 2; ++k) \
;       acc[ai][bj][m][n] = __builtin_amdgcn_mfma_f32_16x16x32_bf16(Bt_[n][k], At[m][k], acc[ai][bj][m][n], 0, 0, 0); \
;     __builtin_amdgcn_s_setprio(0); } while (0)
; #define WAIT_V(n) asm volatile("s_waitcnt vmcnt(" #n ")" ::: "memory")
; #define WAIT_L(n) asm volatile("s_waitcnt lgkmcnt(" #n ")" ::: "memory")
; #define BAR __builtin_amdgcn_s_barrier()
; #define SCHED __builtin_amdgcn_sched_barrier(0)
; template <int MODE>
; DI void gemm_phase(const bf16_t* __restrict__ A, const bf16_t* __restrict__ Bt, int M, int N, int K, const Epi& ep) {
;     ...
;             LDA(At, 0, 1);
;             WAIT_V(2); WAIT_L(0); BAR; MMA(1, 0, At, B0); MMA(1, 1, At, B1); BAR; SCHED;
;             LDB(B0, 1, 0); LDB(B1, 1, 1); SCHED; LDA(At, 1, 0);
;             WAIT_V(0); WAIT_L(0); BAR; MMA(0, 0, At, B0); MMA(0, 1, At, B1); BAR; SCHED;
	s_nop 0
	ds_read_b128 v[96:99], v148 offset:16384
	ds_read_b128 v[188:191], v148 offset:17408
	ds_read_b128 v[192:195], v149 offset:16384
	ds_read_b128 v[196:199], v149 offset:17408
	ds_read_b128 v[200:203], v150 offset:16384
	ds_read_b128 v[204:207], v150 offset:17408
	ds_read_b128 v[208:211], v151 offset:16384
	ds_read_b128 v[214:217], v151 offset:17408
	s_waitcnt vmcnt(2)
	s_waitcnt lgkmcnt(0)
	s_barrier
	s_setprio 1
	v_mfma_f32_16x16x32_bf16 v[0:3], v[104:107], v[208:211], v[0:3]
	v_mfma_f32_16x16x32_bf16 v[4:7], v[112:115], v[208:211], v[4:7]
	v_mfma_f32_16x16x32_bf16 v[156:159], v[104:107], v[96:99], v[156:159]
	v_mfma_f32_16x16x32_bf16 v[160:163], v[112:115], v[96:99], v[160:163]
	v_mfma_f32_16x16x32_bf16 v[164:167], v[104:107], v[192:195], v[164:167]
	v_mfma_f32_16x16x32_bf16 v[168:171], v[112:115], v[192:195], v[168:171]
	v_mfma_f32_16x16x32_bf16 v[172:175], v[104:107], v[200:203], v[172:175]
	v_mfma_f32_16x16x32_bf16 v[176:179], v[112:115], v[200:203], v[176:179]
	v_mfma_f32_16x16x32_bf16 v[0:3], v[108:111], v[214:217], v[0:3]
	v_mfma_f32_16x16x32_bf16 v[4:7], v[116:119], v[214:217], v[4:7]
	v_mfma_f32_16x16x32_bf16 v[156:159], v[108:111], v[188:191], v[156:159]
	v_mfma_f32_16x16x32_bf16 v[160:163], v[116:119], v[188:191], v[160:163]
	v_mfma_f32_16x16x32_bf16 v[164:167], v[108:111], v[196:199], v[164:167]
	v_mfma_f32_16x16x32_bf16 v[168:171], v[116:119], v[196:199], v[168:171]
	v_mfma_f32_16x16x32_bf16 v[172:175], v[108:111], v[204:207], v[172:175]
	v_mfma_f32_16x16x32_bf16 v[176:179], v[116:119], v[204:207], v[176:179]
	s_setprio 0
	s_setprio 1
	v_mfma_f32_16x16x32_bf16 v[8:11], v[120:123], v[96:99], v[8:11]
	v_mfma_f32_16x16x32_bf16 v[12:15], v[180:183], v[96:99], v[12:15]
	v_mfma_f32_16x16x32_bf16 v[24:27], v[120:123], v[192:195], v[24:27]
	v_mfma_f32_16x16x32_bf16 v[28:31], v[180:183], v[192:195], v[28:31]
	v_mfma_f32_16x16x32_bf16 v[60:63], v[120:123], v[200:203], v[60:63]
	v_mfma_f32_16x16x32_bf16 v[16:19], v[120:123], v[208:211], v[16:19]
	v_mfma_f32_16x16x32_bf16 v[8:11], v[124:127], v[188:191], v[8:11]
	v_mfma_f32_16x16x32_bf16 v[12:15], v[184:187], v[188:191], v[12:15]
	v_mfma_f32_16x16x32_bf16 v[24:27], v[124:127], v[196:199], v[24:27]
	v_mfma_f32_16x16x32_bf16 v[28:31], v[184:187], v[196:199], v[28:31]
	v_mfma_f32_16x16x32_bf16 v[188:191], v[124:127], v[204:207], v[60:63]
	v_mfma_f32_16x16x32_bf16 v[60:63], v[180:183], v[200:203], v[100:103]
	v_mfma_f32_16x16x32_bf16 v[196:199], v[124:127], v[214:217], v[16:19]
	v_mfma_f32_16x16x32_bf16 v[16:19], v[180:183], v[208:211], v[20:23]
	v_mfma_f32_16x16x32_bf16 v[192:195], v[184:187], v[204:207], v[60:63]
	v_mfma_f32_16x16x32_bf16 v[180:183], v[184:187], v[214:217], v[16:19]
	s_setprio 0
	s_barrier
	s_nop 3
	ds_read_b128 v[16:19], v152
	ds_read_b128 v[20:23], v152 offset:1024
	ds_read_b128 v[60:63], v152 offset:2048
	ds_read_b128 v[184:187], v152 offset:3072
	ds_read_b128 v[200:203], v153
	ds_read_b128 v[204:207], v153 offset:1024
	ds_read_b128 v[208:211], v153 offset:2048
	ds_read_b128 v[214:217], v153 offset:3072
	ds_read_b128 v[218:221], v148 offset:32768
	ds_read_b128 v[226:229], v148 offset:33792
	ds_read_b128 v[230:233], v149 offset:32768
	ds_read_b128 v[234:237], v149 offset:33792
	ds_read_b128 v[238:241], v150 offset:32768
	ds_read_b128 v[242:245], v150 offset:33792
	ds_read_b128 v[246:249], v151 offset:32768
	ds_read_b128 v[136:139], v151 offset:33792
	s_waitcnt vmcnt(0)
	s_waitcnt lgkmcnt(0)
	s_barrier
; #define LDA(dst, b, h) for (int m = 0; m < 4; ++m) for (int k = 0; k < 2; ++k) \
;     dst[m][k] = *reinterpret_cast<const bf16x8*>((char*)SA(b, h) + lds_byte(wr * 64 + m * 16 + fr, k * 32 + fq * 8))
; #define MMA(ai, bj, At, Bt_) do { __builtin_amdgcn_s_setprio(1); \
;     for (int m = 0; m < 4; ++m) for (int n = 0; n < 2; ++n) for (int k = 0; k < 2; ++k) \
;       acc[ai][bj][m][n] = __builtin_amdgcn_mfma_f32_16x16x32_bf16(Bt_[n][k], At[m][k], acc[ai][bj][m][n], 0, 0, 0); \
;     __builtin_amdgcn_s_setprio(0); } while (0)
; #define WAIT_V(n) asm volatile("s_waitcnt vmcnt(" #n ")" ::: "memory")
; #define WAIT_L(n) asm volatile("s_waitcnt lgkmcnt(" #n ")" ::: "memory")
; #define BAR __builtin_amdgcn_s_barrier()
; #define SCHED __builtin_amdgcn_sched_barrier(0)
; template <int MODE>
; DI void gemm_phase(const bf16_t* __restrict__ A, const bf16_t* __restrict__ Bt, int M, int N, int K, const Epi& ep) {
;     ...
;             WAIT_V(0); WAIT_L(0); BAR; MMA(0, 0, At, B0); MMA(0, 1, At, B1); BAR; SCHED;
;             LDA(At, 1, 1);
;             WAIT_L(0); BAR; MMA(1, 0, At, B0); MMA(1, 1, At, B1); BAR; SCHED;
;         }
;         if (wr == 0) BAR;
	s_setprio 1
	v_mfma_f32_16x16x32_bf16 v[64:67], v[16:19], v[218:221], v[64:67]
	v_mfma_f32_16x16x32_bf16 v[96:99], v[20:23], v[226:229], v[64:67]
	v_mfma_f32_16x16x32_bf16 v[64:67], v[60:63], v[218:221], v[68:71]
	v_mfma_f32_16x16x32_bf16 v[100:103], v[184:187], v[226:229], v[64:67]
	v_mfma_f32_16x16x32_bf16 v[64:67], v[16:19], v[230:233], v[72:75]
	v_mfma_f32_16x16x32_bf16 v[104:107], v[20:23], v[234:237], v[64:67]
	v_mfma_f32_16x16x32_bf16 v[64:67], v[60:63], v[230:233], v[76:79]
	v_mfma_f32_16x16x32_bf16 v[108:111], v[184:187], v[234:237], v[64:67]
	v_mfma_f32_16x16x32_bf16 v[64:67], v[16:19], v[238:241], v[80:83]
	v_mfma_f32_16x16x32_bf16 v[112:115], v[20:23], v[242:245], v[64:67]
	v_mfma_f32_16x16x32_bf16 v[64:67], v[60:63], v[238:241], v[84:87]
	v_mfma_f32_16x16x32_bf16 v[116:119], v[184:187], v[242:245], v[64:67]
	v_mfma_f32_16x16x32_bf16 v[64:67], v[16:19], v[246:249], v[88:91]
	v_mfma_f32_16x16x32_bf16 v[120:123], v[20:23], v[136:139], v[64:67]
	v_mfma_f32_16x16x32_bf16 v[64:67], v[60:63], v[246:249], v[92:95]
	v_mfma_f32_16x16x32_bf16 v[124:127], v[184:187], v[136:139], v[64:67]
	s_setprio 0
	s_setprio 1
	v_mfma_f32_16x16x32_bf16 v[32:35], v[208:211], v[218:221], v[32:35]
	v_mfma_f32_16x16x32_bf16 v[68:71], v[214:217], v[226:229], v[32:35]
	v_mfma_f32_16x16x32_bf16 v[32:35], v[200:203], v[230:233], v[36:39]
	v_mfma_f32_16x16x32_bf16 v[72:75], v[204:207], v[234:237], v[32:35]
	v_mfma_f32_16x16x32_bf16 v[32:35], v[208:211], v[230:233], v[40:43]
	v_mfma_f32_16x16x32_bf16 v[76:79], v[214:217], v[234:237], v[32:35]
	v_mfma_f32_16x16x32_bf16 v[32:35], v[200:203], v[238:241], v[44:47]
	v_mfma_f32_16x16x32_bf16 v[80:83], v[204:207], v[242:245], v[32:35]
	v_mfma_f32_16x16x32_bf16 v[32:35], v[208:211], v[238:241], v[48:51]
	v_mfma_f32_16x16x32_bf16 v[84:87], v[214:217], v[242:245], v[32:35]
	v_mfma_f32_16x16x32_bf16 v[32:35], v[200:203], v[246:249], v[52:55]
	v_mfma_f32_16x16x32_bf16 v[64:67], v[200:203], v[218:221], v[222:225]
	v_mfma_f32_16x16x32_bf16 v[88:91], v[204:207], v[136:139], v[32:35]
	v_mfma_f32_16x16x32_bf16 v[32:35], v[208:211], v[246:249], v[56:59]
	v_mfma_f32_16x16x32_bf16 v[64:67], v[204:207], v[226:229], v[64:67]
	v_mfma_f32_16x16x32_bf16 v[92:95], v[214:217], v[136:139], v[32:35]
	s_setprio 0
	s_barrier
	ds_read_b128 v[136:139], v148 offset:49152
	ds_read_b128 v[218:221], v148 offset:50176
	ds_read_b128 v[222:225], v149 offset:49152
	ds_read_b128 v[226:229], v149 offset:50176
	ds_read_b128 v[230:233], v150 offset:49152
	ds_read_b128 v[234:237], v150 offset:50176
	ds_read_b128 v[238:241], v151 offset:49152
	ds_read_b128 v[242:245], v151 offset:50176
	s_waitcnt lgkmcnt(0)
	s_barrier
	s_setprio 1
	v_mfma_f32_16x16x32_bf16 v[0:3], v[16:19], v[238:241], v[0:3]
	v_mfma_f32_16x16x32_bf16 v[32:35], v[16:19], v[136:139], v[156:159]
	v_mfma_f32_16x16x32_bf16 v[36:39], v[60:63], v[136:139], v[160:163]
	v_mfma_f32_16x16x32_bf16 v[40:43], v[16:19], v[222:225], v[164:167]
	v_mfma_f32_16x16x32_bf16 v[44:47], v[60:63], v[222:225], v[168:171]
	v_mfma_f32_16x16x32_bf16 v[48:51], v[16:19], v[230:233], v[172:175]
	v_mfma_f32_16x16x32_bf16 v[52:55], v[60:63], v[230:233], v[176:179]
	v_mfma_f32_16x16x32_bf16 v[56:59], v[20:23], v[242:245], v[0:3]
	v_mfma_f32_16x16x32_bf16 v[0:3], v[60:63], v[238:241], v[4:7]
	v_mfma_f32_16x16x32_bf16 v[32:35], v[20:23], v[218:221], v[32:35]
	v_mfma_f32_16x16x32_bf16 v[36:39], v[184:187], v[218:221], v[36:39]
	v_mfma_f32_16x16x32_bf16 v[40:43], v[20:23], v[226:229], v[40:43]
	v_mfma_f32_16x16x32_bf16 v[44:47], v[184:187], v[226:229], v[44:47]
	v_mfma_f32_16x16x32_bf16 v[48:51], v[20:23], v[234:237], v[48:51]
	v_mfma_f32_16x16x32_bf16 v[52:55], v[184:187], v[234:237], v[52:55]
	v_mfma_f32_16x16x32_bf16 v[60:63], v[184:187], v[242:245], v[0:3]
	s_setprio 0
	s_setprio 1
	v_mfma_f32_16x16x32_bf16 v[0:3], v[200:203], v[136:139], v[8:11]
	v_mfma_f32_16x16x32_bf16 v[4:7], v[208:211], v[136:139], v[12:15]
	v_mfma_f32_16x16x32_bf16 v[8:11], v[200:203], v[222:225], v[24:27]
	v_mfma_f32_16x16x32_bf16 v[12:15], v[208:211], v[222:225], v[28:31]
	v_mfma_f32_16x16x32_bf16 v[16:19], v[200:203], v[230:233], v[188:191]
	v_mfma_f32_16x16x32_bf16 v[20:23], v[208:211], v[230:233], v[192:195]
	v_mfma_f32_16x16x32_bf16 v[24:27], v[200:203], v[238:241], v[196:199]
	v_mfma_f32_16x16x32_bf16 v[28:31], v[208:211], v[238:241], v[180:183]
	v_mfma_f32_16x16x32_bf16 v[0:3], v[204:207], v[218:221], v[0:3]
	v_mfma_f32_16x16x32_bf16 v[4:7], v[214:217], v[218:221], v[4:7]
	v_mfma_f32_16x16x32_bf16 v[8:11], v[204:207], v[226:229], v[8:11]
	v_mfma_f32_16x16x32_bf16 v[12:15], v[214:217], v[226:229], v[12:15]
	v_mfma_f32_16x16x32_bf16 v[16:19], v[204:207], v[234:237], v[16:19]
	v_mfma_f32_16x16x32_bf16 v[20:23], v[214:217], v[234:237], v[20:23]
	v_mfma_f32_16x16x32_bf16 v[24:27], v[204:207], v[242:245], v[24:27]
	v_mfma_f32_16x16x32_bf16 v[28:31], v[214:217], v[242:245], v[28:31]
	s_setprio 0
	s_barrier
	s_and_saveexec_b64 s[6:7], s[38:39]
	s_cbranch_execz .LBB0_747
	s_barrier

; #define LDA(dst, b, h) for (int m = 0; m < 4; ++m) for (int k = 0; k < 2; ++k) \
;     dst[m][k] = *reinterpret_cast<const bf16x8*>((char*)SA(b, h) + lds_byte(wr * 64 + m * 16 + fr, k * 32 + fq * 8))
; #define LDB(dst, b, h) for (int n = 0; n < 2; ++n) for (int k = 0; k < 2; ++k) \
;     dst[n][k] = *reinterpret_cast<const bf16x8*>((char*)SB(b, h) + lds_byte(wc * 32 + n * 16 + fr, k * 32 + fq * 8))
; #define MMA(ai, bj, At, Bt_) do { __builtin_amdgcn_s_setprio(1); \
;     for (int m = 0; m < 4; ++m) for (int n = 0; n < 2; ++n) for (int k = 0; k < 2; ++k) \
;       acc[ai][bj][m][n] = __builtin_amdgcn_mfma_f32_16x16x32_bf16(Bt_[n][k], At[m][k], acc[ai][bj][m][n], 0, 0, 0); \
;     __builtin_amdgcn_s_setprio(0); } while (0)
; #define WAIT_V(n) asm volatile("s_waitcnt vmcnt(" #n ")" ::: "memory")
; #define WAIT_L(n) asm volatile("s_waitcnt lgkmcnt(" #n ")" ::: "memory")
; #define BAR __builtin_amdgcn_s_barrier()
; #define SCHED __builtin_amdgcn_sched_barrier(0)
; template <int MODE>
; DI void gemm_phase(const bf16_t* __restrict__ A, const bf16_t* __restrict__ Bt, int M, int N, int K, const Epi& ep) {
;     ...
;         STAGE(SB(0, 0), rsB, bcol, 0); STAGE(SB(0, 1), rsB, bcol + HALF, 0); STAGE(SA(0, 0), rsA, brow, 0); STAGE(SA(0, 1), rsA, brow + HALF, 0);
;         if (wr == 1) BAR;
;         WAIT_V(2); BAR;
;         STAGE(SB(1, 0), rsB, bcol, 1); STAGE(SA(1, 0), rsA, brow, 1); STAGE(SB(1, 1), rsB, bcol + HALF, 1);
;         WAIT_V(6); BAR;
;         for (int t = 0; t < nt - 2; t += 2) {
;             LDB(B0, 0, 0); LDB(B1, 0, 1); SCHED; LDA(At, 0, 0); STAGE(SA(1, 1), rsA, brow + HALF, t + 1);
;             WAIT_V(8); WAIT_L(0); BAR; MMA(0, 0, At, B0); MMA(0, 1, At, B1); BAR; SCHED;
;             LDA(At, 0, 1); STAGE(SB(0, 0), rsB, bcol, t + 2); STAGE(SB(0, 1), rsB, bcol + HALF, t + 2); STAGE(SA(0, 0), rsA, brow, t + 2);
;             WAIT_V(8); WAIT_L(0); BAR; MMA(1, 0, At, B0); MMA(1, 1, At, B1); BAR; SCHED;
.LBB0_816:
	s_or_b64 exec, exec, s[0:1]
	v_readfirstlane_b32 s27, v141
	v_readlane_b32 s88, v254, 38
	v_add_u32_e32 v0, 0x2000, v141
	s_or_b32 s0, s38, 0x80
	s_mov_b32 m0, s27
	v_readlane_b32 s89, v254, 39
	v_readlane_b32 s90, v254, 40
	v_readlane_b32 s91, v254, 41
	v_readfirstlane_b32 s15, v0
	v_add_u32_e32 v0, 0x8000, v134
	s_waitcnt vmcnt(2)
	s_barrier
	v_readfirstlane_b32 s7, v0
	s_nop 0
	buffer_load_dwordx4 v128, s[88:91], s0 offen lds
	s_mov_b32 m0, s15
	v_readlane_b32 s44, v254, 34
	v_add_u32_e32 v0, 0xa000, v134
	buffer_load_dwordx4 v129, s[88:91], s0 offen lds
	s_or_b32 s0, s6, 0x80
	s_mov_b32 m0, s7
	v_readlane_b32 s45, v254, 35
	v_readlane_b32 s46, v254, 36
	v_readlane_b32 s47, v254, 37
	v_readfirstlane_b32 s14, v0
	v_readfirstlane_b32 s26, v142
	v_readfirstlane_b32 s30, v143
	s_or_b32 s39, s6, 0x10080
	s_or_b32 s40, s38, 0x10100
	buffer_load_dwordx4 v128, s[44:47], s0 offen lds
	s_mov_b32 m0, s14
	s_or_b32 s41, s6, 0x10100
	buffer_load_dwordx4 v129, s[44:47], s0 offen lds
	s_or_b32 s0, s38, 0x10080
	s_mov_b32 m0, s26
	s_or_b32 s31, s38, 0x10180
	buffer_load_dwordx4 v128, s[88:91], s0 offen lds
	s_mov_b32 m0, s30
	s_or_b32 s42, s38, 0x100
	buffer_load_dwordx4 v129, s[88:91], s0 offen lds
	s_waitcnt vmcnt(6)
	s_barrier
	ds_read_b128 v[0:3], v146
	ds_read_b128 v[4:7], v146 offset:1024
	ds_read_b128 v[8:11], v146 offset:2048
	ds_read_b128 v[12:15], v146 offset:3072
	ds_read_b128 v[16:19], v147
	ds_read_b128 v[20:23], v147 offset:1024
	ds_read_b128 v[24:27], v147 offset:2048
	ds_read_b128 v[28:31], v147 offset:3072
	s_or_b32 s38, s38, 0x180
	s_or_b32 s43, s6, 0x100
	v_readfirstlane_b32 s0, v144
	s_mov_b32 m0, s0
	v_readfirstlane_b32 s1, v145
	ds_read_b128 v[32:35], v148
	ds_read_b128 v[36:39], v148 offset:1024
	ds_read_b128 v[40:43], v149
	ds_read_b128 v[44:47], v149 offset:1024
	ds_read_b128 v[48:51], v150
	ds_read_b128 v[52:55], v150 offset:1024
	ds_read_b128 v[56:59], v151
	ds_read_b128 v[60:63], v151 offset:1024
	buffer_load_dwordx4 v128, s[44:47], s39 offen lds
	s_mov_b32 m0, s1
	s_nop 0
	buffer_load_dwordx4 v129, s[44:47], s39 offen lds
	s_waitcnt vmcnt(8)
	s_waitcnt lgkmcnt(0)
	s_barrier
	s_setprio 1
	v_mfma_f32_16x16x32_bf16 v[64:67], v[0:3], v[32:35], 0
	v_mfma_f32_16x16x32_bf16 v[68:71], v[8:11], v[32:35], 0
	v_mfma_f32_16x16x32_bf16 v[72:75], v[0:3], v[40:43], 0
	v_mfma_f32_16x16x32_bf16 v[76:79], v[8:11], v[40:43], 0
	v_mfma_f32_16x16x32_bf16 v[80:83], v[0:3], v[48:51], 0
	v_mfma_f32_16x16x32_bf16 v[84:87], v[8:11], v[48:51], 0
	v_mfma_f32_16x16x32_bf16 v[88:91], v[0:3], v[56:59], 0
	v_mfma_f32_16x16x32_bf16 v[92:95], v[8:11], v[56:59], 0
	v_mfma_f32_16x16x32_bf16 v[64:67], v[4:7], v[36:39], v[64:67]
	v_mfma_f32_16x16x32_bf16 v[68:71], v[12:15], v[36:39], v[68:71]
	v_mfma_f32_16x16x32_bf16 v[72:75], v[4:7], v[44:47], v[72:75]
	v_mfma_f32_16x16x32_bf16 v[76:79], v[12:15], v[44:47], v[76:79]
	v_mfma_f32_16x16x32_bf16 v[80:83], v[4:7], v[52:55], v[80:83]
	v_mfma_f32_16x16x32_bf16 v[84:87], v[12:15], v[52:55], v[84:87]
	v_mfma_f32_16x16x32_bf16 v[88:91], v[4:7], v[60:63], v[88:91]
	v_mfma_f32_16x16x32_bf16 v[92:95], v[12:15], v[60:63], v[92:95]
	s_setprio 0
	s_setprio 1
	v_mfma_f32_16x16x32_bf16 v[96:99], v[16:19], v[32:35], 0
	v_mfma_f32_16x16x32_bf16 v[32:35], v[24:27], v[32:35], 0
	v_mfma_f32_16x16x32_bf16 v[96:99], v[20:23], v[36:39], v[96:99]
	v_mfma_f32_16x16x32_bf16 v[32:35], v[28:31], v[36:39], v[32:35]
	v_mfma_f32_16x16x32_bf16 v[36:39], v[16:19], v[40:43], 0
	v_mfma_f32_16x16x32_bf16 v[40:43], v[24:27], v[40:43], 0
	v_mfma_f32_16x16x32_bf16 v[36:39], v[20:23], v[44:47], v[36:39]
	v_mfma_f32_16x16x32_bf16 v[40:43], v[28:31], v[44:47], v[40:43]
	v_mfma_f32_16x16x32_bf16 v[44:47], v[16:19], v[48:51], 0
	v_mfma_f32_16x16x32_bf16 v[48:51], v[24:27], v[48:51], 0
	v_mfma_f32_16x16x32_bf16 v[44:47], v[20:23], v[52:55], v[44:47]
	v_mfma_f32_16x16x32_bf16 v[48:51], v[28:31], v[52:55], v[48:51]
	v_mfma_f32_16x16x32_bf16 v[52:55], v[16:19], v[56:59], 0
	v_mfma_f32_16x16x32_bf16 v[56:59], v[24:27], v[56:59], 0
	v_mfma_f32_16x16x32_bf16 v[52:55], v[20:23], v[60:63], v[52:55]
	v_mfma_f32_16x16x32_bf16 v[56:59], v[28:31], v[60:63], v[56:59]
	s_setprio 0
	s_barrier
	v_readfirstlane_b32 s39, v130
	s_mov_b32 m0, s39
	v_readfirstlane_b32 s39, v131
	ds_read_b128 v[60:63], v148 offset:16384
	ds_read_b128 v[100:103], v148 offset:17408
	ds_read_b128 v[104:107], v149 offset:16384
	ds_read_b128 v[108:111], v149 offset:17408
	ds_read_b128 v[112:115], v150 offset:16384
	ds_read_b128 v[116:119], v150 offset:17408
	ds_read_b128 v[120:123], v151 offset:16384
	ds_read_b128 v[124:127], v151 offset:17408
	buffer_load_dwordx4 v128, s[88:91], s42 offen lds
	s_mov_b32 m0, s39
	v_readfirstlane_b32 s39, v132
	buffer_load_dwordx4 v129, s[88:91], s42 offen lds
	s_mov_b32 m0, s39
	v_readfirstlane_b32 s39, v133
	buffer_load_dwordx4 v128, s[88:91], s40 offen lds
	s_mov_b32 m0, s39
	v_readfirstlane_b32 s39, v134
	buffer_load_dwordx4 v129, s[88:91], s40 offen lds
	s_mov_b32 m0, s39
	v_readfirstlane_b32 s39, v135
	buffer_load_dwordx4 v128, s[44:47], s43 offen lds
	s_mov_b32 m0, s39
	s_nop 0
	buffer_load_dwordx4 v129, s[44:47], s43 offen lds
	s_waitcnt vmcnt(8)
	s_waitcnt lgkmcnt(0)
	s_barrier
; #define LDA(dst, b, h) for (int m = 0; m < 4; ++m) for (int k = 0; k < 2; ++k) \
;     dst[m][k] = *reinterpret_cast<const bf16x8*>((char*)SA(b, h) + lds_byte(wr * 64 + m * 16 + fr, k * 32 + fq * 8))
; #define LDB(dst, b, h) for (int n = 0; n < 2; ++n) for (int k = 0; k < 2; ++k) \
;     dst[n][k] = *reinterpret_cast<const bf16x8*>((char*)SB(b, h) + lds_byte(wc * 32 + n * 16 + fr, k * 32 + fq * 8))
; #define MMA(ai, bj, At, Bt_) do { __builtin_amdgcn_s_setprio(1); \
;     for (int m = 0; m < 4; ++m) for (int n = 0; n < 2; ++n) for (int k = 0; k < 2; ++k) \
;       acc[ai][bj][m][n] = __builtin_amdgcn_mfma_f32_16x16x32_bf16(Bt_[n][k], At[m][k], acc[ai][bj][m][n], 0, 0, 0); \
;     __builtin_amdgcn_s_setprio(0); } while (0)
; #define WAIT_V(n) asm volatile("s_waitcnt vmcnt(" #n ")" ::: "memory")
; #define WAIT_L(n) asm volatile("s_waitcnt lgkmcnt(" #n ")" ::: "memory")
; #define BAR __builtin_amdgcn_s_barrier()
; #define SCHED __builtin_amdgcn_sched_barrier(0)
; template <int MODE>
; DI void gemm_phase(const bf16_t* __restrict__ A, const bf16_t* __restrict__ Bt, int M, int N, int K, const Epi& ep) {
;     ...
;             WAIT_V(8); WAIT_L(0); BAR; MMA(1, 0, At, B0); MMA(1, 1, At, B1); BAR; SCHED;
;             LDB(B0, 1, 0); LDB(B1, 1, 1); SCHED; LDA(At, 1, 0); STAGE(SA(0, 1), rsA, brow + HALF, t + 2);
;             WAIT_V(8); WAIT_L(0); BAR; MMA(0, 0, At, B0); MMA(0, 1, At, B1); BAR; SCHED;
	s_setprio 1
	v_mfma_f32_16x16x32_bf16 v[156:159], v[0:3], v[60:63], 0
	v_mfma_f32_16x16x32_bf16 v[164:167], v[0:3], v[104:107], 0
	v_mfma_f32_16x16x32_bf16 v[172:175], v[0:3], v[112:115], 0
	v_mfma_f32_16x16x32_bf16 v[0:3], v[0:3], v[120:123], 0
	v_mfma_f32_16x16x32_bf16 v[156:159], v[4:7], v[100:103], v[156:159]
	v_mfma_f32_16x16x32_bf16 v[164:167], v[4:7], v[108:111], v[164:167]
	v_mfma_f32_16x16x32_bf16 v[172:175], v[4:7], v[116:119], v[172:175]
	v_mfma_f32_16x16x32_bf16 v[0:3], v[4:7], v[124:127], v[0:3]
	v_mfma_f32_16x16x32_bf16 v[4:7], v[8:11], v[120:123], 0
	v_mfma_f32_16x16x32_bf16 v[160:163], v[8:11], v[60:63], 0
	v_mfma_f32_16x16x32_bf16 v[168:171], v[8:11], v[104:107], 0
	v_mfma_f32_16x16x32_bf16 v[176:179], v[8:11], v[112:115], 0
	v_mfma_f32_16x16x32_bf16 v[4:7], v[12:15], v[124:127], v[4:7]
	v_mfma_f32_16x16x32_bf16 v[160:163], v[12:15], v[100:103], v[160:163]
	v_mfma_f32_16x16x32_bf16 v[168:171], v[12:15], v[108:111], v[168:171]
	v_mfma_f32_16x16x32_bf16 v[176:179], v[12:15], v[116:119], v[176:179]
	s_setprio 0
	s_setprio 1
	v_mfma_f32_16x16x32_bf16 v[8:11], v[16:19], v[60:63], 0
	v_mfma_f32_16x16x32_bf16 v[12:15], v[24:27], v[60:63], 0
	v_mfma_f32_16x16x32_bf16 v[8:11], v[20:23], v[100:103], v[8:11]
	v_mfma_f32_16x16x32_bf16 v[12:15], v[28:31], v[100:103], v[12:15]
	v_mfma_f32_16x16x32_bf16 v[60:63], v[16:19], v[104:107], 0
	v_mfma_f32_16x16x32_bf16 v[100:103], v[24:27], v[104:107], 0
	v_mfma_f32_16x16x32_bf16 v[104:107], v[16:19], v[112:115], 0
	v_mfma_f32_16x16x32_bf16 v[16:19], v[16:19], v[120:123], 0
	v_mfma_f32_16x16x32_bf16 v[60:63], v[20:23], v[108:111], v[60:63]
	v_mfma_f32_16x16x32_bf16 v[100:103], v[28:31], v[108:111], v[100:103]
	v_mfma_f32_16x16x32_bf16 v[104:107], v[20:23], v[116:119], v[104:107]
	v_mfma_f32_16x16x32_bf16 v[108:111], v[24:27], v[112:115], 0
	v_mfma_f32_16x16x32_bf16 v[16:19], v[20:23], v[124:127], v[16:19]
	v_mfma_f32_16x16x32_bf16 v[20:23], v[24:27], v[120:123], 0
	v_mfma_f32_16x16x32_bf16 v[108:111], v[28:31], v[116:119], v[108:111]
	v_mfma_f32_16x16x32_bf16 v[20:23], v[28:31], v[124:127], v[20:23]
	s_setprio 0
	s_barrier
	ds_read_b128 v[24:27], v152
	ds_read_b128 v[28:31], v152 offset:1024
	ds_read_b128 v[112:115], v152 offset:2048
	ds_read_b128 v[116:119], v152 offset:3072
	ds_read_b128 v[120:123], v153
	ds_read_b128 v[124:127], v153 offset:1024
	ds_read_b128 v[180:183], v153 offset:2048
	ds_read_b128 v[184:187], v153 offset:3072
	v_readfirstlane_b32 s39, v155
	s_mov_b32 m0, s39
	v_readfirstlane_b32 s39, v140
	ds_read_b128 v[188:191], v148 offset:32768
	ds_read_b128 v[192:195], v148 offset:33792
	ds_read_b128 v[196:199], v149 offset:32768
	ds_read_b128 v[200:203], v149 offset:33792
	ds_read_b128 v[204:207], v150 offset:32768
	ds_read_b128 v[208:211], v150 offset:33792
	ds_read_b128 v[214:217], v151 offset:32768
	ds_read_b128 v[218:221], v151 offset:33792
	buffer_load_dwordx4 v128, s[44:47], s41 offen lds
	s_mov_b32 m0, s39
	s_nop 0
	buffer_load_dwordx4 v129, s[44:47], s41 offen lds
	s_waitcnt vmcnt(8)
	s_waitcnt lgkmcnt(0)
	s_barrier
	s_setprio 1
	v_mfma_f32_16x16x32_bf16 v[64:67], v[24:27], v[188:191], v[64:67]
	v_mfma_f32_16x16x32_bf16 v[68:71], v[112:115], v[188:191], v[68:71]
	v_mfma_f32_16x16x32_bf16 v[72:75], v[24:27], v[196:199], v[72:75]
	v_mfma_f32_16x16x32_bf16 v[76:79], v[112:115], v[196:199], v[76:79]
	v_mfma_f32_16x16x32_bf16 v[80:83], v[24:27], v[204:207], v[80:83]
	v_mfma_f32_16x16x32_bf16 v[84:87], v[112:115], v[204:207], v[84:87]
	v_mfma_f32_16x16x32_bf16 v[88:91], v[24:27], v[214:217], v[88:91]
	v_mfma_f32_16x16x32_bf16 v[92:95], v[112:115], v[214:217], v[92:95]
	v_mfma_f32_16x16x32_bf16 v[64:67], v[28:31], v[192:195], v[64:67]
	v_mfma_f32_16x16x32_bf16 v[68:71], v[116:119], v[192:195], v[68:71]
	v_mfma_f32_16x16x32_bf16 v[72:75], v[28:31], v[200:203], v[72:75]
	v_mfma_f32_16x16x32_bf16 v[76:79], v[116:119], v[200:203], v[76:79]
	v_mfma_f32_16x16x32_bf16 v[80:83], v[28:31], v[208:211], v[80:83]
	v_mfma_f32_16x16x32_bf16 v[84:87], v[116:119], v[208:211], v[84:87]
	v_mfma_f32_16x16x32_bf16 v[88:91], v[28:31], v[218:221], v[88:91]
	v_mfma_f32_16x16x32_bf16 v[92:95], v[116:119], v[218:221], v[92:95]
	s_setprio 0
	s_setprio 1
	v_mfma_f32_16x16x32_bf16 v[96:99], v[120:123], v[188:191], v[96:99]
	v_mfma_f32_16x16x32_bf16 v[32:35], v[180:183], v[188:191], v[32:35]
	v_mfma_f32_16x16x32_bf16 v[36:39], v[120:123], v[196:199], v[36:39]
	v_mfma_f32_16x16x32_bf16 v[40:43], v[180:183], v[196:199], v[40:43]
	v_mfma_f32_16x16x32_bf16 v[44:47], v[120:123], v[204:207], v[44:47]
	v_mfma_f32_16x16x32_bf16 v[48:51], v[180:183], v[204:207], v[48:51]
	v_mfma_f32_16x16x32_bf16 v[52:55], v[120:123], v[214:217], v[52:55]
	v_mfma_f32_16x16x32_bf16 v[56:59], v[180:183], v[214:217], v[56:59]
	v_mfma_f32_16x16x32_bf16 v[96:99], v[124:127], v[192:195], v[96:99]
	v_mfma_f32_16x16x32_bf16 v[32:35], v[184:187], v[192:195], v[32:35]
	v_mfma_f32_16x16x32_bf16 v[36:39], v[124:127], v[200:203], v[36:39]
	v_mfma_f32_16x16x32_bf16 v[40:43], v[184:187], v[200:203], v[40:43]
	v_mfma_f32_16x16x32_bf16 v[44:47], v[124:127], v[208:211], v[44:47]
	v_mfma_f32_16x16x32_bf16 v[48:51], v[184:187], v[208:211], v[48:51]
	v_mfma_f32_16x16x32_bf16 v[52:55], v[124:127], v[218:221], v[52:55]
	v_mfma_f32_16x16x32_bf16 v[56:59], v[184:187], v[218:221], v[56:59]
	s_setprio 0
	s_barrier
; #define LDA(dst, b, h) for (int m = 0; m < 4; ++m) for (int k = 0; k < 2; ++k) \
;     dst[m][k] = *reinterpret_cast<const bf16x8*>((char*)SA(b, h) + lds_byte(wr * 64 + m * 16 + fr, k * 32 + fq * 8))
; #define LDB(dst, b, h) for (int n = 0; n < 2; ++n) for (int k = 0; k < 2; ++k) \
;     dst[n][k] = *reinterpret_cast<const bf16x8*>((char*)SB(b, h) + lds_byte(wc * 32 + n * 16 + fr, k * 32 + fq * 8))
; #define MMA(ai, bj, At, Bt_) do { __builtin_amdgcn_s_setprio(1); \
;     for (int m = 0; m < 4; ++m) for (int n = 0; n < 2; ++n) for (int k = 0; k < 2; ++k) \
;       acc[ai][bj][m][n] = __builtin_amdgcn_mfma_f32_16x16x32_bf16(Bt_[n][k], At[m][k], acc[ai][bj][m][n], 0, 0, 0); \
;     __builtin_amdgcn_s_setprio(0); } while (0)
; #define WAIT_V(n) asm volatile("s_waitcnt vmcnt(" #n ")" ::: "memory")
; #define WAIT_L(n) asm volatile("s_waitcnt lgkmcnt(" #n ")" ::: "memory")
; #define BAR __builtin_amdgcn_s_barrier()
; #define SCHED __builtin_amdgcn_sched_barrier(0)
; template <int MODE>
; DI void gemm_phase(const bf16_t* __restrict__ A, const bf16_t* __restrict__ Bt, int M, int N, int K, const Epi& ep) {
;     ...
;             LDA(At, 1, 1); STAGE(SB(1, 0), rsB, bcol, t + 3); STAGE(SB(1, 1), rsB, bcol + HALF, t + 3); STAGE(SA(1, 0), rsA, brow, t + 3);
;             WAIT_V(8); WAIT_L(0); BAR; MMA(1, 0, At, B0); MMA(1, 1, At, B1); BAR; SCHED;
;         }
;         {
;             LDB(B0, 0, 0); LDB(B1, 0, 1); SCHED; LDA(At, 0, 0); STAGE(SA(1, 1), rsA, brow + HALF, nt - 1);
;             WAIT_V(8); WAIT_L(0); BAR; MMA(0, 0, At, B0); MMA(0, 1, At, B1); BAR; SCHED;
	s_mov_b32 m0, s27
	ds_read_b128 v[188:191], v148 offset:49152
	ds_read_b128 v[192:195], v148 offset:50176
	ds_read_b128 v[196:199], v149 offset:49152
	ds_read_b128 v[200:203], v149 offset:50176
	ds_read_b128 v[204:207], v150 offset:49152
	ds_read_b128 v[208:211], v150 offset:50176
	ds_read_b128 v[214:217], v151 offset:49152
	ds_read_b128 v[218:221], v151 offset:50176
	buffer_load_dwordx4 v128, s[88:91], s38 offen lds
	s_mov_b32 m0, s15
	s_or_b32 s27, s6, 0x180
	buffer_load_dwordx4 v129, s[88:91], s38 offen lds
	s_mov_b32 m0, s26
	s_nop 0
	buffer_load_dwordx4 v128, s[88:91], s31 offen lds
	s_mov_b32 m0, s30
	s_nop 0
	buffer_load_dwordx4 v129, s[88:91], s31 offen lds
	s_mov_b32 m0, s7
	s_nop 0
	buffer_load_dwordx4 v128, s[44:47], s27 offen lds
	s_mov_b32 m0, s14
	s_nop 0
	buffer_load_dwordx4 v129, s[44:47], s27 offen lds
	s_waitcnt vmcnt(8)
	s_waitcnt lgkmcnt(0)
	s_barrier
	s_setprio 1
	v_mfma_f32_16x16x32_bf16 v[0:3], v[24:27], v[214:217], v[0:3]
	v_mfma_f32_16x16x32_bf16 v[4:7], v[112:115], v[214:217], v[4:7]
	v_mfma_f32_16x16x32_bf16 v[156:159], v[24:27], v[188:191], v[156:159]
	v_mfma_f32_16x16x32_bf16 v[160:163], v[112:115], v[188:191], v[160:163]
	v_mfma_f32_16x16x32_bf16 v[164:167], v[24:27], v[196:199], v[164:167]
	v_mfma_f32_16x16x32_bf16 v[168:171], v[112:115], v[196:199], v[168:171]
	v_mfma_f32_16x16x32_bf16 v[172:175], v[24:27], v[204:207], v[172:175]
	v_mfma_f32_16x16x32_bf16 v[176:179], v[112:115], v[204:207], v[176:179]
	v_mfma_f32_16x16x32_bf16 v[0:3], v[28:31], v[218:221], v[0:3]
	v_mfma_f32_16x16x32_bf16 v[4:7], v[116:119], v[218:221], v[4:7]
	v_mfma_f32_16x16x32_bf16 v[156:159], v[28:31], v[192:195], v[156:159]
	v_mfma_f32_16x16x32_bf16 v[160:163], v[116:119], v[192:195], v[160:163]
	v_mfma_f32_16x16x32_bf16 v[164:167], v[28:31], v[200:203], v[164:167]
	v_mfma_f32_16x16x32_bf16 v[168:171], v[116:119], v[200:203], v[168:171]
	v_mfma_f32_16x16x32_bf16 v[172:175], v[28:31], v[208:211], v[172:175]
	v_mfma_f32_16x16x32_bf16 v[176:179], v[116:119], v[208:211], v[176:179]
	s_setprio 0
	s_setprio 1
	v_mfma_f32_16x16x32_bf16 v[8:11], v[120:123], v[188:191], v[8:11]
	v_mfma_f32_16x16x32_bf16 v[12:15], v[180:183], v[188:191], v[12:15]
	v_mfma_f32_16x16x32_bf16 v[24:27], v[120:123], v[196:199], v[60:63]
	v_mfma_f32_16x16x32_bf16 v[28:31], v[180:183], v[196:199], v[100:103]
	v_mfma_f32_16x16x32_bf16 v[60:63], v[120:123], v[204:207], v[104:107]
	v_mfma_f32_16x16x32_bf16 v[100:103], v[180:183], v[204:207], v[108:111]
	v_mfma_f32_16x16x32_bf16 v[16:19], v[120:123], v[214:217], v[16:19]
	v_mfma_f32_16x16x32_bf16 v[20:23], v[180:183], v[214:217], v[20:23]
	v_mfma_f32_16x16x32_bf16 v[8:11], v[124:127], v[192:195], v[8:11]
	v_mfma_f32_16x16x32_bf16 v[12:15], v[184:187], v[192:195], v[12:15]
	v_mfma_f32_16x16x32_bf16 v[24:27], v[124:127], v[200:203], v[24:27]
	v_mfma_f32_16x16x32_bf16 v[28:31], v[184:187], v[200:203], v[28:31]
	v_mfma_f32_16x16x32_bf16 v[60:63], v[124:127], v[208:211], v[60:63]
	v_mfma_f32_16x16x32_bf16 v[100:103], v[184:187], v[208:211], v[100:103]
	v_mfma_f32_16x16x32_bf16 v[16:19], v[124:127], v[218:221], v[16:19]
	v_mfma_f32_16x16x32_bf16 v[20:23], v[184:187], v[218:221], v[20:23]
	s_setprio 0
	s_barrier
	ds_read_b128 v[104:107], v146
	ds_read_b128 v[108:111], v146 offset:1024
	ds_read_b128 v[112:115], v146 offset:2048
	ds_read_b128 v[116:119], v146 offset:3072
	ds_read_b128 v[120:123], v147
	ds_read_b128 v[124:127], v147 offset:1024
	ds_read_b128 v[180:183], v147 offset:2048
	ds_read_b128 v[184:187], v147 offset:3072
	s_or_b32 s6, s6, 0x10180
	s_mov_b32 m0, s0
	ds_read_b128 v[188:191], v148
	ds_read_b128 v[192:195], v148 offset:1024
	ds_read_b128 v[196:199], v149
	ds_read_b128 v[200:203], v149 offset:1024
	ds_read_b128 v[204:207], v150
	ds_read_b128 v[208:211], v150 offset:1024
	ds_read_b128 v[214:217], v151
	ds_read_b128 v[218:221], v151 offset:1024
	buffer_load_dwordx4 v128, s[44:47], s6 offen lds
	s_mov_b32 m0, s1
	s_nop 0
	buffer_load_dwordx4 v129, s[44:47], s6 offen lds
	s_waitcnt vmcnt(8)
	s_waitcnt lgkmcnt(0)
	s_barrier
	s_setprio 1
	v_mfma_f32_16x16x32_bf16 v[64:67], v[104:107], v[188:191], v[64:67]
	v_mfma_f32_16x16x32_bf16 v[68:71], v[112:115], v[188:191], v[68:71]
	v_mfma_f32_16x16x32_bf16 v[72:75], v[104:107], v[196:199], v[72:75]
	v_mfma_f32_16x16x32_bf16 v[76:79], v[112:115], v[196:199], v[76:79]
	v_mfma_f32_16x16x32_bf16 v[80:83], v[104:107], v[204:207], v[80:83]
	v_mfma_f32_16x16x32_bf16 v[84:87], v[112:115], v[204:207], v[84:87]
	v_mfma_f32_16x16x32_bf16 v[88:91], v[104:107], v[214:217], v[88:91]
	v_mfma_f32_16x16x32_bf16 v[92:95], v[112:115], v[214:217], v[92:95]
	v_mfma_f32_16x16x32_bf16 v[64:67], v[108:111], v[192:195], v[64:67]
	v_mfma_f32_16x16x32_bf16 v[68:71], v[116:119], v[192:195], v[68:71]
	v_mfma_f32_16x16x32_bf16 v[72:75], v[108:111], v[200:203], v[72:75]
	v_mfma_f32_16x16x32_bf16 v[76:79], v[116:119], v[200:203], v[76:79]
	v_mfma_f32_16x16x32_bf16 v[80:83], v[108:111], v[208:211], v[80:83]
	v_mfma_f32_16x16x32_bf16 v[84:87], v[116:119], v[208:211], v[84:87]
	v_mfma_f32_16x16x32_bf16 v[88:91], v[108:111], v[218:221], v[88:91]
	v_mfma_f32_16x16x32_bf16 v[92:95], v[116:119], v[218:221], v[92:95]
	s_setprio 0
	s_setprio 1
	v_mfma_f32_16x16x32_bf16 v[32:35], v[180:183], v[188:191], v[32:35]
	v_mfma_f32_16x16x32_bf16 v[36:39], v[120:123], v[196:199], v[36:39]
	v_mfma_f32_16x16x32_bf16 v[40:43], v[180:183], v[196:199], v[40:43]
	v_mfma_f32_16x16x32_bf16 v[44:47], v[120:123], v[204:207], v[44:47]
	v_mfma_f32_16x16x32_bf16 v[48:51], v[180:183], v[204:207], v[48:51]
	v_mfma_f32_16x16x32_bf16 v[52:55], v[120:123], v[214:217], v[52:55]
	v_mfma_f32_16x16x32_bf16 v[56:59], v[180:183], v[214:217], v[56:59]
	v_mfma_f32_16x16x32_bf16 v[96:99], v[120:123], v[188:191], v[96:99]
	v_mfma_f32_16x16x32_bf16 v[32:35], v[184:187], v[192:195], v[32:35]
	v_mfma_f32_16x16x32_bf16 v[36:39], v[124:127], v[200:203], v[36:39]
	v_mfma_f32_16x16x32_bf16 v[40:43], v[184:187], v[200:203], v[40:43]
	v_mfma_f32_16x16x32_bf16 v[44:47], v[124:127], v[208:211], v[44:47]
	v_mfma_f32_16x16x32_bf16 v[48:51], v[184:187], v[208:211], v[48:51]
	v_mfma_f32_16x16x32_bf16 v[52:55], v[124:127], v[218:221], v[52:55]
	v_mfma_f32_16x16x32_bf16 v[56:59], v[184:187], v[218:221], v[56:59]
	v_mfma_f32_16x16x32_bf16 v[222:225], v[124:127], v[192:195], v[96:99]
	s_setprio 0
	s_barrier
; #define LDA(dst, b, h) for (int m = 0; m < 4; ++m) for (int k = 0; k < 2; ++k) \
;     dst[m][k] = *reinterpret_cast<const bf16x8*>((char*)SA(b, h) + lds_byte(wr * 64 + m * 16 + fr, k * 32 + fq * 8))
; #define LDB(dst, b, h) for (int n = 0; n < 2; ++n) for (int k = 0; k < 2; ++k) \
;     dst[n][k] = *reinterpret_cast<const bf16x8*>((char*)SB(b, h) + lds_byte(wc * 32 + n * 16 + fr, k * 32 + fq * 8))
; #define MMA(ai, bj, At, Bt_) do { __builtin_amdgcn_s_setprio(1); \
;     for (int m = 0; m < 4; ++m) for (int n = 0; n < 2; ++n) for (int k = 0; k < 2; ++k) \
;       acc[ai][bj][m][n] = __builtin_amdgcn_mfma_f32_16x16x32_bf16(Bt_[n][k], At[m][k], acc[ai][bj][m][n], 0, 0, 0); \
;     __builtin_amdgcn_s_setprio(0); } while (0)
; #define WAIT_V(n) asm volatile("s_waitcnt vmcnt(" #n ")" ::: "memory")
; #define WAIT_L(n) asm volatile("s_waitcnt lgkmcnt(" #n ")" ::: "memory")
; #define BAR __builtin_amdgcn_s_barrier()
; #define SCHED __builtin_amdgcn_sched_barrier(0)
; template <int MODE>
; DI void gemm_phase(const bf16_t* __restrict__ A, const bf16_t* __restrict__ Bt, int M, int N, int K, const Epi& ep) {
;     ...
;             LDA(At, 0, 1);
;             WAIT_V(2); WAIT_L(0); BAR; MMA(1, 0, At, B0); MMA(1, 1, At, B1); BAR; SCHED;
;             LDB(B0, 1, 0); LDB(B1, 1, 1); SCHED; LDA(At, 1, 0);
;             WAIT_V(0); WAIT_L(0); BAR; MMA(0, 0, At, B0); MMA(0, 1, At, B1); BAR; SCHED;
	s_nop 0
	ds_read_b128 v[96:99], v148 offset:16384
	ds_read_b128 v[188:191], v148 offset:17408
	ds_read_b128 v[192:195], v149 offset:16384
	ds_read_b128 v[196:199], v149 offset:17408
	ds_read_b128 v[200:203], v150 offset:16384
	ds_read_b128 v[204:207], v150 offset:17408
	ds_read_b128 v[208:211], v151 offset:16384
	ds_read_b128 v[214:217], v151 offset:17408
	s_waitcnt vmcnt(2)
	s_waitcnt lgkmcnt(0)
	s_barrier
	s_setprio 1
	v_mfma_f32_16x16x32_bf16 v[0:3], v[104:107], v[208:211], v[0:3]
	v_mfma_f32_16x16x32_bf16 v[4:7], v[112:115], v[208:211], v[4:7]
	v_mfma_f32_16x16x32_bf16 v[156:159], v[104:107], v[96:99], v[156:159]
	v_mfma_f32_16x16x32_bf16 v[160:163], v[112:115], v[96:99], v[160:163]
	v_mfma_f32_16x16x32_bf16 v[164:167], v[104:107], v[192:195], v[164:167]
	v_mfma_f32_16x16x32_bf16 v[168:171], v[112:115], v[192:195], v[168:171]
	v_mfma_f32_16x16x32_bf16 v[172:175], v[104:107], v[200:203], v[172:175]
	v_mfma_f32_16x16x32_bf16 v[176:179], v[112:115], v[200:203], v[176:179]
	v_mfma_f32_16x16x32_bf16 v[0:3], v[108:111], v[214:217], v[0:3]
	v_mfma_f32_16x16x32_bf16 v[4:7], v[116:119], v[214:217], v[4:7]
	v_mfma_f32_16x16x32_bf16 v[156:159], v[108:111], v[188:191], v[156:159]
	v_mfma_f32_16x16x32_bf16 v[160:163], v[116:119], v[188:191], v[160:163]
	v_mfma_f32_16x16x32_bf16 v[164:167], v[108:111], v[196:199], v[164:167]
	v_mfma_f32_16x16x32_bf16 v[168:171], v[116:119], v[196:199], v[168:171]
	v_mfma_f32_16x16x32_bf16 v[172:175], v[108:111], v[204:207], v[172:175]
	v_mfma_f32_16x16x32_bf16 v[176:179], v[116:119], v[204:207], v[176:179]
	s_setprio 0
	s_setprio 1
	v_mfma_f32_16x16x32_bf16 v[8:11], v[120:123], v[96:99], v[8:11]
	v_mfma_f32_16x16x32_bf16 v[12:15], v[180:183], v[96:99], v[12:15]
	v_mfma_f32_16x16x32_bf16 v[24:27], v[120:123], v[192:195], v[24:27]
	v_mfma_f32_16x16x32_bf16 v[28:31], v[180:183], v[192:195], v[28:31]
	v_mfma_f32_16x16x32_bf16 v[60:63], v[120:123], v[200:203], v[60:63]
	v_mfma_f32_16x16x32_bf16 v[16:19], v[120:123], v[208:211], v[16:19]
	v_mfma_f32_16x16x32_bf16 v[8:11], v[124:127], v[188:191], v[8:11]
	v_mfma_f32_16x16x32_bf16 v[12:15], v[184:187], v[188:191], v[12:15]
	v_mfma_f32_16x16x32_bf16 v[24:27], v[124:127], v[196:199], v[24:27]
	v_mfma_f32_16x16x32_bf16 v[28:31], v[184:187], v[196:199], v[28:31]
	v_mfma_f32_16x16x32_bf16 v[188:191], v[124:127], v[204:207], v[60:63]
	v_mfma_f32_16x16x32_bf16 v[60:63], v[180:183], v[200:203], v[100:103]
	v_mfma_f32_16x16x32_bf16 v[196:199], v[124:127], v[214:217], v[16:19]
	v_mfma_f32_16x16x32_bf16 v[16:19], v[180:183], v[208:211], v[20:23]
	v_mfma_f32_16x16x32_bf16 v[192:195], v[184:187], v[204:207], v[60:63]
	v_mfma_f32_16x16x32_bf16 v[180:183], v[184:187], v[214:217], v[16:19]
	s_setprio 0
	s_barrier
	s_nop 3
	ds_read_b128 v[16:19], v152
	ds_read_b128 v[20:23], v152 offset:1024
	ds_read_b128 v[60:63], v152 offset:2048
	ds_read_b128 v[184:187], v152 offset:3072
	ds_read_b128 v[200:203], v153
	ds_read_b128 v[204:207], v153 offset:1024
	ds_read_b128 v[208:211], v153 offset:2048
	ds_read_b128 v[214:217], v153 offset:3072
	ds_read_b128 v[218:221], v148 offset:32768
	ds_read_b128 v[226:229], v148 offset:33792
	ds_read_b128 v[230:233], v149 offset:32768
	ds_read_b128 v[234:237], v149 offset:33792
	ds_read_b128 v[238:241], v150 offset:32768
	ds_read_b128 v[242:245], v150 offset:33792
	ds_read_b128 v[246:249], v151 offset:32768
	ds_read_b128 v[136:139], v151 offset:33792
	s_waitcnt vmcnt(0)
	s_waitcnt lgkmcnt(0)
	s_barrier
; #define LDA(dst, b, h) for (int m = 0; m < 4; ++m) for (int k = 0; k < 2; ++k) \
;     dst[m][k] = *reinterpret_cast<const bf16x8*>((char*)SA(b, h) + lds_byte(wr * 64 + m * 16 + fr, k * 32 + fq * 8))
; #define MMA(ai, bj, At, Bt_) do { __builtin_amdgcn_s_setprio(1); \
;     for (int m = 0; m < 4; ++m) for (int n = 0; n < 2; ++n) for (int k = 0; k < 2; ++k) \
;       acc[ai][bj][m][n] = __builtin_amdgcn_mfma_f32_16x16x32_bf16(Bt_[n][k], At[m][k], acc[ai][bj][m][n], 0, 0, 0); \
;     __builtin_amdgcn_s_setprio(0); } while (0)
; #define WAIT_V(n) asm volatile("s_waitcnt vmcnt(" #n ")" ::: "memory")
; #define WAIT_L(n) asm volatile("s_waitcnt lgkmcnt(" #n ")" ::: "memory")
; #define BAR __builtin_amdgcn_s_barrier()
; #define SCHED __builtin_amdgcn_sched_barrier(0)
; template <int MODE>
; DI void gemm_phase(const bf16_t* __restrict__ A, const bf16_t* __restrict__ Bt, int M, int N, int K, const Epi& ep) {
;     ...
;             WAIT_V(0); WAIT_L(0); BAR; MMA(0, 0, At, B0); MMA(0, 1, At, B1); BAR; SCHED;
;             LDA(At, 1, 1);
;             WAIT_L(0); BAR; MMA(1, 0, At, B0); MMA(1, 1, At, B1); BAR; SCHED;
;         }
;         if (wr == 0) BAR;
	s_setprio 1
	v_mfma_f32_16x16x32_bf16 v[64:67], v[16:19], v[218:221], v[64:67]
	v_mfma_f32_16x16x32_bf16 v[96:99], v[20:23], v[226:229], v[64:67]
	v_mfma_f32_16x16x32_bf16 v[64:67], v[60:63], v[218:221], v[68:71]
	v_mfma_f32_16x16x32_bf16 v[100:103], v[184:187], v[226:229], v[64:67]
	v_mfma_f32_16x16x32_bf16 v[64:67], v[16:19], v[230:233], v[72:75]
	v_mfma_f32_16x16x32_bf16 v[104:107], v[20:23], v[234:237], v[64:67]
	v_mfma_f32_16x16x32_bf16 v[64:67], v[60:63], v[230:233], v[76:79]
	v_mfma_f32_16x16x32_bf16 v[108:111], v[184:187], v[234:237], v[64:67]
	v_mfma_f32_16x16x32_bf16 v[64:67], v[16:19], v[238:241], v[80:83]
	v_mfma_f32_16x16x32_bf16 v[112:115], v[20:23], v[242:245], v[64:67]
	v_mfma_f32_16x16x32_bf16 v[64:67], v[60:63], v[238:241], v[84:87]
	v_mfma_f32_16x16x32_bf16 v[116:119], v[184:187], v[242:245], v[64:67]
	v_mfma_f32_16x16x32_bf16 v[64:67], v[16:19], v[246:249], v[88:91]
	v_mfma_f32_16x16x32_bf16 v[120:123], v[20:23], v[136:139], v[64:67]
	v_mfma_f32_16x16x32_bf16 v[64:67], v[60:63], v[246:249], v[92:95]
	v_mfma_f32_16x16x32_bf16 v[124:127], v[184:187], v[136:139], v[64:67]
	s_setprio 0
	s_setprio 1
	v_mfma_f32_16x16x32_bf16 v[32:35], v[208:211], v[218:221], v[32:35]
	v_mfma_f32_16x16x32_bf16 v[68:71], v[214:217], v[226:229], v[32:35]
	v_mfma_f32_16x16x32_bf16 v[32:35], v[200:203], v[230:233], v[36:39]
	v_mfma_f32_16x16x32_bf16 v[72:75], v[204:207], v[234:237], v[32:35]
	v_mfma_f32_16x16x32_bf16 v[32:35], v[208:211], v[230:233], v[40:43]
	v_mfma_f32_16x16x32_bf16 v[76:79], v[214:217], v[234:237], v[32:35]
	v_mfma_f32_16x16x32_bf16 v[32:35], v[200:203], v[238:241], v[44:47]
	v_mfma_f32_16x16x32_bf16 v[80:83], v[204:207], v[242:245], v[32:35]
	v_mfma_f32_16x16x32_bf16 v[32:35], v[208:211], v[238:241], v[48:51]
	v_mfma_f32_16x16x32_bf16 v[84:87], v[214:217], v[242:245], v[32:35]
	v_mfma_f32_16x16x32_bf16 v[32:35], v[200:203], v[246:249], v[52:55]
	v_mfma_f32_16x16x32_bf16 v[64:67], v[200:203], v[218:221], v[222:225]
	v_mfma_f32_16x16x32_bf16 v[88:91], v[204:207], v[136:139], v[32:35]
	v_mfma_f32_16x16x32_bf16 v[32:35], v[208:211], v[246:249], v[56:59]
	v_mfma_f32_16x16x32_bf16 v[64:67], v[204:207], v[226:229], v[64:67]
	v_mfma_f32_16x16x32_bf16 v[92:95], v[214:217], v[136:139], v[32:35]
	s_setprio 0
	s_barrier
	ds_read_b128 v[136:139], v148 offset:49152
	ds_read_b128 v[218:221], v148 offset:50176
	ds_read_b128 v[222:225], v149 offset:49152
	ds_read_b128 v[226:229], v149 offset:50176
	ds_read_b128 v[230:233], v150 offset:49152
	ds_read_b128 v[234:237], v150 offset:50176
	ds_read_b128 v[238:241], v151 offset:49152
	ds_read_b128 v[242:245], v151 offset:50176
	s_waitcnt lgkmcnt(0)
	s_barrier
	s_setprio 1
	v_mfma_f32_16x16x32_bf16 v[0:3], v[16:19], v[238:241], v[0:3]
	v_mfma_f32_16x16x32_bf16 v[32:35], v[16:19], v[136:139], v[156:159]
	v_mfma_f32_16x16x32_bf16 v[36:39], v[60:63], v[136:139], v[160:163]
	v_mfma_f32_16x16x32_bf16 v[40:43], v[16:19], v[222:225], v[164:167]
	v_mfma_f32_16x16x32_bf16 v[44:47], v[60:63], v[222:225], v[168:171]
	v_mfma_f32_16x16x32_bf16 v[48:51], v[16:19], v[230:233], v[172:175]
	v_mfma_f32_16x16x32_bf16 v[52:55], v[60:63], v[230:233], v[176:179]
	v_mfma_f32_16x16x32_bf16 v[56:59], v[20:23], v[242:245], v[0:3]
	v_mfma_f32_16x16x32_bf16 v[0:3], v[60:63], v[238:241], v[4:7]
	v_mfma_f32_16x16x32_bf16 v[32:35], v[20:23], v[218:221], v[32:35]
	v_mfma_f32_16x16x32_bf16 v[36:39], v[184:187], v[218:221], v[36:39]
	v_mfma_f32_16x16x32_bf16 v[40:43], v[20:23], v[226:229], v[40:43]
	v_mfma_f32_16x16x32_bf16 v[44:47], v[184:187], v[226:229], v[44:47]
	v_mfma_f32_16x16x32_bf16 v[48:51], v[20:23], v[234:237], v[48:51]
	v_mfma_f32_16x16x32_bf16 v[52:55], v[184:187], v[234:237], v[52:55]
	v_mfma_f32_16x16x32_bf16 v[60:63], v[184:187], v[242:245], v[0:3]
	s_setprio 0
	s_setprio 1
	v_mfma_f32_16x16x32_bf16 v[0:3], v[200:203], v[136:139], v[8:11]
	v_mfma_f32_16x16x32_bf16 v[4:7], v[208:211], v[136:139], v[12:15]
	v_mfma_f32_16x16x32_bf16 v[8:11], v[200:203], v[222:225], v[24:27]
	v_mfma_f32_16x16x32_bf16 v[12:15], v[208:211], v[222:225], v[28:31]
	v_mfma_f32_16x16x32_bf16 v[16:19], v[200:203], v[230:233], v[188:191]
	v_mfma_f32_16x16x32_bf16 v[20:23], v[208:211], v[230:233], v[192:195]
	v_mfma_f32_16x16x32_bf16 v[24:27], v[200:203], v[238:241], v[196:199]
	v_mfma_f32_16x16x32_bf16 v[28:31], v[208:211], v[238:241], v[180:183]
	v_mfma_f32_16x16x32_bf16 v[0:3], v[204:207], v[218:221], v[0:3]
	v_mfma_f32_16x16x32_bf16 v[4:7], v[214:217], v[218:221], v[4:7]
	v_mfma_f32_16x16x32_bf16 v[8:11], v[204:207], v[226:229], v[8:11]
	v_mfma_f32_16x16x32_bf16 v[12:15], v[214:217], v[226:229], v[12:15]
	v_mfma_f32_16x16x32_bf16 v[16:19], v[204:207], v[234:237], v[16:19]
	v_mfma_f32_16x16x32_bf16 v[20:23], v[214:217], v[234:237], v[20:23]
	v_mfma_f32_16x16x32_bf16 v[24:27], v[204:207], v[242:245], v[24:27]
	v_mfma_f32_16x16x32_bf16 v[28:31], v[214:217], v[242:245], v[28:31]
	s_setprio 0
	s_barrier
	s_and_saveexec_b64 s[0:1], s[36:37]
	s_cbranch_execz .LBB0_818
	s_barrier

; #define LDA(dst, b, h) for (int m = 0; m < 4; ++m) for (int k = 0; k < 2; ++k) \
;     dst[m][k] = *reinterpret_cast<const bf16x8*>((char*)SA(b, h) + lds_byte(wr * 64 + m * 16 + fr, k * 32 + fq * 8))
; #define LDB(dst, b, h) for (int n = 0; n < 2; ++n) for (int k = 0; k < 2; ++k) \
;     dst[n][k] = *reinterpret_cast<const bf16x8*>((char*)SB(b, h) + lds_byte(wc * 32 + n * 16 + fr, k * 32 + fq * 8))
; #define MMA(ai, bj, At, Bt_) do { __builtin_amdgcn_s_setprio(1); \
;     for (int m = 0; m < 4; ++m) for (int n = 0; n < 2; ++n) for (int k = 0; k < 2; ++k) \
;       acc[ai][bj][m][n] = __builtin_amdgcn_mfma_f32_16x16x32_bf16(Bt_[n][k], At[m][k], acc[ai][bj][m][n], 0, 0, 0); \
;     __builtin_amdgcn_s_setprio(0); } while (0)
; #define WAIT_V(n) asm volatile("s_waitcnt vmcnt(" #n ")" ::: "memory")
; #define WAIT_L(n) asm volatile("s_waitcnt lgkmcnt(" #n ")" ::: "memory")
; #define BAR __builtin_amdgcn_s_barrier()
; #define SCHED __builtin_amdgcn_sched_barrier(0)
; template <int MODE>
; DI void gemm_phase(const bf16_t* __restrict__ A, const bf16_t* __restrict__ Bt, int M, int N, int K, const Epi& ep) {
;     ...
;             LDB(B0, 0, 0); LDB(B1, 0, 1); SCHED; LDA(At, 0, 0); STAGE(SA(1, 1), rsA, brow + HALF, t + 1);
;             WAIT_V(8); WAIT_L(0); BAR; MMA(0, 0, At, B0); MMA(0, 1, At, B1); BAR; SCHED;
;             LDA(At, 0, 1); STAGE(SB(0, 0), rsB, bcol, t + 2); STAGE(SB(0, 1), rsB, bcol + HALF, t + 2); STAGE(SA(0, 0), rsA, brow, t + 2);
;             WAIT_V(8); WAIT_L(0); BAR; MMA(1, 0, At, B0); MMA(1, 1, At, B1); BAR; SCHED;
;             LDB(B0, 1, 0); LDB(B1, 1, 1); SCHED; LDA(At, 1, 0); STAGE(SA(0, 1), rsA, brow + HALF, t + 2);
;             WAIT_V(8); WAIT_L(0); BAR; MMA(0, 0, At, B0); MMA(0, 1, At, B1); BAR; SCHED;
;             LDA(At, 1, 1); STAGE(SB(1, 0), rsB, bcol, t + 3); STAGE(SB(1, 1), rsB, bcol + HALF, t + 3); STAGE(SA(1, 0), rsA, brow, t + 3);
;             WAIT_V(8); WAIT_L(0); BAR; MMA(1, 0, At, B0); MMA(1, 1, At, B1); BAR; SCHED;
.LBB0_1023:
	ds_read_b128 v[156:159], v147
	ds_read_b128 v[160:163], v147 offset:1024
	ds_read_b128 v[164:167], v147 offset:2048
	ds_read_b128 v[168:171], v147 offset:3072
	ds_read_b128 v[172:175], v148
	ds_read_b128 v[176:179], v148 offset:1024
	ds_read_b128 v[180:183], v148 offset:2048
	ds_read_b128 v[184:187], v148 offset:3072
	s_add_i32 s42, s31, s41
	v_readfirstlane_b32 s15, v144
	s_add_i32 s14, s42, 0x40080
	s_mov_b32 s26, s10
	s_mov_b32 s27, s11
	s_mov_b32 m0, s15
	v_readfirstlane_b32 s15, v145
	ds_read_b128 v[188:191], v149
	ds_read_b128 v[192:195], v149 offset:1024
	ds_read_b128 v[196:199], v150
	ds_read_b128 v[200:203], v150 offset:1024
	ds_read_b128 v[204:207], v151
	ds_read_b128 v[208:211], v151 offset:1024
	ds_read_b128 v[214:217], v152
	ds_read_b128 v[218:221], v152 offset:1024
	buffer_load_dwordx4 v128, s[24:27], s14 offen lds
	s_mov_b32 m0, s15
	s_nop 0
	buffer_load_dwordx4 v129, s[24:27], s14 offen lds
	s_waitcnt vmcnt(8)
	s_waitcnt lgkmcnt(0)
	s_barrier
	s_setprio 1
	v_mfma_f32_16x16x32_bf16 v[124:127], v[156:159], v[188:191], v[124:127]
	v_mfma_f32_16x16x32_bf16 v[120:123], v[164:167], v[188:191], v[120:123]
	v_mfma_f32_16x16x32_bf16 v[116:119], v[156:159], v[196:199], v[116:119]
	v_mfma_f32_16x16x32_bf16 v[112:115], v[164:167], v[196:199], v[112:115]
	v_mfma_f32_16x16x32_bf16 v[108:111], v[156:159], v[204:207], v[108:111]
	v_mfma_f32_16x16x32_bf16 v[104:107], v[164:167], v[204:207], v[104:107]
	v_mfma_f32_16x16x32_bf16 v[100:103], v[156:159], v[214:217], v[100:103]
	v_mfma_f32_16x16x32_bf16 v[96:99], v[164:167], v[214:217], v[96:99]
	v_mfma_f32_16x16x32_bf16 v[124:127], v[160:163], v[192:195], v[124:127]
	v_mfma_f32_16x16x32_bf16 v[120:123], v[168:171], v[192:195], v[120:123]
	v_mfma_f32_16x16x32_bf16 v[116:119], v[160:163], v[200:203], v[116:119]
	v_mfma_f32_16x16x32_bf16 v[112:115], v[168:171], v[200:203], v[112:115]
	v_mfma_f32_16x16x32_bf16 v[108:111], v[160:163], v[208:211], v[108:111]
	v_mfma_f32_16x16x32_bf16 v[104:107], v[168:171], v[208:211], v[104:107]
	v_mfma_f32_16x16x32_bf16 v[100:103], v[160:163], v[218:221], v[100:103]
	v_mfma_f32_16x16x32_bf16 v[96:99], v[168:171], v[218:221], v[96:99]
	s_setprio 0
	s_setprio 1
	v_mfma_f32_16x16x32_bf16 v[92:95], v[172:175], v[188:191], v[92:95]
	v_mfma_f32_16x16x32_bf16 v[88:91], v[180:183], v[188:191], v[88:91]
	v_mfma_f32_16x16x32_bf16 v[84:87], v[172:175], v[196:199], v[84:87]
	v_mfma_f32_16x16x32_bf16 v[80:83], v[180:183], v[196:199], v[80:83]
	v_mfma_f32_16x16x32_bf16 v[76:79], v[172:175], v[204:207], v[76:79]
	v_mfma_f32_16x16x32_bf16 v[72:75], v[180:183], v[204:207], v[72:75]
	v_mfma_f32_16x16x32_bf16 v[68:71], v[172:175], v[214:217], v[68:71]
	v_mfma_f32_16x16x32_bf16 v[64:67], v[180:183], v[214:217], v[64:67]
	v_mfma_f32_16x16x32_bf16 v[92:95], v[176:179], v[192:195], v[92:95]
	v_mfma_f32_16x16x32_bf16 v[88:91], v[184:187], v[192:195], v[88:91]
	v_mfma_f32_16x16x32_bf16 v[84:87], v[176:179], v[200:203], v[84:87]
	v_mfma_f32_16x16x32_bf16 v[80:83], v[184:187], v[200:203], v[80:83]
	v_mfma_f32_16x16x32_bf16 v[76:79], v[176:179], v[208:211], v[76:79]
	v_mfma_f32_16x16x32_bf16 v[72:75], v[184:187], v[208:211], v[72:75]
	v_mfma_f32_16x16x32_bf16 v[68:71], v[176:179], v[218:221], v[68:71]
	v_mfma_f32_16x16x32_bf16 v[64:67], v[184:187], v[218:221], v[64:67]
	s_setprio 0
	s_barrier
	s_add_i32 s43, s6, s41
	v_readfirstlane_b32 s45, v130
	s_add_i32 s44, s43, 0x100
	s_mov_b32 s14, s10
	s_mov_b32 s15, s11
	s_mov_b32 m0, s45
	v_readfirstlane_b32 s45, v131
	ds_read_b128 v[188:191], v149 offset:16384
	ds_read_b128 v[192:195], v149 offset:17408
	ds_read_b128 v[196:199], v150 offset:16384
	ds_read_b128 v[200:203], v150 offset:17408
	ds_read_b128 v[204:207], v151 offset:16384
	ds_read_b128 v[208:211], v151 offset:17408
	ds_read_b128 v[214:217], v152 offset:16384
	ds_read_b128 v[218:221], v152 offset:17408
	buffer_load_dwordx4 v128, s[12:15], s44 offen lds
	s_mov_b32 m0, s45
	v_readfirstlane_b32 s45, v132
	buffer_load_dwordx4 v129, s[12:15], s44 offen lds
	s_add_i32 s44, s43, 0x40100
	s_mov_b32 m0, s45
	v_readfirstlane_b32 s45, v133
	buffer_load_dwordx4 v128, s[12:15], s44 offen lds
	s_mov_b32 m0, s45
	v_readfirstlane_b32 s45, v134
	buffer_load_dwordx4 v129, s[12:15], s44 offen lds
	s_add_i32 s44, s42, 0x100
	s_mov_b32 m0, s45
	v_readfirstlane_b32 s45, v135
	buffer_load_dwordx4 v128, s[24:27], s44 offen lds
	s_mov_b32 m0, s45
	s_nop 0
	buffer_load_dwordx4 v129, s[24:27], s44 offen lds
	s_waitcnt vmcnt(8)
	s_waitcnt lgkmcnt(0)
	s_barrier
	s_setprio 1
	v_mfma_f32_16x16x32_bf16 v[60:63], v[156:159], v[188:191], v[60:63]
	v_mfma_f32_16x16x32_bf16 v[56:59], v[164:167], v[188:191], v[56:59]
	v_mfma_f32_16x16x32_bf16 v[52:55], v[156:159], v[196:199], v[52:55]
	v_mfma_f32_16x16x32_bf16 v[48:51], v[164:167], v[196:199], v[48:51]
	v_mfma_f32_16x16x32_bf16 v[44:47], v[156:159], v[204:207], v[44:47]
	v_mfma_f32_16x16x32_bf16 v[40:43], v[164:167], v[204:207], v[40:43]
	v_mfma_f32_16x16x32_bf16 v[36:39], v[156:159], v[214:217], v[36:39]
	v_mfma_f32_16x16x32_bf16 v[32:35], v[164:167], v[214:217], v[32:35]
	v_mfma_f32_16x16x32_bf16 v[60:63], v[160:163], v[192:195], v[60:63]
	v_mfma_f32_16x16x32_bf16 v[56:59], v[168:171], v[192:195], v[56:59]
	v_mfma_f32_16x16x32_bf16 v[52:55], v[160:163], v[200:203], v[52:55]
	v_mfma_f32_16x16x32_bf16 v[48:51], v[168:171], v[200:203], v[48:51]
	v_mfma_f32_16x16x32_bf16 v[44:47], v[160:163], v[208:211], v[44:47]
	v_mfma_f32_16x16x32_bf16 v[40:43], v[168:171], v[208:211], v[40:43]
	v_mfma_f32_16x16x32_bf16 v[36:39], v[160:163], v[218:221], v[36:39]
	v_mfma_f32_16x16x32_bf16 v[32:35], v[168:171], v[218:221], v[32:35]
	s_setprio 0
	s_setprio 1
	v_mfma_f32_16x16x32_bf16 v[28:31], v[172:175], v[188:191], v[28:31]
	v_mfma_f32_16x16x32_bf16 v[24:27], v[180:183], v[188:191], v[24:27]
	v_mfma_f32_16x16x32_bf16 v[20:23], v[172:175], v[196:199], v[20:23]
	v_mfma_f32_16x16x32_bf16 v[16:19], v[180:183], v[196:199], v[16:19]
	v_mfma_f32_16x16x32_bf16 v[12:15], v[172:175], v[204:207], v[12:15]
	v_mfma_f32_16x16x32_bf16 v[8:11], v[180:183], v[204:207], v[8:11]
	v_mfma_f32_16x16x32_bf16 v[4:7], v[172:175], v[214:217], v[4:7]
	v_mfma_f32_16x16x32_bf16 v[0:3], v[180:183], v[214:217], v[0:3]
	v_mfma_f32_16x16x32_bf16 v[28:31], v[176:179], v[192:195], v[28:31]
	v_mfma_f32_16x16x32_bf16 v[24:27], v[184:187], v[192:195], v[24:27]
	v_mfma_f32_16x16x32_bf16 v[20:23], v[176:179], v[200:203], v[20:23]
	v_mfma_f32_16x16x32_bf16 v[16:19], v[184:187], v[200:203], v[16:19]
	v_mfma_f32_16x16x32_bf16 v[12:15], v[176:179], v[208:211], v[12:15]
	v_mfma_f32_16x16x32_bf16 v[8:11], v[184:187], v[208:211], v[8:11]
	v_mfma_f32_16x16x32_bf16 v[4:7], v[176:179], v[218:221], v[4:7]
	v_mfma_f32_16x16x32_bf16 v[0:3], v[184:187], v[218:221], v[0:3]
	s_setprio 0
	s_barrier
; #define LDA(dst, b, h) for (int m = 0; m < 4; ++m) for (int k = 0; k < 2; ++k) \
;     dst[m][k] = *reinterpret_cast<const bf16x8*>((char*)SA(b, h) + lds_byte(wr * 64 + m * 16 + fr, k * 32 + fq * 8))
; #define LDB(dst, b, h) for (int n = 0; n < 2; ++n) for (int k = 0; k < 2; ++k) \
;     dst[n][k] = *reinterpret_cast<const bf16x8*>((char*)SB(b, h) + lds_byte(wc * 32 + n * 16 + fr, k * 32 + fq * 8))
; #define MMA(ai, bj, At, Bt_) do { __builtin_amdgcn_s_setprio(1); \
;     for (int m = 0; m < 4; ++m) for (int n = 0; n < 2; ++n) for (int k = 0; k < 2; ++k) \
;       acc[ai][bj][m][n] = __builtin_amdgcn_mfma_f32_16x16x32_bf16(Bt_[n][k], At[m][k], acc[ai][bj][m][n], 0, 0, 0); \
;     __builtin_amdgcn_s_setprio(0); } while (0)
; #define WAIT_V(n) asm volatile("s_waitcnt vmcnt(" #n ")" ::: "memory")
; #define WAIT_L(n) asm volatile("s_waitcnt lgkmcnt(" #n ")" ::: "memory")
; #define BAR __builtin_amdgcn_s_barrier()
; #define SCHED __builtin_amdgcn_sched_barrier(0)
; template <int MODE>
; DI void gemm_phase(const bf16_t* __restrict__ A, const bf16_t* __restrict__ Bt, int M, int N, int K, const Epi& ep) {
;     ...
;         for (int t = 0; t < nt - 2; t += 2) {
;             LDB(B0, 0, 0); LDB(B1, 0, 1); SCHED; LDA(At, 0, 0); STAGE(SA(1, 1), rsA, brow + HALF, t + 1);
;             WAIT_V(8); WAIT_L(0); BAR; MMA(0, 0, At, B0); MMA(0, 1, At, B1); BAR; SCHED;
;             LDA(At, 0, 1); STAGE(SB(0, 0), rsB, bcol, t + 2); STAGE(SB(0, 1), rsB, bcol + HALF, t + 2); STAGE(SA(0, 0), rsA, brow, t + 2);
;             WAIT_V(8); WAIT_L(0); BAR; MMA(1, 0, At, B0); MMA(1, 1, At, B1); BAR; SCHED;
;             LDB(B0, 1, 0); LDB(B1, 1, 1); SCHED; LDA(At, 1, 0); STAGE(SA(0, 1), rsA, brow + HALF, t + 2);
;             WAIT_V(8); WAIT_L(0); BAR; MMA(0, 0, At, B0); MMA(0, 1, At, B1); BAR; SCHED;
;             LDA(At, 1, 1); STAGE(SB(1, 0), rsB, bcol, t + 3); STAGE(SB(1, 1), rsB, bcol + HALF, t + 3); STAGE(SA(1, 0), rsA, brow, t + 3);
;             WAIT_V(8); WAIT_L(0); BAR; MMA(1, 0, At, B0); MMA(1, 1, At, B1); BAR; SCHED;
;         }
	ds_read_b128 v[156:159], v153
	ds_read_b128 v[160:163], v153 offset:1024
	ds_read_b128 v[164:167], v153 offset:2048
	ds_read_b128 v[168:171], v153 offset:3072
	ds_read_b128 v[172:175], v154
	ds_read_b128 v[176:179], v154 offset:1024
	ds_read_b128 v[180:183], v154 offset:2048
	ds_read_b128 v[184:187], v154 offset:3072
	v_readfirstlane_b32 s45, v136
	s_add_i32 s44, s42, 0x40100
	s_mov_b32 m0, s45
	v_readfirstlane_b32 s45, v137
	ds_read_b128 v[188:191], v149 offset:32768
	ds_read_b128 v[192:195], v149 offset:33792
	ds_read_b128 v[196:199], v150 offset:32768
	ds_read_b128 v[200:203], v150 offset:33792
	ds_read_b128 v[204:207], v151 offset:32768
	ds_read_b128 v[208:211], v151 offset:33792
	ds_read_b128 v[214:217], v152 offset:32768
	ds_read_b128 v[218:221], v152 offset:33792
	buffer_load_dwordx4 v128, s[24:27], s44 offen lds
	s_mov_b32 m0, s45
	s_nop 0
	buffer_load_dwordx4 v129, s[24:27], s44 offen lds
	s_waitcnt vmcnt(8)
	s_waitcnt lgkmcnt(0)
	s_barrier
	s_setprio 1
	v_mfma_f32_16x16x32_bf16 v[124:127], v[156:159], v[188:191], v[124:127]
	v_mfma_f32_16x16x32_bf16 v[120:123], v[164:167], v[188:191], v[120:123]
	v_mfma_f32_16x16x32_bf16 v[116:119], v[156:159], v[196:199], v[116:119]
	v_mfma_f32_16x16x32_bf16 v[112:115], v[164:167], v[196:199], v[112:115]
	v_mfma_f32_16x16x32_bf16 v[108:111], v[156:159], v[204:207], v[108:111]
	v_mfma_f32_16x16x32_bf16 v[104:107], v[164:167], v[204:207], v[104:107]
	v_mfma_f32_16x16x32_bf16 v[100:103], v[156:159], v[214:217], v[100:103]
	v_mfma_f32_16x16x32_bf16 v[96:99], v[164:167], v[214:217], v[96:99]
	v_mfma_f32_16x16x32_bf16 v[124:127], v[160:163], v[192:195], v[124:127]
	v_mfma_f32_16x16x32_bf16 v[120:123], v[168:171], v[192:195], v[120:123]
	v_mfma_f32_16x16x32_bf16 v[116:119], v[160:163], v[200:203], v[116:119]
	v_mfma_f32_16x16x32_bf16 v[112:115], v[168:171], v[200:203], v[112:115]
	v_mfma_f32_16x16x32_bf16 v[108:111], v[160:163], v[208:211], v[108:111]
	v_mfma_f32_16x16x32_bf16 v[104:107], v[168:171], v[208:211], v[104:107]
	v_mfma_f32_16x16x32_bf16 v[100:103], v[160:163], v[218:221], v[100:103]
	v_mfma_f32_16x16x32_bf16 v[96:99], v[168:171], v[218:221], v[96:99]
	s_setprio 0
	s_setprio 1
	v_mfma_f32_16x16x32_bf16 v[92:95], v[172:175], v[188:191], v[92:95]
	v_mfma_f32_16x16x32_bf16 v[88:91], v[180:183], v[188:191], v[88:91]
	v_mfma_f32_16x16x32_bf16 v[84:87], v[172:175], v[196:199], v[84:87]
	v_mfma_f32_16x16x32_bf16 v[80:83], v[180:183], v[196:199], v[80:83]
	v_mfma_f32_16x16x32_bf16 v[76:79], v[172:175], v[204:207], v[76:79]
	v_mfma_f32_16x16x32_bf16 v[72:75], v[180:183], v[204:207], v[72:75]
	v_mfma_f32_16x16x32_bf16 v[68:71], v[172:175], v[214:217], v[68:71]
	v_mfma_f32_16x16x32_bf16 v[64:67], v[180:183], v[214:217], v[64:67]
	v_mfma_f32_16x16x32_bf16 v[92:95], v[176:179], v[192:195], v[92:95]
	v_mfma_f32_16x16x32_bf16 v[88:91], v[184:187], v[192:195], v[88:91]
	v_mfma_f32_16x16x32_bf16 v[84:87], v[176:179], v[200:203], v[84:87]
	v_mfma_f32_16x16x32_bf16 v[80:83], v[184:187], v[200:203], v[80:83]
	v_mfma_f32_16x16x32_bf16 v[76:79], v[176:179], v[208:211], v[76:79]
	v_mfma_f32_16x16x32_bf16 v[72:75], v[184:187], v[208:211], v[72:75]
	v_mfma_f32_16x16x32_bf16 v[68:71], v[176:179], v[218:221], v[68:71]
	v_mfma_f32_16x16x32_bf16 v[64:67], v[184:187], v[218:221], v[64:67]
	s_setprio 0
	s_barrier
	v_readfirstlane_b32 s45, v138
	s_add_i32 s44, s43, 0x180
	s_mov_b32 m0, s45
	v_readfirstlane_b32 s45, v139
	ds_read_b128 v[188:191], v149 offset:49152
	ds_read_b128 v[192:195], v149 offset:50176
	ds_read_b128 v[196:199], v150 offset:49152
	ds_read_b128 v[200:203], v150 offset:50176
	ds_read_b128 v[204:207], v151 offset:49152
	ds_read_b128 v[208:211], v151 offset:50176
	ds_read_b128 v[214:217], v152 offset:49152
	ds_read_b128 v[218:221], v152 offset:50176
	buffer_load_dwordx4 v128, s[12:15], s44 offen lds
	s_mov_b32 m0, s45
	s_add_i32 s43, s43, 0x40180
	buffer_load_dwordx4 v129, s[12:15], s44 offen lds
	v_readfirstlane_b32 s44, v142
	s_mov_b32 m0, s44
	v_readfirstlane_b32 s44, v143
	buffer_load_dwordx4 v128, s[12:15], s43 offen lds
	s_mov_b32 m0, s44
	s_addk_i32 s42, 0x180
	buffer_load_dwordx4 v129, s[12:15], s43 offen lds
	v_readfirstlane_b32 s14, v140
	s_mov_b32 m0, s14
	v_readfirstlane_b32 s14, v141
	buffer_load_dwordx4 v128, s[24:27], s42 offen lds
	s_mov_b32 m0, s14
	s_nop 0
	buffer_load_dwordx4 v129, s[24:27], s42 offen lds
	s_waitcnt vmcnt(8)
	s_waitcnt lgkmcnt(0)
	s_barrier
	s_setprio 1
	v_mfma_f32_16x16x32_bf16 v[60:63], v[156:159], v[188:191], v[60:63]
	v_mfma_f32_16x16x32_bf16 v[56:59], v[164:167], v[188:191], v[56:59]
	v_mfma_f32_16x16x32_bf16 v[52:55], v[156:159], v[196:199], v[52:55]
	v_mfma_f32_16x16x32_bf16 v[48:51], v[164:167], v[196:199], v[48:51]
	v_mfma_f32_16x16x32_bf16 v[44:47], v[156:159], v[204:207], v[44:47]
	v_mfma_f32_16x16x32_bf16 v[40:43], v[164:167], v[204:207], v[40:43]
	v_mfma_f32_16x16x32_bf16 v[36:39], v[156:159], v[214:217], v[36:39]
	v_mfma_f32_16x16x32_bf16 v[32:35], v[164:167], v[214:217], v[32:35]
	v_mfma_f32_16x16x32_bf16 v[60:63], v[160:163], v[192:195], v[60:63]
	v_mfma_f32_16x16x32_bf16 v[56:59], v[168:171], v[192:195], v[56:59]
	v_mfma_f32_16x16x32_bf16 v[52:55], v[160:163], v[200:203], v[52:55]
	v_mfma_f32_16x16x32_bf16 v[48:51], v[168:171], v[200:203], v[48:51]
	v_mfma_f32_16x16x32_bf16 v[44:47], v[160:163], v[208:211], v[44:47]
	v_mfma_f32_16x16x32_bf16 v[40:43], v[168:171], v[208:211], v[40:43]
	v_mfma_f32_16x16x32_bf16 v[36:39], v[160:163], v[218:221], v[36:39]
	v_mfma_f32_16x16x32_bf16 v[32:35], v[168:171], v[218:221], v[32:35]
	s_setprio 0
	s_setprio 1
	v_mfma_f32_16x16x32_bf16 v[28:31], v[172:175], v[188:191], v[28:31]
	v_mfma_f32_16x16x32_bf16 v[24:27], v[180:183], v[188:191], v[24:27]
	v_mfma_f32_16x16x32_bf16 v[20:23], v[172:175], v[196:199], v[20:23]
	v_mfma_f32_16x16x32_bf16 v[16:19], v[180:183], v[196:199], v[16:19]
	v_mfma_f32_16x16x32_bf16 v[12:15], v[172:175], v[204:207], v[12:15]
	v_mfma_f32_16x16x32_bf16 v[8:11], v[180:183], v[204:207], v[8:11]
	v_mfma_f32_16x16x32_bf16 v[4:7], v[172:175], v[214:217], v[4:7]
	v_mfma_f32_16x16x32_bf16 v[0:3], v[180:183], v[214:217], v[0:3]
	v_mfma_f32_16x16x32_bf16 v[28:31], v[176:179], v[192:195], v[28:31]
	v_mfma_f32_16x16x32_bf16 v[24:27], v[184:187], v[192:195], v[24:27]
	v_mfma_f32_16x16x32_bf16 v[20:23], v[176:179], v[200:203], v[20:23]
	v_mfma_f32_16x16x32_bf16 v[16:19], v[184:187], v[200:203], v[16:19]
	v_mfma_f32_16x16x32_bf16 v[12:15], v[176:179], v[208:211], v[12:15]
	v_mfma_f32_16x16x32_bf16 v[8:11], v[184:187], v[208:211], v[8:11]
	v_mfma_f32_16x16x32_bf16 v[4:7], v[176:179], v[218:221], v[4:7]
	v_mfma_f32_16x16x32_bf16 v[0:3], v[184:187], v[218:221], v[0:3]
	s_setprio 0
	s_barrier
; #define LDA(dst, b, h) for (int m = 0; m < 4; ++m) for (int k = 0; k < 2; ++k) \
;     dst[m][k] = *reinterpret_cast<const bf16x8*>((char*)SA(b, h) + lds_byte(wr * 64 + m * 16 + fr, k * 32 + fq * 8))
; #define LDB(dst, b, h) for (int n = 0; n < 2; ++n) for (int k = 0; k < 2; ++k) \
;     dst[n][k] = *reinterpret_cast<const bf16x8*>((char*)SB(b, h) + lds_byte(wc * 32 + n * 16 + fr, k * 32 + fq * 8))
; #define MMA(ai, bj, At, Bt_) do { __builtin_amdgcn_s_setprio(1); \
;     for (int m = 0; m < 4; ++m) for (int n = 0; n < 2; ++n) for (int k = 0; k < 2; ++k) \
;       acc[ai][bj][m][n] = __builtin_amdgcn_mfma_f32_16x16x32_bf16(Bt_[n][k], At[m][k], acc[ai][bj][m][n], 0, 0, 0); \
;     __builtin_amdgcn_s_setprio(0); } while (0)
; #define WAIT_V(n) asm volatile("s_waitcnt vmcnt(" #n ")" ::: "memory")
; #define WAIT_L(n) asm volatile("s_waitcnt lgkmcnt(" #n ")" ::: "memory")
; #define BAR __builtin_amdgcn_s_barrier()
; #define SCHED __builtin_amdgcn_sched_barrier(0)
; template <int MODE>
; DI void gemm_phase(const bf16_t* __restrict__ A, const bf16_t* __restrict__ Bt, int M, int N, int K, const Epi& ep) {
;     ...
;             WAIT_V(8); WAIT_L(0); BAR; MMA(0, 0, At, B0); MMA(0, 1, At, B1); BAR; SCHED;
;             LDA(At, 0, 1); STAGE(SB(0, 0), rsB, bcol, t + 2); STAGE(SB(0, 1), rsB, bcol + HALF, t + 2); STAGE(SA(0, 0), rsA, brow, t + 2);
;             WAIT_V(8); WAIT_L(0); BAR; MMA(1, 0, At, B0); MMA(1, 1, At, B1); BAR; SCHED;
;             LDB(B0, 1, 0); LDB(B1, 1, 1); SCHED; LDA(At, 1, 0); STAGE(SA(0, 1), rsA, brow + HALF, t + 2);
;             WAIT_V(8); WAIT_L(0); BAR; MMA(0, 0, At, B0); MMA(0, 1, At, B1); BAR; SCHED;
;             LDA(At, 1, 1); STAGE(SB(1, 0), rsB, bcol, t + 3); STAGE(SB(1, 1), rsB, bcol + HALF, t + 3); STAGE(SA(1, 0), rsA, brow, t + 3);
;             WAIT_V(8); WAIT_L(0); BAR; MMA(1, 0, At, B0); MMA(1, 1, At, B1); BAR; SCHED;
;         }
;         {
;             LDB(B0, 0, 0); LDB(B1, 0, 1); SCHED; LDA(At, 0, 0); STAGE(SA(1, 1), rsA, brow + HALF, nt - 1);
;             WAIT_V(8); WAIT_L(0); BAR; MMA(0, 0, At, B0); MMA(0, 1, At, B1); BAR; SCHED;
;             LDA(At, 0, 1);
;             WAIT_V(2); WAIT_L(0); BAR; MMA(1, 0, At, B0); MMA(1, 1, At, B1); BAR; SCHED;
	s_add_i32 s40, s40, 2
	s_addk_i32 s41, 0x100
	s_cmp_gt_u32 s40, 11
	s_cbranch_scc0 .LBB0_1023
	ds_read_b128 v[156:159], v147
	ds_read_b128 v[160:163], v147 offset:1024
	ds_read_b128 v[164:167], v147 offset:2048
	ds_read_b128 v[168:171], v147 offset:3072
	ds_read_b128 v[172:175], v148
	ds_read_b128 v[176:179], v148 offset:1024
	ds_read_b128 v[180:183], v148 offset:2048
	ds_read_b128 v[184:187], v148 offset:3072
	s_or_b32 s6, s7, 0x780
	v_readfirstlane_b32 s7, v144
	s_mov_b32 m0, s7
	v_readfirstlane_b32 s7, v145
	ds_read_b128 v[188:191], v149
	ds_read_b128 v[192:195], v149 offset:1024
	ds_read_b128 v[196:199], v150
	ds_read_b128 v[200:203], v150 offset:1024
	ds_read_b128 v[204:207], v151
	ds_read_b128 v[208:211], v151 offset:1024
	ds_read_b128 v[214:217], v152
	ds_read_b128 v[218:221], v152 offset:1024
	buffer_load_dwordx4 v128, s[24:27], s6 offen lds
	s_mov_b32 m0, s7
	s_nop 0
	buffer_load_dwordx4 v129, s[24:27], s6 offen lds
	s_waitcnt vmcnt(8)
	s_waitcnt lgkmcnt(0)
	s_barrier
	s_setprio 1
	v_mfma_f32_16x16x32_bf16 v[124:127], v[156:159], v[188:191], v[124:127]
	v_mfma_f32_16x16x32_bf16 v[120:123], v[164:167], v[188:191], v[120:123]
	v_mfma_f32_16x16x32_bf16 v[116:119], v[156:159], v[196:199], v[116:119]
	v_mfma_f32_16x16x32_bf16 v[112:115], v[164:167], v[196:199], v[112:115]
	v_mfma_f32_16x16x32_bf16 v[108:111], v[156:159], v[204:207], v[108:111]
	v_mfma_f32_16x16x32_bf16 v[124:127], v[160:163], v[192:195], v[124:127]
	v_mfma_f32_16x16x32_bf16 v[120:123], v[168:171], v[192:195], v[120:123]
	v_mfma_f32_16x16x32_bf16 v[116:119], v[160:163], v[200:203], v[116:119]
	v_mfma_f32_16x16x32_bf16 v[112:115], v[168:171], v[200:203], v[112:115]
	v_mfma_f32_16x16x32_bf16 v[222:225], v[160:163], v[208:211], v[108:111]
	v_mfma_f32_16x16x32_bf16 v[104:107], v[164:167], v[204:207], v[104:107]
	v_mfma_f32_16x16x32_bf16 v[100:103], v[156:159], v[214:217], v[100:103]
	v_mfma_f32_16x16x32_bf16 v[96:99], v[164:167], v[214:217], v[96:99]
	v_mfma_f32_16x16x32_bf16 v[226:229], v[168:171], v[208:211], v[104:107]
	v_mfma_f32_16x16x32_bf16 v[230:233], v[160:163], v[218:221], v[100:103]
	v_mfma_f32_16x16x32_bf16 v[234:237], v[168:171], v[218:221], v[96:99]
	s_setprio 0
	s_setprio 1
	v_mfma_f32_16x16x32_bf16 v[92:95], v[172:175], v[188:191], v[92:95]
	v_mfma_f32_16x16x32_bf16 v[88:91], v[180:183], v[188:191], v[88:91]
	v_mfma_f32_16x16x32_bf16 v[84:87], v[172:175], v[196:199], v[84:87]
	v_mfma_f32_16x16x32_bf16 v[80:83], v[180:183], v[196:199], v[80:83]
	v_mfma_f32_16x16x32_bf16 v[92:95], v[176:179], v[192:195], v[92:95]
	v_mfma_f32_16x16x32_bf16 v[88:91], v[184:187], v[192:195], v[88:91]
	v_mfma_f32_16x16x32_bf16 v[84:87], v[176:179], v[200:203], v[84:87]
	v_mfma_f32_16x16x32_bf16 v[80:83], v[184:187], v[200:203], v[80:83]
	v_mfma_f32_16x16x32_bf16 v[76:79], v[172:175], v[204:207], v[76:79]
	v_mfma_f32_16x16x32_bf16 v[72:75], v[180:183], v[204:207], v[72:75]
	v_mfma_f32_16x16x32_bf16 v[68:71], v[172:175], v[214:217], v[68:71]
	v_mfma_f32_16x16x32_bf16 v[64:67], v[180:183], v[214:217], v[64:67]
	v_mfma_f32_16x16x32_bf16 v[188:191], v[176:179], v[208:211], v[76:79]
	v_mfma_f32_16x16x32_bf16 v[192:195], v[184:187], v[208:211], v[72:75]
	v_mfma_f32_16x16x32_bf16 v[196:199], v[176:179], v[218:221], v[68:71]
	v_mfma_f32_16x16x32_bf16 v[200:203], v[184:187], v[218:221], v[64:67]
	s_setprio 0
	s_barrier
	s_nop 1
	ds_read_b128 v[64:67], v149 offset:16384
	ds_read_b128 v[68:71], v149 offset:17408
	ds_read_b128 v[72:75], v150 offset:16384
	ds_read_b128 v[76:79], v150 offset:17408
	ds_read_b128 v[96:99], v151 offset:16384
	ds_read_b128 v[100:103], v151 offset:17408
	ds_read_b128 v[104:107], v152 offset:16384
	ds_read_b128 v[108:111], v152 offset:17408
	s_waitcnt vmcnt(2)
	s_waitcnt lgkmcnt(0)
	s_barrier
	s_setprio 1
	v_mfma_f32_16x16x32_bf16 v[60:63], v[156:159], v[64:67], v[60:63]
	v_mfma_f32_16x16x32_bf16 v[56:59], v[164:167], v[64:67], v[56:59]
	v_mfma_f32_16x16x32_bf16 v[52:55], v[156:159], v[72:75], v[52:55]
	v_mfma_f32_16x16x32_bf16 v[48:51], v[164:167], v[72:75], v[48:51]
	v_mfma_f32_16x16x32_bf16 v[60:63], v[160:163], v[68:71], v[60:63]
	v_mfma_f32_16x16x32_bf16 v[56:59], v[168:171], v[68:71], v[56:59]
	v_mfma_f32_16x16x32_bf16 v[52:55], v[160:163], v[76:79], v[52:55]
	v_mfma_f32_16x16x32_bf16 v[48:51], v[168:171], v[76:79], v[48:51]
	v_mfma_f32_16x16x32_bf16 v[44:47], v[156:159], v[96:99], v[44:47]
	v_mfma_f32_16x16x32_bf16 v[40:43], v[164:167], v[96:99], v[40:43]
	v_mfma_f32_16x16x32_bf16 v[36:39], v[156:159], v[104:107], v[36:39]
	v_mfma_f32_16x16x32_bf16 v[32:35], v[164:167], v[104:107], v[32:35]
	v_mfma_f32_16x16x32_bf16 v[204:207], v[160:163], v[100:103], v[44:47]
	v_mfma_f32_16x16x32_bf16 v[208:211], v[168:171], v[100:103], v[40:43]
	v_mfma_f32_16x16x32_bf16 v[156:159], v[160:163], v[108:111], v[36:39]
	v_mfma_f32_16x16x32_bf16 v[160:163], v[168:171], v[108:111], v[32:35]
	s_setprio 0
	s_setprio 1
	v_mfma_f32_16x16x32_bf16 v[28:31], v[172:175], v[64:67], v[28:31]
	v_mfma_f32_16x16x32_bf16 v[24:27], v[180:183], v[64:67], v[24:27]
	v_mfma_f32_16x16x32_bf16 v[20:23], v[172:175], v[72:75], v[20:23]
	v_mfma_f32_16x16x32_bf16 v[16:19], v[180:183], v[72:75], v[16:19]
	v_mfma_f32_16x16x32_bf16 v[28:31], v[176:179], v[68:71], v[28:31]
	v_mfma_f32_16x16x32_bf16 v[24:27], v[184:187], v[68:71], v[24:27]
	v_mfma_f32_16x16x32_bf16 v[20:23], v[176:179], v[76:79], v[20:23]
	v_mfma_f32_16x16x32_bf16 v[16:19], v[184:187], v[76:79], v[16:19]
	v_mfma_f32_16x16x32_bf16 v[12:15], v[172:175], v[96:99], v[12:15]
	v_mfma_f32_16x16x32_bf16 v[8:11], v[180:183], v[96:99], v[8:11]
	v_mfma_f32_16x16x32_bf16 v[4:7], v[172:175], v[104:107], v[4:7]
	v_mfma_f32_16x16x32_bf16 v[0:3], v[180:183], v[104:107], v[0:3]
	v_mfma_f32_16x16x32_bf16 v[164:167], v[176:179], v[100:103], v[12:15]
	v_mfma_f32_16x16x32_bf16 v[168:171], v[184:187], v[100:103], v[8:11]
	v_mfma_f32_16x16x32_bf16 v[172:175], v[176:179], v[108:111], v[4:7]
	v_mfma_f32_16x16x32_bf16 v[176:179], v[184:187], v[108:111], v[0:3]
	s_setprio 0
	s_barrier
; #define LDA(dst, b, h) for (int m = 0; m < 4; ++m) for (int k = 0; k < 2; ++k) \
;     dst[m][k] = *reinterpret_cast<const bf16x8*>((char*)SA(b, h) + lds_byte(wr * 64 + m * 16 + fr, k * 32 + fq * 8))
; #define LDB(dst, b, h) for (int n = 0; n < 2; ++n) for (int k = 0; k < 2; ++k) \
;     dst[n][k] = *reinterpret_cast<const bf16x8*>((char*)SB(b, h) + lds_byte(wc * 32 + n * 16 + fr, k * 32 + fq * 8))
; #define MMA(ai, bj, At, Bt_) do { __builtin_amdgcn_s_setprio(1); \
;     for (int m = 0; m < 4; ++m) for (int n = 0; n < 2; ++n) for (int k = 0; k < 2; ++k) \
;       acc[ai][bj][m][n] = __builtin_amdgcn_mfma_f32_16x16x32_bf16(Bt_[n][k], At[m][k], acc[ai][bj][m][n], 0, 0, 0); \
;     __builtin_amdgcn_s_setprio(0); } while (0)
; #define WAIT_V(n) asm volatile("s_waitcnt vmcnt(" #n ")" ::: "memory")
; #define WAIT_L(n) asm volatile("s_waitcnt lgkmcnt(" #n ")" ::: "memory")
; #define BAR __builtin_amdgcn_s_barrier()
; #define SCHED __builtin_amdgcn_sched_barrier(0)
; template <int MODE>
; DI void gemm_phase(const bf16_t* __restrict__ A, const bf16_t* __restrict__ Bt, int M, int N, int K, const Epi& ep) {
;     ...
;             LDB(B0, 1, 0); LDB(B1, 1, 1); SCHED; LDA(At, 1, 0);
;             WAIT_V(0); WAIT_L(0); BAR; MMA(0, 0, At, B0); MMA(0, 1, At, B1); BAR; SCHED;
;             LDA(At, 1, 1);
;             WAIT_L(0); BAR; MMA(1, 0, At, B0); MMA(1, 1, At, B1); BAR; SCHED;
;         }
;         if (wr == 0) BAR;
	s_nop 1
	ds_read_b128 v[0:3], v153
	ds_read_b128 v[4:7], v153 offset:1024
	ds_read_b128 v[8:11], v153 offset:2048
	ds_read_b128 v[12:15], v153 offset:3072
	ds_read_b128 v[180:183], v154
	ds_read_b128 v[184:187], v154 offset:1024
	ds_read_b128 v[214:217], v154 offset:2048
	ds_read_b128 v[218:221], v154 offset:3072
	ds_read_b128 v[32:35], v149 offset:32768
	ds_read_b128 v[36:39], v149 offset:33792
	ds_read_b128 v[40:43], v150 offset:32768
	ds_read_b128 v[44:47], v150 offset:33792
	ds_read_b128 v[238:241], v151 offset:32768
	ds_read_b128 v[242:245], v151 offset:33792
	ds_read_b128 v[246:249], v152 offset:32768
	ds_read_b128 v[64:67], v152 offset:33792
	s_waitcnt vmcnt(0)
	s_waitcnt lgkmcnt(0)
	s_barrier
	s_setprio 1
	v_mfma_f32_16x16x32_bf16 v[68:71], v[0:3], v[32:35], v[124:127]
	v_mfma_f32_16x16x32_bf16 v[96:99], v[4:7], v[36:39], v[68:71]
	v_mfma_f32_16x16x32_bf16 v[68:71], v[8:11], v[32:35], v[120:123]
	v_mfma_f32_16x16x32_bf16 v[100:103], v[12:15], v[36:39], v[68:71]
	v_mfma_f32_16x16x32_bf16 v[68:71], v[0:3], v[40:43], v[116:119]
	v_mfma_f32_16x16x32_bf16 v[104:107], v[4:7], v[44:47], v[68:71]
	v_mfma_f32_16x16x32_bf16 v[68:71], v[8:11], v[40:43], v[112:115]
	v_mfma_f32_16x16x32_bf16 v[108:111], v[12:15], v[44:47], v[68:71]
	v_mfma_f32_16x16x32_bf16 v[68:71], v[0:3], v[238:241], v[222:225]
	v_mfma_f32_16x16x32_bf16 v[112:115], v[4:7], v[242:245], v[68:71]
	v_mfma_f32_16x16x32_bf16 v[68:71], v[8:11], v[238:241], v[226:229]
	v_mfma_f32_16x16x32_bf16 v[116:119], v[12:15], v[242:245], v[68:71]
	v_mfma_f32_16x16x32_bf16 v[68:71], v[0:3], v[246:249], v[230:233]
	v_mfma_f32_16x16x32_bf16 v[120:123], v[4:7], v[64:67], v[68:71]
	v_mfma_f32_16x16x32_bf16 v[68:71], v[8:11], v[246:249], v[234:237]
	v_mfma_f32_16x16x32_bf16 v[124:127], v[12:15], v[64:67], v[68:71]
	s_setprio 0
	s_setprio 1
	v_mfma_f32_16x16x32_bf16 v[68:71], v[180:183], v[32:35], v[92:95]
	v_mfma_f32_16x16x32_bf16 v[32:35], v[214:217], v[32:35], v[88:91]
	v_mfma_f32_16x16x32_bf16 v[222:225], v[184:187], v[36:39], v[68:71]
	v_mfma_f32_16x16x32_bf16 v[68:71], v[218:221], v[36:39], v[32:35]
	v_mfma_f32_16x16x32_bf16 v[32:35], v[180:183], v[40:43], v[84:87]
	v_mfma_f32_16x16x32_bf16 v[72:75], v[184:187], v[44:47], v[32:35]
	v_mfma_f32_16x16x32_bf16 v[32:35], v[214:217], v[40:43], v[80:83]
	v_mfma_f32_16x16x32_bf16 v[76:79], v[218:221], v[44:47], v[32:35]
	v_mfma_f32_16x16x32_bf16 v[32:35], v[180:183], v[238:241], v[188:191]
	v_mfma_f32_16x16x32_bf16 v[80:83], v[184:187], v[242:245], v[32:35]
	v_mfma_f32_16x16x32_bf16 v[32:35], v[214:217], v[238:241], v[192:195]
	v_mfma_f32_16x16x32_bf16 v[84:87], v[218:221], v[242:245], v[32:35]
	v_mfma_f32_16x16x32_bf16 v[32:35], v[180:183], v[246:249], v[196:199]
	v_mfma_f32_16x16x32_bf16 v[88:91], v[184:187], v[64:67], v[32:35]
	v_mfma_f32_16x16x32_bf16 v[32:35], v[214:217], v[246:249], v[200:203]
	v_mfma_f32_16x16x32_bf16 v[92:95], v[218:221], v[64:67], v[32:35]
	s_setprio 0
	s_barrier
	ds_read_b128 v[64:67], v149 offset:49152
	ds_read_b128 v[188:191], v149 offset:50176
	ds_read_b128 v[192:195], v150 offset:49152
	ds_read_b128 v[196:199], v150 offset:50176
	ds_read_b128 v[200:203], v151 offset:49152
	ds_read_b128 v[226:229], v151 offset:50176
	ds_read_b128 v[230:233], v152 offset:49152
	ds_read_b128 v[234:237], v152 offset:50176
	s_waitcnt lgkmcnt(0)
	s_barrier
	s_setprio 1
	v_mfma_f32_16x16x32_bf16 v[32:35], v[0:3], v[64:67], v[60:63]
	v_mfma_f32_16x16x32_bf16 v[40:43], v[0:3], v[192:195], v[52:55]
	v_mfma_f32_16x16x32_bf16 v[44:47], v[8:11], v[192:195], v[48:51]
	v_mfma_f32_16x16x32_bf16 v[48:51], v[0:3], v[200:203], v[204:207]
	v_mfma_f32_16x16x32_bf16 v[0:3], v[0:3], v[230:233], v[156:159]
	v_mfma_f32_16x16x32_bf16 v[36:39], v[8:11], v[64:67], v[56:59]
	v_mfma_f32_16x16x32_bf16 v[52:55], v[8:11], v[200:203], v[208:211]
	v_mfma_f32_16x16x32_bf16 v[56:59], v[4:7], v[234:237], v[0:3]
	v_mfma_f32_16x16x32_bf16 v[0:3], v[8:11], v[230:233], v[160:163]
	v_mfma_f32_16x16x32_bf16 v[32:35], v[4:7], v[188:191], v[32:35]
	v_mfma_f32_16x16x32_bf16 v[36:39], v[12:15], v[188:191], v[36:39]
	v_mfma_f32_16x16x32_bf16 v[40:43], v[4:7], v[196:199], v[40:43]
	v_mfma_f32_16x16x32_bf16 v[44:47], v[12:15], v[196:199], v[44:47]
	v_mfma_f32_16x16x32_bf16 v[48:51], v[4:7], v[226:229], v[48:51]
	v_mfma_f32_16x16x32_bf16 v[52:55], v[12:15], v[226:229], v[52:55]
	v_mfma_f32_16x16x32_bf16 v[60:63], v[12:15], v[234:237], v[0:3]
	s_setprio 0
	s_setprio 1
	v_mfma_f32_16x16x32_bf16 v[0:3], v[180:183], v[64:67], v[28:31]
	v_mfma_f32_16x16x32_bf16 v[4:7], v[214:217], v[64:67], v[24:27]
	v_mfma_f32_16x16x32_bf16 v[8:11], v[180:183], v[192:195], v[20:23]
	v_mfma_f32_16x16x32_bf16 v[12:15], v[214:217], v[192:195], v[16:19]
	v_mfma_f32_16x16x32_bf16 v[16:19], v[180:183], v[200:203], v[164:167]
	v_mfma_f32_16x16x32_bf16 v[20:23], v[214:217], v[200:203], v[168:171]
	v_mfma_f32_16x16x32_bf16 v[24:27], v[180:183], v[230:233], v[172:175]
	v_mfma_f32_16x16x32_bf16 v[28:31], v[214:217], v[230:233], v[176:179]
	v_mfma_f32_16x16x32_bf16 v[0:3], v[184:187], v[188:191], v[0:3]
	v_mfma_f32_16x16x32_bf16 v[4:7], v[218:221], v[188:191], v[4:7]
	v_mfma_f32_16x16x32_bf16 v[8:11], v[184:187], v[196:199], v[8:11]
	v_mfma_f32_16x16x32_bf16 v[12:15], v[218:221], v[196:199], v[12:15]
	v_mfma_f32_16x16x32_bf16 v[16:19], v[184:187], v[226:229], v[16:19]
	v_mfma_f32_16x16x32_bf16 v[20:23], v[218:221], v[226:229], v[20:23]
	v_mfma_f32_16x16x32_bf16 v[24:27], v[184:187], v[234:237], v[24:27]
	v_mfma_f32_16x16x32_bf16 v[28:31], v[218:221], v[234:237], v[28:31]
	s_setprio 0
	s_barrier
	s_and_saveexec_b64 s[6:7], s[38:39]
	s_cbranch_execz .LBB0_1015
	s_barrier
	s_branch .LBB0_1015

; #define LDA(dst, b, h) for (int m = 0; m < 4; ++m) for (int k = 0; k < 2; ++k) \
;     dst[m][k] = *reinterpret_cast<const bf16x8*>((char*)SA(b, h) + lds_byte(wr * 64 + m * 16 + fr, k * 32 + fq * 8))
; #define LDB(dst, b, h) for (int n = 0; n < 2; ++n) for (int k = 0; k < 2; ++k) \
;     dst[n][k] = *reinterpret_cast<const bf16x8*>((char*)SB(b, h) + lds_byte(wc * 32 + n * 16 + fr, k * 32 + fq * 8))
; #define MMA(ai, bj, At, Bt_) do { __builtin_amdgcn_s_setprio(1); \
;     for (int m = 0; m < 4; ++m) for (int n = 0; n < 2; ++n) for (int k = 0; k < 2; ++k) \
;       acc[ai][bj][m][n] = __builtin_amdgcn_mfma_f32_16x16x32_bf16(Bt_[n][k], At[m][k], acc[ai][bj][m][n], 0, 0, 0); \
;     __builtin_amdgcn_s_setprio(0); } while (0)
; #define WAIT_V(n) asm volatile("s_waitcnt vmcnt(" #n ")" ::: "memory")
; #define WAIT_L(n) asm volatile("s_waitcnt lgkmcnt(" #n ")" ::: "memory")
; #define BAR __builtin_amdgcn_s_barrier()
; #define SCHED __builtin_amdgcn_sched_barrier(0)
; template <int MODE>
; DI void gemm_phase(const bf16_t* __restrict__ A, const bf16_t* __restrict__ Bt, int M, int N, int K, const Epi& ep) {
;     ...
;         for (int t = 0; t < nt - 2; t += 2) {
;             LDB(B0, 0, 0); LDB(B1, 0, 1); SCHED; LDA(At, 0, 0); STAGE(SA(1, 1), rsA, brow + HALF, t + 1);
;             WAIT_V(8); WAIT_L(0); BAR; MMA(0, 0, At, B0); MMA(0, 1, At, B1); BAR; SCHED;
;             LDA(At, 0, 1); STAGE(SB(0, 0), rsB, bcol, t + 2); STAGE(SB(0, 1), rsB, bcol + HALF, t + 2); STAGE(SA(0, 0), rsA, brow, t + 2);
;             WAIT_V(8); WAIT_L(0); BAR; MMA(1, 0, At, B0); MMA(1, 1, At, B1); BAR; SCHED;
.LBB0_1150:
	ds_read_b128 v[128:131], v186
	ds_read_b128 v[132:135], v186 offset:1024
	ds_read_b128 v[136:139], v186 offset:2048
	ds_read_b128 v[140:143], v186 offset:3072
	ds_read_b128 v[144:147], v187
	ds_read_b128 v[148:151], v187 offset:1024
	ds_read_b128 v[152:155], v187 offset:2048
	ds_read_b128 v[156:159], v187 offset:3072
	s_add_i32 s41, s0, s40
	v_readfirstlane_b32 s43, v184
	s_add_i32 s42, s41, 0x40080
	s_mov_b32 m0, s43
	v_readfirstlane_b32 s43, v185
	ds_read_b128 v[160:163], v188
	ds_read_b128 v[164:167], v188 offset:1024
	ds_read_b128 v[196:199], v189
	ds_read_b128 v[200:203], v189 offset:1024
	ds_read_b128 v[204:207], v190
	ds_read_b128 v[208:211], v190 offset:1024
	ds_read_b128 v[214:217], v191
	ds_read_b128 v[218:221], v191 offset:1024
	buffer_load_dwordx4 v168, s[8:11], s42 offen lds
	s_mov_b32 m0, s43
	s_nop 0
	buffer_load_dwordx4 v169, s[8:11], s42 offen lds
	s_waitcnt vmcnt(8)
	s_waitcnt lgkmcnt(0)
	s_barrier
	s_setprio 1
	v_mfma_f32_16x16x32_bf16 v[124:127], v[128:131], v[160:163], v[124:127]
	v_mfma_f32_16x16x32_bf16 v[120:123], v[136:139], v[160:163], v[120:123]
	v_mfma_f32_16x16x32_bf16 v[116:119], v[128:131], v[196:199], v[116:119]
	v_mfma_f32_16x16x32_bf16 v[112:115], v[136:139], v[196:199], v[112:115]
	v_mfma_f32_16x16x32_bf16 v[108:111], v[128:131], v[204:207], v[108:111]
	v_mfma_f32_16x16x32_bf16 v[104:107], v[136:139], v[204:207], v[104:107]
	v_mfma_f32_16x16x32_bf16 v[100:103], v[128:131], v[214:217], v[100:103]
	v_mfma_f32_16x16x32_bf16 v[96:99], v[136:139], v[214:217], v[96:99]
	v_mfma_f32_16x16x32_bf16 v[124:127], v[132:135], v[164:167], v[124:127]
	v_mfma_f32_16x16x32_bf16 v[120:123], v[140:143], v[164:167], v[120:123]
	v_mfma_f32_16x16x32_bf16 v[116:119], v[132:135], v[200:203], v[116:119]
	v_mfma_f32_16x16x32_bf16 v[112:115], v[140:143], v[200:203], v[112:115]
	v_mfma_f32_16x16x32_bf16 v[108:111], v[132:135], v[208:211], v[108:111]
	v_mfma_f32_16x16x32_bf16 v[104:107], v[140:143], v[208:211], v[104:107]
	v_mfma_f32_16x16x32_bf16 v[100:103], v[132:135], v[218:221], v[100:103]
	v_mfma_f32_16x16x32_bf16 v[96:99], v[140:143], v[218:221], v[96:99]
	s_setprio 0
	s_setprio 1
	v_mfma_f32_16x16x32_bf16 v[92:95], v[144:147], v[160:163], v[92:95]
	v_mfma_f32_16x16x32_bf16 v[88:91], v[152:155], v[160:163], v[88:91]
	v_mfma_f32_16x16x32_bf16 v[84:87], v[144:147], v[196:199], v[84:87]
	v_mfma_f32_16x16x32_bf16 v[80:83], v[152:155], v[196:199], v[80:83]
	v_mfma_f32_16x16x32_bf16 v[76:79], v[144:147], v[204:207], v[76:79]
	v_mfma_f32_16x16x32_bf16 v[72:75], v[152:155], v[204:207], v[72:75]
	v_mfma_f32_16x16x32_bf16 v[68:71], v[144:147], v[214:217], v[68:71]
	v_mfma_f32_16x16x32_bf16 v[64:67], v[152:155], v[214:217], v[64:67]
	v_mfma_f32_16x16x32_bf16 v[92:95], v[148:151], v[164:167], v[92:95]
	v_mfma_f32_16x16x32_bf16 v[88:91], v[156:159], v[164:167], v[88:91]
	v_mfma_f32_16x16x32_bf16 v[84:87], v[148:151], v[200:203], v[84:87]
	v_mfma_f32_16x16x32_bf16 v[80:83], v[156:159], v[200:203], v[80:83]
	v_mfma_f32_16x16x32_bf16 v[76:79], v[148:151], v[208:211], v[76:79]
	v_mfma_f32_16x16x32_bf16 v[72:75], v[156:159], v[208:211], v[72:75]
	v_mfma_f32_16x16x32_bf16 v[68:71], v[148:151], v[218:221], v[68:71]
	v_mfma_f32_16x16x32_bf16 v[64:67], v[156:159], v[218:221], v[64:67]
	s_setprio 0
	s_barrier
	s_add_i32 s42, s1, s40
	v_readfirstlane_b32 s44, v170
	s_add_i32 s43, s42, 0x100
	s_mov_b32 s66, s10
	s_mov_b32 s67, s11
	s_mov_b32 m0, s44
	v_readfirstlane_b32 s44, v171
	ds_read_b128 v[160:163], v188 offset:16384
	ds_read_b128 v[164:167], v188 offset:17408
	ds_read_b128 v[196:199], v189 offset:16384
	ds_read_b128 v[200:203], v189 offset:17408
	ds_read_b128 v[204:207], v190 offset:16384
	ds_read_b128 v[208:211], v190 offset:17408
	ds_read_b128 v[214:217], v191 offset:16384
	ds_read_b128 v[218:221], v191 offset:17408
	buffer_load_dwordx4 v168, s[64:67], s43 offen lds
	s_mov_b32 m0, s44
	v_readfirstlane_b32 s44, v172
	buffer_load_dwordx4 v169, s[64:67], s43 offen lds
	s_add_i32 s43, s42, 0x40100
	s_mov_b32 m0, s44
	v_readfirstlane_b32 s44, v173
	buffer_load_dwordx4 v168, s[64:67], s43 offen lds
	s_mov_b32 m0, s44
	v_readfirstlane_b32 s44, v174
	buffer_load_dwordx4 v169, s[64:67], s43 offen lds
	s_add_i32 s43, s41, 0x100
	s_mov_b32 m0, s44
	v_readfirstlane_b32 s44, v175
	buffer_load_dwordx4 v168, s[8:11], s43 offen lds
	s_mov_b32 m0, s44
	s_nop 0
	buffer_load_dwordx4 v169, s[8:11], s43 offen lds
	s_waitcnt vmcnt(8)
	s_waitcnt lgkmcnt(0)
	s_barrier
	s_setprio 1
	v_mfma_f32_16x16x32_bf16 v[60:63], v[128:131], v[160:163], v[60:63]
	v_mfma_f32_16x16x32_bf16 v[56:59], v[136:139], v[160:163], v[56:59]
	v_mfma_f32_16x16x32_bf16 v[52:55], v[128:131], v[196:199], v[52:55]
	v_mfma_f32_16x16x32_bf16 v[48:51], v[136:139], v[196:199], v[48:51]
	v_mfma_f32_16x16x32_bf16 v[44:47], v[128:131], v[204:207], v[44:47]
	v_mfma_f32_16x16x32_bf16 v[40:43], v[136:139], v[204:207], v[40:43]
	v_mfma_f32_16x16x32_bf16 v[36:39], v[128:131], v[214:217], v[36:39]
	v_mfma_f32_16x16x32_bf16 v[32:35], v[136:139], v[214:217], v[32:35]
	v_mfma_f32_16x16x32_bf16 v[60:63], v[132:135], v[164:167], v[60:63]
	v_mfma_f32_16x16x32_bf16 v[56:59], v[140:143], v[164:167], v[56:59]
	v_mfma_f32_16x16x32_bf16 v[52:55], v[132:135], v[200:203], v[52:55]
	v_mfma_f32_16x16x32_bf16 v[48:51], v[140:143], v[200:203], v[48:51]
	v_mfma_f32_16x16x32_bf16 v[44:47], v[132:135], v[208:211], v[44:47]
	v_mfma_f32_16x16x32_bf16 v[40:43], v[140:143], v[208:211], v[40:43]
	v_mfma_f32_16x16x32_bf16 v[36:39], v[132:135], v[218:221], v[36:39]
	v_mfma_f32_16x16x32_bf16 v[32:35], v[140:143], v[218:221], v[32:35]
	s_setprio 0
	s_setprio 1
	v_mfma_f32_16x16x32_bf16 v[28:31], v[144:147], v[160:163], v[28:31]
	v_mfma_f32_16x16x32_bf16 v[24:27], v[152:155], v[160:163], v[24:27]
	v_mfma_f32_16x16x32_bf16 v[20:23], v[144:147], v[196:199], v[20:23]
	v_mfma_f32_16x16x32_bf16 v[16:19], v[152:155], v[196:199], v[16:19]
	v_mfma_f32_16x16x32_bf16 v[12:15], v[144:147], v[204:207], v[12:15]
	v_mfma_f32_16x16x32_bf16 v[8:11], v[152:155], v[204:207], v[8:11]
	v_mfma_f32_16x16x32_bf16 v[4:7], v[144:147], v[214:217], v[4:7]
	v_mfma_f32_16x16x32_bf16 v[0:3], v[152:155], v[214:217], v[0:3]
	v_mfma_f32_16x16x32_bf16 v[28:31], v[148:151], v[164:167], v[28:31]
	v_mfma_f32_16x16x32_bf16 v[24:27], v[156:159], v[164:167], v[24:27]
	v_mfma_f32_16x16x32_bf16 v[20:23], v[148:151], v[200:203], v[20:23]
	v_mfma_f32_16x16x32_bf16 v[16:19], v[156:159], v[200:203], v[16:19]
	v_mfma_f32_16x16x32_bf16 v[12:15], v[148:151], v[208:211], v[12:15]
	v_mfma_f32_16x16x32_bf16 v[8:11], v[156:159], v[208:211], v[8:11]
	v_mfma_f32_16x16x32_bf16 v[4:7], v[148:151], v[218:221], v[4:7]
	v_mfma_f32_16x16x32_bf16 v[0:3], v[156:159], v[218:221], v[0:3]
	s_setprio 0
	s_barrier
; #define LDA(dst, b, h) for (int m = 0; m < 4; ++m) for (int k = 0; k < 2; ++k) \
;     dst[m][k] = *reinterpret_cast<const bf16x8*>((char*)SA(b, h) + lds_byte(wr * 64 + m * 16 + fr, k * 32 + fq * 8))
; #define LDB(dst, b, h) for (int n = 0; n < 2; ++n) for (int k = 0; k < 2; ++k) \
;     dst[n][k] = *reinterpret_cast<const bf16x8*>((char*)SB(b, h) + lds_byte(wc * 32 + n * 16 + fr, k * 32 + fq * 8))
; #define MMA(ai, bj, At, Bt_) do { __builtin_amdgcn_s_setprio(1); \
;     for (int m = 0; m < 4; ++m) for (int n = 0; n < 2; ++n) for (int k = 0; k < 2; ++k) \
;       acc[ai][bj][m][n] = __builtin_amdgcn_mfma_f32_16x16x32_bf16(Bt_[n][k], At[m][k], acc[ai][bj][m][n], 0, 0, 0); \
;     __builtin_amdgcn_s_setprio(0); } while (0)
; #define WAIT_V(n) asm volatile("s_waitcnt vmcnt(" #n ")" ::: "memory")
; #define WAIT_L(n) asm volatile("s_waitcnt lgkmcnt(" #n ")" ::: "memory")
; #define BAR __builtin_amdgcn_s_barrier()
; #define SCHED __builtin_amdgcn_sched_barrier(0)
; template <int MODE>
; DI void gemm_phase(const bf16_t* __restrict__ A, const bf16_t* __restrict__ Bt, int M, int N, int K, const Epi& ep) {
;     ...
;             LDB(B0, 1, 0); LDB(B1, 1, 1); SCHED; LDA(At, 1, 0); STAGE(SA(0, 1), rsA, brow + HALF, t + 2);
;             WAIT_V(8); WAIT_L(0); BAR; MMA(0, 0, At, B0); MMA(0, 1, At, B1); BAR; SCHED;
;             LDA(At, 1, 1); STAGE(SB(1, 0), rsB, bcol, t + 3); STAGE(SB(1, 1), rsB, bcol + HALF, t + 3); STAGE(SA(1, 0), rsA, brow, t + 3);
;             WAIT_V(8); WAIT_L(0); BAR; MMA(1, 0, At, B0); MMA(1, 1, At, B1); BAR; SCHED;
	ds_read_b128 v[128:131], v192
	ds_read_b128 v[132:135], v192 offset:1024
	ds_read_b128 v[136:139], v192 offset:2048
	ds_read_b128 v[140:143], v192 offset:3072
	ds_read_b128 v[144:147], v193
	ds_read_b128 v[148:151], v193 offset:1024
	ds_read_b128 v[152:155], v193 offset:2048
	ds_read_b128 v[156:159], v193 offset:3072
	v_readfirstlane_b32 s44, v176
	s_add_i32 s43, s41, 0x40100
	s_mov_b32 m0, s44
	v_readfirstlane_b32 s44, v177
	ds_read_b128 v[160:163], v188 offset:32768
	ds_read_b128 v[164:167], v188 offset:33792
	ds_read_b128 v[196:199], v189 offset:32768
	ds_read_b128 v[200:203], v189 offset:33792
	ds_read_b128 v[204:207], v190 offset:32768
	ds_read_b128 v[208:211], v190 offset:33792
	ds_read_b128 v[214:217], v191 offset:32768
	ds_read_b128 v[218:221], v191 offset:33792
	buffer_load_dwordx4 v168, s[8:11], s43 offen lds
	s_mov_b32 m0, s44
	s_nop 0
	buffer_load_dwordx4 v169, s[8:11], s43 offen lds
	s_waitcnt vmcnt(8)
	s_waitcnt lgkmcnt(0)
	s_barrier
	s_setprio 1
	v_mfma_f32_16x16x32_bf16 v[124:127], v[128:131], v[160:163], v[124:127]
	v_mfma_f32_16x16x32_bf16 v[120:123], v[136:139], v[160:163], v[120:123]
	v_mfma_f32_16x16x32_bf16 v[116:119], v[128:131], v[196:199], v[116:119]
	v_mfma_f32_16x16x32_bf16 v[112:115], v[136:139], v[196:199], v[112:115]
	v_mfma_f32_16x16x32_bf16 v[108:111], v[128:131], v[204:207], v[108:111]
	v_mfma_f32_16x16x32_bf16 v[104:107], v[136:139], v[204:207], v[104:107]
	v_mfma_f32_16x16x32_bf16 v[100:103], v[128:131], v[214:217], v[100:103]
	v_mfma_f32_16x16x32_bf16 v[96:99], v[136:139], v[214:217], v[96:99]
	v_mfma_f32_16x16x32_bf16 v[124:127], v[132:135], v[164:167], v[124:127]
	v_mfma_f32_16x16x32_bf16 v[120:123], v[140:143], v[164:167], v[120:123]
	v_mfma_f32_16x16x32_bf16 v[116:119], v[132:135], v[200:203], v[116:119]
	v_mfma_f32_16x16x32_bf16 v[112:115], v[140:143], v[200:203], v[112:115]
	v_mfma_f32_16x16x32_bf16 v[108:111], v[132:135], v[208:211], v[108:111]
	v_mfma_f32_16x16x32_bf16 v[104:107], v[140:143], v[208:211], v[104:107]
	v_mfma_f32_16x16x32_bf16 v[100:103], v[132:135], v[218:221], v[100:103]
	v_mfma_f32_16x16x32_bf16 v[96:99], v[140:143], v[218:221], v[96:99]
	s_setprio 0
	s_setprio 1
	v_mfma_f32_16x16x32_bf16 v[92:95], v[144:147], v[160:163], v[92:95]
	v_mfma_f32_16x16x32_bf16 v[88:91], v[152:155], v[160:163], v[88:91]
	v_mfma_f32_16x16x32_bf16 v[84:87], v[144:147], v[196:199], v[84:87]
	v_mfma_f32_16x16x32_bf16 v[80:83], v[152:155], v[196:199], v[80:83]
	v_mfma_f32_16x16x32_bf16 v[76:79], v[144:147], v[204:207], v[76:79]
	v_mfma_f32_16x16x32_bf16 v[72:75], v[152:155], v[204:207], v[72:75]
	v_mfma_f32_16x16x32_bf16 v[68:71], v[144:147], v[214:217], v[68:71]
	v_mfma_f32_16x16x32_bf16 v[64:67], v[152:155], v[214:217], v[64:67]
	v_mfma_f32_16x16x32_bf16 v[92:95], v[148:151], v[164:167], v[92:95]
	v_mfma_f32_16x16x32_bf16 v[88:91], v[156:159], v[164:167], v[88:91]
	v_mfma_f32_16x16x32_bf16 v[84:87], v[148:151], v[200:203], v[84:87]
	v_mfma_f32_16x16x32_bf16 v[80:83], v[156:159], v[200:203], v[80:83]
	v_mfma_f32_16x16x32_bf16 v[76:79], v[148:151], v[208:211], v[76:79]
	v_mfma_f32_16x16x32_bf16 v[72:75], v[156:159], v[208:211], v[72:75]
	v_mfma_f32_16x16x32_bf16 v[68:71], v[148:151], v[218:221], v[68:71]
	v_mfma_f32_16x16x32_bf16 v[64:67], v[156:159], v[218:221], v[64:67]
	s_setprio 0
	s_barrier
	v_readfirstlane_b32 s44, v178
	s_add_i32 s43, s42, 0x180
	s_mov_b32 m0, s44
	v_readfirstlane_b32 s44, v179
	ds_read_b128 v[160:163], v188 offset:49152
	ds_read_b128 v[164:167], v188 offset:50176
	ds_read_b128 v[196:199], v189 offset:49152
	ds_read_b128 v[200:203], v189 offset:50176
	ds_read_b128 v[204:207], v190 offset:49152
	ds_read_b128 v[208:211], v190 offset:50176
	ds_read_b128 v[214:217], v191 offset:49152
	ds_read_b128 v[218:221], v191 offset:50176
	buffer_load_dwordx4 v168, s[64:67], s43 offen lds
	s_mov_b32 m0, s44
	s_add_i32 s42, s42, 0x40180
	buffer_load_dwordx4 v169, s[64:67], s43 offen lds
	v_readfirstlane_b32 s43, v182
	s_mov_b32 m0, s43
	v_readfirstlane_b32 s43, v183
	buffer_load_dwordx4 v168, s[64:67], s42 offen lds
	s_mov_b32 m0, s43
	s_addk_i32 s41, 0x180
	buffer_load_dwordx4 v169, s[64:67], s42 offen lds
	v_readfirstlane_b32 s42, v180
	s_mov_b32 m0, s42
	v_readfirstlane_b32 s42, v181
	buffer_load_dwordx4 v168, s[8:11], s41 offen lds
	s_mov_b32 m0, s42
	s_nop 0
	buffer_load_dwordx4 v169, s[8:11], s41 offen lds
	s_waitcnt vmcnt(8)
	s_waitcnt lgkmcnt(0)
	s_barrier
	s_setprio 1
	v_mfma_f32_16x16x32_bf16 v[60:63], v[128:131], v[160:163], v[60:63]
	v_mfma_f32_16x16x32_bf16 v[56:59], v[136:139], v[160:163], v[56:59]
	v_mfma_f32_16x16x32_bf16 v[52:55], v[128:131], v[196:199], v[52:55]
	v_mfma_f32_16x16x32_bf16 v[48:51], v[136:139], v[196:199], v[48:51]
	v_mfma_f32_16x16x32_bf16 v[44:47], v[128:131], v[204:207], v[44:47]
	v_mfma_f32_16x16x32_bf16 v[40:43], v[136:139], v[204:207], v[40:43]
	v_mfma_f32_16x16x32_bf16 v[36:39], v[128:131], v[214:217], v[36:39]
	v_mfma_f32_16x16x32_bf16 v[32:35], v[136:139], v[214:217], v[32:35]
	v_mfma_f32_16x16x32_bf16 v[60:63], v[132:135], v[164:167], v[60:63]
	v_mfma_f32_16x16x32_bf16 v[56:59], v[140:143], v[164:167], v[56:59]
	v_mfma_f32_16x16x32_bf16 v[52:55], v[132:135], v[200:203], v[52:55]
	v_mfma_f32_16x16x32_bf16 v[48:51], v[140:143], v[200:203], v[48:51]
	v_mfma_f32_16x16x32_bf16 v[44:47], v[132:135], v[208:211], v[44:47]
	v_mfma_f32_16x16x32_bf16 v[40:43], v[140:143], v[208:211], v[40:43]
	v_mfma_f32_16x16x32_bf16 v[36:39], v[132:135], v[218:221], v[36:39]
	v_mfma_f32_16x16x32_bf16 v[32:35], v[140:143], v[218:221], v[32:35]
	s_setprio 0
	s_setprio 1
	v_mfma_f32_16x16x32_bf16 v[28:31], v[144:147], v[160:163], v[28:31]
	v_mfma_f32_16x16x32_bf16 v[24:27], v[152:155], v[160:163], v[24:27]
	v_mfma_f32_16x16x32_bf16 v[20:23], v[144:147], v[196:199], v[20:23]
	v_mfma_f32_16x16x32_bf16 v[16:19], v[152:155], v[196:199], v[16:19]
	v_mfma_f32_16x16x32_bf16 v[12:15], v[144:147], v[204:207], v[12:15]
	v_mfma_f32_16x16x32_bf16 v[8:11], v[152:155], v[204:207], v[8:11]
	v_mfma_f32_16x16x32_bf16 v[4:7], v[144:147], v[214:217], v[4:7]
	v_mfma_f32_16x16x32_bf16 v[0:3], v[152:155], v[214:217], v[0:3]
	v_mfma_f32_16x16x32_bf16 v[28:31], v[148:151], v[164:167], v[28:31]
	v_mfma_f32_16x16x32_bf16 v[24:27], v[156:159], v[164:167], v[24:27]
	v_mfma_f32_16x16x32_bf16 v[20:23], v[148:151], v[200:203], v[20:23]
	v_mfma_f32_16x16x32_bf16 v[16:19], v[156:159], v[200:203], v[16:19]
	v_mfma_f32_16x16x32_bf16 v[12:15], v[148:151], v[208:211], v[12:15]
	v_mfma_f32_16x16x32_bf16 v[8:11], v[156:159], v[208:211], v[8:11]
	v_mfma_f32_16x16x32_bf16 v[4:7], v[148:151], v[218:221], v[4:7]
	v_mfma_f32_16x16x32_bf16 v[0:3], v[156:159], v[218:221], v[0:3]
	s_setprio 0
	s_barrier
; #define LDA(dst, b, h) for (int m = 0; m < 4; ++m) for (int k = 0; k < 2; ++k) \
;     dst[m][k] = *reinterpret_cast<const bf16x8*>((char*)SA(b, h) + lds_byte(wr * 64 + m * 16 + fr, k * 32 + fq * 8))
; #define LDB(dst, b, h) for (int n = 0; n < 2; ++n) for (int k = 0; k < 2; ++k) \
;     dst[n][k] = *reinterpret_cast<const bf16x8*>((char*)SB(b, h) + lds_byte(wc * 32 + n * 16 + fr, k * 32 + fq * 8))
; #define MMA(ai, bj, At, Bt_) do { __builtin_amdgcn_s_setprio(1); \
;     for (int m = 0; m < 4; ++m) for (int n = 0; n < 2; ++n) for (int k = 0; k < 2; ++k) \
;       acc[ai][bj][m][n] = __builtin_amdgcn_mfma_f32_16x16x32_bf16(Bt_[n][k], At[m][k], acc[ai][bj][m][n], 0, 0, 0); \
;     __builtin_amdgcn_s_setprio(0); } while (0)
; #define WAIT_V(n) asm volatile("s_waitcnt vmcnt(" #n ")" ::: "memory")
; #define WAIT_L(n) asm volatile("s_waitcnt lgkmcnt(" #n ")" ::: "memory")
; #define BAR __builtin_amdgcn_s_barrier()
; #define SCHED __builtin_amdgcn_sched_barrier(0)
; template <int MODE>
; DI void gemm_phase(const bf16_t* __restrict__ A, const bf16_t* __restrict__ Bt, int M, int N, int K, const Epi& ep) {
;     ...
;             WAIT_V(8); WAIT_L(0); BAR; MMA(0, 0, At, B0); MMA(0, 1, At, B1); BAR; SCHED;
;             LDA(At, 0, 1); STAGE(SB(0, 0), rsB, bcol, t + 2); STAGE(SB(0, 1), rsB, bcol + HALF, t + 2); STAGE(SA(0, 0), rsA, brow, t + 2);
;             WAIT_V(8); WAIT_L(0); BAR; MMA(1, 0, At, B0); MMA(1, 1, At, B1); BAR; SCHED;
;             LDB(B0, 1, 0); LDB(B1, 1, 1); SCHED; LDA(At, 1, 0); STAGE(SA(0, 1), rsA, brow + HALF, t + 2);
;             WAIT_V(8); WAIT_L(0); BAR; MMA(0, 0, At, B0); MMA(0, 1, At, B1); BAR; SCHED;
;             LDA(At, 1, 1); STAGE(SB(1, 0), rsB, bcol, t + 3); STAGE(SB(1, 1), rsB, bcol + HALF, t + 3); STAGE(SA(1, 0), rsA, brow, t + 3);
;             WAIT_V(8); WAIT_L(0); BAR; MMA(1, 0, At, B0); MMA(1, 1, At, B1); BAR; SCHED;
;         }
;         {
;             LDB(B0, 0, 0); LDB(B1, 0, 1); SCHED; LDA(At, 0, 0); STAGE(SA(1, 1), rsA, brow + HALF, nt - 1);
;             WAIT_V(8); WAIT_L(0); BAR; MMA(0, 0, At, B0); MMA(0, 1, At, B1); BAR; SCHED;
;             LDA(At, 0, 1);
;             WAIT_V(2); WAIT_L(0); BAR; MMA(1, 0, At, B0); MMA(1, 1, At, B1); BAR; SCHED;
	s_add_i32 s31, s31, 2
	s_addk_i32 s40, 0x100
	s_cmp_lt_u32 s31, 12
	s_cbranch_scc1 .LBB0_1150
	ds_read_b128 v[128:131], v186
	ds_read_b128 v[132:135], v186 offset:1024
	ds_read_b128 v[136:139], v186 offset:2048
	ds_read_b128 v[140:143], v186 offset:3072
	ds_read_b128 v[144:147], v187
	ds_read_b128 v[148:151], v187 offset:1024
	ds_read_b128 v[152:155], v187 offset:2048
	ds_read_b128 v[156:159], v187 offset:3072
	v_readfirstlane_b32 s1, v184
	s_or_b32 s0, s30, 0x40780
	s_mov_b32 m0, s1
	v_readfirstlane_b32 s1, v185
	ds_read_b128 v[160:163], v188
	ds_read_b128 v[164:167], v188 offset:1024
	ds_read_b128 v[196:199], v189
	ds_read_b128 v[200:203], v189 offset:1024
	ds_read_b128 v[204:207], v190
	ds_read_b128 v[208:211], v190 offset:1024
	ds_read_b128 v[214:217], v191
	ds_read_b128 v[218:221], v191 offset:1024
	buffer_load_dwordx4 v168, s[8:11], s0 offen lds
	s_mov_b32 m0, s1
	s_nop 0
	buffer_load_dwordx4 v169, s[8:11], s0 offen lds
	s_waitcnt vmcnt(8)
	s_waitcnt lgkmcnt(0)
	s_barrier
	s_setprio 1
	v_mfma_f32_16x16x32_bf16 v[124:127], v[128:131], v[160:163], v[124:127]
	v_mfma_f32_16x16x32_bf16 v[120:123], v[136:139], v[160:163], v[120:123]
	v_mfma_f32_16x16x32_bf16 v[116:119], v[128:131], v[196:199], v[116:119]
	v_mfma_f32_16x16x32_bf16 v[112:115], v[136:139], v[196:199], v[112:115]
	v_mfma_f32_16x16x32_bf16 v[108:111], v[128:131], v[204:207], v[108:111]
	v_mfma_f32_16x16x32_bf16 v[124:127], v[132:135], v[164:167], v[124:127]
	v_mfma_f32_16x16x32_bf16 v[120:123], v[140:143], v[164:167], v[120:123]
	v_mfma_f32_16x16x32_bf16 v[116:119], v[132:135], v[200:203], v[116:119]
	v_mfma_f32_16x16x32_bf16 v[112:115], v[140:143], v[200:203], v[112:115]
	v_mfma_f32_16x16x32_bf16 v[222:225], v[132:135], v[208:211], v[108:111]
	v_mfma_f32_16x16x32_bf16 v[104:107], v[136:139], v[204:207], v[104:107]
	v_mfma_f32_16x16x32_bf16 v[100:103], v[128:131], v[214:217], v[100:103]
	v_mfma_f32_16x16x32_bf16 v[96:99], v[136:139], v[214:217], v[96:99]
	v_mfma_f32_16x16x32_bf16 v[226:229], v[140:143], v[208:211], v[104:107]
	v_mfma_f32_16x16x32_bf16 v[230:233], v[132:135], v[218:221], v[100:103]
	v_mfma_f32_16x16x32_bf16 v[234:237], v[140:143], v[218:221], v[96:99]
	s_setprio 0
	s_setprio 1
	v_mfma_f32_16x16x32_bf16 v[92:95], v[144:147], v[160:163], v[92:95]
	v_mfma_f32_16x16x32_bf16 v[88:91], v[152:155], v[160:163], v[88:91]
	v_mfma_f32_16x16x32_bf16 v[84:87], v[144:147], v[196:199], v[84:87]
	v_mfma_f32_16x16x32_bf16 v[80:83], v[152:155], v[196:199], v[80:83]
	v_mfma_f32_16x16x32_bf16 v[92:95], v[148:151], v[164:167], v[92:95]
	v_mfma_f32_16x16x32_bf16 v[88:91], v[156:159], v[164:167], v[88:91]
	v_mfma_f32_16x16x32_bf16 v[84:87], v[148:151], v[200:203], v[84:87]
	v_mfma_f32_16x16x32_bf16 v[80:83], v[156:159], v[200:203], v[80:83]
	v_mfma_f32_16x16x32_bf16 v[76:79], v[144:147], v[204:207], v[76:79]
	v_mfma_f32_16x16x32_bf16 v[72:75], v[152:155], v[204:207], v[72:75]
	v_mfma_f32_16x16x32_bf16 v[68:71], v[144:147], v[214:217], v[68:71]
	v_mfma_f32_16x16x32_bf16 v[64:67], v[152:155], v[214:217], v[64:67]
	v_mfma_f32_16x16x32_bf16 v[160:163], v[148:151], v[208:211], v[76:79]
	v_mfma_f32_16x16x32_bf16 v[164:167], v[156:159], v[208:211], v[72:75]
	v_mfma_f32_16x16x32_bf16 v[196:199], v[148:151], v[218:221], v[68:71]
	v_mfma_f32_16x16x32_bf16 v[200:203], v[156:159], v[218:221], v[64:67]
	s_setprio 0
	s_barrier
	s_nop 1
	ds_read_b128 v[64:67], v188 offset:16384
	ds_read_b128 v[68:71], v188 offset:17408
	ds_read_b128 v[72:75], v189 offset:16384
	ds_read_b128 v[76:79], v189 offset:17408
	ds_read_b128 v[96:99], v190 offset:16384
	ds_read_b128 v[100:103], v190 offset:17408
	ds_read_b128 v[104:107], v191 offset:16384
	ds_read_b128 v[108:111], v191 offset:17408
	s_waitcnt vmcnt(2)
	s_waitcnt lgkmcnt(0)
	s_barrier
	s_setprio 1
	v_mfma_f32_16x16x32_bf16 v[60:63], v[128:131], v[64:67], v[60:63]
	v_mfma_f32_16x16x32_bf16 v[56:59], v[136:139], v[64:67], v[56:59]
	v_mfma_f32_16x16x32_bf16 v[52:55], v[128:131], v[72:75], v[52:55]
	v_mfma_f32_16x16x32_bf16 v[48:51], v[136:139], v[72:75], v[48:51]
	v_mfma_f32_16x16x32_bf16 v[60:63], v[132:135], v[68:71], v[60:63]
	v_mfma_f32_16x16x32_bf16 v[56:59], v[140:143], v[68:71], v[56:59]
	v_mfma_f32_16x16x32_bf16 v[52:55], v[132:135], v[76:79], v[52:55]
	v_mfma_f32_16x16x32_bf16 v[48:51], v[140:143], v[76:79], v[48:51]
	v_mfma_f32_16x16x32_bf16 v[44:47], v[128:131], v[96:99], v[44:47]
	v_mfma_f32_16x16x32_bf16 v[40:43], v[136:139], v[96:99], v[40:43]
	v_mfma_f32_16x16x32_bf16 v[36:39], v[128:131], v[104:107], v[36:39]
	v_mfma_f32_16x16x32_bf16 v[32:35], v[136:139], v[104:107], v[32:35]
	v_mfma_f32_16x16x32_bf16 v[204:207], v[132:135], v[100:103], v[44:47]
	v_mfma_f32_16x16x32_bf16 v[208:211], v[140:143], v[100:103], v[40:43]
	v_mfma_f32_16x16x32_bf16 v[128:131], v[132:135], v[108:111], v[36:39]
	v_mfma_f32_16x16x32_bf16 v[132:135], v[140:143], v[108:111], v[32:35]
	s_setprio 0
	s_setprio 1
	v_mfma_f32_16x16x32_bf16 v[28:31], v[144:147], v[64:67], v[28:31]
	v_mfma_f32_16x16x32_bf16 v[24:27], v[152:155], v[64:67], v[24:27]
	v_mfma_f32_16x16x32_bf16 v[20:23], v[144:147], v[72:75], v[20:23]
	v_mfma_f32_16x16x32_bf16 v[16:19], v[152:155], v[72:75], v[16:19]
	v_mfma_f32_16x16x32_bf16 v[28:31], v[148:151], v[68:71], v[28:31]
	v_mfma_f32_16x16x32_bf16 v[24:27], v[156:159], v[68:71], v[24:27]
	v_mfma_f32_16x16x32_bf16 v[20:23], v[148:151], v[76:79], v[20:23]
	v_mfma_f32_16x16x32_bf16 v[16:19], v[156:159], v[76:79], v[16:19]
	v_mfma_f32_16x16x32_bf16 v[12:15], v[144:147], v[96:99], v[12:15]
	v_mfma_f32_16x16x32_bf16 v[8:11], v[152:155], v[96:99], v[8:11]
	v_mfma_f32_16x16x32_bf16 v[4:7], v[144:147], v[104:107], v[4:7]
	v_mfma_f32_16x16x32_bf16 v[0:3], v[152:155], v[104:107], v[0:3]
	v_mfma_f32_16x16x32_bf16 v[136:139], v[148:151], v[100:103], v[12:15]
	v_mfma_f32_16x16x32_bf16 v[140:143], v[156:159], v[100:103], v[8:11]
	v_mfma_f32_16x16x32_bf16 v[144:147], v[148:151], v[108:111], v[4:7]
	v_mfma_f32_16x16x32_bf16 v[148:151], v[156:159], v[108:111], v[0:3]
	s_setprio 0
	s_barrier
; #define LDA(dst, b, h) for (int m = 0; m < 4; ++m) for (int k = 0; k < 2; ++k) \
;     dst[m][k] = *reinterpret_cast<const bf16x8*>((char*)SA(b, h) + lds_byte(wr * 64 + m * 16 + fr, k * 32 + fq * 8))
; #define LDB(dst, b, h) for (int n = 0; n < 2; ++n) for (int k = 0; k < 2; ++k) \
;     dst[n][k] = *reinterpret_cast<const bf16x8*>((char*)SB(b, h) + lds_byte(wc * 32 + n * 16 + fr, k * 32 + fq * 8))
; #define MMA(ai, bj, At, Bt_) do { __builtin_amdgcn_s_setprio(1); \
;     for (int m = 0; m < 4; ++m) for (int n = 0; n < 2; ++n) for (int k = 0; k < 2; ++k) \
;       acc[ai][bj][m][n] = __builtin_amdgcn_mfma_f32_16x16x32_bf16(Bt_[n][k], At[m][k], acc[ai][bj][m][n], 0, 0, 0); \
;     __builtin_amdgcn_s_setprio(0); } while (0)
; #define WAIT_V(n) asm volatile("s_waitcnt vmcnt(" #n ")" ::: "memory")
; #define WAIT_L(n) asm volatile("s_waitcnt lgkmcnt(" #n ")" ::: "memory")
; #define BAR __builtin_amdgcn_s_barrier()
; #define SCHED __builtin_amdgcn_sched_barrier(0)
; template <int MODE>
; DI void gemm_phase(const bf16_t* __restrict__ A, const bf16_t* __restrict__ Bt, int M, int N, int K, const Epi& ep) {
;     ...
;             LDB(B0, 1, 0); LDB(B1, 1, 1); SCHED; LDA(At, 1, 0);
;             WAIT_V(0); WAIT_L(0); BAR; MMA(0, 0, At, B0); MMA(0, 1, At, B1); BAR; SCHED;
;             LDA(At, 1, 1);
;             WAIT_L(0); BAR; MMA(1, 0, At, B0); MMA(1, 1, At, B1); BAR; SCHED;
;         }
;         if (wr == 0) BAR;
	s_nop 1
	ds_read_b128 v[0:3], v192
	ds_read_b128 v[4:7], v192 offset:1024
	ds_read_b128 v[8:11], v192 offset:2048
	ds_read_b128 v[12:15], v192 offset:3072
	ds_read_b128 v[152:155], v193
	ds_read_b128 v[156:159], v193 offset:1024
	ds_read_b128 v[214:217], v193 offset:2048
	ds_read_b128 v[218:221], v193 offset:3072
	ds_read_b128 v[32:35], v188 offset:32768
	ds_read_b128 v[36:39], v188 offset:33792
	ds_read_b128 v[40:43], v189 offset:32768
	ds_read_b128 v[44:47], v189 offset:33792
	ds_read_b128 v[238:241], v190 offset:32768
	ds_read_b128 v[242:245], v190 offset:33792
	ds_read_b128 v[246:249], v191 offset:32768
	ds_read_b128 v[64:67], v191 offset:33792
	s_waitcnt vmcnt(0)
	s_waitcnt lgkmcnt(0)
	s_barrier
	s_setprio 1
	v_mfma_f32_16x16x32_bf16 v[68:71], v[0:3], v[32:35], v[124:127]
	v_mfma_f32_16x16x32_bf16 v[96:99], v[4:7], v[36:39], v[68:71]
	v_mfma_f32_16x16x32_bf16 v[68:71], v[8:11], v[32:35], v[120:123]
	v_mfma_f32_16x16x32_bf16 v[100:103], v[12:15], v[36:39], v[68:71]
	v_mfma_f32_16x16x32_bf16 v[68:71], v[0:3], v[40:43], v[116:119]
	v_mfma_f32_16x16x32_bf16 v[104:107], v[4:7], v[44:47], v[68:71]
	v_mfma_f32_16x16x32_bf16 v[68:71], v[8:11], v[40:43], v[112:115]
	v_mfma_f32_16x16x32_bf16 v[108:111], v[12:15], v[44:47], v[68:71]
	v_mfma_f32_16x16x32_bf16 v[68:71], v[0:3], v[238:241], v[222:225]
	v_mfma_f32_16x16x32_bf16 v[112:115], v[4:7], v[242:245], v[68:71]
	v_mfma_f32_16x16x32_bf16 v[68:71], v[8:11], v[238:241], v[226:229]
	v_mfma_f32_16x16x32_bf16 v[116:119], v[12:15], v[242:245], v[68:71]
	v_mfma_f32_16x16x32_bf16 v[68:71], v[0:3], v[246:249], v[230:233]
	v_mfma_f32_16x16x32_bf16 v[120:123], v[4:7], v[64:67], v[68:71]
	v_mfma_f32_16x16x32_bf16 v[68:71], v[8:11], v[246:249], v[234:237]
	v_mfma_f32_16x16x32_bf16 v[124:127], v[12:15], v[64:67], v[68:71]
	s_setprio 0
	s_setprio 1
	v_mfma_f32_16x16x32_bf16 v[68:71], v[152:155], v[32:35], v[92:95]
	v_mfma_f32_16x16x32_bf16 v[32:35], v[214:217], v[32:35], v[88:91]
	v_mfma_f32_16x16x32_bf16 v[222:225], v[156:159], v[36:39], v[68:71]
	v_mfma_f32_16x16x32_bf16 v[68:71], v[218:221], v[36:39], v[32:35]
	v_mfma_f32_16x16x32_bf16 v[32:35], v[152:155], v[40:43], v[84:87]
	v_mfma_f32_16x16x32_bf16 v[72:75], v[156:159], v[44:47], v[32:35]
	v_mfma_f32_16x16x32_bf16 v[32:35], v[214:217], v[40:43], v[80:83]
	v_mfma_f32_16x16x32_bf16 v[76:79], v[218:221], v[44:47], v[32:35]
	v_mfma_f32_16x16x32_bf16 v[32:35], v[152:155], v[238:241], v[160:163]
	v_mfma_f32_16x16x32_bf16 v[80:83], v[156:159], v[242:245], v[32:35]
	v_mfma_f32_16x16x32_bf16 v[32:35], v[214:217], v[238:241], v[164:167]
	v_mfma_f32_16x16x32_bf16 v[84:87], v[218:221], v[242:245], v[32:35]
	v_mfma_f32_16x16x32_bf16 v[32:35], v[152:155], v[246:249], v[196:199]
	v_mfma_f32_16x16x32_bf16 v[88:91], v[156:159], v[64:67], v[32:35]
	v_mfma_f32_16x16x32_bf16 v[32:35], v[214:217], v[246:249], v[200:203]
	v_mfma_f32_16x16x32_bf16 v[92:95], v[218:221], v[64:67], v[32:35]
	s_setprio 0
	s_barrier
	ds_read_b128 v[64:67], v188 offset:49152
	ds_read_b128 v[160:163], v188 offset:50176
	ds_read_b128 v[164:167], v189 offset:49152
	ds_read_b128 v[196:199], v189 offset:50176
	ds_read_b128 v[200:203], v190 offset:49152
	ds_read_b128 v[226:229], v190 offset:50176
	ds_read_b128 v[230:233], v191 offset:49152
	ds_read_b128 v[234:237], v191 offset:50176
	s_waitcnt lgkmcnt(0)
	s_barrier
	s_setprio 1
	v_mfma_f32_16x16x32_bf16 v[32:35], v[0:3], v[64:67], v[60:63]
	v_mfma_f32_16x16x32_bf16 v[40:43], v[0:3], v[164:167], v[52:55]
	v_mfma_f32_16x16x32_bf16 v[44:47], v[8:11], v[164:167], v[48:51]
	v_mfma_f32_16x16x32_bf16 v[48:51], v[0:3], v[200:203], v[204:207]
	v_mfma_f32_16x16x32_bf16 v[0:3], v[0:3], v[230:233], v[128:131]
	v_mfma_f32_16x16x32_bf16 v[36:39], v[8:11], v[64:67], v[56:59]
	v_mfma_f32_16x16x32_bf16 v[52:55], v[8:11], v[200:203], v[208:211]
	v_mfma_f32_16x16x32_bf16 v[56:59], v[4:7], v[234:237], v[0:3]
	v_mfma_f32_16x16x32_bf16 v[0:3], v[8:11], v[230:233], v[132:135]
	v_mfma_f32_16x16x32_bf16 v[32:35], v[4:7], v[160:163], v[32:35]
	v_mfma_f32_16x16x32_bf16 v[36:39], v[12:15], v[160:163], v[36:39]
	v_mfma_f32_16x16x32_bf16 v[40:43], v[4:7], v[196:199], v[40:43]
	v_mfma_f32_16x16x32_bf16 v[44:47], v[12:15], v[196:199], v[44:47]
	v_mfma_f32_16x16x32_bf16 v[48:51], v[4:7], v[226:229], v[48:51]
	v_mfma_f32_16x16x32_bf16 v[52:55], v[12:15], v[226:229], v[52:55]
	v_mfma_f32_16x16x32_bf16 v[60:63], v[12:15], v[234:237], v[0:3]
	s_setprio 0
	s_setprio 1
	v_mfma_f32_16x16x32_bf16 v[0:3], v[152:155], v[64:67], v[28:31]
	v_mfma_f32_16x16x32_bf16 v[4:7], v[214:217], v[64:67], v[24:27]
	v_mfma_f32_16x16x32_bf16 v[8:11], v[152:155], v[164:167], v[20:23]
	v_mfma_f32_16x16x32_bf16 v[12:15], v[214:217], v[164:167], v[16:19]
	v_mfma_f32_16x16x32_bf16 v[16:19], v[152:155], v[200:203], v[136:139]
	v_mfma_f32_16x16x32_bf16 v[20:23], v[214:217], v[200:203], v[140:143]
	v_mfma_f32_16x16x32_bf16 v[24:27], v[152:155], v[230:233], v[144:147]
	v_mfma_f32_16x16x32_bf16 v[28:31], v[214:217], v[230:233], v[148:151]
	v_mfma_f32_16x16x32_bf16 v[0:3], v[156:159], v[160:163], v[0:3]
	v_mfma_f32_16x16x32_bf16 v[4:7], v[218:221], v[160:163], v[4:7]
	v_mfma_f32_16x16x32_bf16 v[8:11], v[156:159], v[196:199], v[8:11]
	v_mfma_f32_16x16x32_bf16 v[12:15], v[218:221], v[196:199], v[12:15]
	v_mfma_f32_16x16x32_bf16 v[16:19], v[156:159], v[226:229], v[16:19]
	v_mfma_f32_16x16x32_bf16 v[20:23], v[218:221], v[226:229], v[20:23]
	v_mfma_f32_16x16x32_bf16 v[24:27], v[156:159], v[234:237], v[24:27]
	v_mfma_f32_16x16x32_bf16 v[28:31], v[218:221], v[234:237], v[28:31]
	s_setprio 0
	s_barrier
	s_and_saveexec_b64 s[0:1], s[38:39]
	s_cbranch_execz .LBB0_1153
	s_barrier

; #define LDA(dst, b, h) for (int m = 0; m < 4; ++m) for (int k = 0; k < 2; ++k) \
;     dst[m][k] = *reinterpret_cast<const bf16x8*>((char*)SA(b, h) + lds_byte(wr * 64 + m * 16 + fr, k * 32 + fq * 8))
; #define LDB(dst, b, h) for (int n = 0; n < 2; ++n) for (int k = 0; k < 2; ++k) \
;     dst[n][k] = *reinterpret_cast<const bf16x8*>((char*)SB(b, h) + lds_byte(wc * 32 + n * 16 + fr, k * 32 + fq * 8))
; #define MMA(ai, bj, At, Bt_) do { __builtin_amdgcn_s_setprio(1); \
;     for (int m = 0; m < 4; ++m) for (int n = 0; n < 2; ++n) for (int k = 0; k < 2; ++k) \
;       acc[ai][bj][m][n] = __builtin_amdgcn_mfma_f32_16x16x32_bf16(Bt_[n][k], At[m][k], acc[ai][bj][m][n], 0, 0, 0); \
;     __builtin_amdgcn_s_setprio(0); } while (0)
; #define WAIT_V(n) asm volatile("s_waitcnt vmcnt(" #n ")" ::: "memory")
; #define WAIT_L(n) asm volatile("s_waitcnt lgkmcnt(" #n ")" ::: "memory")
; #define BAR __builtin_amdgcn_s_barrier()
; #define SCHED __builtin_amdgcn_sched_barrier(0)
; template <int MODE>
; DI void gemm_phase(const bf16_t* __restrict__ A, const bf16_t* __restrict__ Bt, int M, int N, int K, const Epi& ep) {
;     ...
;         for (int t = 0; t < nt - 2; t += 2) {
;             LDB(B0, 0, 0); LDB(B1, 0, 1); SCHED; LDA(At, 0, 0); STAGE(SA(1, 1), rsA, brow + HALF, t + 1);
;             WAIT_V(8); WAIT_L(0); BAR; MMA(0, 0, At, B0); MMA(0, 1, At, B1); BAR; SCHED;
;             LDA(At, 0, 1); STAGE(SB(0, 0), rsB, bcol, t + 2); STAGE(SB(0, 1), rsB, bcol + HALF, t + 2); STAGE(SA(0, 0), rsA, brow, t + 2);
;             WAIT_V(8); WAIT_L(0); BAR; MMA(1, 0, At, B0); MMA(1, 1, At, B1); BAR; SCHED;
.LBB0_1452:
	ds_read_b128 v[156:159], v147
	ds_read_b128 v[160:163], v147 offset:1024
	ds_read_b128 v[164:167], v147 offset:2048
	ds_read_b128 v[168:171], v147 offset:3072
	ds_read_b128 v[172:175], v148
	ds_read_b128 v[176:179], v148 offset:1024
	ds_read_b128 v[180:183], v148 offset:2048
	ds_read_b128 v[184:187], v148 offset:3072
	s_add_i32 s40, s6, s27
	v_readfirstlane_b32 s42, v144
	s_add_i32 s41, s40, 0xb0080
	s_mov_b32 s30, s10
	s_mov_b32 s31, s11
	s_mov_b32 m0, s42
	v_readfirstlane_b32 s42, v145
	ds_read_b128 v[188:191], v149
	ds_read_b128 v[192:195], v149 offset:1024
	ds_read_b128 v[196:199], v150
	ds_read_b128 v[200:203], v150 offset:1024
	ds_read_b128 v[204:207], v151
	ds_read_b128 v[208:211], v151 offset:1024
	ds_read_b128 v[214:217], v152
	ds_read_b128 v[218:221], v152 offset:1024
	buffer_load_dwordx4 v128, s[28:31], s41 offen lds
	s_mov_b32 m0, s42
	s_nop 0
	buffer_load_dwordx4 v129, s[28:31], s41 offen lds
	s_waitcnt vmcnt(8)
	s_waitcnt lgkmcnt(0)
	s_barrier
	s_setprio 1
	v_mfma_f32_16x16x32_bf16 v[124:127], v[156:159], v[188:191], v[124:127]
	v_mfma_f32_16x16x32_bf16 v[120:123], v[164:167], v[188:191], v[120:123]
	v_mfma_f32_16x16x32_bf16 v[116:119], v[156:159], v[196:199], v[116:119]
	v_mfma_f32_16x16x32_bf16 v[112:115], v[164:167], v[196:199], v[112:115]
	v_mfma_f32_16x16x32_bf16 v[108:111], v[156:159], v[204:207], v[108:111]
	v_mfma_f32_16x16x32_bf16 v[104:107], v[164:167], v[204:207], v[104:107]
	v_mfma_f32_16x16x32_bf16 v[100:103], v[156:159], v[214:217], v[100:103]
	v_mfma_f32_16x16x32_bf16 v[96:99], v[164:167], v[214:217], v[96:99]
	v_mfma_f32_16x16x32_bf16 v[124:127], v[160:163], v[192:195], v[124:127]
	v_mfma_f32_16x16x32_bf16 v[120:123], v[168:171], v[192:195], v[120:123]
	v_mfma_f32_16x16x32_bf16 v[116:119], v[160:163], v[200:203], v[116:119]
	v_mfma_f32_16x16x32_bf16 v[112:115], v[168:171], v[200:203], v[112:115]
	v_mfma_f32_16x16x32_bf16 v[108:111], v[160:163], v[208:211], v[108:111]
	v_mfma_f32_16x16x32_bf16 v[104:107], v[168:171], v[208:211], v[104:107]
	v_mfma_f32_16x16x32_bf16 v[100:103], v[160:163], v[218:221], v[100:103]
	v_mfma_f32_16x16x32_bf16 v[96:99], v[168:171], v[218:221], v[96:99]
	s_setprio 0
	s_setprio 1
	v_mfma_f32_16x16x32_bf16 v[92:95], v[172:175], v[188:191], v[92:95]
	v_mfma_f32_16x16x32_bf16 v[88:91], v[180:183], v[188:191], v[88:91]
	v_mfma_f32_16x16x32_bf16 v[84:87], v[172:175], v[196:199], v[84:87]
	v_mfma_f32_16x16x32_bf16 v[80:83], v[180:183], v[196:199], v[80:83]
	v_mfma_f32_16x16x32_bf16 v[76:79], v[172:175], v[204:207], v[76:79]
	v_mfma_f32_16x16x32_bf16 v[72:75], v[180:183], v[204:207], v[72:75]
	v_mfma_f32_16x16x32_bf16 v[68:71], v[172:175], v[214:217], v[68:71]
	v_mfma_f32_16x16x32_bf16 v[64:67], v[180:183], v[214:217], v[64:67]
	v_mfma_f32_16x16x32_bf16 v[92:95], v[176:179], v[192:195], v[92:95]
	v_mfma_f32_16x16x32_bf16 v[88:91], v[184:187], v[192:195], v[88:91]
	v_mfma_f32_16x16x32_bf16 v[84:87], v[176:179], v[200:203], v[84:87]
	v_mfma_f32_16x16x32_bf16 v[80:83], v[184:187], v[200:203], v[80:83]
	v_mfma_f32_16x16x32_bf16 v[76:79], v[176:179], v[208:211], v[76:79]
	v_mfma_f32_16x16x32_bf16 v[72:75], v[184:187], v[208:211], v[72:75]
	v_mfma_f32_16x16x32_bf16 v[68:71], v[176:179], v[218:221], v[68:71]
	v_mfma_f32_16x16x32_bf16 v[64:67], v[184:187], v[218:221], v[64:67]
	s_setprio 0
	s_barrier
	s_add_i32 s41, s23, s27
	v_readfirstlane_b32 s43, v130
	s_add_i32 s42, s41, 0x100
	s_mov_b32 s70, s10
	s_mov_b32 s71, s11
	s_mov_b32 m0, s43
	v_readfirstlane_b32 s43, v131
	ds_read_b128 v[188:191], v149 offset:16384
	ds_read_b128 v[192:195], v149 offset:17408
	ds_read_b128 v[196:199], v150 offset:16384
	ds_read_b128 v[200:203], v150 offset:17408
	ds_read_b128 v[204:207], v151 offset:16384
	ds_read_b128 v[208:211], v151 offset:17408
	ds_read_b128 v[214:217], v152 offset:16384
	ds_read_b128 v[218:221], v152 offset:17408
	buffer_load_dwordx4 v128, s[68:71], s42 offen lds
	s_mov_b32 m0, s43
	v_readfirstlane_b32 s43, v132
	buffer_load_dwordx4 v129, s[68:71], s42 offen lds
	s_add_i32 s42, s41, 0xb0100
	s_mov_b32 m0, s43
	v_readfirstlane_b32 s43, v133
	buffer_load_dwordx4 v128, s[68:71], s42 offen lds
	s_mov_b32 m0, s43
	v_readfirstlane_b32 s43, v134
	buffer_load_dwordx4 v129, s[68:71], s42 offen lds
	s_add_i32 s42, s40, 0x100
	s_mov_b32 m0, s43
	v_readfirstlane_b32 s43, v135
	buffer_load_dwordx4 v128, s[28:31], s42 offen lds
	s_mov_b32 m0, s43
	s_nop 0
	buffer_load_dwordx4 v129, s[28:31], s42 offen lds
	s_waitcnt vmcnt(8)
	s_waitcnt lgkmcnt(0)
	s_barrier
	s_setprio 1
	v_mfma_f32_16x16x32_bf16 v[60:63], v[156:159], v[188:191], v[60:63]
	v_mfma_f32_16x16x32_bf16 v[56:59], v[164:167], v[188:191], v[56:59]
	v_mfma_f32_16x16x32_bf16 v[52:55], v[156:159], v[196:199], v[52:55]
	v_mfma_f32_16x16x32_bf16 v[48:51], v[164:167], v[196:199], v[48:51]
	v_mfma_f32_16x16x32_bf16 v[44:47], v[156:159], v[204:207], v[44:47]
	v_mfma_f32_16x16x32_bf16 v[40:43], v[164:167], v[204:207], v[40:43]
	v_mfma_f32_16x16x32_bf16 v[36:39], v[156:159], v[214:217], v[36:39]
	v_mfma_f32_16x16x32_bf16 v[32:35], v[164:167], v[214:217], v[32:35]
	v_mfma_f32_16x16x32_bf16 v[60:63], v[160:163], v[192:195], v[60:63]
	v_mfma_f32_16x16x32_bf16 v[56:59], v[168:171], v[192:195], v[56:59]
	v_mfma_f32_16x16x32_bf16 v[52:55], v[160:163], v[200:203], v[52:55]
	v_mfma_f32_16x16x32_bf16 v[48:51], v[168:171], v[200:203], v[48:51]
	v_mfma_f32_16x16x32_bf16 v[44:47], v[160:163], v[208:211], v[44:47]
	v_mfma_f32_16x16x32_bf16 v[40:43], v[168:171], v[208:211], v[40:43]
	v_mfma_f32_16x16x32_bf16 v[36:39], v[160:163], v[218:221], v[36:39]
	v_mfma_f32_16x16x32_bf16 v[32:35], v[168:171], v[218:221], v[32:35]
	s_setprio 0
	s_setprio 1
	v_mfma_f32_16x16x32_bf16 v[28:31], v[172:175], v[188:191], v[28:31]
	v_mfma_f32_16x16x32_bf16 v[24:27], v[180:183], v[188:191], v[24:27]
	v_mfma_f32_16x16x32_bf16 v[20:23], v[172:175], v[196:199], v[20:23]
	v_mfma_f32_16x16x32_bf16 v[16:19], v[180:183], v[196:199], v[16:19]
	v_mfma_f32_16x16x32_bf16 v[12:15], v[172:175], v[204:207], v[12:15]
	v_mfma_f32_16x16x32_bf16 v[8:11], v[180:183], v[204:207], v[8:11]
	v_mfma_f32_16x16x32_bf16 v[4:7], v[172:175], v[214:217], v[4:7]
	v_mfma_f32_16x16x32_bf16 v[0:3], v[180:183], v[214:217], v[0:3]
	v_mfma_f32_16x16x32_bf16 v[28:31], v[176:179], v[192:195], v[28:31]
	v_mfma_f32_16x16x32_bf16 v[24:27], v[184:187], v[192:195], v[24:27]
	v_mfma_f32_16x16x32_bf16 v[20:23], v[176:179], v[200:203], v[20:23]
	v_mfma_f32_16x16x32_bf16 v[16:19], v[184:187], v[200:203], v[16:19]
	v_mfma_f32_16x16x32_bf16 v[12:15], v[176:179], v[208:211], v[12:15]
	v_mfma_f32_16x16x32_bf16 v[8:11], v[184:187], v[208:211], v[8:11]
	v_mfma_f32_16x16x32_bf16 v[4:7], v[176:179], v[218:221], v[4:7]
	v_mfma_f32_16x16x32_bf16 v[0:3], v[184:187], v[218:221], v[0:3]
	s_setprio 0
	s_barrier
; #define LDA(dst, b, h) for (int m = 0; m < 4; ++m) for (int k = 0; k < 2; ++k) \
;     dst[m][k] = *reinterpret_cast<const bf16x8*>((char*)SA(b, h) + lds_byte(wr * 64 + m * 16 + fr, k * 32 + fq * 8))
; #define LDB(dst, b, h) for (int n = 0; n < 2; ++n) for (int k = 0; k < 2; ++k) \
;     dst[n][k] = *reinterpret_cast<const bf16x8*>((char*)SB(b, h) + lds_byte(wc * 32 + n * 16 + fr, k * 32 + fq * 8))
; #define MMA(ai, bj, At, Bt_) do { __builtin_amdgcn_s_setprio(1); \
;     for (int m = 0; m < 4; ++m) for (int n = 0; n < 2; ++n) for (int k = 0; k < 2; ++k) \
;       acc[ai][bj][m][n] = __builtin_amdgcn_mfma_f32_16x16x32_bf16(Bt_[n][k], At[m][k], acc[ai][bj][m][n], 0, 0, 0); \
;     __builtin_amdgcn_s_setprio(0); } while (0)
; #define WAIT_V(n) asm volatile("s_waitcnt vmcnt(" #n ")" ::: "memory")
; #define WAIT_L(n) asm volatile("s_waitcnt lgkmcnt(" #n ")" ::: "memory")
; #define BAR __builtin_amdgcn_s_barrier()
; #define SCHED __builtin_amdgcn_sched_barrier(0)
; template <int MODE>
; DI void gemm_phase(const bf16_t* __restrict__ A, const bf16_t* __restrict__ Bt, int M, int N, int K, const Epi& ep) {
;     ...
;             LDB(B0, 1, 0); LDB(B1, 1, 1); SCHED; LDA(At, 1, 0); STAGE(SA(0, 1), rsA, brow + HALF, t + 2);
;             WAIT_V(8); WAIT_L(0); BAR; MMA(0, 0, At, B0); MMA(0, 1, At, B1); BAR; SCHED;
;             LDA(At, 1, 1); STAGE(SB(1, 0), rsB, bcol, t + 3); STAGE(SB(1, 1), rsB, bcol + HALF, t + 3); STAGE(SA(1, 0), rsA, brow, t + 3);
;             WAIT_V(8); WAIT_L(0); BAR; MMA(1, 0, At, B0); MMA(1, 1, At, B1); BAR; SCHED;
	ds_read_b128 v[156:159], v153
	ds_read_b128 v[160:163], v153 offset:1024
	ds_read_b128 v[164:167], v153 offset:2048
	ds_read_b128 v[168:171], v153 offset:3072
	ds_read_b128 v[172:175], v154
	ds_read_b128 v[176:179], v154 offset:1024
	ds_read_b128 v[180:183], v154 offset:2048
	ds_read_b128 v[184:187], v154 offset:3072
	v_readfirstlane_b32 s43, v136
	s_add_i32 s42, s40, 0xb0100
	s_mov_b32 m0, s43
	v_readfirstlane_b32 s43, v137
	ds_read_b128 v[188:191], v149 offset:32768
	ds_read_b128 v[192:195], v149 offset:33792
	ds_read_b128 v[196:199], v150 offset:32768
	ds_read_b128 v[200:203], v150 offset:33792
	ds_read_b128 v[204:207], v151 offset:32768
	ds_read_b128 v[208:211], v151 offset:33792
	ds_read_b128 v[214:217], v152 offset:32768
	ds_read_b128 v[218:221], v152 offset:33792
	buffer_load_dwordx4 v128, s[28:31], s42 offen lds
	s_mov_b32 m0, s43
	s_nop 0
	buffer_load_dwordx4 v129, s[28:31], s42 offen lds
	s_waitcnt vmcnt(8)
	s_waitcnt lgkmcnt(0)
	s_barrier
	s_setprio 1
	v_mfma_f32_16x16x32_bf16 v[124:127], v[156:159], v[188:191], v[124:127]
	v_mfma_f32_16x16x32_bf16 v[120:123], v[164:167], v[188:191], v[120:123]
	v_mfma_f32_16x16x32_bf16 v[116:119], v[156:159], v[196:199], v[116:119]
	v_mfma_f32_16x16x32_bf16 v[112:115], v[164:167], v[196:199], v[112:115]
	v_mfma_f32_16x16x32_bf16 v[108:111], v[156:159], v[204:207], v[108:111]
	v_mfma_f32_16x16x32_bf16 v[104:107], v[164:167], v[204:207], v[104:107]
	v_mfma_f32_16x16x32_bf16 v[100:103], v[156:159], v[214:217], v[100:103]
	v_mfma_f32_16x16x32_bf16 v[96:99], v[164:167], v[214:217], v[96:99]
	v_mfma_f32_16x16x32_bf16 v[124:127], v[160:163], v[192:195], v[124:127]
	v_mfma_f32_16x16x32_bf16 v[120:123], v[168:171], v[192:195], v[120:123]
	v_mfma_f32_16x16x32_bf16 v[116:119], v[160:163], v[200:203], v[116:119]
	v_mfma_f32_16x16x32_bf16 v[112:115], v[168:171], v[200:203], v[112:115]
	v_mfma_f32_16x16x32_bf16 v[108:111], v[160:163], v[208:211], v[108:111]
	v_mfma_f32_16x16x32_bf16 v[104:107], v[168:171], v[208:211], v[104:107]
	v_mfma_f32_16x16x32_bf16 v[100:103], v[160:163], v[218:221], v[100:103]
	v_mfma_f32_16x16x32_bf16 v[96:99], v[168:171], v[218:221], v[96:99]
	s_setprio 0
	s_setprio 1
	v_mfma_f32_16x16x32_bf16 v[92:95], v[172:175], v[188:191], v[92:95]
	v_mfma_f32_16x16x32_bf16 v[88:91], v[180:183], v[188:191], v[88:91]
	v_mfma_f32_16x16x32_bf16 v[84:87], v[172:175], v[196:199], v[84:87]
	v_mfma_f32_16x16x32_bf16 v[80:83], v[180:183], v[196:199], v[80:83]
	v_mfma_f32_16x16x32_bf16 v[76:79], v[172:175], v[204:207], v[76:79]
	v_mfma_f32_16x16x32_bf16 v[72:75], v[180:183], v[204:207], v[72:75]
	v_mfma_f32_16x16x32_bf16 v[68:71], v[172:175], v[214:217], v[68:71]
	v_mfma_f32_16x16x32_bf16 v[64:67], v[180:183], v[214:217], v[64:67]
	v_mfma_f32_16x16x32_bf16 v[92:95], v[176:179], v[192:195], v[92:95]
	v_mfma_f32_16x16x32_bf16 v[88:91], v[184:187], v[192:195], v[88:91]
	v_mfma_f32_16x16x32_bf16 v[84:87], v[176:179], v[200:203], v[84:87]
	v_mfma_f32_16x16x32_bf16 v[80:83], v[184:187], v[200:203], v[80:83]
	v_mfma_f32_16x16x32_bf16 v[76:79], v[176:179], v[208:211], v[76:79]
	v_mfma_f32_16x16x32_bf16 v[72:75], v[184:187], v[208:211], v[72:75]
	v_mfma_f32_16x16x32_bf16 v[68:71], v[176:179], v[218:221], v[68:71]
	v_mfma_f32_16x16x32_bf16 v[64:67], v[184:187], v[218:221], v[64:67]
	s_setprio 0
	s_barrier
	v_readfirstlane_b32 s43, v138
	s_add_i32 s42, s41, 0x180
	s_mov_b32 m0, s43
	v_readfirstlane_b32 s43, v139
	ds_read_b128 v[188:191], v149 offset:49152
	ds_read_b128 v[192:195], v149 offset:50176
	ds_read_b128 v[196:199], v150 offset:49152
	ds_read_b128 v[200:203], v150 offset:50176
	ds_read_b128 v[204:207], v151 offset:49152
	ds_read_b128 v[208:211], v151 offset:50176
	ds_read_b128 v[214:217], v152 offset:49152
	ds_read_b128 v[218:221], v152 offset:50176
	buffer_load_dwordx4 v128, s[68:71], s42 offen lds
	s_mov_b32 m0, s43
	s_add_i32 s41, s41, 0xb0180
	buffer_load_dwordx4 v129, s[68:71], s42 offen lds
	v_readfirstlane_b32 s42, v142
	s_mov_b32 m0, s42
	v_readfirstlane_b32 s42, v143
	buffer_load_dwordx4 v128, s[68:71], s41 offen lds
	s_mov_b32 m0, s42
	s_addk_i32 s40, 0x180
	buffer_load_dwordx4 v129, s[68:71], s41 offen lds
	v_readfirstlane_b32 s41, v140
	s_mov_b32 m0, s41
	v_readfirstlane_b32 s41, v141
	buffer_load_dwordx4 v128, s[28:31], s40 offen lds
	s_mov_b32 m0, s41
	s_nop 0
	buffer_load_dwordx4 v129, s[28:31], s40 offen lds
	s_waitcnt vmcnt(8)
	s_waitcnt lgkmcnt(0)
	s_barrier
	s_setprio 1
	v_mfma_f32_16x16x32_bf16 v[60:63], v[156:159], v[188:191], v[60:63]
	v_mfma_f32_16x16x32_bf16 v[56:59], v[164:167], v[188:191], v[56:59]
	v_mfma_f32_16x16x32_bf16 v[52:55], v[156:159], v[196:199], v[52:55]
	v_mfma_f32_16x16x32_bf16 v[48:51], v[164:167], v[196:199], v[48:51]
	v_mfma_f32_16x16x32_bf16 v[44:47], v[156:159], v[204:207], v[44:47]
	v_mfma_f32_16x16x32_bf16 v[40:43], v[164:167], v[204:207], v[40:43]
	v_mfma_f32_16x16x32_bf16 v[36:39], v[156:159], v[214:217], v[36:39]
	v_mfma_f32_16x16x32_bf16 v[32:35], v[164:167], v[214:217], v[32:35]
	v_mfma_f32_16x16x32_bf16 v[60:63], v[160:163], v[192:195], v[60:63]
	v_mfma_f32_16x16x32_bf16 v[56:59], v[168:171], v[192:195], v[56:59]
	v_mfma_f32_16x16x32_bf16 v[52:55], v[160:163], v[200:203], v[52:55]
	v_mfma_f32_16x16x32_bf16 v[48:51], v[168:171], v[200:203], v[48:51]
	v_mfma_f32_16x16x32_bf16 v[44:47], v[160:163], v[208:211], v[44:47]
	v_mfma_f32_16x16x32_bf16 v[40:43], v[168:171], v[208:211], v[40:43]
	v_mfma_f32_16x16x32_bf16 v[36:39], v[160:163], v[218:221], v[36:39]
	v_mfma_f32_16x16x32_bf16 v[32:35], v[168:171], v[218:221], v[32:35]
	s_setprio 0
	s_setprio 1
	v_mfma_f32_16x16x32_bf16 v[28:31], v[172:175], v[188:191], v[28:31]
	v_mfma_f32_16x16x32_bf16 v[24:27], v[180:183], v[188:191], v[24:27]
	v_mfma_f32_16x16x32_bf16 v[20:23], v[172:175], v[196:199], v[20:23]
	v_mfma_f32_16x16x32_bf16 v[16:19], v[180:183], v[196:199], v[16:19]
	v_mfma_f32_16x16x32_bf16 v[12:15], v[172:175], v[204:207], v[12:15]
	v_mfma_f32_16x16x32_bf16 v[8:11], v[180:183], v[204:207], v[8:11]
	v_mfma_f32_16x16x32_bf16 v[4:7], v[172:175], v[214:217], v[4:7]
	v_mfma_f32_16x16x32_bf16 v[0:3], v[180:183], v[214:217], v[0:3]
	v_mfma_f32_16x16x32_bf16 v[28:31], v[176:179], v[192:195], v[28:31]
	v_mfma_f32_16x16x32_bf16 v[24:27], v[184:187], v[192:195], v[24:27]
	v_mfma_f32_16x16x32_bf16 v[20:23], v[176:179], v[200:203], v[20:23]
	v_mfma_f32_16x16x32_bf16 v[16:19], v[184:187], v[200:203], v[16:19]
	v_mfma_f32_16x16x32_bf16 v[12:15], v[176:179], v[208:211], v[12:15]
	v_mfma_f32_16x16x32_bf16 v[8:11], v[184:187], v[208:211], v[8:11]
	v_mfma_f32_16x16x32_bf16 v[4:7], v[176:179], v[218:221], v[4:7]
	v_mfma_f32_16x16x32_bf16 v[0:3], v[184:187], v[218:221], v[0:3]
	s_setprio 0
	s_barrier
; #define LDA(dst, b, h) for (int m = 0; m < 4; ++m) for (int k = 0; k < 2; ++k) \
;     dst[m][k] = *reinterpret_cast<const bf16x8*>((char*)SA(b, h) + lds_byte(wr * 64 + m * 16 + fr, k * 32 + fq * 8))
; #define LDB(dst, b, h) for (int n = 0; n < 2; ++n) for (int k = 0; k < 2; ++k) \
;     dst[n][k] = *reinterpret_cast<const bf16x8*>((char*)SB(b, h) + lds_byte(wc * 32 + n * 16 + fr, k * 32 + fq * 8))
; #define MMA(ai, bj, At, Bt_) do { __builtin_amdgcn_s_setprio(1); \
;     for (int m = 0; m < 4; ++m) for (int n = 0; n < 2; ++n) for (int k = 0; k < 2; ++k) \
;       acc[ai][bj][m][n] = __builtin_amdgcn_mfma_f32_16x16x32_bf16(Bt_[n][k], At[m][k], acc[ai][bj][m][n], 0, 0, 0); \
;     __builtin_amdgcn_s_setprio(0); } while (0)
; #define WAIT_V(n) asm volatile("s_waitcnt vmcnt(" #n ")" ::: "memory")
; #define WAIT_L(n) asm volatile("s_waitcnt lgkmcnt(" #n ")" ::: "memory")
; #define BAR __builtin_amdgcn_s_barrier()
; #define SCHED __builtin_amdgcn_sched_barrier(0)
; template <int MODE>
; DI void gemm_phase(const bf16_t* __restrict__ A, const bf16_t* __restrict__ Bt, int M, int N, int K, const Epi& ep) {
;     ...
;             WAIT_V(8); WAIT_L(0); BAR; MMA(0, 0, At, B0); MMA(0, 1, At, B1); BAR; SCHED;
;             LDA(At, 0, 1); STAGE(SB(0, 0), rsB, bcol, t + 2); STAGE(SB(0, 1), rsB, bcol + HALF, t + 2); STAGE(SA(0, 0), rsA, brow, t + 2);
;             WAIT_V(8); WAIT_L(0); BAR; MMA(1, 0, At, B0); MMA(1, 1, At, B1); BAR; SCHED;
;             LDB(B0, 1, 0); LDB(B1, 1, 1); SCHED; LDA(At, 1, 0); STAGE(SA(0, 1), rsA, brow + HALF, t + 2);
;             WAIT_V(8); WAIT_L(0); BAR; MMA(0, 0, At, B0); MMA(0, 1, At, B1); BAR; SCHED;
;             LDA(At, 1, 1); STAGE(SB(1, 0), rsB, bcol, t + 3); STAGE(SB(1, 1), rsB, bcol + HALF, t + 3); STAGE(SA(1, 0), rsA, brow, t + 3);
;             WAIT_V(8); WAIT_L(0); BAR; MMA(1, 0, At, B0); MMA(1, 1, At, B1); BAR; SCHED;
;         }
;         {
;             LDB(B0, 0, 0); LDB(B1, 0, 1); SCHED; LDA(At, 0, 0); STAGE(SA(1, 1), rsA, brow + HALF, nt - 1);
;             WAIT_V(8); WAIT_L(0); BAR; MMA(0, 0, At, B0); MMA(0, 1, At, B1); BAR; SCHED;
;             LDA(At, 0, 1);
;             WAIT_V(2); WAIT_L(0); BAR; MMA(1, 0, At, B0); MMA(1, 1, At, B1); BAR; SCHED;
	s_add_i32 s7, s7, 2
	s_addk_i32 s27, 0x100
	s_cmp_gt_u32 s7, 39
	s_cbranch_scc0 .LBB0_1452
	ds_read_b128 v[156:159], v147
	ds_read_b128 v[160:163], v147 offset:1024
	ds_read_b128 v[164:167], v147 offset:2048
	ds_read_b128 v[168:171], v147 offset:3072
	ds_read_b128 v[172:175], v148
	ds_read_b128 v[176:179], v148 offset:1024
	ds_read_b128 v[180:183], v148 offset:2048
	ds_read_b128 v[184:187], v148 offset:3072
	v_readfirstlane_b32 s7, v144
	s_or_b32 s6, s26, 0x1580
	s_mov_b32 m0, s7
	v_readfirstlane_b32 s7, v145
	ds_read_b128 v[188:191], v149
	ds_read_b128 v[192:195], v149 offset:1024
	ds_read_b128 v[196:199], v150
	ds_read_b128 v[200:203], v150 offset:1024
	ds_read_b128 v[204:207], v151
	ds_read_b128 v[208:211], v151 offset:1024
	ds_read_b128 v[214:217], v152
	ds_read_b128 v[218:221], v152 offset:1024
	buffer_load_dwordx4 v128, s[28:31], s6 offen lds
	s_mov_b32 m0, s7
	s_nop 0
	buffer_load_dwordx4 v129, s[28:31], s6 offen lds
	s_waitcnt vmcnt(8)
	s_waitcnt lgkmcnt(0)
	s_barrier
	s_setprio 1
	v_mfma_f32_16x16x32_bf16 v[124:127], v[156:159], v[188:191], v[124:127]
	v_mfma_f32_16x16x32_bf16 v[120:123], v[164:167], v[188:191], v[120:123]
	v_mfma_f32_16x16x32_bf16 v[116:119], v[156:159], v[196:199], v[116:119]
	v_mfma_f32_16x16x32_bf16 v[112:115], v[164:167], v[196:199], v[112:115]
	v_mfma_f32_16x16x32_bf16 v[108:111], v[156:159], v[204:207], v[108:111]
	v_mfma_f32_16x16x32_bf16 v[124:127], v[160:163], v[192:195], v[124:127]
	v_mfma_f32_16x16x32_bf16 v[120:123], v[168:171], v[192:195], v[120:123]
	v_mfma_f32_16x16x32_bf16 v[116:119], v[160:163], v[200:203], v[116:119]
	v_mfma_f32_16x16x32_bf16 v[112:115], v[168:171], v[200:203], v[112:115]
	v_mfma_f32_16x16x32_bf16 v[222:225], v[160:163], v[208:211], v[108:111]
	v_mfma_f32_16x16x32_bf16 v[104:107], v[164:167], v[204:207], v[104:107]
	v_mfma_f32_16x16x32_bf16 v[100:103], v[156:159], v[214:217], v[100:103]
	v_mfma_f32_16x16x32_bf16 v[96:99], v[164:167], v[214:217], v[96:99]
	v_mfma_f32_16x16x32_bf16 v[226:229], v[168:171], v[208:211], v[104:107]
	v_mfma_f32_16x16x32_bf16 v[230:233], v[160:163], v[218:221], v[100:103]
	v_mfma_f32_16x16x32_bf16 v[234:237], v[168:171], v[218:221], v[96:99]
	s_setprio 0
	s_setprio 1
	v_mfma_f32_16x16x32_bf16 v[92:95], v[172:175], v[188:191], v[92:95]
	v_mfma_f32_16x16x32_bf16 v[88:91], v[180:183], v[188:191], v[88:91]
	v_mfma_f32_16x16x32_bf16 v[84:87], v[172:175], v[196:199], v[84:87]
	v_mfma_f32_16x16x32_bf16 v[80:83], v[180:183], v[196:199], v[80:83]
	v_mfma_f32_16x16x32_bf16 v[92:95], v[176:179], v[192:195], v[92:95]
	v_mfma_f32_16x16x32_bf16 v[88:91], v[184:187], v[192:195], v[88:91]
	v_mfma_f32_16x16x32_bf16 v[84:87], v[176:179], v[200:203], v[84:87]
	v_mfma_f32_16x16x32_bf16 v[80:83], v[184:187], v[200:203], v[80:83]
	v_mfma_f32_16x16x32_bf16 v[76:79], v[172:175], v[204:207], v[76:79]
	v_mfma_f32_16x16x32_bf16 v[72:75], v[180:183], v[204:207], v[72:75]
	v_mfma_f32_16x16x32_bf16 v[68:71], v[172:175], v[214:217], v[68:71]
	v_mfma_f32_16x16x32_bf16 v[64:67], v[180:183], v[214:217], v[64:67]
	v_mfma_f32_16x16x32_bf16 v[188:191], v[176:179], v[208:211], v[76:79]
	v_mfma_f32_16x16x32_bf16 v[192:195], v[184:187], v[208:211], v[72:75]
	v_mfma_f32_16x16x32_bf16 v[196:199], v[176:179], v[218:221], v[68:71]
	v_mfma_f32_16x16x32_bf16 v[200:203], v[184:187], v[218:221], v[64:67]
	s_setprio 0
	s_barrier
	s_nop 1
	ds_read_b128 v[64:67], v149 offset:16384
	ds_read_b128 v[68:71], v149 offset:17408
	ds_read_b128 v[72:75], v150 offset:16384
	ds_read_b128 v[76:79], v150 offset:17408
	ds_read_b128 v[96:99], v151 offset:16384
	ds_read_b128 v[100:103], v151 offset:17408
	ds_read_b128 v[104:107], v152 offset:16384
	ds_read_b128 v[108:111], v152 offset:17408
	s_waitcnt vmcnt(2)
	s_waitcnt lgkmcnt(0)
	s_barrier
	s_setprio 1
	v_mfma_f32_16x16x32_bf16 v[60:63], v[156:159], v[64:67], v[60:63]
	v_mfma_f32_16x16x32_bf16 v[56:59], v[164:167], v[64:67], v[56:59]
	v_mfma_f32_16x16x32_bf16 v[52:55], v[156:159], v[72:75], v[52:55]
	v_mfma_f32_16x16x32_bf16 v[48:51], v[164:167], v[72:75], v[48:51]
	v_mfma_f32_16x16x32_bf16 v[60:63], v[160:163], v[68:71], v[60:63]
	v_mfma_f32_16x16x32_bf16 v[56:59], v[168:171], v[68:71], v[56:59]
	v_mfma_f32_16x16x32_bf16 v[52:55], v[160:163], v[76:79], v[52:55]
	v_mfma_f32_16x16x32_bf16 v[48:51], v[168:171], v[76:79], v[48:51]
	v_mfma_f32_16x16x32_bf16 v[44:47], v[156:159], v[96:99], v[44:47]
	v_mfma_f32_16x16x32_bf16 v[40:43], v[164:167], v[96:99], v[40:43]
	v_mfma_f32_16x16x32_bf16 v[36:39], v[156:159], v[104:107], v[36:39]
	v_mfma_f32_16x16x32_bf16 v[32:35], v[164:167], v[104:107], v[32:35]
	v_mfma_f32_16x16x32_bf16 v[204:207], v[160:163], v[100:103], v[44:47]
	v_mfma_f32_16x16x32_bf16 v[208:211], v[168:171], v[100:103], v[40:43]
	v_mfma_f32_16x16x32_bf16 v[156:159], v[160:163], v[108:111], v[36:39]
	v_mfma_f32_16x16x32_bf16 v[160:163], v[168:171], v[108:111], v[32:35]
	s_setprio 0
	s_setprio 1
	v_mfma_f32_16x16x32_bf16 v[28:31], v[172:175], v[64:67], v[28:31]
	v_mfma_f32_16x16x32_bf16 v[24:27], v[180:183], v[64:67], v[24:27]
	v_mfma_f32_16x16x32_bf16 v[20:23], v[172:175], v[72:75], v[20:23]
	v_mfma_f32_16x16x32_bf16 v[16:19], v[180:183], v[72:75], v[16:19]
	v_mfma_f32_16x16x32_bf16 v[28:31], v[176:179], v[68:71], v[28:31]
	v_mfma_f32_16x16x32_bf16 v[24:27], v[184:187], v[68:71], v[24:27]
	v_mfma_f32_16x16x32_bf16 v[20:23], v[176:179], v[76:79], v[20:23]
	v_mfma_f32_16x16x32_bf16 v[16:19], v[184:187], v[76:79], v[16:19]
	v_mfma_f32_16x16x32_bf16 v[12:15], v[172:175], v[96:99], v[12:15]
	v_mfma_f32_16x16x32_bf16 v[8:11], v[180:183], v[96:99], v[8:11]
	v_mfma_f32_16x16x32_bf16 v[4:7], v[172:175], v[104:107], v[4:7]
	v_mfma_f32_16x16x32_bf16 v[0:3], v[180:183], v[104:107], v[0:3]
	v_mfma_f32_16x16x32_bf16 v[164:167], v[176:179], v[100:103], v[12:15]
	v_mfma_f32_16x16x32_bf16 v[168:171], v[184:187], v[100:103], v[8:11]
	v_mfma_f32_16x16x32_bf16 v[172:175], v[176:179], v[108:111], v[4:7]
	v_mfma_f32_16x16x32_bf16 v[176:179], v[184:187], v[108:111], v[0:3]
	s_setprio 0
	s_barrier
; #define LDA(dst, b, h) for (int m = 0; m < 4; ++m) for (int k = 0; k < 2; ++k) \
;     dst[m][k] = *reinterpret_cast<const bf16x8*>((char*)SA(b, h) + lds_byte(wr * 64 + m * 16 + fr, k * 32 + fq * 8))
; #define LDB(dst, b, h) for (int n = 0; n < 2; ++n) for (int k = 0; k < 2; ++k) \
;     dst[n][k] = *reinterpret_cast<const bf16x8*>((char*)SB(b, h) + lds_byte(wc * 32 + n * 16 + fr, k * 32 + fq * 8))
; #define MMA(ai, bj, At, Bt_) do { __builtin_amdgcn_s_setprio(1); \
;     for (int m = 0; m < 4; ++m) for (int n = 0; n < 2; ++n) for (int k = 0; k < 2; ++k) \
;       acc[ai][bj][m][n] = __builtin_amdgcn_mfma_f32_16x16x32_bf16(Bt_[n][k], At[m][k], acc[ai][bj][m][n], 0, 0, 0); \
;     __builtin_amdgcn_s_setprio(0); } while (0)
; #define WAIT_V(n) asm volatile("s_waitcnt vmcnt(" #n ")" ::: "memory")
; #define WAIT_L(n) asm volatile("s_waitcnt lgkmcnt(" #n ")" ::: "memory")
; #define BAR __builtin_amdgcn_s_barrier()
; #define SCHED __builtin_amdgcn_sched_barrier(0)
; template <int MODE>
; DI void gemm_phase(const bf16_t* __restrict__ A, const bf16_t* __restrict__ Bt, int M, int N, int K, const Epi& ep) {
;     ...
;             LDB(B0, 1, 0); LDB(B1, 1, 1); SCHED; LDA(At, 1, 0);
;             WAIT_V(0); WAIT_L(0); BAR; MMA(0, 0, At, B0); MMA(0, 1, At, B1); BAR; SCHED;
;             LDA(At, 1, 1);
;             WAIT_L(0); BAR; MMA(1, 0, At, B0); MMA(1, 1, At, B1); BAR; SCHED;
;         }
;         if (wr == 0) BAR;
	s_nop 1
	ds_read_b128 v[0:3], v153
	ds_read_b128 v[4:7], v153 offset:1024
	ds_read_b128 v[8:11], v153 offset:2048
	ds_read_b128 v[12:15], v153 offset:3072
	ds_read_b128 v[180:183], v154
	ds_read_b128 v[184:187], v154 offset:1024
	ds_read_b128 v[214:217], v154 offset:2048
	ds_read_b128 v[218:221], v154 offset:3072
	ds_read_b128 v[32:35], v149 offset:32768
	ds_read_b128 v[36:39], v149 offset:33792
	ds_read_b128 v[40:43], v150 offset:32768
	ds_read_b128 v[44:47], v150 offset:33792
	ds_read_b128 v[238:241], v151 offset:32768
	ds_read_b128 v[242:245], v151 offset:33792
	ds_read_b128 v[246:249], v152 offset:32768
	ds_read_b128 v[64:67], v152 offset:33792
	s_waitcnt vmcnt(0)
	s_waitcnt lgkmcnt(0)
	s_barrier
	s_setprio 1
	v_mfma_f32_16x16x32_bf16 v[68:71], v[0:3], v[32:35], v[124:127]
	v_mfma_f32_16x16x32_bf16 v[96:99], v[4:7], v[36:39], v[68:71]
	v_mfma_f32_16x16x32_bf16 v[68:71], v[8:11], v[32:35], v[120:123]
	v_mfma_f32_16x16x32_bf16 v[100:103], v[12:15], v[36:39], v[68:71]
	v_mfma_f32_16x16x32_bf16 v[68:71], v[0:3], v[40:43], v[116:119]
	v_mfma_f32_16x16x32_bf16 v[104:107], v[4:7], v[44:47], v[68:71]
	v_mfma_f32_16x16x32_bf16 v[68:71], v[8:11], v[40:43], v[112:115]
	v_mfma_f32_16x16x32_bf16 v[108:111], v[12:15], v[44:47], v[68:71]
	v_mfma_f32_16x16x32_bf16 v[68:71], v[0:3], v[238:241], v[222:225]
	v_mfma_f32_16x16x32_bf16 v[112:115], v[4:7], v[242:245], v[68:71]
	v_mfma_f32_16x16x32_bf16 v[68:71], v[8:11], v[238:241], v[226:229]
	v_mfma_f32_16x16x32_bf16 v[116:119], v[12:15], v[242:245], v[68:71]
	v_mfma_f32_16x16x32_bf16 v[68:71], v[0:3], v[246:249], v[230:233]
	v_mfma_f32_16x16x32_bf16 v[120:123], v[4:7], v[64:67], v[68:71]
	v_mfma_f32_16x16x32_bf16 v[68:71], v[8:11], v[246:249], v[234:237]
	v_mfma_f32_16x16x32_bf16 v[124:127], v[12:15], v[64:67], v[68:71]
	s_setprio 0
	s_setprio 1
	v_mfma_f32_16x16x32_bf16 v[68:71], v[180:183], v[32:35], v[92:95]
	v_mfma_f32_16x16x32_bf16 v[32:35], v[214:217], v[32:35], v[88:91]
	v_mfma_f32_16x16x32_bf16 v[222:225], v[184:187], v[36:39], v[68:71]
	v_mfma_f32_16x16x32_bf16 v[68:71], v[218:221], v[36:39], v[32:35]
	v_mfma_f32_16x16x32_bf16 v[32:35], v[180:183], v[40:43], v[84:87]
	v_mfma_f32_16x16x32_bf16 v[72:75], v[184:187], v[44:47], v[32:35]
	v_mfma_f32_16x16x32_bf16 v[32:35], v[214:217], v[40:43], v[80:83]
	v_mfma_f32_16x16x32_bf16 v[76:79], v[218:221], v[44:47], v[32:35]
	v_mfma_f32_16x16x32_bf16 v[32:35], v[180:183], v[238:241], v[188:191]
	v_mfma_f32_16x16x32_bf16 v[80:83], v[184:187], v[242:245], v[32:35]
	v_mfma_f32_16x16x32_bf16 v[32:35], v[214:217], v[238:241], v[192:195]
	v_mfma_f32_16x16x32_bf16 v[84:87], v[218:221], v[242:245], v[32:35]
	v_mfma_f32_16x16x32_bf16 v[32:35], v[180:183], v[246:249], v[196:199]
	v_mfma_f32_16x16x32_bf16 v[88:91], v[184:187], v[64:67], v[32:35]
	v_mfma_f32_16x16x32_bf16 v[32:35], v[214:217], v[246:249], v[200:203]
	v_mfma_f32_16x16x32_bf16 v[92:95], v[218:221], v[64:67], v[32:35]
	s_setprio 0
	s_barrier
	ds_read_b128 v[64:67], v149 offset:49152
	ds_read_b128 v[188:191], v149 offset:50176
	ds_read_b128 v[192:195], v150 offset:49152
	ds_read_b128 v[196:199], v150 offset:50176
	ds_read_b128 v[200:203], v151 offset:49152
	ds_read_b128 v[226:229], v151 offset:50176
	ds_read_b128 v[230:233], v152 offset:49152
	ds_read_b128 v[234:237], v152 offset:50176
	s_waitcnt lgkmcnt(0)
	s_barrier
	s_setprio 1
	v_mfma_f32_16x16x32_bf16 v[32:35], v[0:3], v[64:67], v[60:63]
	v_mfma_f32_16x16x32_bf16 v[40:43], v[0:3], v[192:195], v[52:55]
	v_mfma_f32_16x16x32_bf16 v[44:47], v[8:11], v[192:195], v[48:51]
	v_mfma_f32_16x16x32_bf16 v[48:51], v[0:3], v[200:203], v[204:207]
	v_mfma_f32_16x16x32_bf16 v[0:3], v[0:3], v[230:233], v[156:159]
	v_mfma_f32_16x16x32_bf16 v[36:39], v[8:11], v[64:67], v[56:59]
	v_mfma_f32_16x16x32_bf16 v[52:55], v[8:11], v[200:203], v[208:211]
	v_mfma_f32_16x16x32_bf16 v[56:59], v[4:7], v[234:237], v[0:3]
	v_mfma_f32_16x16x32_bf16 v[0:3], v[8:11], v[230:233], v[160:163]
	v_mfma_f32_16x16x32_bf16 v[32:35], v[4:7], v[188:191], v[32:35]
	v_mfma_f32_16x16x32_bf16 v[36:39], v[12:15], v[188:191], v[36:39]
	v_mfma_f32_16x16x32_bf16 v[40:43], v[4:7], v[196:199], v[40:43]
	v_mfma_f32_16x16x32_bf16 v[44:47], v[12:15], v[196:199], v[44:47]
	v_mfma_f32_16x16x32_bf16 v[48:51], v[4:7], v[226:229], v[48:51]
	v_mfma_f32_16x16x32_bf16 v[52:55], v[12:15], v[226:229], v[52:55]
	v_mfma_f32_16x16x32_bf16 v[60:63], v[12:15], v[234:237], v[0:3]
	s_setprio 0
	s_setprio 1
	v_mfma_f32_16x16x32_bf16 v[0:3], v[180:183], v[64:67], v[28:31]
	v_mfma_f32_16x16x32_bf16 v[4:7], v[214:217], v[64:67], v[24:27]
	v_mfma_f32_16x16x32_bf16 v[8:11], v[180:183], v[192:195], v[20:23]
	v_mfma_f32_16x16x32_bf16 v[12:15], v[214:217], v[192:195], v[16:19]
	v_mfma_f32_16x16x32_bf16 v[16:19], v[180:183], v[200:203], v[164:167]
	v_mfma_f32_16x16x32_bf16 v[20:23], v[214:217], v[200:203], v[168:171]
	v_mfma_f32_16x16x32_bf16 v[24:27], v[180:183], v[230:233], v[172:175]
	v_mfma_f32_16x16x32_bf16 v[28:31], v[214:217], v[230:233], v[176:179]
	v_mfma_f32_16x16x32_bf16 v[0:3], v[184:187], v[188:191], v[0:3]
	v_mfma_f32_16x16x32_bf16 v[4:7], v[218:221], v[188:191], v[4:7]
	v_mfma_f32_16x16x32_bf16 v[8:11], v[184:187], v[196:199], v[8:11]
	v_mfma_f32_16x16x32_bf16 v[12:15], v[218:221], v[196:199], v[12:15]
	v_mfma_f32_16x16x32_bf16 v[16:19], v[184:187], v[226:229], v[16:19]
	v_mfma_f32_16x16x32_bf16 v[20:23], v[218:221], v[226:229], v[20:23]
	v_mfma_f32_16x16x32_bf16 v[24:27], v[184:187], v[234:237], v[24:27]
	v_mfma_f32_16x16x32_bf16 v[28:31], v[218:221], v[234:237], v[28:31]
	s_setprio 0
	s_barrier
	s_and_saveexec_b64 s[6:7], s[38:39]
	s_cbranch_execz .LBB0_1444
	s_barrier
	s_branch .LBB0_1444
